# speedup vs baseline: 1.0372x; 1.0359x over previous
; __device__ __forceinline__ void gemm_phase(const Ctx& cx, const GemmArgs& g_, char* shm) {
;     ...
;     for (int bj = 0; bj < 2; ++bj)
; #pragma unroll
;       for (int n = 0; n < 2; ++n) {
;         const int tok = bcol + bj * 128 + wc * 32 + n * 16 + fr;
;         float ssq = 0.f;
;         float rs = 1.f;
;         if ((g.epi == EPI_PROJ || g.epi == EPI_RELU2) && g.gate != nullptr)
;           rs = rsqrtf(((const float*)g.gate)[tok] * (1.0f / DM) + 1e-6f);
; #pragma unroll
;         for (int ai = 0; ai < 2; ++ai) {
;           uint2 pend = make_uint2(0u, 0u);
;     ...
; #pragma unroll
;           for (int m = 0; m < 4; ++m) {
;             const int n0 = brow + ai * 128 + wr * 64 + m * 16 + fq * 4;
;             f32x4 a = acc[ai][bj][m][n];
;             if (g.epi == EPI_PROJ || g.epi == EPI_RELU2) { a[0] *= rs; a[1] *= rs; a[2] *= rs; a[3] *= rs; }
;             if (g.epi == EPI_PROJ) {
;               if (n0 >= C_GLAX) {
;                 const int i = n0 - C_GLAX;
;                 const float4 b4 = *(const float4*)(g.hin + i);
;                 float xs[4] = {a[0] + b4.x, a[1] + b4.y, a[2] + b4.z, a[3] + b4.w};
; #pragma unroll
;                 for (int j = 0; j < 4; ++j)
;                   xs[j] = (fminf(xs[j], 0.f) - __logf(1.0f + __expf(-fabsf(xs[j])))) * (1.0f / 16.0f);
;                 *(float4*)(g.f32buf + (size_t)tok * 1024 + i) = make_float4(xs[0], xs[1], xs[2], xs[3]);
;               } else {
;                 float o0 = a[0], o1 = a[1], o2 = a[2], o3 = a[3];
;                 const bool r128 = (n0 >= C_DSAQ && n0 < C_HGQ) || (n0 >= C_DSAK && n0 < C_DSAV);
;                 const bool r64 = (n0 >= C_IDXQ && n0 < C_GLAA);
;                 if (r128 || r64) {
;                   float4 cs;
;                   float sc;
;                   if (r128) {
;                     cs = *(const float4*)(g.w + ((size_t)tok * 64 + ((n0 & 127) >> 1)) * 2);
;                     sc = (n0 < C_HGQ) ? 0.08838834764831845f : 1.0f;
;                   } else {
;                     cs = *(const float4*)(g.hout + ((size_t)tok * 32 + ((n0 & 63) >> 1)) * 2);
;                     sc = (n0 < C_IDXK) ? 0.125f : 1.0f;
;                   }
;                   o0 = (a[0] * cs.x - a[1] * cs.y) * sc; o1 = (a[1] * cs.x + a[0] * cs.y) * sc;
;                   o2 = (a[2] * cs.z - a[3] * cs.w) * sc; o3 = (a[3] * cs.z + a[2] * cs.w) * sc;
;                 }
.LBB0_248:
	s_cmp_eq_u32 s38, 5
	s_cbranch_scc1 .Lmy_fast_relu
	s_cmp_lg_u32 s38, 0
	s_cbranch_scc1 .Lmy_slow_epi
	s_cmpk_lt_u32 s2, 0x1800
	s_cbranch_scc1 .Lmy_fast_proj
	s_cmpk_lt_u32 s2, 0x2000
	s_cbranch_scc1 .Lmy_slow_epi
	s_cmpk_lt_u32 s2, 0x5800
	s_cbranch_scc1 .Lmy_fast_proj
	s_branch .Lmy_slow_epi
.Lmy_fast_proj:
	v_or_b32_e32 v194, s4, v168
	v_add_u32_e32 v186, s2, v169
	v_add_u32_e32 v186, v186, v170
	v_ashrrev_i32_e32 v187, 31, v186
	v_mad_i64_i32 v[184:185], s[6:7], v194, s39, 0
	v_lshl_add_u64 v[184:185], v[184:185], 1, s[20:21]
	v_lshl_add_u64 v[184:185], v[186:187], 1, v[184:185]
	s_lshl_b32 s8, s39, 5
	s_mov_b32 s9, 0
	s_lshl_b32 s10, s39, 8
	s_mov_b32 s11, 0
	s_lshl_b32 s6, s39, 4
	s_sub_i32 s6, 64, s6
	v_and_b32_e32 v192, 8, v168
	v_cmp_ne_u32_e32 vcc, 0, v192
	v_mov_b32_e32 v193, s6
	s_nop 1
	v_cndmask_b32_e32 v192, 0, v193, vcc
	v_cndmask_b32_e64 v193, 0, -1, vcc
	v_lshl_add_u64 v[184:185], v[184:185], 0, v[192:193]
	s_lshl_b32 s6, s39, 4
	s_mov_b32 s7, 0
	v_mov_b32_e32 v198, 1.0
	v_mov_b32_e32 v199, 1.0
	v_mov_b32_e32 v200, 1.0
	v_mov_b32_e32 v201, 1.0
	s_andn2_b64 vcc, exec, s[40:41]
	s_cbranch_vccnz .Lmy_nors_proj
	v_ashrrev_i32_e32 v195, 31, v194
	v_lshl_add_u64 v[196:197], v[194:195], 2, s[22:23]
	global_load_dword v198, v[196:197], off
	global_load_dword v199, v[196:197], off offset:64
	global_load_dword v200, v[196:197], off offset:512
	global_load_dword v201, v[196:197], off offset:576
	v_mov_b32_e32 v187, 0x358637bd
	s_waitcnt vmcnt(0)
	v_fmamk_f32 v198, v198, 0x3a000000, v187
	v_mul_f32_e32 v186, 0x4b800000, v198
	v_cmp_gt_f32_e32 vcc, 0x800000, v198
	s_nop 1
	v_cndmask_b32_e32 v198, v198, v186, vcc
	v_rsq_f32_e32 v198, v198
	s_nop 0
	v_mul_f32_e32 v186, 0x45800000, v198
	v_cndmask_b32_e32 v198, v198, v186, vcc
	v_fmamk_f32 v199, v199, 0x3a000000, v187
	v_mul_f32_e32 v186, 0x4b800000, v199
	v_cmp_gt_f32_e32 vcc, 0x800000, v199
	s_nop 1
	v_cndmask_b32_e32 v199, v199, v186, vcc
	v_rsq_f32_e32 v199, v199
	s_nop 0
	v_mul_f32_e32 v186, 0x45800000, v199
	v_cndmask_b32_e32 v199, v199, v186, vcc
	v_fmamk_f32 v200, v200, 0x3a000000, v187
	v_mul_f32_e32 v186, 0x4b800000, v200
	v_cmp_gt_f32_e32 vcc, 0x800000, v200
	s_nop 1
	v_cndmask_b32_e32 v200, v200, v186, vcc
	v_rsq_f32_e32 v200, v200
	s_nop 0
	v_mul_f32_e32 v186, 0x45800000, v200
	v_cndmask_b32_e32 v200, v200, v186, vcc
	v_fmamk_f32 v201, v201, 0x3a000000, v187
	v_mul_f32_e32 v186, 0x4b800000, v201
	v_cmp_gt_f32_e32 vcc, 0x800000, v201
	s_nop 1
	v_cndmask_b32_e32 v201, v201, v186, vcc
	v_rsq_f32_e32 v201, v201
	s_nop 0
	v_mul_f32_e32 v186, 0x45800000, v201
	v_cndmask_b32_e32 v201, v201, v186, vcc
.Lmy_nors_proj:
	v_mov_b32_e32 v188, v184
	v_mov_b32_e32 v189, v185
	v_lshl_add_u64 v[190:191], v[188:189], 0, s[6:7]
	v_mov_b32_e32 v186, v198
	v_pk_mul_f32 v[128:129], v[128:129], v[186:187] op_sel_hi:[1,0]
	v_pk_mul_f32 v[130:131], v[130:131], v[186:187] op_sel_hi:[1,0]
	v_pk_mul_f32 v[124:125], v[124:125], v[186:187] op_sel_hi:[1,0]
	v_pk_mul_f32 v[126:127], v[126:127], v[186:187] op_sel_hi:[1,0]
	v_cvt_pk_bf16_f32 v204, v128, v129
	v_cvt_pk_bf16_f32 v205, v130, v131
	v_cvt_pk_bf16_f32 v206, v124, v125
	v_cvt_pk_bf16_f32 v207, v126, v127
	s_nop 1
	v_permlane16_swap_b32_e32 v204, v206
	v_permlane16_swap_b32_e32 v205, v207
	v_pk_mul_f32 v[120:121], v[120:121], v[186:187] op_sel_hi:[1,0]
	v_pk_mul_f32 v[122:123], v[122:123], v[186:187] op_sel_hi:[1,0]
	v_pk_mul_f32 v[116:117], v[116:117], v[186:187] op_sel_hi:[1,0]
	v_pk_mul_f32 v[118:119], v[118:119], v[186:187] op_sel_hi:[1,0]
	v_cvt_pk_bf16_f32 v208, v120, v121
	v_cvt_pk_bf16_f32 v209, v122, v123
	v_cvt_pk_bf16_f32 v210, v116, v117
	v_cvt_pk_bf16_f32 v211, v118, v119
	s_nop 1
	v_permlane16_swap_b32_e32 v208, v210
	v_permlane16_swap_b32_e32 v209, v211
	v_mov_b32_e32 v220, v208
	v_mov_b32_e32 v221, v209
	v_mov_b32_e32 v222, v210
	v_mov_b32_e32 v223, v211
	v_mov_b32_dpp v208, v204 row_ror:8 row_mask:0xf bank_mask:0x3
	v_mov_b32_dpp v209, v205 row_ror:8 row_mask:0xf bank_mask:0x3
	v_mov_b32_dpp v210, v206 row_ror:8 row_mask:0xf bank_mask:0x3
	v_mov_b32_dpp v211, v207 row_ror:8 row_mask:0xf bank_mask:0x3
	v_mov_b32_dpp v204, v220 row_ror:8 row_mask:0xf bank_mask:0xc
	v_mov_b32_dpp v205, v221 row_ror:8 row_mask:0xf bank_mask:0xc
	v_mov_b32_dpp v206, v222 row_ror:8 row_mask:0xf bank_mask:0xc
	v_mov_b32_dpp v207, v223 row_ror:8 row_mask:0xf bank_mask:0xc
	global_store_dwordx4 v[188:189], v[204:207], off offset:32
	global_store_dwordx4 v[190:191], v[208:211], off offset:32
	v_pk_mul_f32 v[112:113], v[112:113], v[186:187] op_sel_hi:[1,0]
	v_pk_mul_f32 v[114:115], v[114:115], v[186:187] op_sel_hi:[1,0]
	v_pk_mul_f32 v[108:109], v[108:109], v[186:187] op_sel_hi:[1,0]
	v_pk_mul_f32 v[110:111], v[110:111], v[186:187] op_sel_hi:[1,0]
	v_cvt_pk_bf16_f32 v212, v112, v113
	v_cvt_pk_bf16_f32 v213, v114, v115
	v_cvt_pk_bf16_f32 v214, v108, v109
	v_cvt_pk_bf16_f32 v215, v110, v111
	s_nop 1
	v_permlane16_swap_b32_e32 v212, v214
	v_permlane16_swap_b32_e32 v213, v215
	v_pk_mul_f32 v[104:105], v[104:105], v[186:187] op_sel_hi:[1,0]
	v_pk_mul_f32 v[106:107], v[106:107], v[186:187] op_sel_hi:[1,0]
	v_pk_mul_f32 v[100:101], v[100:101], v[186:187] op_sel_hi:[1,0]
	v_pk_mul_f32 v[102:103], v[102:103], v[186:187] op_sel_hi:[1,0]
	v_cvt_pk_bf16_f32 v216, v104, v105
	v_cvt_pk_bf16_f32 v217, v106, v107
	v_cvt_pk_bf16_f32 v218, v100, v101
	v_cvt_pk_bf16_f32 v219, v102, v103
	s_nop 1
	v_permlane16_swap_b32_e32 v216, v218
	v_permlane16_swap_b32_e32 v217, v219
	v_mov_b32_e32 v220, v216
	v_mov_b32_e32 v221, v217
	v_mov_b32_e32 v222, v218
	v_mov_b32_e32 v223, v219
	v_mov_b32_dpp v216, v212 row_ror:8 row_mask:0xf bank_mask:0x3
; __device__ __forceinline__ void gemm_phase(const Ctx& cx, const GemmArgs& g_, char* shm) {
;     ...
; #pragma unroll
;           for (int m = 0; m < 4; ++m) {
;             const int n0 = brow + ai * 128 + wr * 64 + m * 16 + fq * 4;
;             f32x4 a = acc[ai][bj][m][n];
;             if (g.epi == EPI_PROJ || g.epi == EPI_RELU2) { a[0] *= rs; a[1] *= rs; a[2] *= rs; a[3] *= rs; }
;             if (g.epi == EPI_PROJ) {
;               if (n0 >= C_GLAX) {
;                 const int i = n0 - C_GLAX;
;                 const float4 b4 = *(const float4*)(g.hin + i);
;                 float xs[4] = {a[0] + b4.x, a[1] + b4.y, a[2] + b4.z, a[3] + b4.w};
; #pragma unroll
;                 for (int j = 0; j < 4; ++j)
;                   xs[j] = (fminf(xs[j], 0.f) - __logf(1.0f + __expf(-fabsf(xs[j])))) * (1.0f / 16.0f);
;                 *(float4*)(g.f32buf + (size_t)tok * 1024 + i) = make_float4(xs[0], xs[1], xs[2], xs[3]);
;               } else {
;                 float o0 = a[0], o1 = a[1], o2 = a[2], o3 = a[3];
;                 const bool r128 = (n0 >= C_DSAQ && n0 < C_HGQ) || (n0 >= C_DSAK && n0 < C_DSAV);
;                 const bool r64 = (n0 >= C_IDXQ && n0 < C_GLAA);
;                 if (r128 || r64) {
;                   float4 cs;
;                   float sc;
;                   if (r128) {
;                     cs = *(const float4*)(g.w + ((size_t)tok * 64 + ((n0 & 127) >> 1)) * 2);
;                     sc = (n0 < C_HGQ) ? 0.08838834764831845f : 1.0f;
;                   } else {
;                     cs = *(const float4*)(g.hout + ((size_t)tok * 32 + ((n0 & 63) >> 1)) * 2);
;                     sc = (n0 < C_IDXK) ? 0.125f : 1.0f;
;                   }
;                   o0 = (a[0] * cs.x - a[1] * cs.y) * sc; o1 = (a[1] * cs.x + a[0] * cs.y) * sc;
;                   o2 = (a[2] * cs.z - a[3] * cs.w) * sc; o3 = (a[3] * cs.z + a[2] * cs.w) * sc;
;                 }
;                 uint2 o; o.x = pack2(o0, o1); o.y = pack2(o2, o3);
;                 EMIT_BF16(g.ldo, o);
	v_mov_b32_dpp v217, v213 row_ror:8 row_mask:0xf bank_mask:0x3
	v_mov_b32_dpp v218, v214 row_ror:8 row_mask:0xf bank_mask:0x3
	v_mov_b32_dpp v219, v215 row_ror:8 row_mask:0xf bank_mask:0x3
	v_mov_b32_dpp v212, v220 row_ror:8 row_mask:0xf bank_mask:0xc
	v_mov_b32_dpp v213, v221 row_ror:8 row_mask:0xf bank_mask:0xc
	v_mov_b32_dpp v214, v222 row_ror:8 row_mask:0xf bank_mask:0xc
	v_mov_b32_dpp v215, v223 row_ror:8 row_mask:0xf bank_mask:0xc
	global_store_dwordx4 v[188:189], v[212:215], off offset:288
	global_store_dwordx4 v[190:191], v[216:219], off offset:288
	v_lshl_add_u64 v[188:189], v[184:185], 0, s[8:9]
	v_lshl_add_u64 v[190:191], v[188:189], 0, s[6:7]
	v_mov_b32_e32 v186, v199
	v_pk_mul_f32 v[96:97], v[96:97], v[186:187] op_sel_hi:[1,0]
	v_pk_mul_f32 v[98:99], v[98:99], v[186:187] op_sel_hi:[1,0]
	v_pk_mul_f32 v[92:93], v[92:93], v[186:187] op_sel_hi:[1,0]
	v_pk_mul_f32 v[94:95], v[94:95], v[186:187] op_sel_hi:[1,0]
	v_cvt_pk_bf16_f32 v224, v96, v97
	v_cvt_pk_bf16_f32 v225, v98, v99
	v_cvt_pk_bf16_f32 v226, v92, v93
	v_cvt_pk_bf16_f32 v227, v94, v95
	s_nop 1
	v_permlane16_swap_b32_e32 v224, v226
	v_permlane16_swap_b32_e32 v225, v227
	v_pk_mul_f32 v[88:89], v[88:89], v[186:187] op_sel_hi:[1,0]
	v_pk_mul_f32 v[90:91], v[90:91], v[186:187] op_sel_hi:[1,0]
	v_pk_mul_f32 v[84:85], v[84:85], v[186:187] op_sel_hi:[1,0]
	v_pk_mul_f32 v[86:87], v[86:87], v[186:187] op_sel_hi:[1,0]
	v_cvt_pk_bf16_f32 v228, v88, v89
	v_cvt_pk_bf16_f32 v229, v90, v91
	v_cvt_pk_bf16_f32 v230, v84, v85
	v_cvt_pk_bf16_f32 v231, v86, v87
	s_nop 1
	v_permlane16_swap_b32_e32 v228, v230
	v_permlane16_swap_b32_e32 v229, v231
	v_mov_b32_e32 v220, v228
	v_mov_b32_e32 v221, v229
	v_mov_b32_e32 v222, v230
	v_mov_b32_e32 v223, v231
	v_mov_b32_dpp v228, v224 row_ror:8 row_mask:0xf bank_mask:0x3
	v_mov_b32_dpp v229, v225 row_ror:8 row_mask:0xf bank_mask:0x3
	v_mov_b32_dpp v230, v226 row_ror:8 row_mask:0xf bank_mask:0x3
	v_mov_b32_dpp v231, v227 row_ror:8 row_mask:0xf bank_mask:0x3
	v_mov_b32_dpp v224, v220 row_ror:8 row_mask:0xf bank_mask:0xc
	v_mov_b32_dpp v225, v221 row_ror:8 row_mask:0xf bank_mask:0xc
	v_mov_b32_dpp v226, v222 row_ror:8 row_mask:0xf bank_mask:0xc
	v_mov_b32_dpp v227, v223 row_ror:8 row_mask:0xf bank_mask:0xc
	global_store_dwordx4 v[188:189], v[224:227], off offset:32
	global_store_dwordx4 v[190:191], v[228:231], off offset:32
	v_pk_mul_f32 v[80:81], v[80:81], v[186:187] op_sel_hi:[1,0]
	v_pk_mul_f32 v[82:83], v[82:83], v[186:187] op_sel_hi:[1,0]
	v_pk_mul_f32 v[76:77], v[76:77], v[186:187] op_sel_hi:[1,0]
	v_pk_mul_f32 v[78:79], v[78:79], v[186:187] op_sel_hi:[1,0]
	v_cvt_pk_bf16_f32 v232, v80, v81
	v_cvt_pk_bf16_f32 v233, v82, v83
	v_cvt_pk_bf16_f32 v234, v76, v77
	v_cvt_pk_bf16_f32 v235, v78, v79
	s_nop 1
	v_permlane16_swap_b32_e32 v232, v234
	v_permlane16_swap_b32_e32 v233, v235
	v_pk_mul_f32 v[72:73], v[72:73], v[186:187] op_sel_hi:[1,0]
	v_pk_mul_f32 v[74:75], v[74:75], v[186:187] op_sel_hi:[1,0]
	v_pk_mul_f32 v[68:69], v[68:69], v[186:187] op_sel_hi:[1,0]
	v_pk_mul_f32 v[70:71], v[70:71], v[186:187] op_sel_hi:[1,0]
	v_cvt_pk_bf16_f32 v236, v72, v73
	v_cvt_pk_bf16_f32 v237, v74, v75
	v_cvt_pk_bf16_f32 v238, v68, v69
	v_cvt_pk_bf16_f32 v239, v70, v71
	s_nop 1
	v_permlane16_swap_b32_e32 v236, v238
	v_permlane16_swap_b32_e32 v237, v239
	v_mov_b32_e32 v220, v236
	v_mov_b32_e32 v221, v237
	v_mov_b32_e32 v222, v238
	v_mov_b32_e32 v223, v239
	v_mov_b32_dpp v236, v232 row_ror:8 row_mask:0xf bank_mask:0x3
	v_mov_b32_dpp v237, v233 row_ror:8 row_mask:0xf bank_mask:0x3
	v_mov_b32_dpp v238, v234 row_ror:8 row_mask:0xf bank_mask:0x3
	v_mov_b32_dpp v239, v235 row_ror:8 row_mask:0xf bank_mask:0x3
	v_mov_b32_dpp v232, v220 row_ror:8 row_mask:0xf bank_mask:0xc
	v_mov_b32_dpp v233, v221 row_ror:8 row_mask:0xf bank_mask:0xc
	v_mov_b32_dpp v234, v222 row_ror:8 row_mask:0xf bank_mask:0xc
	v_mov_b32_dpp v235, v223 row_ror:8 row_mask:0xf bank_mask:0xc
	global_store_dwordx4 v[188:189], v[232:235], off offset:288
	global_store_dwordx4 v[190:191], v[236:239], off offset:288
	v_lshl_add_u64 v[188:189], v[184:185], 0, s[10:11]
	v_lshl_add_u64 v[190:191], v[188:189], 0, s[6:7]
	v_mov_b32_e32 v186, v200
	v_pk_mul_f32 v[64:65], v[64:65], v[186:187] op_sel_hi:[1,0]
	v_pk_mul_f32 v[66:67], v[66:67], v[186:187] op_sel_hi:[1,0]
	v_pk_mul_f32 v[60:61], v[60:61], v[186:187] op_sel_hi:[1,0]
	v_pk_mul_f32 v[62:63], v[62:63], v[186:187] op_sel_hi:[1,0]
	v_cvt_pk_bf16_f32 v204, v64, v65
	v_cvt_pk_bf16_f32 v205, v66, v67
	v_cvt_pk_bf16_f32 v206, v60, v61
	v_cvt_pk_bf16_f32 v207, v62, v63
	s_nop 1
	v_permlane16_swap_b32_e32 v204, v206
	v_permlane16_swap_b32_e32 v205, v207
	v_pk_mul_f32 v[56:57], v[56:57], v[186:187] op_sel_hi:[1,0]
	v_pk_mul_f32 v[58:59], v[58:59], v[186:187] op_sel_hi:[1,0]
	v_pk_mul_f32 v[52:53], v[52:53], v[186:187] op_sel_hi:[1,0]
	v_pk_mul_f32 v[54:55], v[54:55], v[186:187] op_sel_hi:[1,0]
	v_cvt_pk_bf16_f32 v208, v56, v57
	v_cvt_pk_bf16_f32 v209, v58, v59
	v_cvt_pk_bf16_f32 v210, v52, v53
	v_cvt_pk_bf16_f32 v211, v54, v55
	s_nop 1
	v_permlane16_swap_b32_e32 v208, v210
	v_permlane16_swap_b32_e32 v209, v211
	v_mov_b32_e32 v220, v208
	v_mov_b32_e32 v221, v209
	v_mov_b32_e32 v222, v210
	v_mov_b32_e32 v223, v211
	v_mov_b32_dpp v208, v204 row_ror:8 row_mask:0xf bank_mask:0x3
	v_mov_b32_dpp v209, v205 row_ror:8 row_mask:0xf bank_mask:0x3
	v_mov_b32_dpp v210, v206 row_ror:8 row_mask:0xf bank_mask:0x3
	v_mov_b32_dpp v211, v207 row_ror:8 row_mask:0xf bank_mask:0x3
	v_mov_b32_dpp v204, v220 row_ror:8 row_mask:0xf bank_mask:0xc
; __device__ __forceinline__ void gemm_phase(const Ctx& cx, const GemmArgs& g_, char* shm) {
;     ...
; #pragma unroll
;           for (int m = 0; m < 4; ++m) {
;             const int n0 = brow + ai * 128 + wr * 64 + m * 16 + fq * 4;
;             f32x4 a = acc[ai][bj][m][n];
;             if (g.epi == EPI_PROJ || g.epi == EPI_RELU2) { a[0] *= rs; a[1] *= rs; a[2] *= rs; a[3] *= rs; }
;             if (g.epi == EPI_PROJ) {
;               if (n0 >= C_GLAX) {
;                 const int i = n0 - C_GLAX;
;                 const float4 b4 = *(const float4*)(g.hin + i);
;                 float xs[4] = {a[0] + b4.x, a[1] + b4.y, a[2] + b4.z, a[3] + b4.w};
; #pragma unroll
;                 for (int j = 0; j < 4; ++j)
;                   xs[j] = (fminf(xs[j], 0.f) - __logf(1.0f + __expf(-fabsf(xs[j])))) * (1.0f / 16.0f);
;                 *(float4*)(g.f32buf + (size_t)tok * 1024 + i) = make_float4(xs[0], xs[1], xs[2], xs[3]);
;               } else {
;                 float o0 = a[0], o1 = a[1], o2 = a[2], o3 = a[3];
;                 const bool r128 = (n0 >= C_DSAQ && n0 < C_HGQ) || (n0 >= C_DSAK && n0 < C_DSAV);
;                 const bool r64 = (n0 >= C_IDXQ && n0 < C_GLAA);
;                 if (r128 || r64) {
;                   float4 cs;
;                   float sc;
;                   if (r128) {
;                     cs = *(const float4*)(g.w + ((size_t)tok * 64 + ((n0 & 127) >> 1)) * 2);
;                     sc = (n0 < C_HGQ) ? 0.08838834764831845f : 1.0f;
;                   } else {
;                     cs = *(const float4*)(g.hout + ((size_t)tok * 32 + ((n0 & 63) >> 1)) * 2);
;                     sc = (n0 < C_IDXK) ? 0.125f : 1.0f;
;                   }
;                   o0 = (a[0] * cs.x - a[1] * cs.y) * sc; o1 = (a[1] * cs.x + a[0] * cs.y) * sc;
;                   o2 = (a[2] * cs.z - a[3] * cs.w) * sc; o3 = (a[3] * cs.z + a[2] * cs.w) * sc;
;                 }
;                 uint2 o; o.x = pack2(o0, o1); o.y = pack2(o2, o3);
;                 EMIT_BF16(g.ldo, o);
	v_mov_b32_dpp v205, v221 row_ror:8 row_mask:0xf bank_mask:0xc
	v_mov_b32_dpp v206, v222 row_ror:8 row_mask:0xf bank_mask:0xc
	v_mov_b32_dpp v207, v223 row_ror:8 row_mask:0xf bank_mask:0xc
	global_store_dwordx4 v[188:189], v[204:207], off offset:32
	global_store_dwordx4 v[190:191], v[208:211], off offset:32
	v_pk_mul_f32 v[48:49], v[48:49], v[186:187] op_sel_hi:[1,0]
	v_pk_mul_f32 v[50:51], v[50:51], v[186:187] op_sel_hi:[1,0]
	v_pk_mul_f32 v[44:45], v[44:45], v[186:187] op_sel_hi:[1,0]
	v_pk_mul_f32 v[46:47], v[46:47], v[186:187] op_sel_hi:[1,0]
	v_cvt_pk_bf16_f32 v212, v48, v49
	v_cvt_pk_bf16_f32 v213, v50, v51
	v_cvt_pk_bf16_f32 v214, v44, v45
	v_cvt_pk_bf16_f32 v215, v46, v47
	s_nop 1
	v_permlane16_swap_b32_e32 v212, v214
	v_permlane16_swap_b32_e32 v213, v215
	v_pk_mul_f32 v[40:41], v[40:41], v[186:187] op_sel_hi:[1,0]
	v_pk_mul_f32 v[42:43], v[42:43], v[186:187] op_sel_hi:[1,0]
	v_pk_mul_f32 v[36:37], v[36:37], v[186:187] op_sel_hi:[1,0]
	v_pk_mul_f32 v[38:39], v[38:39], v[186:187] op_sel_hi:[1,0]
	v_cvt_pk_bf16_f32 v216, v40, v41
	v_cvt_pk_bf16_f32 v217, v42, v43
	v_cvt_pk_bf16_f32 v218, v36, v37
	v_cvt_pk_bf16_f32 v219, v38, v39
	s_nop 1
	v_permlane16_swap_b32_e32 v216, v218
	v_permlane16_swap_b32_e32 v217, v219
	v_mov_b32_e32 v220, v216
	v_mov_b32_e32 v221, v217
	v_mov_b32_e32 v222, v218
	v_mov_b32_e32 v223, v219
	v_mov_b32_dpp v216, v212 row_ror:8 row_mask:0xf bank_mask:0x3
	v_mov_b32_dpp v217, v213 row_ror:8 row_mask:0xf bank_mask:0x3
	v_mov_b32_dpp v218, v214 row_ror:8 row_mask:0xf bank_mask:0x3
	v_mov_b32_dpp v219, v215 row_ror:8 row_mask:0xf bank_mask:0x3
	v_mov_b32_dpp v212, v220 row_ror:8 row_mask:0xf bank_mask:0xc
	v_mov_b32_dpp v213, v221 row_ror:8 row_mask:0xf bank_mask:0xc
	v_mov_b32_dpp v214, v222 row_ror:8 row_mask:0xf bank_mask:0xc
	v_mov_b32_dpp v215, v223 row_ror:8 row_mask:0xf bank_mask:0xc
	global_store_dwordx4 v[188:189], v[212:215], off offset:288
	global_store_dwordx4 v[190:191], v[216:219], off offset:288
	v_lshl_add_u64 v[188:189], v[184:185], 0, s[10:11]
	v_lshl_add_u64 v[188:189], v[188:189], 0, s[8:9]
	v_lshl_add_u64 v[190:191], v[188:189], 0, s[6:7]
	v_mov_b32_e32 v186, v201
	v_pk_mul_f32 v[32:33], v[32:33], v[186:187] op_sel_hi:[1,0]
	v_pk_mul_f32 v[34:35], v[34:35], v[186:187] op_sel_hi:[1,0]
	v_pk_mul_f32 v[28:29], v[28:29], v[186:187] op_sel_hi:[1,0]
	v_pk_mul_f32 v[30:31], v[30:31], v[186:187] op_sel_hi:[1,0]
	v_cvt_pk_bf16_f32 v224, v32, v33
	v_cvt_pk_bf16_f32 v225, v34, v35
	v_cvt_pk_bf16_f32 v226, v28, v29
	v_cvt_pk_bf16_f32 v227, v30, v31
	s_nop 1
	v_permlane16_swap_b32_e32 v224, v226
	v_permlane16_swap_b32_e32 v225, v227
	v_pk_mul_f32 v[24:25], v[24:25], v[186:187] op_sel_hi:[1,0]
	v_pk_mul_f32 v[26:27], v[26:27], v[186:187] op_sel_hi:[1,0]
	v_pk_mul_f32 v[20:21], v[20:21], v[186:187] op_sel_hi:[1,0]
	v_pk_mul_f32 v[22:23], v[22:23], v[186:187] op_sel_hi:[1,0]
	v_cvt_pk_bf16_f32 v228, v24, v25
	v_cvt_pk_bf16_f32 v229, v26, v27
	v_cvt_pk_bf16_f32 v230, v20, v21
	v_cvt_pk_bf16_f32 v231, v22, v23
	s_nop 1
	v_permlane16_swap_b32_e32 v228, v230
	v_permlane16_swap_b32_e32 v229, v231
	v_mov_b32_e32 v220, v228
	v_mov_b32_e32 v221, v229
	v_mov_b32_e32 v222, v230
	v_mov_b32_e32 v223, v231
	v_mov_b32_dpp v228, v224 row_ror:8 row_mask:0xf bank_mask:0x3
	v_mov_b32_dpp v229, v225 row_ror:8 row_mask:0xf bank_mask:0x3
	v_mov_b32_dpp v230, v226 row_ror:8 row_mask:0xf bank_mask:0x3
	v_mov_b32_dpp v231, v227 row_ror:8 row_mask:0xf bank_mask:0x3
	v_mov_b32_dpp v224, v220 row_ror:8 row_mask:0xf bank_mask:0xc
	v_mov_b32_dpp v225, v221 row_ror:8 row_mask:0xf bank_mask:0xc
	v_mov_b32_dpp v226, v222 row_ror:8 row_mask:0xf bank_mask:0xc
	v_mov_b32_dpp v227, v223 row_ror:8 row_mask:0xf bank_mask:0xc
	global_store_dwordx4 v[188:189], v[224:227], off offset:32
	global_store_dwordx4 v[190:191], v[228:231], off offset:32
	v_pk_mul_f32 v[16:17], v[16:17], v[186:187] op_sel_hi:[1,0]
	v_pk_mul_f32 v[18:19], v[18:19], v[186:187] op_sel_hi:[1,0]
	v_pk_mul_f32 v[12:13], v[12:13], v[186:187] op_sel_hi:[1,0]
	v_pk_mul_f32 v[14:15], v[14:15], v[186:187] op_sel_hi:[1,0]
	v_cvt_pk_bf16_f32 v232, v16, v17
	v_cvt_pk_bf16_f32 v233, v18, v19
	v_cvt_pk_bf16_f32 v234, v12, v13
	v_cvt_pk_bf16_f32 v235, v14, v15
	s_nop 1
	v_permlane16_swap_b32_e32 v232, v234
	v_permlane16_swap_b32_e32 v233, v235
	v_pk_mul_f32 v[8:9], v[8:9], v[186:187] op_sel_hi:[1,0]
	v_pk_mul_f32 v[10:11], v[10:11], v[186:187] op_sel_hi:[1,0]
	v_pk_mul_f32 v[4:5], v[4:5], v[186:187] op_sel_hi:[1,0]
	v_pk_mul_f32 v[6:7], v[6:7], v[186:187] op_sel_hi:[1,0]
	v_cvt_pk_bf16_f32 v236, v8, v9
	v_cvt_pk_bf16_f32 v237, v10, v11
	v_cvt_pk_bf16_f32 v238, v4, v5
	v_cvt_pk_bf16_f32 v239, v6, v7
	s_nop 1
	v_permlane16_swap_b32_e32 v236, v238
	v_permlane16_swap_b32_e32 v237, v239
	v_mov_b32_e32 v220, v236
	v_mov_b32_e32 v221, v237
	v_mov_b32_e32 v222, v238
	v_mov_b32_e32 v223, v239
	v_mov_b32_dpp v236, v232 row_ror:8 row_mask:0xf bank_mask:0x3
	v_mov_b32_dpp v237, v233 row_ror:8 row_mask:0xf bank_mask:0x3
	v_mov_b32_dpp v238, v234 row_ror:8 row_mask:0xf bank_mask:0x3
	v_mov_b32_dpp v239, v235 row_ror:8 row_mask:0xf bank_mask:0x3
	v_mov_b32_dpp v232, v220 row_ror:8 row_mask:0xf bank_mask:0xc
	v_mov_b32_dpp v233, v221 row_ror:8 row_mask:0xf bank_mask:0xc
	v_mov_b32_dpp v234, v222 row_ror:8 row_mask:0xf bank_mask:0xc
	v_mov_b32_dpp v235, v223 row_ror:8 row_mask:0xf bank_mask:0xc
	global_store_dwordx4 v[188:189], v[232:235], off offset:288
	global_store_dwordx4 v[190:191], v[236:239], off offset:288
	s_branch .LBB0_231

; __device__ __forceinline__ void gemm_phase(const Ctx& cx, const GemmArgs& g_, char* shm) {
;     ...
; #pragma unroll
;           for (int m = 0; m < 4; ++m) {
;             const int n0 = brow + ai * 128 + wr * 64 + m * 16 + fq * 4;
;             f32x4 a = acc[ai][bj][m][n];
;             if (g.epi == EPI_PROJ || g.epi == EPI_RELU2) { a[0] *= rs; a[1] *= rs; a[2] *= rs; a[3] *= rs; }
;             if (g.epi == EPI_PROJ) {
;               if (n0 >= C_GLAX) {
;                 const int i = n0 - C_GLAX;
;                 const float4 b4 = *(const float4*)(g.hin + i);
;                 float xs[4] = {a[0] + b4.x, a[1] + b4.y, a[2] + b4.z, a[3] + b4.w};
; #pragma unroll
;                 for (int j = 0; j < 4; ++j)
;                   xs[j] = (fminf(xs[j], 0.f) - __logf(1.0f + __expf(-fabsf(xs[j])))) * (1.0f / 16.0f);
;                 *(float4*)(g.f32buf + (size_t)tok * 1024 + i) = make_float4(xs[0], xs[1], xs[2], xs[3]);
;               } else {
;                 float o0 = a[0], o1 = a[1], o2 = a[2], o3 = a[3];
;                 const bool r128 = (n0 >= C_DSAQ && n0 < C_HGQ) || (n0 >= C_DSAK && n0 < C_DSAV);
;                 const bool r64 = (n0 >= C_IDXQ && n0 < C_GLAA);
;                 if (r128 || r64) {
;                   float4 cs;
;                   float sc;
;                   if (r128) {
;                     cs = *(const float4*)(g.w + ((size_t)tok * 64 + ((n0 & 127) >> 1)) * 2);
;                     sc = (n0 < C_HGQ) ? 0.08838834764831845f : 1.0f;
;                   } else {
;                     cs = *(const float4*)(g.hout + ((size_t)tok * 32 + ((n0 & 63) >> 1)) * 2);
;                     sc = (n0 < C_IDXK) ? 0.125f : 1.0f;
;                   }
;                   o0 = (a[0] * cs.x - a[1] * cs.y) * sc; o1 = (a[1] * cs.x + a[0] * cs.y) * sc;
;                   o2 = (a[2] * cs.z - a[3] * cs.w) * sc; o3 = (a[3] * cs.z + a[2] * cs.w) * sc;
;                 }
;                 uint2 o; o.x = pack2(o0, o1); o.y = pack2(o2, o3);
;                 EMIT_BF16(g.ldo, o);
;               }
;             } else if (g.epi == EPI_RELU2) {
;               float r0 = fmaxf(a[0], 0.f), r1 = fmaxf(a[1], 0.f), r2 = fmaxf(a[2], 0.f), r3 = fmaxf(a[3], 0.f);
;               uint2 o; o.x = pack2(r0 * r0, r1 * r1); o.y = pack2(r2 * r2, r3 * r3);
;               EMIT_BF16(g.ldo, o);
.Lmy_nors_relu:
	v_mov_b32_e32 v188, v184
	v_mov_b32_e32 v189, v185
	v_lshl_add_u64 v[190:191], v[188:189], 0, s[6:7]
	v_mov_b32_e32 v186, v198
	v_pk_mul_f32 v[128:129], v[128:129], v[186:187] op_sel_hi:[1,0]
	v_pk_mul_f32 v[130:131], v[130:131], v[186:187] op_sel_hi:[1,0]
	v_pk_mul_f32 v[124:125], v[124:125], v[186:187] op_sel_hi:[1,0]
	v_pk_mul_f32 v[126:127], v[126:127], v[186:187] op_sel_hi:[1,0]
	v_max_f32_e32 v128, v128, v128
	v_max_f32_e32 v128, 0, v128
	v_max_f32_e32 v129, v129, v129
	v_max_f32_e32 v129, 0, v129
	v_max_f32_e32 v130, v130, v130
	v_max_f32_e32 v130, 0, v130
	v_max_f32_e32 v131, v131, v131
	v_max_f32_e32 v131, 0, v131
	v_max_f32_e32 v124, v124, v124
	v_max_f32_e32 v124, 0, v124
	v_max_f32_e32 v125, v125, v125
	v_max_f32_e32 v125, 0, v125
	v_max_f32_e32 v126, v126, v126
	v_max_f32_e32 v126, 0, v126
	v_max_f32_e32 v127, v127, v127
	v_max_f32_e32 v127, 0, v127
	v_pk_mul_f32 v[128:129], v[128:129], v[128:129]
	v_pk_mul_f32 v[130:131], v[130:131], v[130:131]
	v_pk_mul_f32 v[124:125], v[124:125], v[124:125]
	v_pk_mul_f32 v[126:127], v[126:127], v[126:127]
	v_cvt_pk_bf16_f32 v204, v128, v129
	v_cvt_pk_bf16_f32 v205, v130, v131
	v_cvt_pk_bf16_f32 v206, v124, v125
	v_cvt_pk_bf16_f32 v207, v126, v127
	s_nop 1
	v_permlane16_swap_b32_e32 v204, v206
	v_permlane16_swap_b32_e32 v205, v207
	v_pk_mul_f32 v[120:121], v[120:121], v[186:187] op_sel_hi:[1,0]
	v_pk_mul_f32 v[122:123], v[122:123], v[186:187] op_sel_hi:[1,0]
	v_pk_mul_f32 v[116:117], v[116:117], v[186:187] op_sel_hi:[1,0]
	v_pk_mul_f32 v[118:119], v[118:119], v[186:187] op_sel_hi:[1,0]
	v_max_f32_e32 v120, v120, v120
	v_max_f32_e32 v120, 0, v120
	v_max_f32_e32 v121, v121, v121
	v_max_f32_e32 v121, 0, v121
	v_max_f32_e32 v122, v122, v122
	v_max_f32_e32 v122, 0, v122
	v_max_f32_e32 v123, v123, v123
	v_max_f32_e32 v123, 0, v123
	v_max_f32_e32 v116, v116, v116
	v_max_f32_e32 v116, 0, v116
	v_max_f32_e32 v117, v117, v117
	v_max_f32_e32 v117, 0, v117
	v_max_f32_e32 v118, v118, v118
	v_max_f32_e32 v118, 0, v118
	v_max_f32_e32 v119, v119, v119
	v_max_f32_e32 v119, 0, v119
	v_pk_mul_f32 v[120:121], v[120:121], v[120:121]
	v_pk_mul_f32 v[122:123], v[122:123], v[122:123]
	v_pk_mul_f32 v[116:117], v[116:117], v[116:117]
	v_pk_mul_f32 v[118:119], v[118:119], v[118:119]
	v_cvt_pk_bf16_f32 v208, v120, v121
	v_cvt_pk_bf16_f32 v209, v122, v123
	v_cvt_pk_bf16_f32 v210, v116, v117
	v_cvt_pk_bf16_f32 v211, v118, v119
	s_nop 1
	v_permlane16_swap_b32_e32 v208, v210
	v_permlane16_swap_b32_e32 v209, v211
	v_mov_b32_e32 v220, v208
	v_mov_b32_e32 v221, v209
	v_mov_b32_e32 v222, v210
	v_mov_b32_e32 v223, v211
	v_mov_b32_dpp v208, v204 row_ror:8 row_mask:0xf bank_mask:0x3
	v_mov_b32_dpp v209, v205 row_ror:8 row_mask:0xf bank_mask:0x3
	v_mov_b32_dpp v210, v206 row_ror:8 row_mask:0xf bank_mask:0x3
	v_mov_b32_dpp v211, v207 row_ror:8 row_mask:0xf bank_mask:0x3
	v_mov_b32_dpp v204, v220 row_ror:8 row_mask:0xf bank_mask:0xc
	v_mov_b32_dpp v205, v221 row_ror:8 row_mask:0xf bank_mask:0xc
	v_mov_b32_dpp v206, v222 row_ror:8 row_mask:0xf bank_mask:0xc
	v_mov_b32_dpp v207, v223 row_ror:8 row_mask:0xf bank_mask:0xc
	global_store_dwordx4 v[188:189], v[204:207], off offset:32
	global_store_dwordx4 v[190:191], v[208:211], off offset:32
	v_pk_mul_f32 v[112:113], v[112:113], v[186:187] op_sel_hi:[1,0]
	v_pk_mul_f32 v[114:115], v[114:115], v[186:187] op_sel_hi:[1,0]
	v_pk_mul_f32 v[108:109], v[108:109], v[186:187] op_sel_hi:[1,0]
	v_pk_mul_f32 v[110:111], v[110:111], v[186:187] op_sel_hi:[1,0]
	v_max_f32_e32 v112, v112, v112
	v_max_f32_e32 v112, 0, v112
	v_max_f32_e32 v113, v113, v113
	v_max_f32_e32 v113, 0, v113
	v_max_f32_e32 v114, v114, v114
	v_max_f32_e32 v114, 0, v114
	v_max_f32_e32 v115, v115, v115
	v_max_f32_e32 v115, 0, v115
	v_max_f32_e32 v108, v108, v108
	v_max_f32_e32 v108, 0, v108
	v_max_f32_e32 v109, v109, v109
	v_max_f32_e32 v109, 0, v109
	v_max_f32_e32 v110, v110, v110
	v_max_f32_e32 v110, 0, v110
	v_max_f32_e32 v111, v111, v111
	v_max_f32_e32 v111, 0, v111
	v_pk_mul_f32 v[112:113], v[112:113], v[112:113]
	v_pk_mul_f32 v[114:115], v[114:115], v[114:115]
	v_pk_mul_f32 v[108:109], v[108:109], v[108:109]
	v_pk_mul_f32 v[110:111], v[110:111], v[110:111]
	v_cvt_pk_bf16_f32 v212, v112, v113
	v_cvt_pk_bf16_f32 v213, v114, v115
	v_cvt_pk_bf16_f32 v214, v108, v109
	v_cvt_pk_bf16_f32 v215, v110, v111
	s_nop 1
	v_permlane16_swap_b32_e32 v212, v214
	v_permlane16_swap_b32_e32 v213, v215
	v_pk_mul_f32 v[104:105], v[104:105], v[186:187] op_sel_hi:[1,0]
	v_pk_mul_f32 v[106:107], v[106:107], v[186:187] op_sel_hi:[1,0]
	v_pk_mul_f32 v[100:101], v[100:101], v[186:187] op_sel_hi:[1,0]
	v_pk_mul_f32 v[102:103], v[102:103], v[186:187] op_sel_hi:[1,0]
	v_max_f32_e32 v104, v104, v104
	v_max_f32_e32 v104, 0, v104
	v_max_f32_e32 v105, v105, v105
	v_max_f32_e32 v105, 0, v105
	v_max_f32_e32 v106, v106, v106
	v_max_f32_e32 v106, 0, v106
	v_max_f32_e32 v107, v107, v107
	v_max_f32_e32 v107, 0, v107
	v_max_f32_e32 v100, v100, v100
	v_max_f32_e32 v100, 0, v100
	v_max_f32_e32 v101, v101, v101
	v_max_f32_e32 v101, 0, v101
	v_max_f32_e32 v102, v102, v102
	v_max_f32_e32 v102, 0, v102
	v_max_f32_e32 v103, v103, v103
	v_max_f32_e32 v103, 0, v103
	v_pk_mul_f32 v[104:105], v[104:105], v[104:105]
	v_pk_mul_f32 v[106:107], v[106:107], v[106:107]
	v_pk_mul_f32 v[100:101], v[100:101], v[100:101]
	v_pk_mul_f32 v[102:103], v[102:103], v[102:103]
	v_cvt_pk_bf16_f32 v216, v104, v105
	v_cvt_pk_bf16_f32 v217, v106, v107
	v_cvt_pk_bf16_f32 v218, v100, v101
	v_cvt_pk_bf16_f32 v219, v102, v103
	s_nop 1
	v_permlane16_swap_b32_e32 v216, v218
	v_permlane16_swap_b32_e32 v217, v219
	v_mov_b32_e32 v220, v216
	v_mov_b32_e32 v221, v217
	v_mov_b32_e32 v222, v218
; __device__ __forceinline__ void gemm_phase(const Ctx& cx, const GemmArgs& g_, char* shm) {
;     ...
; #pragma unroll
;           for (int m = 0; m < 4; ++m) {
;             const int n0 = brow + ai * 128 + wr * 64 + m * 16 + fq * 4;
;             f32x4 a = acc[ai][bj][m][n];
;             if (g.epi == EPI_PROJ || g.epi == EPI_RELU2) { a[0] *= rs; a[1] *= rs; a[2] *= rs; a[3] *= rs; }
;             if (g.epi == EPI_PROJ) {
;               if (n0 >= C_GLAX) {
;                 const int i = n0 - C_GLAX;
;                 const float4 b4 = *(const float4*)(g.hin + i);
;                 float xs[4] = {a[0] + b4.x, a[1] + b4.y, a[2] + b4.z, a[3] + b4.w};
; #pragma unroll
;                 for (int j = 0; j < 4; ++j)
;                   xs[j] = (fminf(xs[j], 0.f) - __logf(1.0f + __expf(-fabsf(xs[j])))) * (1.0f / 16.0f);
;                 *(float4*)(g.f32buf + (size_t)tok * 1024 + i) = make_float4(xs[0], xs[1], xs[2], xs[3]);
;               } else {
;                 float o0 = a[0], o1 = a[1], o2 = a[2], o3 = a[3];
;                 const bool r128 = (n0 >= C_DSAQ && n0 < C_HGQ) || (n0 >= C_DSAK && n0 < C_DSAV);
;                 const bool r64 = (n0 >= C_IDXQ && n0 < C_GLAA);
;                 if (r128 || r64) {
;                   float4 cs;
;                   float sc;
;                   if (r128) {
;                     cs = *(const float4*)(g.w + ((size_t)tok * 64 + ((n0 & 127) >> 1)) * 2);
;                     sc = (n0 < C_HGQ) ? 0.08838834764831845f : 1.0f;
;                   } else {
;                     cs = *(const float4*)(g.hout + ((size_t)tok * 32 + ((n0 & 63) >> 1)) * 2);
;                     sc = (n0 < C_IDXK) ? 0.125f : 1.0f;
;                   }
;                   o0 = (a[0] * cs.x - a[1] * cs.y) * sc; o1 = (a[1] * cs.x + a[0] * cs.y) * sc;
;                   o2 = (a[2] * cs.z - a[3] * cs.w) * sc; o3 = (a[3] * cs.z + a[2] * cs.w) * sc;
;                 }
;                 uint2 o; o.x = pack2(o0, o1); o.y = pack2(o2, o3);
;                 EMIT_BF16(g.ldo, o);
;               }
;             } else if (g.epi == EPI_RELU2) {
;               float r0 = fmaxf(a[0], 0.f), r1 = fmaxf(a[1], 0.f), r2 = fmaxf(a[2], 0.f), r3 = fmaxf(a[3], 0.f);
;               uint2 o; o.x = pack2(r0 * r0, r1 * r1); o.y = pack2(r2 * r2, r3 * r3);
;               EMIT_BF16(g.ldo, o);
	v_mov_b32_e32 v223, v219
	v_mov_b32_dpp v216, v212 row_ror:8 row_mask:0xf bank_mask:0x3
	v_mov_b32_dpp v217, v213 row_ror:8 row_mask:0xf bank_mask:0x3
	v_mov_b32_dpp v218, v214 row_ror:8 row_mask:0xf bank_mask:0x3
	v_mov_b32_dpp v219, v215 row_ror:8 row_mask:0xf bank_mask:0x3
	v_mov_b32_dpp v212, v220 row_ror:8 row_mask:0xf bank_mask:0xc
	v_mov_b32_dpp v213, v221 row_ror:8 row_mask:0xf bank_mask:0xc
	v_mov_b32_dpp v214, v222 row_ror:8 row_mask:0xf bank_mask:0xc
	v_mov_b32_dpp v215, v223 row_ror:8 row_mask:0xf bank_mask:0xc
	global_store_dwordx4 v[188:189], v[212:215], off offset:288
	global_store_dwordx4 v[190:191], v[216:219], off offset:288
	v_lshl_add_u64 v[188:189], v[184:185], 0, s[8:9]
	v_lshl_add_u64 v[190:191], v[188:189], 0, s[6:7]
	v_mov_b32_e32 v186, v199
	v_pk_mul_f32 v[96:97], v[96:97], v[186:187] op_sel_hi:[1,0]
	v_pk_mul_f32 v[98:99], v[98:99], v[186:187] op_sel_hi:[1,0]
	v_pk_mul_f32 v[92:93], v[92:93], v[186:187] op_sel_hi:[1,0]
	v_pk_mul_f32 v[94:95], v[94:95], v[186:187] op_sel_hi:[1,0]
	v_max_f32_e32 v96, v96, v96
	v_max_f32_e32 v96, 0, v96
	v_max_f32_e32 v97, v97, v97
	v_max_f32_e32 v97, 0, v97
	v_max_f32_e32 v98, v98, v98
	v_max_f32_e32 v98, 0, v98
	v_max_f32_e32 v99, v99, v99
	v_max_f32_e32 v99, 0, v99
	v_max_f32_e32 v92, v92, v92
	v_max_f32_e32 v92, 0, v92
	v_max_f32_e32 v93, v93, v93
	v_max_f32_e32 v93, 0, v93
	v_max_f32_e32 v94, v94, v94
	v_max_f32_e32 v94, 0, v94
	v_max_f32_e32 v95, v95, v95
	v_max_f32_e32 v95, 0, v95
	v_pk_mul_f32 v[96:97], v[96:97], v[96:97]
	v_pk_mul_f32 v[98:99], v[98:99], v[98:99]
	v_pk_mul_f32 v[92:93], v[92:93], v[92:93]
	v_pk_mul_f32 v[94:95], v[94:95], v[94:95]
	v_cvt_pk_bf16_f32 v224, v96, v97
	v_cvt_pk_bf16_f32 v225, v98, v99
	v_cvt_pk_bf16_f32 v226, v92, v93
	v_cvt_pk_bf16_f32 v227, v94, v95
	s_nop 1
	v_permlane16_swap_b32_e32 v224, v226
	v_permlane16_swap_b32_e32 v225, v227
	v_pk_mul_f32 v[88:89], v[88:89], v[186:187] op_sel_hi:[1,0]
	v_pk_mul_f32 v[90:91], v[90:91], v[186:187] op_sel_hi:[1,0]
	v_pk_mul_f32 v[84:85], v[84:85], v[186:187] op_sel_hi:[1,0]
	v_pk_mul_f32 v[86:87], v[86:87], v[186:187] op_sel_hi:[1,0]
	v_max_f32_e32 v88, v88, v88
	v_max_f32_e32 v88, 0, v88
	v_max_f32_e32 v89, v89, v89
	v_max_f32_e32 v89, 0, v89
	v_max_f32_e32 v90, v90, v90
	v_max_f32_e32 v90, 0, v90
	v_max_f32_e32 v91, v91, v91
	v_max_f32_e32 v91, 0, v91
	v_max_f32_e32 v84, v84, v84
	v_max_f32_e32 v84, 0, v84
	v_max_f32_e32 v85, v85, v85
	v_max_f32_e32 v85, 0, v85
	v_max_f32_e32 v86, v86, v86
	v_max_f32_e32 v86, 0, v86
	v_max_f32_e32 v87, v87, v87
	v_max_f32_e32 v87, 0, v87
	v_pk_mul_f32 v[88:89], v[88:89], v[88:89]
	v_pk_mul_f32 v[90:91], v[90:91], v[90:91]
	v_pk_mul_f32 v[84:85], v[84:85], v[84:85]
	v_pk_mul_f32 v[86:87], v[86:87], v[86:87]
	v_cvt_pk_bf16_f32 v228, v88, v89
	v_cvt_pk_bf16_f32 v229, v90, v91
	v_cvt_pk_bf16_f32 v230, v84, v85
	v_cvt_pk_bf16_f32 v231, v86, v87
	s_nop 1
	v_permlane16_swap_b32_e32 v228, v230
	v_permlane16_swap_b32_e32 v229, v231
	v_mov_b32_e32 v220, v228
	v_mov_b32_e32 v221, v229
	v_mov_b32_e32 v222, v230
	v_mov_b32_e32 v223, v231
	v_mov_b32_dpp v228, v224 row_ror:8 row_mask:0xf bank_mask:0x3
	v_mov_b32_dpp v229, v225 row_ror:8 row_mask:0xf bank_mask:0x3
	v_mov_b32_dpp v230, v226 row_ror:8 row_mask:0xf bank_mask:0x3
	v_mov_b32_dpp v231, v227 row_ror:8 row_mask:0xf bank_mask:0x3
	v_mov_b32_dpp v224, v220 row_ror:8 row_mask:0xf bank_mask:0xc
	v_mov_b32_dpp v225, v221 row_ror:8 row_mask:0xf bank_mask:0xc
	v_mov_b32_dpp v226, v222 row_ror:8 row_mask:0xf bank_mask:0xc
	v_mov_b32_dpp v227, v223 row_ror:8 row_mask:0xf bank_mask:0xc
	global_store_dwordx4 v[188:189], v[224:227], off offset:32
	global_store_dwordx4 v[190:191], v[228:231], off offset:32
	v_pk_mul_f32 v[80:81], v[80:81], v[186:187] op_sel_hi:[1,0]
	v_pk_mul_f32 v[82:83], v[82:83], v[186:187] op_sel_hi:[1,0]
	v_pk_mul_f32 v[76:77], v[76:77], v[186:187] op_sel_hi:[1,0]
	v_pk_mul_f32 v[78:79], v[78:79], v[186:187] op_sel_hi:[1,0]
	v_max_f32_e32 v80, v80, v80
	v_max_f32_e32 v80, 0, v80
	v_max_f32_e32 v81, v81, v81
	v_max_f32_e32 v81, 0, v81
	v_max_f32_e32 v82, v82, v82
	v_max_f32_e32 v82, 0, v82
	v_max_f32_e32 v83, v83, v83
	v_max_f32_e32 v83, 0, v83
	v_max_f32_e32 v76, v76, v76
	v_max_f32_e32 v76, 0, v76
	v_max_f32_e32 v77, v77, v77
	v_max_f32_e32 v77, 0, v77
	v_max_f32_e32 v78, v78, v78
	v_max_f32_e32 v78, 0, v78
	v_max_f32_e32 v79, v79, v79
	v_max_f32_e32 v79, 0, v79
	v_pk_mul_f32 v[80:81], v[80:81], v[80:81]
	v_pk_mul_f32 v[82:83], v[82:83], v[82:83]
	v_pk_mul_f32 v[76:77], v[76:77], v[76:77]
	v_pk_mul_f32 v[78:79], v[78:79], v[78:79]
	v_cvt_pk_bf16_f32 v232, v80, v81
	v_cvt_pk_bf16_f32 v233, v82, v83
	v_cvt_pk_bf16_f32 v234, v76, v77
	v_cvt_pk_bf16_f32 v235, v78, v79
	s_nop 1
	v_permlane16_swap_b32_e32 v232, v234
	v_permlane16_swap_b32_e32 v233, v235
	v_pk_mul_f32 v[72:73], v[72:73], v[186:187] op_sel_hi:[1,0]
	v_pk_mul_f32 v[74:75], v[74:75], v[186:187] op_sel_hi:[1,0]
	v_pk_mul_f32 v[68:69], v[68:69], v[186:187] op_sel_hi:[1,0]
	v_pk_mul_f32 v[70:71], v[70:71], v[186:187] op_sel_hi:[1,0]
	v_max_f32_e32 v72, v72, v72
	v_max_f32_e32 v72, 0, v72
	v_max_f32_e32 v73, v73, v73
	v_max_f32_e32 v73, 0, v73
	v_max_f32_e32 v74, v74, v74
	v_max_f32_e32 v74, 0, v74
	v_max_f32_e32 v75, v75, v75
	v_max_f32_e32 v75, 0, v75
	v_max_f32_e32 v68, v68, v68
	v_max_f32_e32 v68, 0, v68
	v_max_f32_e32 v69, v69, v69
	v_max_f32_e32 v69, 0, v69
	v_max_f32_e32 v70, v70, v70
	v_max_f32_e32 v70, 0, v70
	v_max_f32_e32 v71, v71, v71
	v_max_f32_e32 v71, 0, v71
	v_pk_mul_f32 v[72:73], v[72:73], v[72:73]
	v_pk_mul_f32 v[74:75], v[74:75], v[74:75]
	v_pk_mul_f32 v[68:69], v[68:69], v[68:69]
	v_pk_mul_f32 v[70:71], v[70:71], v[70:71]
; __device__ __forceinline__ void gemm_phase(const Ctx& cx, const GemmArgs& g_, char* shm) {
;     ...
; #pragma unroll
;           for (int m = 0; m < 4; ++m) {
;             const int n0 = brow + ai * 128 + wr * 64 + m * 16 + fq * 4;
;             f32x4 a = acc[ai][bj][m][n];
;             if (g.epi == EPI_PROJ || g.epi == EPI_RELU2) { a[0] *= rs; a[1] *= rs; a[2] *= rs; a[3] *= rs; }
;             if (g.epi == EPI_PROJ) {
;               if (n0 >= C_GLAX) {
;                 const int i = n0 - C_GLAX;
;                 const float4 b4 = *(const float4*)(g.hin + i);
;                 float xs[4] = {a[0] + b4.x, a[1] + b4.y, a[2] + b4.z, a[3] + b4.w};
; #pragma unroll
;                 for (int j = 0; j < 4; ++j)
;                   xs[j] = (fminf(xs[j], 0.f) - __logf(1.0f + __expf(-fabsf(xs[j])))) * (1.0f / 16.0f);
;                 *(float4*)(g.f32buf + (size_t)tok * 1024 + i) = make_float4(xs[0], xs[1], xs[2], xs[3]);
;               } else {
;                 float o0 = a[0], o1 = a[1], o2 = a[2], o3 = a[3];
;                 const bool r128 = (n0 >= C_DSAQ && n0 < C_HGQ) || (n0 >= C_DSAK && n0 < C_DSAV);
;                 const bool r64 = (n0 >= C_IDXQ && n0 < C_GLAA);
;                 if (r128 || r64) {
;                   float4 cs;
;                   float sc;
;                   if (r128) {
;                     cs = *(const float4*)(g.w + ((size_t)tok * 64 + ((n0 & 127) >> 1)) * 2);
;                     sc = (n0 < C_HGQ) ? 0.08838834764831845f : 1.0f;
;                   } else {
;                     cs = *(const float4*)(g.hout + ((size_t)tok * 32 + ((n0 & 63) >> 1)) * 2);
;                     sc = (n0 < C_IDXK) ? 0.125f : 1.0f;
;                   }
;                   o0 = (a[0] * cs.x - a[1] * cs.y) * sc; o1 = (a[1] * cs.x + a[0] * cs.y) * sc;
;                   o2 = (a[2] * cs.z - a[3] * cs.w) * sc; o3 = (a[3] * cs.z + a[2] * cs.w) * sc;
;                 }
;                 uint2 o; o.x = pack2(o0, o1); o.y = pack2(o2, o3);
;                 EMIT_BF16(g.ldo, o);
;               }
;             } else if (g.epi == EPI_RELU2) {
;               float r0 = fmaxf(a[0], 0.f), r1 = fmaxf(a[1], 0.f), r2 = fmaxf(a[2], 0.f), r3 = fmaxf(a[3], 0.f);
;               uint2 o; o.x = pack2(r0 * r0, r1 * r1); o.y = pack2(r2 * r2, r3 * r3);
;               EMIT_BF16(g.ldo, o);
	v_cvt_pk_bf16_f32 v236, v72, v73
	v_cvt_pk_bf16_f32 v237, v74, v75
	v_cvt_pk_bf16_f32 v238, v68, v69
	v_cvt_pk_bf16_f32 v239, v70, v71
	s_nop 1
	v_permlane16_swap_b32_e32 v236, v238
	v_permlane16_swap_b32_e32 v237, v239
	v_mov_b32_e32 v220, v236
	v_mov_b32_e32 v221, v237
	v_mov_b32_e32 v222, v238
	v_mov_b32_e32 v223, v239
	v_mov_b32_dpp v236, v232 row_ror:8 row_mask:0xf bank_mask:0x3
	v_mov_b32_dpp v237, v233 row_ror:8 row_mask:0xf bank_mask:0x3
	v_mov_b32_dpp v238, v234 row_ror:8 row_mask:0xf bank_mask:0x3
	v_mov_b32_dpp v239, v235 row_ror:8 row_mask:0xf bank_mask:0x3
	v_mov_b32_dpp v232, v220 row_ror:8 row_mask:0xf bank_mask:0xc
	v_mov_b32_dpp v233, v221 row_ror:8 row_mask:0xf bank_mask:0xc
	v_mov_b32_dpp v234, v222 row_ror:8 row_mask:0xf bank_mask:0xc
	v_mov_b32_dpp v235, v223 row_ror:8 row_mask:0xf bank_mask:0xc
	global_store_dwordx4 v[188:189], v[232:235], off offset:288
	global_store_dwordx4 v[190:191], v[236:239], off offset:288
	v_lshl_add_u64 v[188:189], v[184:185], 0, s[10:11]
	v_lshl_add_u64 v[190:191], v[188:189], 0, s[6:7]
	v_mov_b32_e32 v186, v200
	v_pk_mul_f32 v[64:65], v[64:65], v[186:187] op_sel_hi:[1,0]
	v_pk_mul_f32 v[66:67], v[66:67], v[186:187] op_sel_hi:[1,0]
	v_pk_mul_f32 v[60:61], v[60:61], v[186:187] op_sel_hi:[1,0]
	v_pk_mul_f32 v[62:63], v[62:63], v[186:187] op_sel_hi:[1,0]
	v_max_f32_e32 v64, v64, v64
	v_max_f32_e32 v64, 0, v64
	v_max_f32_e32 v65, v65, v65
	v_max_f32_e32 v65, 0, v65
	v_max_f32_e32 v66, v66, v66
	v_max_f32_e32 v66, 0, v66
	v_max_f32_e32 v67, v67, v67
	v_max_f32_e32 v67, 0, v67
	v_max_f32_e32 v60, v60, v60
	v_max_f32_e32 v60, 0, v60
	v_max_f32_e32 v61, v61, v61
	v_max_f32_e32 v61, 0, v61
	v_max_f32_e32 v62, v62, v62
	v_max_f32_e32 v62, 0, v62
	v_max_f32_e32 v63, v63, v63
	v_max_f32_e32 v63, 0, v63
	v_pk_mul_f32 v[64:65], v[64:65], v[64:65]
	v_pk_mul_f32 v[66:67], v[66:67], v[66:67]
	v_pk_mul_f32 v[60:61], v[60:61], v[60:61]
	v_pk_mul_f32 v[62:63], v[62:63], v[62:63]
	v_cvt_pk_bf16_f32 v204, v64, v65
	v_cvt_pk_bf16_f32 v205, v66, v67
	v_cvt_pk_bf16_f32 v206, v60, v61
	v_cvt_pk_bf16_f32 v207, v62, v63
	s_nop 1
	v_permlane16_swap_b32_e32 v204, v206
	v_permlane16_swap_b32_e32 v205, v207
	v_pk_mul_f32 v[56:57], v[56:57], v[186:187] op_sel_hi:[1,0]
	v_pk_mul_f32 v[58:59], v[58:59], v[186:187] op_sel_hi:[1,0]
	v_pk_mul_f32 v[52:53], v[52:53], v[186:187] op_sel_hi:[1,0]
	v_pk_mul_f32 v[54:55], v[54:55], v[186:187] op_sel_hi:[1,0]
	v_max_f32_e32 v56, v56, v56
	v_max_f32_e32 v56, 0, v56
	v_max_f32_e32 v57, v57, v57
	v_max_f32_e32 v57, 0, v57
	v_max_f32_e32 v58, v58, v58
	v_max_f32_e32 v58, 0, v58
	v_max_f32_e32 v59, v59, v59
	v_max_f32_e32 v59, 0, v59
	v_max_f32_e32 v52, v52, v52
	v_max_f32_e32 v52, 0, v52
	v_max_f32_e32 v53, v53, v53
	v_max_f32_e32 v53, 0, v53
	v_max_f32_e32 v54, v54, v54
	v_max_f32_e32 v54, 0, v54
	v_max_f32_e32 v55, v55, v55
	v_max_f32_e32 v55, 0, v55
	v_pk_mul_f32 v[56:57], v[56:57], v[56:57]
	v_pk_mul_f32 v[58:59], v[58:59], v[58:59]
	v_pk_mul_f32 v[52:53], v[52:53], v[52:53]
	v_pk_mul_f32 v[54:55], v[54:55], v[54:55]
	v_cvt_pk_bf16_f32 v208, v56, v57
	v_cvt_pk_bf16_f32 v209, v58, v59
	v_cvt_pk_bf16_f32 v210, v52, v53
	v_cvt_pk_bf16_f32 v211, v54, v55
	s_nop 1
	v_permlane16_swap_b32_e32 v208, v210
	v_permlane16_swap_b32_e32 v209, v211
	v_mov_b32_e32 v220, v208
	v_mov_b32_e32 v221, v209
	v_mov_b32_e32 v222, v210
	v_mov_b32_e32 v223, v211
	v_mov_b32_dpp v208, v204 row_ror:8 row_mask:0xf bank_mask:0x3
	v_mov_b32_dpp v209, v205 row_ror:8 row_mask:0xf bank_mask:0x3
	v_mov_b32_dpp v210, v206 row_ror:8 row_mask:0xf bank_mask:0x3
	v_mov_b32_dpp v211, v207 row_ror:8 row_mask:0xf bank_mask:0x3
	v_mov_b32_dpp v204, v220 row_ror:8 row_mask:0xf bank_mask:0xc
	v_mov_b32_dpp v205, v221 row_ror:8 row_mask:0xf bank_mask:0xc
	v_mov_b32_dpp v206, v222 row_ror:8 row_mask:0xf bank_mask:0xc
	v_mov_b32_dpp v207, v223 row_ror:8 row_mask:0xf bank_mask:0xc
	global_store_dwordx4 v[188:189], v[204:207], off offset:32
	global_store_dwordx4 v[190:191], v[208:211], off offset:32
	v_pk_mul_f32 v[48:49], v[48:49], v[186:187] op_sel_hi:[1,0]
	v_pk_mul_f32 v[50:51], v[50:51], v[186:187] op_sel_hi:[1,0]
	v_pk_mul_f32 v[44:45], v[44:45], v[186:187] op_sel_hi:[1,0]
	v_pk_mul_f32 v[46:47], v[46:47], v[186:187] op_sel_hi:[1,0]
	v_max_f32_e32 v48, v48, v48
	v_max_f32_e32 v48, 0, v48
	v_max_f32_e32 v49, v49, v49
	v_max_f32_e32 v49, 0, v49
	v_max_f32_e32 v50, v50, v50
	v_max_f32_e32 v50, 0, v50
	v_max_f32_e32 v51, v51, v51
	v_max_f32_e32 v51, 0, v51
	v_max_f32_e32 v44, v44, v44
	v_max_f32_e32 v44, 0, v44
	v_max_f32_e32 v45, v45, v45
	v_max_f32_e32 v45, 0, v45
	v_max_f32_e32 v46, v46, v46
	v_max_f32_e32 v46, 0, v46
	v_max_f32_e32 v47, v47, v47
	v_max_f32_e32 v47, 0, v47
	v_pk_mul_f32 v[48:49], v[48:49], v[48:49]
	v_pk_mul_f32 v[50:51], v[50:51], v[50:51]
	v_pk_mul_f32 v[44:45], v[44:45], v[44:45]
	v_pk_mul_f32 v[46:47], v[46:47], v[46:47]
	v_cvt_pk_bf16_f32 v212, v48, v49
	v_cvt_pk_bf16_f32 v213, v50, v51
	v_cvt_pk_bf16_f32 v214, v44, v45
	v_cvt_pk_bf16_f32 v215, v46, v47
	s_nop 1
	v_permlane16_swap_b32_e32 v212, v214
	v_permlane16_swap_b32_e32 v213, v215
	v_pk_mul_f32 v[40:41], v[40:41], v[186:187] op_sel_hi:[1,0]
	v_pk_mul_f32 v[42:43], v[42:43], v[186:187] op_sel_hi:[1,0]
	v_pk_mul_f32 v[36:37], v[36:37], v[186:187] op_sel_hi:[1,0]
	v_pk_mul_f32 v[38:39], v[38:39], v[186:187] op_sel_hi:[1,0]
	v_max_f32_e32 v40, v40, v40
	v_max_f32_e32 v40, 0, v40
	v_max_f32_e32 v41, v41, v41
	v_max_f32_e32 v41, 0, v41
	v_max_f32_e32 v42, v42, v42
	v_max_f32_e32 v42, 0, v42
	v_max_f32_e32 v43, v43, v43
	v_max_f32_e32 v43, 0, v43
	v_max_f32_e32 v36, v36, v36
	v_max_f32_e32 v36, 0, v36
	v_max_f32_e32 v37, v37, v37
	v_max_f32_e32 v37, 0, v37
; __device__ __forceinline__ void gemm_phase(const Ctx& cx, const GemmArgs& g_, char* shm) {
;     ...
; #pragma unroll
;           for (int m = 0; m < 4; ++m) {
;             const int n0 = brow + ai * 128 + wr * 64 + m * 16 + fq * 4;
;             f32x4 a = acc[ai][bj][m][n];
;             if (g.epi == EPI_PROJ || g.epi == EPI_RELU2) { a[0] *= rs; a[1] *= rs; a[2] *= rs; a[3] *= rs; }
;             if (g.epi == EPI_PROJ) {
;               if (n0 >= C_GLAX) {
;                 const int i = n0 - C_GLAX;
;                 const float4 b4 = *(const float4*)(g.hin + i);
;                 float xs[4] = {a[0] + b4.x, a[1] + b4.y, a[2] + b4.z, a[3] + b4.w};
; #pragma unroll
;                 for (int j = 0; j < 4; ++j)
;                   xs[j] = (fminf(xs[j], 0.f) - __logf(1.0f + __expf(-fabsf(xs[j])))) * (1.0f / 16.0f);
;                 *(float4*)(g.f32buf + (size_t)tok * 1024 + i) = make_float4(xs[0], xs[1], xs[2], xs[3]);
;               } else {
;                 float o0 = a[0], o1 = a[1], o2 = a[2], o3 = a[3];
;                 const bool r128 = (n0 >= C_DSAQ && n0 < C_HGQ) || (n0 >= C_DSAK && n0 < C_DSAV);
;                 const bool r64 = (n0 >= C_IDXQ && n0 < C_GLAA);
;                 if (r128 || r64) {
;                   float4 cs;
;                   float sc;
;                   if (r128) {
;                     cs = *(const float4*)(g.w + ((size_t)tok * 64 + ((n0 & 127) >> 1)) * 2);
;                     sc = (n0 < C_HGQ) ? 0.08838834764831845f : 1.0f;
;                   } else {
;                     cs = *(const float4*)(g.hout + ((size_t)tok * 32 + ((n0 & 63) >> 1)) * 2);
;                     sc = (n0 < C_IDXK) ? 0.125f : 1.0f;
;                   }
;                   o0 = (a[0] * cs.x - a[1] * cs.y) * sc; o1 = (a[1] * cs.x + a[0] * cs.y) * sc;
;                   o2 = (a[2] * cs.z - a[3] * cs.w) * sc; o3 = (a[3] * cs.z + a[2] * cs.w) * sc;
;                 }
;                 uint2 o; o.x = pack2(o0, o1); o.y = pack2(o2, o3);
;                 EMIT_BF16(g.ldo, o);
;               }
;             } else if (g.epi == EPI_RELU2) {
;               float r0 = fmaxf(a[0], 0.f), r1 = fmaxf(a[1], 0.f), r2 = fmaxf(a[2], 0.f), r3 = fmaxf(a[3], 0.f);
;               uint2 o; o.x = pack2(r0 * r0, r1 * r1); o.y = pack2(r2 * r2, r3 * r3);
;               EMIT_BF16(g.ldo, o);
	v_max_f32_e32 v38, v38, v38
	v_max_f32_e32 v38, 0, v38
	v_max_f32_e32 v39, v39, v39
	v_max_f32_e32 v39, 0, v39
	v_pk_mul_f32 v[40:41], v[40:41], v[40:41]
	v_pk_mul_f32 v[42:43], v[42:43], v[42:43]
	v_pk_mul_f32 v[36:37], v[36:37], v[36:37]
	v_pk_mul_f32 v[38:39], v[38:39], v[38:39]
	v_cvt_pk_bf16_f32 v216, v40, v41
	v_cvt_pk_bf16_f32 v217, v42, v43
	v_cvt_pk_bf16_f32 v218, v36, v37
	v_cvt_pk_bf16_f32 v219, v38, v39
	s_nop 1
	v_permlane16_swap_b32_e32 v216, v218
	v_permlane16_swap_b32_e32 v217, v219
	v_mov_b32_e32 v220, v216
	v_mov_b32_e32 v221, v217
	v_mov_b32_e32 v222, v218
	v_mov_b32_e32 v223, v219
	v_mov_b32_dpp v216, v212 row_ror:8 row_mask:0xf bank_mask:0x3
	v_mov_b32_dpp v217, v213 row_ror:8 row_mask:0xf bank_mask:0x3
	v_mov_b32_dpp v218, v214 row_ror:8 row_mask:0xf bank_mask:0x3
	v_mov_b32_dpp v219, v215 row_ror:8 row_mask:0xf bank_mask:0x3
	v_mov_b32_dpp v212, v220 row_ror:8 row_mask:0xf bank_mask:0xc
	v_mov_b32_dpp v213, v221 row_ror:8 row_mask:0xf bank_mask:0xc
	v_mov_b32_dpp v214, v222 row_ror:8 row_mask:0xf bank_mask:0xc
	v_mov_b32_dpp v215, v223 row_ror:8 row_mask:0xf bank_mask:0xc
	global_store_dwordx4 v[188:189], v[212:215], off offset:288
	global_store_dwordx4 v[190:191], v[216:219], off offset:288
	v_lshl_add_u64 v[188:189], v[184:185], 0, s[10:11]
	v_lshl_add_u64 v[188:189], v[188:189], 0, s[8:9]
	v_lshl_add_u64 v[190:191], v[188:189], 0, s[6:7]
	v_mov_b32_e32 v186, v201
	v_pk_mul_f32 v[32:33], v[32:33], v[186:187] op_sel_hi:[1,0]
	v_pk_mul_f32 v[34:35], v[34:35], v[186:187] op_sel_hi:[1,0]
	v_pk_mul_f32 v[28:29], v[28:29], v[186:187] op_sel_hi:[1,0]
	v_pk_mul_f32 v[30:31], v[30:31], v[186:187] op_sel_hi:[1,0]
	v_max_f32_e32 v32, v32, v32
	v_max_f32_e32 v32, 0, v32
	v_max_f32_e32 v33, v33, v33
	v_max_f32_e32 v33, 0, v33
	v_max_f32_e32 v34, v34, v34
	v_max_f32_e32 v34, 0, v34
	v_max_f32_e32 v35, v35, v35
	v_max_f32_e32 v35, 0, v35
	v_max_f32_e32 v28, v28, v28
	v_max_f32_e32 v28, 0, v28
	v_max_f32_e32 v29, v29, v29
	v_max_f32_e32 v29, 0, v29
	v_max_f32_e32 v30, v30, v30
	v_max_f32_e32 v30, 0, v30
	v_max_f32_e32 v31, v31, v31
	v_max_f32_e32 v31, 0, v31
	v_pk_mul_f32 v[32:33], v[32:33], v[32:33]
	v_pk_mul_f32 v[34:35], v[34:35], v[34:35]
	v_pk_mul_f32 v[28:29], v[28:29], v[28:29]
	v_pk_mul_f32 v[30:31], v[30:31], v[30:31]
	v_cvt_pk_bf16_f32 v224, v32, v33
	v_cvt_pk_bf16_f32 v225, v34, v35
	v_cvt_pk_bf16_f32 v226, v28, v29
	v_cvt_pk_bf16_f32 v227, v30, v31
	s_nop 1
	v_permlane16_swap_b32_e32 v224, v226
	v_permlane16_swap_b32_e32 v225, v227
	v_pk_mul_f32 v[24:25], v[24:25], v[186:187] op_sel_hi:[1,0]
	v_pk_mul_f32 v[26:27], v[26:27], v[186:187] op_sel_hi:[1,0]
	v_pk_mul_f32 v[20:21], v[20:21], v[186:187] op_sel_hi:[1,0]
	v_pk_mul_f32 v[22:23], v[22:23], v[186:187] op_sel_hi:[1,0]
	v_max_f32_e32 v24, v24, v24
	v_max_f32_e32 v24, 0, v24
	v_max_f32_e32 v25, v25, v25
	v_max_f32_e32 v25, 0, v25
	v_max_f32_e32 v26, v26, v26
	v_max_f32_e32 v26, 0, v26
	v_max_f32_e32 v27, v27, v27
	v_max_f32_e32 v27, 0, v27
	v_max_f32_e32 v20, v20, v20
	v_max_f32_e32 v20, 0, v20
	v_max_f32_e32 v21, v21, v21
	v_max_f32_e32 v21, 0, v21
	v_max_f32_e32 v22, v22, v22
	v_max_f32_e32 v22, 0, v22
	v_max_f32_e32 v23, v23, v23
	v_max_f32_e32 v23, 0, v23
	v_pk_mul_f32 v[24:25], v[24:25], v[24:25]
	v_pk_mul_f32 v[26:27], v[26:27], v[26:27]
	v_pk_mul_f32 v[20:21], v[20:21], v[20:21]
	v_pk_mul_f32 v[22:23], v[22:23], v[22:23]
	v_cvt_pk_bf16_f32 v228, v24, v25
	v_cvt_pk_bf16_f32 v229, v26, v27
	v_cvt_pk_bf16_f32 v230, v20, v21
	v_cvt_pk_bf16_f32 v231, v22, v23
	s_nop 1
	v_permlane16_swap_b32_e32 v228, v230
	v_permlane16_swap_b32_e32 v229, v231
; __device__ __forceinline__ void gemm_phase(const Ctx& cx, const GemmArgs& g_, char* shm) {
;     ...
; #pragma unroll
;           for (int m = 0; m < 4; ++m) {
;             const int n0 = brow + ai * 128 + wr * 64 + m * 16 + fq * 4;
;             f32x4 a = acc[ai][bj][m][n];
;             if (g.epi == EPI_PROJ || g.epi == EPI_RELU2) { a[0] *= rs; a[1] *= rs; a[2] *= rs; a[3] *= rs; }
;             if (g.epi == EPI_PROJ) {
;               if (n0 >= C_GLAX) {
;                 const int i = n0 - C_GLAX;
;                 const float4 b4 = *(const float4*)(g.hin + i);
;                 float xs[4] = {a[0] + b4.x, a[1] + b4.y, a[2] + b4.z, a[3] + b4.w};
; #pragma unroll
;                 for (int j = 0; j < 4; ++j)
;                   xs[j] = (fminf(xs[j], 0.f) - __logf(1.0f + __expf(-fabsf(xs[j])))) * (1.0f / 16.0f);
;                 *(float4*)(g.f32buf + (size_t)tok * 1024 + i) = make_float4(xs[0], xs[1], xs[2], xs[3]);
;               } else {
;                 float o0 = a[0], o1 = a[1], o2 = a[2], o3 = a[3];
;                 const bool r128 = (n0 >= C_DSAQ && n0 < C_HGQ) || (n0 >= C_DSAK && n0 < C_DSAV);
;                 const bool r64 = (n0 >= C_IDXQ && n0 < C_GLAA);
;                 if (r128 || r64) {
;                   float4 cs;
;                   float sc;
;                   if (r128) {
;                     cs = *(const float4*)(g.w + ((size_t)tok * 64 + ((n0 & 127) >> 1)) * 2);
;                     sc = (n0 < C_HGQ) ? 0.08838834764831845f : 1.0f;
;                   } else {
;                     cs = *(const float4*)(g.hout + ((size_t)tok * 32 + ((n0 & 63) >> 1)) * 2);
;                     sc = (n0 < C_IDXK) ? 0.125f : 1.0f;
;                   }
;                   o0 = (a[0] * cs.x - a[1] * cs.y) * sc; o1 = (a[1] * cs.x + a[0] * cs.y) * sc;
;                   o2 = (a[2] * cs.z - a[3] * cs.w) * sc; o3 = (a[3] * cs.z + a[2] * cs.w) * sc;
;                 }
;                 uint2 o; o.x = pack2(o0, o1); o.y = pack2(o2, o3);
;                 EMIT_BF16(g.ldo, o);
;               }
;             } else if (g.epi == EPI_RELU2) {
;               float r0 = fmaxf(a[0], 0.f), r1 = fmaxf(a[1], 0.f), r2 = fmaxf(a[2], 0.f), r3 = fmaxf(a[3], 0.f);
;               uint2 o; o.x = pack2(r0 * r0, r1 * r1); o.y = pack2(r2 * r2, r3 * r3);
;               EMIT_BF16(g.ldo, o);
	v_mov_b32_e32 v220, v228
	v_mov_b32_e32 v221, v229
	v_mov_b32_e32 v222, v230
	v_mov_b32_e32 v223, v231
	v_mov_b32_dpp v228, v224 row_ror:8 row_mask:0xf bank_mask:0x3
	v_mov_b32_dpp v229, v225 row_ror:8 row_mask:0xf bank_mask:0x3
	v_mov_b32_dpp v230, v226 row_ror:8 row_mask:0xf bank_mask:0x3
	v_mov_b32_dpp v231, v227 row_ror:8 row_mask:0xf bank_mask:0x3
	v_mov_b32_dpp v224, v220 row_ror:8 row_mask:0xf bank_mask:0xc
	v_mov_b32_dpp v225, v221 row_ror:8 row_mask:0xf bank_mask:0xc
	v_mov_b32_dpp v226, v222 row_ror:8 row_mask:0xf bank_mask:0xc
	v_mov_b32_dpp v227, v223 row_ror:8 row_mask:0xf bank_mask:0xc
	global_store_dwordx4 v[188:189], v[224:227], off offset:32
	global_store_dwordx4 v[190:191], v[228:231], off offset:32
	v_pk_mul_f32 v[16:17], v[16:17], v[186:187] op_sel_hi:[1,0]
	v_pk_mul_f32 v[18:19], v[18:19], v[186:187] op_sel_hi:[1,0]
	v_pk_mul_f32 v[12:13], v[12:13], v[186:187] op_sel_hi:[1,0]
	v_pk_mul_f32 v[14:15], v[14:15], v[186:187] op_sel_hi:[1,0]
	v_max_f32_e32 v16, v16, v16
	v_max_f32_e32 v16, 0, v16
	v_max_f32_e32 v17, v17, v17
	v_max_f32_e32 v17, 0, v17
	v_max_f32_e32 v18, v18, v18
	v_max_f32_e32 v18, 0, v18
	v_max_f32_e32 v19, v19, v19
	v_max_f32_e32 v19, 0, v19
	v_max_f32_e32 v12, v12, v12
	v_max_f32_e32 v12, 0, v12
	v_max_f32_e32 v13, v13, v13
	v_max_f32_e32 v13, 0, v13
	v_max_f32_e32 v14, v14, v14
	v_max_f32_e32 v14, 0, v14
	v_max_f32_e32 v15, v15, v15
	v_max_f32_e32 v15, 0, v15
	v_pk_mul_f32 v[16:17], v[16:17], v[16:17]
	v_pk_mul_f32 v[18:19], v[18:19], v[18:19]
	v_pk_mul_f32 v[12:13], v[12:13], v[12:13]
	v_pk_mul_f32 v[14:15], v[14:15], v[14:15]
	v_cvt_pk_bf16_f32 v232, v16, v17
	v_cvt_pk_bf16_f32 v233, v18, v19
	v_cvt_pk_bf16_f32 v234, v12, v13
	v_cvt_pk_bf16_f32 v235, v14, v15
	s_nop 1
	v_permlane16_swap_b32_e32 v232, v234
	v_permlane16_swap_b32_e32 v233, v235
	v_pk_mul_f32 v[8:9], v[8:9], v[186:187] op_sel_hi:[1,0]
	v_pk_mul_f32 v[10:11], v[10:11], v[186:187] op_sel_hi:[1,0]
	v_pk_mul_f32 v[4:5], v[4:5], v[186:187] op_sel_hi:[1,0]
	v_pk_mul_f32 v[6:7], v[6:7], v[186:187] op_sel_hi:[1,0]
	v_max_f32_e32 v8, v8, v8
	v_max_f32_e32 v8, 0, v8
	v_max_f32_e32 v9, v9, v9
	v_max_f32_e32 v9, 0, v9
	v_max_f32_e32 v10, v10, v10
	v_max_f32_e32 v10, 0, v10
	v_max_f32_e32 v11, v11, v11
	v_max_f32_e32 v11, 0, v11
	v_max_f32_e32 v4, v4, v4
	v_max_f32_e32 v4, 0, v4
	v_max_f32_e32 v5, v5, v5
	v_max_f32_e32 v5, 0, v5
	v_max_f32_e32 v6, v6, v6
	v_max_f32_e32 v6, 0, v6
	v_max_f32_e32 v7, v7, v7
	v_max_f32_e32 v7, 0, v7
	v_pk_mul_f32 v[8:9], v[8:9], v[8:9]
	v_pk_mul_f32 v[10:11], v[10:11], v[10:11]
	v_pk_mul_f32 v[4:5], v[4:5], v[4:5]
	v_pk_mul_f32 v[6:7], v[6:7], v[6:7]
	v_cvt_pk_bf16_f32 v236, v8, v9
	v_cvt_pk_bf16_f32 v237, v10, v11
	v_cvt_pk_bf16_f32 v238, v4, v5
	v_cvt_pk_bf16_f32 v239, v6, v7
	s_nop 1
	v_permlane16_swap_b32_e32 v236, v238
	v_permlane16_swap_b32_e32 v237, v239
	v_mov_b32_e32 v220, v236
	v_mov_b32_e32 v221, v237
	v_mov_b32_e32 v222, v238
	v_mov_b32_e32 v223, v239
	v_mov_b32_dpp v236, v232 row_ror:8 row_mask:0xf bank_mask:0x3
	v_mov_b32_dpp v237, v233 row_ror:8 row_mask:0xf bank_mask:0x3
	v_mov_b32_dpp v238, v234 row_ror:8 row_mask:0xf bank_mask:0x3
	v_mov_b32_dpp v239, v235 row_ror:8 row_mask:0xf bank_mask:0x3
	v_mov_b32_dpp v232, v220 row_ror:8 row_mask:0xf bank_mask:0xc
	v_mov_b32_dpp v233, v221 row_ror:8 row_mask:0xf bank_mask:0xc
	v_mov_b32_dpp v234, v222 row_ror:8 row_mask:0xf bank_mask:0xc
	v_mov_b32_dpp v235, v223 row_ror:8 row_mask:0xf bank_mask:0xc
	global_store_dwordx4 v[188:189], v[232:235], off offset:288
	global_store_dwordx4 v[190:191], v[236:239], off offset:288
	s_branch .LBB0_231

; __device__ __forceinline__ void gemm_phase(const Ctx& cx, const GemmArgs& g_, char* shm) {
;     ...
;             } else if (g.epi == EPI_RES) {
;               const float4 hv = *(const float4*)(g.hin + (size_t)tok * DM + n0);
;               const float h0 = hv.x + a[0], h1 = hv.y + a[1], h2 = hv.z + a[2], h3 = hv.w + a[3];
;               *(float4*)(g.hout + (size_t)tok * DM + n0) = make_float4(h0, h1, h2, h3);
;               if (g.w != nullptr) {
;                 const float4 nw = *(const float4*)(g.w + n0);
;                 uint2 o; o.x = pack2(h0 * nw.x, h1 * nw.y); o.y = pack2(h2 * nw.z, h3 * nw.w);
;                 EMIT_BF16(DM, o);
;                 ssq += h0 * h0 + h1 * h1 + h2 * h2 + h3 * h3;
;               }
.LBB0_261:
	v_mov_b32_e32 v179, 0
	s_and_b64 vcc, exec, s[52:53]
	s_cbranch_vccz .LBB0_265
	v_ashrrev_i32_e32 v141, 31, v140
	v_lshlrev_b64 v[144:145], 2, v[140:141]
	v_lshl_add_u64 v[132:133], v[148:149], 0, v[144:145]
	s_nop 0
	flat_load_dwordx4 v[132:135], v[132:133]
	v_lshl_add_u64 v[144:145], v[146:147], 0, v[144:145]
	s_andn2_b64 vcc, exec, s[42:43]
	s_waitcnt vmcnt(0) lgkmcnt(0)
	v_pk_add_f32 v[132:133], v[128:129], v[132:133]
	v_pk_add_f32 v[134:135], v[130:131], v[134:135]
	flat_store_dwordx4 v[144:145], v[132:135]
	s_cbranch_vccnz .LBB0_264
	v_lshl_add_u64 v[144:145], v[140:141], 2, s[30:31]
	global_load_dwordx4 v[150:153], v[144:145], off
	s_waitcnt vmcnt(0)
	v_pk_mul_f32 v[144:145], v[134:135], v[152:153]
	s_nop 0
	v_cvt_pk_bf16_f32 v176, v144, v145
	v_pk_mul_f32 v[144:145], v[132:133], v[150:151]
	v_pk_mul_f32 v[132:133], v[132:133], v[132:133]
	v_pk_mul_f32 v[134:135], v[134:135], v[134:135]
	v_add_f32_e32 v2, v132, v133
	v_add_f32_e32 v2, v2, v134
	v_cvt_pk_bf16_f32 v178, v144, v145
	v_add_f32_e32 v179, v2, v135
	s_branch .LBB0_265

; __device__ __forceinline__ float b2f(u16 b) { return __uint_as_float(((uint32_t)b) << 16); }
; __device__ __forceinline__ float sigmoidf_(float x) { return 1.0f / (1.0f + __expf(-x)); }
; __device__ __forceinline__ void gemm_phase(const Ctx& cx, const GemmArgs& g_, char* shm) {
;     ...
;             } else {
;               const uint2 gv = *(const uint2*)(g.gate + (size_t)tok * NP + n0);
;               float v0 = sigmoidf_(b2f((u16)(gv.x & 0xffff))) * a[0], v1 = sigmoidf_(b2f((u16)(gv.x >> 16))) * a[1];
;               float v2 = sigmoidf_(b2f((u16)(gv.y & 0xffff))) * a[2], v3 = sigmoidf_(b2f((u16)(gv.y >> 16))) * a[3];
;               uint2* mp = (uint2*)(g.outb + (size_t)tok * DM + n0);
;               if (g.epi != EPI_BR0) {
;                 const uint2 pv = *mp;
;                 v0 += b2f((u16)(pv.x & 0xffff)); v1 += b2f((u16)(pv.x >> 16));
;                 v2 += b2f((u16)(pv.y & 0xffff)); v3 += b2f((u16)(pv.y >> 16));
;               }
;               uint2 o; o.x = pack2(v0, v1); o.y = pack2(v2, v3);
;               *mp = o;
;             }
.LBB0_268:
	v_lshlrev_b64 v[132:133], 12, v[136:137]
	v_mov_b64_e32 v[144:145], s[22:23]
	v_cndmask_b32_e64 v2, 0, 1, s[44:45]
	v_lshl_add_u64 v[134:135], s[20:21], 0, v[132:133]
	v_mad_i64_i32 v[156:157], s[52:53], v136, s76, v[144:145]
	s_andn2_b64 vcc, exec, s[4:5]
	v_ashrrev_i32_e32 v141, 31, v140
	v_cmp_ne_u32_e64 s[4:5], 1, v2
	s_cbranch_vccnz .LBB0_272
	v_lshlrev_b64 v[150:151], 1, v[140:141]
	v_lshl_add_u64 v[144:145], v[156:157], 0, v[150:151]
	s_nop 0
	flat_load_dwordx2 v[152:153], v[144:145]
	v_lshl_add_u64 v[150:151], v[134:135], 0, v[150:151]
	s_waitcnt vmcnt(0) lgkmcnt(0)
	v_lshlrev_b32_e32 v2, 16, v152
	v_mul_f32_e32 v2, 0xbfb8aa3b, v2
	v_exp_f32_e32 v144, v2
	v_and_b32_e32 v2, 0xffff0000, v152
	v_mul_f32_e32 v2, 0xbfb8aa3b, v2
	v_exp_f32_e32 v145, v2
	s_nop 0
	v_pk_add_f32 v[144:145], v[144:145], 1.0 op_sel_hi:[1,0]
	s_nop 0
	v_div_scale_f32 v2, s[2:3], v145, v145, 1.0
	v_rcp_f32_e32 v139, v2
	s_nop 0
	v_fma_f32 v152, -v2, v139, 1.0
	v_fmac_f32_e32 v139, v152, v139
	v_div_scale_f32 v152, vcc, 1.0, v145, 1.0
	v_mul_f32_e32 v158, v152, v139
	v_fma_f32 v159, -v2, v158, v152
	v_fmac_f32_e32 v158, v159, v139
	v_fma_f32 v2, -v2, v158, v152
	v_div_fmas_f32 v2, v2, v139, v158
	v_div_fixup_f32 v145, v2, v145, 1.0
	v_div_scale_f32 v2, s[2:3], v144, v144, 1.0
	v_rcp_f32_e32 v139, v2
	s_nop 0
	v_fma_f32 v152, -v2, v139, 1.0
	v_fmac_f32_e32 v139, v152, v139
	v_div_scale_f32 v152, vcc, 1.0, v144, 1.0
	v_mul_f32_e32 v158, v152, v139
	v_fma_f32 v159, -v2, v158, v152
	v_fmac_f32_e32 v158, v159, v139
	v_fma_f32 v2, -v2, v158, v152
	v_div_fmas_f32 v2, v2, v139, v158
	v_div_fixup_f32 v144, v2, v144, 1.0
	v_lshlrev_b32_e32 v2, 16, v153
	v_mul_f32_e32 v2, 0xbfb8aa3b, v2
	v_exp_f32_e32 v152, v2
	v_and_b32_e32 v2, 0xffff0000, v153
	v_mul_f32_e32 v2, 0xbfb8aa3b, v2
	v_exp_f32_e32 v153, v2
	v_pk_mul_f32 v[144:145], v[128:129], v[144:145]
	v_pk_add_f32 v[152:153], v[152:153], 1.0 op_sel_hi:[1,0]
	s_nop 0
	v_div_scale_f32 v2, s[2:3], v153, v153, 1.0
	v_rcp_f32_e32 v139, v2
	s_nop 0
	v_fma_f32 v158, -v2, v139, 1.0
	v_fmac_f32_e32 v139, v158, v139
	v_div_scale_f32 v158, vcc, 1.0, v153, 1.0
	v_mul_f32_e32 v159, v158, v139
	v_fma_f32 v160, -v2, v159, v158
	v_fmac_f32_e32 v159, v160, v139
	v_fma_f32 v2, -v2, v159, v158
	v_div_fmas_f32 v2, v2, v139, v159
	v_div_fixup_f32 v153, v2, v153, 1.0
	v_div_scale_f32 v2, s[2:3], v152, v152, 1.0
	v_rcp_f32_e32 v139, v2
	s_nop 0
	v_fma_f32 v158, -v2, v139, 1.0
	v_fmac_f32_e32 v139, v158, v139
	v_div_scale_f32 v158, vcc, 1.0, v152, 1.0
	v_mul_f32_e32 v159, v158, v139
	v_fma_f32 v160, -v2, v159, v158
	v_fmac_f32_e32 v159, v160, v139
	v_fma_f32 v2, -v2, v159, v158
	v_div_fmas_f32 v2, v2, v139, v159
	v_div_fixup_f32 v152, v2, v152, 1.0
	v_pk_mul_f32 v[152:153], v[130:131], v[152:153]
	s_and_b64 vcc, exec, s[4:5]
	s_cbranch_vccnz .LBB0_271
	flat_load_dwordx2 v[158:159], v[150:151]
	s_waitcnt vmcnt(0) lgkmcnt(0)
	v_lshlrev_b32_e32 v160, 16, v158
	v_and_b32_e32 v161, 0xffff0000, v158
	v_lshlrev_b32_e32 v158, 16, v159
	v_and_b32_e32 v159, 0xffff0000, v159
	v_pk_add_f32 v[144:145], v[144:145], v[160:161]
	v_pk_add_f32 v[152:153], v[152:153], v[158:159]

; __device__ __forceinline__ void gemm_phase(const Ctx& cx, const GemmArgs& g_, char* shm) {
;     ...
;               } else {
;                 float o0 = a[0], o1 = a[1], o2 = a[2], o3 = a[3];
;                 const bool r128 = (n0 >= C_DSAQ && n0 < C_HGQ) || (n0 >= C_DSAK && n0 < C_DSAV);
;                 const bool r64 = (n0 >= C_IDXQ && n0 < C_GLAA);
;                 if (r128 || r64) {
;                   float4 cs;
;                   float sc;
;                   if (r128) {
;                     cs = *(const float4*)(g.w + ((size_t)tok * 64 + ((n0 & 127) >> 1)) * 2);
;                     sc = (n0 < C_HGQ) ? 0.08838834764831845f : 1.0f;
;                   } else {
;                     cs = *(const float4*)(g.hout + ((size_t)tok * 32 + ((n0 & 63) >> 1)) * 2);
;                     sc = (n0 < C_IDXK) ? 0.125f : 1.0f;
;                   }
;                   o0 = (a[0] * cs.x - a[1] * cs.y) * sc; o1 = (a[1] * cs.x + a[0] * cs.y) * sc;
;                   o2 = (a[2] * cs.z - a[3] * cs.w) * sc; o3 = (a[3] * cs.z + a[2] * cs.w) * sc;
;                 }
.LBB0_272:
	s_movk_i32 s0, 0xe100
	v_mad_i64_i32 v[152:153], s[52:53], v136, s0, v[146:147]
	v_lshlrev_b64 v[144:145], 9, v[136:137]
	s_or_b64 s[58:59], s[6:7], s[10:11]
	s_movk_i32 s0, 0x5c00
	v_lshl_add_u64 v[150:151], s[30:31], 0, v[144:145]
	v_lshl_add_u64 v[144:145], s[24:25], 0, v[132:133]
	s_xor_b64 s[56:57], s[58:59], -1
	s_and_b64 vcc, exec, s[2:3]
	v_cmp_gt_i32_e64 s[6:7], s0, v140
	s_cbranch_vccz .LBB0_284
	s_and_saveexec_b64 s[2:3], s[6:7]
	s_xor_b64 s[2:3], exec, s[2:3]
	s_cbranch_execz .LBB0_281
	v_add_u32_e32 v2, 0xffffa700, v138
	v_cmp_gt_u32_e32 vcc, s77, v2
	s_or_b64 s[10:11], s[58:59], vcc
	s_and_saveexec_b64 s[6:7], s[10:11]
	s_cbranch_execz .LBB0_280
	s_and_saveexec_b64 s[10:11], s[56:57]
	s_xor_b64 s[10:11], exec, s[10:11]
	s_movk_i32 s0, 0x5b00
	v_lshlrev_b32_e32 v2, 2, v0
	v_cmp_gt_u32_e32 vcc, s0, v138
	v_lshl_add_u64 v[132:133], v[152:153], 0, v[2:3]
	s_nop 0
	v_cndmask_b32_e32 v2, 1.0, v166, vcc
	s_andn2_saveexec_b64 s[10:11], s[10:11]
	v_and_b32_e32 v2, 0x4c, v140
	v_lshlrev_b32_e32 v2, 2, v2
	v_cmp_gt_i32_e32 vcc, s81, v140
	v_lshl_add_u64 v[132:133], v[150:151], 0, v[2:3]
	s_nop 0
	v_cndmask_b32_e32 v2, 1.0, v167, vcc
	s_or_b64 exec, exec, s[10:11]
	s_nop 0
	flat_load_dwordx4 v[158:161], v[132:133]
	s_waitcnt vmcnt(0) lgkmcnt(0)
	v_pk_mul_f32 v[132:133], v[128:129], v[158:159] op_sel:[1,1] op_sel_hi:[1,0]
	s_nop 0
	v_pk_fma_f32 v[176:177], v[128:129], v[158:159], v[132:133] neg_lo:[0,0,1] neg_hi:[0,0,1]
	v_pk_fma_f32 v[128:129], v[128:129], v[158:159], v[132:133] op_sel_hi:[0,1,1]
	v_mov_b32_e32 v132, v131
	v_pk_mul_f32 v[132:133], v[132:133], v[160:161] op_sel:[0,1] op_sel_hi:[0,0]
	v_pk_fma_f32 v[158:159], v[130:131], v[160:161], v[132:133] neg_lo:[0,0,1] neg_hi:[0,0,1]
	v_pk_fma_f32 v[130:131], v[130:131], v[160:161], v[132:133] op_sel_hi:[0,1,1]
	v_mov_b32_e32 v177, v129
	v_mov_b32_e32 v159, v131
	v_pk_mul_f32 v[128:129], v[2:3], v[176:177] op_sel_hi:[0,1]
	v_pk_mul_f32 v[130:131], v[2:3], v[158:159] op_sel_hi:[0,1]

; __device__ __forceinline__ void gemm_phase(const Ctx& cx, const GemmArgs& g_, char* shm) {
;     ...
;               if (n0 >= C_GLAX) {
;                 const int i = n0 - C_GLAX;
;                 const float4 b4 = *(const float4*)(g.hin + i);
;                 float xs[4] = {a[0] + b4.x, a[1] + b4.y, a[2] + b4.z, a[3] + b4.w};
; #pragma unroll
;                 for (int j = 0; j < 4; ++j)
;                   xs[j] = (fminf(xs[j], 0.f) - __logf(1.0f + __expf(-fabsf(xs[j])))) * (1.0f / 16.0f);
;                 *(float4*)(g.f32buf + (size_t)tok * 1024 + i) = make_float4(xs[0], xs[1], xs[2], xs[3]);
.LBB0_281:
	s_andn2_saveexec_b64 s[2:3], s[2:3]
	s_cbranch_execz .LBB0_283
	v_add_u32_e32 v2, 0xffffa400, v140
	v_lshlrev_b64 v[160:161], 2, v[2:3]
	v_lshl_add_u64 v[132:133], s[26:27], 0, v[160:161]
	s_nop 0
	flat_load_dwordx4 v[176:179], v[132:133]
	s_mov_b32 s0, 0x3d800000
	v_lshl_add_u64 v[160:161], v[144:145], 0, v[160:161]
	s_waitcnt vmcnt(0) lgkmcnt(0)
	v_add_f32_e32 v2, v128, v176
	v_min_f32_e32 v128, 0, v2
	v_mul_f32_e64 v2, |v2|, s82
	v_exp_f32_e32 v2, v2
	v_add_f32_e32 v132, v129, v177
	v_add_f32_e32 v133, v130, v178
	v_add_f32_e32 v139, v131, v179
	v_add_f32_e32 v2, 1.0, v2
	v_cmp_gt_f32_e32 vcc, s83, v2
	v_mov_b32_e32 v176, 0
	v_mov_b32_e32 v178, 0
	v_cndmask_b32_e64 v129, 0, 32, vcc
	v_ldexp_f32 v2, v2, v129
	v_log_f32_e32 v2, v2
	s_nop 0
	v_mul_f32_e32 v129, 0x3f317217, v2
	v_fma_f32 v129, v2, s86, -v129
	v_fmac_f32_e32 v129, 0x3377d1cf, v2
	v_fmac_f32_e32 v129, 0x3f317217, v2
	v_cmp_lt_f32_e64 s[6:7], |v2|, s87
	s_nop 1
	v_cndmask_b32_e64 v2, v2, v129, s[6:7]
	v_cndmask_b32_e32 v129, 0, v165, vcc
	v_sub_f32_e32 v130, v2, v129
	v_mul_f32_e64 v2, |v132|, s82
	v_exp_f32_e32 v2, v2
	v_min_f32_e32 v129, 0, v132
	v_min_f32_e32 v132, 0, v133
	v_add_f32_e32 v2, 1.0, v2
	v_cmp_gt_f32_e32 vcc, s83, v2
	s_nop 1
	v_cndmask_b32_e64 v131, 0, 32, vcc
	v_ldexp_f32 v2, v2, v131
	v_log_f32_e32 v2, v2
	s_nop 0
	v_mul_f32_e32 v131, 0x3f317217, v2
	v_fma_f32 v131, v2, s86, -v131
	v_fmac_f32_e32 v131, 0x3377d1cf, v2
	v_fmac_f32_e32 v131, 0x3f317217, v2
	v_cmp_lt_f32_e64 s[6:7], |v2|, s87
	s_nop 1
	v_cndmask_b32_e64 v2, v2, v131, s[6:7]
	v_cndmask_b32_e32 v131, 0, v165, vcc
	v_sub_f32_e32 v131, v2, v131
	v_mul_f32_e64 v2, |v133|, s82
	v_exp_f32_e32 v2, v2
	v_pk_add_f32 v[128:129], v[128:129], v[130:131] neg_lo:[0,1] neg_hi:[0,1]
	v_add_f32_e32 v2, 1.0, v2
	v_cmp_gt_f32_e32 vcc, s83, v2
	v_pk_mul_f32 v[128:129], v[128:129], s[0:1] op_sel_hi:[1,0]
	s_nop 0
	v_cndmask_b32_e64 v133, 0, 32, vcc
	v_ldexp_f32 v2, v2, v133
	v_log_f32_e32 v2, v2
	s_nop 0
	v_mul_f32_e32 v133, 0x3f317217, v2
	v_fma_f32 v133, v2, s86, -v133
	v_fmac_f32_e32 v133, 0x3377d1cf, v2
	v_fmac_f32_e32 v133, 0x3f317217, v2
	v_cmp_lt_f32_e64 s[6:7], |v2|, s87
	s_nop 1
	v_cndmask_b32_e64 v2, v2, v133, s[6:7]
	v_cndmask_b32_e32 v133, 0, v165, vcc
	v_sub_f32_e32 v158, v2, v133
	v_mul_f32_e64 v2, |v139|, s82
	v_exp_f32_e32 v2, v2
	v_min_f32_e32 v133, 0, v139
	v_add_f32_e32 v2, 1.0, v2
	v_cmp_gt_f32_e32 vcc, s83, v2
	s_nop 1
	v_cndmask_b32_e64 v139, 0, 32, vcc
	v_ldexp_f32 v2, v2, v139
	v_log_f32_e32 v2, v2
	s_nop 0
	v_mul_f32_e32 v139, 0x3f317217, v2
	v_fma_f32 v139, v2, s86, -v139
	v_fmac_f32_e32 v139, 0x3377d1cf, v2
	v_fmac_f32_e32 v139, 0x3f317217, v2
	v_cmp_lt_f32_e64 s[6:7], |v2|, s87
	s_nop 1
	v_cndmask_b32_e64 v2, v2, v139, s[6:7]
	v_cndmask_b32_e32 v139, 0, v165, vcc
	v_sub_f32_e32 v159, v2, v139
	v_pk_add_f32 v[130:131], v[132:133], v[158:159] neg_lo:[0,1] neg_hi:[0,1]
	s_nop 0
	v_pk_mul_f32 v[130:131], v[130:131], s[0:1] op_sel_hi:[1,0]
	flat_store_dwordx4 v[160:161], v[128:131]

; __device__ __forceinline__ void gemm_phase(const Ctx& cx, const GemmArgs& g_, char* shm) {
;     ...
;             } else if (g.epi == EPI_RELU2) {
;               float r0 = fmaxf(a[0], 0.f), r1 = fmaxf(a[1], 0.f), r2 = fmaxf(a[2], 0.f), r3 = fmaxf(a[3], 0.f);
;               uint2 o; o.x = pack2(r0 * r0, r1 * r1); o.y = pack2(r2 * r2, r3 * r3);
;               EMIT_BF16(g.ldo, o);
.LBB0_293:
	s_cmp_gt_i32 s38, 4
	s_cbranch_scc0 .LBB0_297
	s_cmp_eq_u32 s38, 5
	s_mov_b64 s[6:7], -1
	s_cbranch_scc0 .LBB0_296
	v_max_f32_e32 v2, v126, v126
	v_max_f32_e32 v128, 0, v2
	v_max_f32_e32 v2, v127, v127
	v_max_f32_e32 v129, 0, v2
	v_pk_mul_f32 v[128:129], v[128:129], v[128:129]
	v_max_f32_e32 v2, v124, v124
	v_cvt_pk_bf16_f32 v131, v128, v129
	v_max_f32_e32 v128, 0, v2
	v_max_f32_e32 v2, v125, v125
	v_max_f32_e32 v129, 0, v2
	v_pk_mul_f32 v[128:129], v[128:129], v[128:129]
	v_ashrrev_i32_e32 v133, 31, v132
	v_cvt_pk_bf16_f32 v130, v128, v129
	v_mov_b32_e32 v128, v178
	v_mov_b32_e32 v129, v176
	s_nop 0
	v_permlane16_swap_b32_e32 v128, v130
	v_permlane16_swap_b32_e32 v129, v131
	v_lshl_add_u64 v[160:161], v[132:133], 1, v[158:159]
	s_nop 0
	flat_store_dwordx4 v[160:161], v[128:131] offset:32
	s_mov_b64 s[6:7], 0

; __device__ __forceinline__ void gemm_phase(const Ctx& cx, const GemmArgs& g_, char* shm) {
;     ...
;             } else if (g.epi == EPI_RES) {
;               const float4 hv = *(const float4*)(g.hin + (size_t)tok * DM + n0);
;               const float h0 = hv.x + a[0], h1 = hv.y + a[1], h2 = hv.z + a[2], h3 = hv.w + a[3];
;               *(float4*)(g.hout + (size_t)tok * DM + n0) = make_float4(h0, h1, h2, h3);
;               if (g.w != nullptr) {
;                 const float4 nw = *(const float4*)(g.w + n0);
;                 uint2 o; o.x = pack2(h0 * nw.x, h1 * nw.y); o.y = pack2(h2 * nw.z, h3 * nw.w);
;                 EMIT_BF16(DM, o);
;                 ssq += h0 * h0 + h1 * h1 + h2 * h2 + h3 * h3;
;               }
.LBB0_297:
	s_and_b64 vcc, exec, s[10:11]
	v_mov_b32_e32 v133, v179
	s_cbranch_vccz .LBB0_300
	v_ashrrev_i32_e32 v139, 31, v138
	v_lshl_add_u64 v[160:161], v[138:139], 0, v[0:1]
	v_lshlrev_b64 v[180:181], 2, v[160:161]
	v_lshl_add_u64 v[128:129], v[148:149], 0, v[180:181]
	s_nop 0
	flat_load_dwordx4 v[128:131], v[128:129] offset:64
	s_andn2_b64 vcc, exec, s[42:43]
	v_lshl_add_u64 v[180:181], v[146:147], 0, v[180:181]
	v_mov_b32_e32 v133, v179
	s_waitcnt vmcnt(0) lgkmcnt(0)
	v_pk_add_f32 v[128:129], v[124:125], v[128:129]
	v_pk_add_f32 v[130:131], v[126:127], v[130:131]
	flat_store_dwordx4 v[180:181], v[128:131] offset:64
	s_cbranch_vccnz .LBB0_300
	v_lshl_add_u64 v[160:161], v[160:161], 2, s[30:31]
	global_load_dwordx4 v[180:183], v[160:161], off offset:64
	v_ashrrev_i32_e32 v133, 31, v132
	s_waitcnt vmcnt(0)
	v_pk_mul_f32 v[160:161], v[130:131], v[182:183]
	s_nop 0
	v_cvt_pk_bf16_f32 v183, v160, v161
	v_pk_mul_f32 v[160:161], v[128:129], v[180:181]
	v_pk_mul_f32 v[128:129], v[128:129], v[128:129]
	v_pk_mul_f32 v[130:131], v[130:131], v[130:131]
	v_add_f32_e32 v2, v128, v129
	v_cvt_pk_bf16_f32 v182, v160, v161
	v_mov_b32_e32 v180, v178
	v_mov_b32_e32 v181, v176
	v_add_f32_e32 v2, v2, v130
	v_permlane16_swap_b32_e32 v180, v182
	v_permlane16_swap_b32_e32 v181, v183
	v_lshl_add_u64 v[160:161], v[132:133], 1, v[134:135]
	v_add_f32_e32 v2, v2, v131
	flat_store_dwordx4 v[160:161], v[180:183] offset:32
	v_add_f32_e32 v133, v179, v2

; __device__ __forceinline__ float b2f(u16 b) { return __uint_as_float(((uint32_t)b) << 16); }
; __device__ __forceinline__ float sigmoidf_(float x) { return 1.0f / (1.0f + __expf(-x)); }
; __device__ __forceinline__ void gemm_phase(const Ctx& cx, const GemmArgs& g_, char* shm) {
;     ...
;             } else {
;               const uint2 gv = *(const uint2*)(g.gate + (size_t)tok * NP + n0);
;               float v0 = sigmoidf_(b2f((u16)(gv.x & 0xffff))) * a[0], v1 = sigmoidf_(b2f((u16)(gv.x >> 16))) * a[1];
;               float v2 = sigmoidf_(b2f((u16)(gv.y & 0xffff))) * a[2], v3 = sigmoidf_(b2f((u16)(gv.y >> 16))) * a[3];
;               uint2* mp = (uint2*)(g.outb + (size_t)tok * DM + n0);
;               if (g.epi != EPI_BR0) {
;                 const uint2 pv = *mp;
;                 v0 += b2f((u16)(pv.x & 0xffff)); v1 += b2f((u16)(pv.x >> 16));
;                 v2 += b2f((u16)(pv.y & 0xffff)); v3 += b2f((u16)(pv.y >> 16));
;               }
;               uint2 o; o.x = pack2(v0, v1); o.y = pack2(v2, v3);
;               *mp = o;
;             }
.LBB0_302:
	v_lshl_add_u64 v[128:129], v[138:139], 0, v[0:1]
	v_lshlrev_b64 v[130:131], 1, v[128:129]
	v_lshl_add_u64 v[128:129], v[156:157], 0, v[130:131]
	s_nop 0
	flat_load_dwordx2 v[160:161], v[128:129] offset:32
	v_lshl_add_u64 v[130:131], v[134:135], 0, v[130:131]
	s_waitcnt vmcnt(0) lgkmcnt(0)
	v_lshlrev_b32_e32 v2, 16, v160
	v_mul_f32_e32 v2, 0xbfb8aa3b, v2
	v_exp_f32_e32 v128, v2
	v_and_b32_e32 v2, 0xffff0000, v160
	v_mul_f32_e32 v2, 0xbfb8aa3b, v2
	v_exp_f32_e32 v129, v2
	s_nop 0
	v_pk_add_f32 v[128:129], v[128:129], 1.0 op_sel_hi:[1,0]
	s_nop 0
	v_div_scale_f32 v2, s[2:3], v129, v129, 1.0
	v_rcp_f32_e32 v133, v2
	s_nop 0
	v_fma_f32 v160, -v2, v133, 1.0
	v_fmac_f32_e32 v133, v160, v133
	v_div_scale_f32 v160, vcc, 1.0, v129, 1.0
	v_mul_f32_e32 v177, v160, v133
	v_fma_f32 v180, -v2, v177, v160
	v_fmac_f32_e32 v177, v180, v133
	v_fma_f32 v2, -v2, v177, v160
	v_div_fmas_f32 v2, v2, v133, v177
	v_div_fixup_f32 v129, v2, v129, 1.0
	v_div_scale_f32 v2, s[2:3], v128, v128, 1.0
	v_rcp_f32_e32 v133, v2
	s_nop 0
	v_fma_f32 v160, -v2, v133, 1.0
	v_fmac_f32_e32 v133, v160, v133
	v_div_scale_f32 v160, vcc, 1.0, v128, 1.0
	v_mul_f32_e32 v177, v160, v133
	v_fma_f32 v180, -v2, v177, v160
	v_fmac_f32_e32 v177, v180, v133
	v_fma_f32 v2, -v2, v177, v160
	v_div_fmas_f32 v2, v2, v133, v177
	v_div_fixup_f32 v128, v2, v128, 1.0
	v_lshlrev_b32_e32 v2, 16, v161
	v_mul_f32_e32 v2, 0xbfb8aa3b, v2
	v_exp_f32_e32 v160, v2
	v_and_b32_e32 v2, 0xffff0000, v161
	v_mul_f32_e32 v2, 0xbfb8aa3b, v2
	v_exp_f32_e32 v161, v2
	v_pk_mul_f32 v[128:129], v[124:125], v[128:129]
	v_pk_add_f32 v[160:161], v[160:161], 1.0 op_sel_hi:[1,0]
	s_nop 0
	v_div_scale_f32 v2, s[2:3], v161, v161, 1.0
	v_rcp_f32_e32 v133, v2
	s_nop 0
	v_fma_f32 v177, -v2, v133, 1.0
	v_fmac_f32_e32 v133, v177, v133
	v_div_scale_f32 v177, vcc, 1.0, v161, 1.0
	v_mul_f32_e32 v180, v177, v133
	v_fma_f32 v181, -v2, v180, v177
	v_fmac_f32_e32 v180, v181, v133
	v_fma_f32 v2, -v2, v180, v177
	v_div_fmas_f32 v2, v2, v133, v180
	v_div_fixup_f32 v161, v2, v161, 1.0
	v_div_scale_f32 v2, s[2:3], v160, v160, 1.0
	v_rcp_f32_e32 v133, v2
	s_nop 0
	v_fma_f32 v177, -v2, v133, 1.0
	v_fmac_f32_e32 v133, v177, v133
	v_div_scale_f32 v177, vcc, 1.0, v160, 1.0
	v_mul_f32_e32 v180, v177, v133
	v_fma_f32 v181, -v2, v180, v177
	v_fmac_f32_e32 v180, v181, v133
	v_fma_f32 v2, -v2, v180, v177
	v_div_fmas_f32 v2, v2, v133, v180
	v_div_fixup_f32 v160, v2, v160, 1.0
	v_pk_mul_f32 v[160:161], v[126:127], v[160:161]
	s_and_b64 vcc, exec, s[4:5]
	s_cbranch_vccnz .LBB0_304
	flat_load_dwordx2 v[180:181], v[130:131] offset:32
	s_waitcnt vmcnt(0) lgkmcnt(0)
	v_lshlrev_b32_e32 v182, 16, v180
	v_and_b32_e32 v183, 0xffff0000, v180
	v_lshlrev_b32_e32 v180, 16, v181
	v_and_b32_e32 v181, 0xffff0000, v181
	v_pk_add_f32 v[128:129], v[128:129], v[182:183]
	v_pk_add_f32 v[160:161], v[160:161], v[180:181]

; __device__ __forceinline__ void gemm_phase(const Ctx& cx, const GemmArgs& g_, char* shm) {
;     ...
; #pragma unroll
;           for (int m = 0; m < 4; ++m) {
;             const int n0 = brow + ai * 128 + wr * 64 + m * 16 + fq * 4;
;             f32x4 a = acc[ai][bj][m][n];
;             if (g.epi == EPI_PROJ || g.epi == EPI_RELU2) { a[0] *= rs; a[1] *= rs; a[2] *= rs; a[3] *= rs; }
;             if (g.epi == EPI_PROJ) {
;               if (n0 >= C_GLAX) {
;                 const int i = n0 - C_GLAX;
;                 const float4 b4 = *(const float4*)(g.hin + i);
;                 float xs[4] = {a[0] + b4.x, a[1] + b4.y, a[2] + b4.z, a[3] + b4.w};
; #pragma unroll
;                 for (int j = 0; j < 4; ++j)
;                   xs[j] = (fminf(xs[j], 0.f) - __logf(1.0f + __expf(-fabsf(xs[j])))) * (1.0f / 16.0f);
;                 *(float4*)(g.f32buf + (size_t)tok * 1024 + i) = make_float4(xs[0], xs[1], xs[2], xs[3]);
;               } else {
;                 float o0 = a[0], o1 = a[1], o2 = a[2], o3 = a[3];
;                 const bool r128 = (n0 >= C_DSAQ && n0 < C_HGQ) || (n0 >= C_DSAK && n0 < C_DSAV);
;                 const bool r64 = (n0 >= C_IDXQ && n0 < C_GLAA);
;                 if (r128 || r64) {
;                   float4 cs;
;                   float sc;
;                   if (r128) {
;                     cs = *(const float4*)(g.w + ((size_t)tok * 64 + ((n0 & 127) >> 1)) * 2);
;                     sc = (n0 < C_HGQ) ? 0.08838834764831845f : 1.0f;
;                   } else {
;                     cs = *(const float4*)(g.hout + ((size_t)tok * 32 + ((n0 & 63) >> 1)) * 2);
;                     sc = (n0 < C_IDXK) ? 0.125f : 1.0f;
;                   }
;                   o0 = (a[0] * cs.x - a[1] * cs.y) * sc; o1 = (a[1] * cs.x + a[0] * cs.y) * sc;
;                   o2 = (a[2] * cs.z - a[3] * cs.w) * sc; o3 = (a[3] * cs.z + a[2] * cs.w) * sc;
;                 }
;                 uint2 o; o.x = pack2(o0, o1); o.y = pack2(o2, o3);
;                 EMIT_BF16(g.ldo, o);
.LBB0_305:
	v_or_b32_e32 v177, v138, v173
	s_movk_i32 s0, 0x5c00
	s_and_b64 vcc, exec, s[2:3]
	v_cmp_gt_i32_e64 s[6:7], s0, v177
	s_cbranch_vccz .LBB0_317
	s_and_saveexec_b64 s[2:3], s[6:7]
	s_xor_b64 s[2:3], exec, s[2:3]
	s_cbranch_execz .LBB0_314
	v_add_u32_e32 v2, 0xffffa700, v138
	v_cmp_gt_u32_e32 vcc, s77, v2
	s_or_b64 s[10:11], s[58:59], vcc
	s_and_saveexec_b64 s[6:7], s[10:11]
	s_cbranch_execz .LBB0_313
	s_and_saveexec_b64 s[10:11], s[56:57]
	s_xor_b64 s[10:11], exec, s[10:11]
	v_lshlrev_b32_e32 v2, 2, v0
	s_movk_i32 s0, 0x5b00
	v_lshl_add_u64 v[128:129], v[152:153], 0, v[2:3]
	v_cmp_gt_u32_e32 vcc, s0, v138
	v_lshl_add_u64 v[128:129], v[128:129], 0, 64
	s_nop 0
	v_cndmask_b32_e32 v2, 1.0, v166, vcc
	s_andn2_saveexec_b64 s[10:11], s[10:11]
	v_and_b32_e32 v2, 0x5c, v177
	v_lshlrev_b32_e32 v2, 2, v2
	v_cmp_gt_i32_e32 vcc, s81, v177
	v_lshl_add_u64 v[128:129], v[150:151], 0, v[2:3]
	s_nop 0
	v_cndmask_b32_e32 v2, 1.0, v167, vcc
	s_or_b64 exec, exec, s[10:11]
	s_nop 0
	flat_load_dwordx4 v[128:131], v[128:129]
	s_waitcnt vmcnt(0) lgkmcnt(0)
	v_pk_mul_f32 v[160:161], v[124:125], v[128:129] op_sel:[1,1] op_sel_hi:[1,0]
	s_nop 0
	v_pk_fma_f32 v[180:181], v[124:125], v[128:129], v[160:161] neg_lo:[0,0,1] neg_hi:[0,0,1]
	v_pk_fma_f32 v[124:125], v[124:125], v[128:129], v[160:161] op_sel_hi:[0,1,1]
	v_mov_b32_e32 v128, v127
	v_pk_mul_f32 v[128:129], v[128:129], v[130:131] op_sel:[0,1] op_sel_hi:[0,0]
	v_pk_fma_f32 v[160:161], v[126:127], v[130:131], v[128:129] neg_lo:[0,0,1] neg_hi:[0,0,1]
	v_pk_fma_f32 v[126:127], v[126:127], v[130:131], v[128:129] op_sel_hi:[0,1,1]
	v_mov_b32_e32 v181, v125
	v_mov_b32_e32 v161, v127
	v_pk_mul_f32 v[124:125], v[2:3], v[180:181] op_sel_hi:[0,1]
	v_pk_mul_f32 v[126:127], v[2:3], v[160:161] op_sel_hi:[0,1]
.LBB0_313:
	s_or_b64 exec, exec, s[6:7]
	v_cvt_pk_bf16_f32 v127, v126, v127
	v_cvt_pk_bf16_f32 v126, v124, v125
	v_mov_b32_e32 v124, v178
	v_mov_b32_e32 v125, v176
	v_ashrrev_i32_e32 v133, 31, v132
	v_permlane16_swap_b32_e32 v124, v126
	v_permlane16_swap_b32_e32 v125, v127
	v_lshl_add_u64 v[128:129], v[132:133], 1, v[158:159]
	s_nop 0
	flat_store_dwordx4 v[128:129], v[124:127] offset:32
.LBB0_314:
	s_andn2_saveexec_b64 s[2:3], s[2:3]
	s_cbranch_execz .LBB0_316
	v_add_u32_e32 v2, 0xffffa400, v177
	v_lshlrev_b64 v[160:161], 2, v[2:3]
	v_lshl_add_u64 v[128:129], s[26:27], 0, v[160:161]
	s_nop 0
	flat_load_dwordx4 v[128:131], v[128:129]
	s_mov_b32 s0, 0x3d800000
	v_lshl_add_u64 v[160:161], v[144:145], 0, v[160:161]
	s_waitcnt vmcnt(0) lgkmcnt(0)
	v_add_f32_e32 v2, v124, v128
	v_min_f32_e32 v124, 0, v2
	v_mul_f32_e64 v2, |v2|, s82
	v_exp_f32_e32 v2, v2
	v_add_f32_e32 v128, v125, v129
	v_add_f32_e32 v129, v126, v130
	v_add_f32_e32 v131, v127, v131
	v_add_f32_e32 v2, 1.0, v2
	v_cmp_gt_f32_e32 vcc, s83, v2
	s_nop 1
	v_cndmask_b32_e64 v125, 0, 32, vcc
	v_ldexp_f32 v2, v2, v125
	v_log_f32_e32 v2, v2
	s_nop 0
	v_mul_f32_e32 v125, 0x3f317217, v2
	v_fma_f32 v125, v2, s86, -v125
	v_fmac_f32_e32 v125, 0x3377d1cf, v2
	v_fmac_f32_e32 v125, 0x3f317217, v2
	v_cmp_lt_f32_e64 s[6:7], |v2|, s87
	s_nop 1
	v_cndmask_b32_e64 v2, v2, v125, s[6:7]
	v_cndmask_b32_e32 v125, 0, v165, vcc
	v_sub_f32_e32 v126, v2, v125
	v_mul_f32_e64 v2, |v128|, s82
	v_exp_f32_e32 v2, v2
	v_min_f32_e32 v125, 0, v128
	v_min_f32_e32 v128, 0, v129
	v_add_f32_e32 v2, 1.0, v2
	v_cmp_gt_f32_e32 vcc, s83, v2
	s_nop 1
	v_cndmask_b32_e64 v127, 0, 32, vcc
	v_ldexp_f32 v2, v2, v127
	v_log_f32_e32 v2, v2
	s_nop 0
	v_mul_f32_e32 v127, 0x3f317217, v2
	v_fma_f32 v127, v2, s86, -v127
	v_fmac_f32_e32 v127, 0x3377d1cf, v2
	v_fmac_f32_e32 v127, 0x3f317217, v2
	v_cmp_lt_f32_e64 s[6:7], |v2|, s87
	s_nop 1
	v_cndmask_b32_e64 v2, v2, v127, s[6:7]
	v_cndmask_b32_e32 v127, 0, v165, vcc
	v_sub_f32_e32 v127, v2, v127
	v_mul_f32_e64 v2, |v129|, s82
	v_exp_f32_e32 v2, v2
	v_pk_add_f32 v[124:125], v[124:125], v[126:127] neg_lo:[0,1] neg_hi:[0,1]
	v_add_f32_e32 v2, 1.0, v2
	v_cmp_gt_f32_e32 vcc, s83, v2
	v_pk_mul_f32 v[124:125], v[124:125], s[0:1] op_sel_hi:[1,0]
	s_nop 0
	v_cndmask_b32_e64 v129, 0, 32, vcc
	v_ldexp_f32 v2, v2, v129
	v_log_f32_e32 v2, v2
	s_nop 0
	v_mul_f32_e32 v129, 0x3f317217, v2
	v_fma_f32 v129, v2, s86, -v129
	v_fmac_f32_e32 v129, 0x3377d1cf, v2
	v_fmac_f32_e32 v129, 0x3f317217, v2
	v_cmp_lt_f32_e64 s[6:7], |v2|, s87
	s_nop 1
	v_cndmask_b32_e64 v2, v2, v129, s[6:7]
	v_cndmask_b32_e32 v129, 0, v165, vcc
	v_sub_f32_e32 v130, v2, v129
	v_mul_f32_e64 v2, |v131|, s82
	v_exp_f32_e32 v2, v2
	v_min_f32_e32 v129, 0, v131
	v_add_f32_e32 v2, 1.0, v2
	v_cmp_gt_f32_e32 vcc, s83, v2
	s_nop 1
	v_cndmask_b32_e64 v131, 0, 32, vcc
	v_ldexp_f32 v2, v2, v131
	v_log_f32_e32 v2, v2
	s_nop 0
	v_mul_f32_e32 v131, 0x3f317217, v2
	v_fma_f32 v131, v2, s86, -v131
	v_fmac_f32_e32 v131, 0x3377d1cf, v2
	v_fmac_f32_e32 v131, 0x3f317217, v2
	v_cmp_lt_f32_e64 s[6:7], |v2|, s87
	s_nop 1
	v_cndmask_b32_e64 v2, v2, v131, s[6:7]
	v_cndmask_b32_e32 v131, 0, v165, vcc
	v_sub_f32_e32 v131, v2, v131
	v_pk_add_f32 v[126:127], v[128:129], v[130:131] neg_lo:[0,1] neg_hi:[0,1]
	s_nop 0
	v_pk_mul_f32 v[126:127], v[126:127], s[0:1] op_sel_hi:[1,0]
	flat_store_dwordx4 v[160:161], v[124:127]

; __device__ __forceinline__ void gemm_phase(const Ctx& cx, const GemmArgs& g_, char* shm) {
;     ...
;             } else if (g.epi == EPI_RES) {
;               const float4 hv = *(const float4*)(g.hin + (size_t)tok * DM + n0);
;               const float h0 = hv.x + a[0], h1 = hv.y + a[1], h2 = hv.z + a[2], h3 = hv.w + a[3];
;               *(float4*)(g.hout + (size_t)tok * DM + n0) = make_float4(h0, h1, h2, h3);
;               if (g.w != nullptr) {
;                 const float4 nw = *(const float4*)(g.w + n0);
;                 uint2 o; o.x = pack2(h0 * nw.x, h1 * nw.y); o.y = pack2(h2 * nw.z, h3 * nw.w);
;                 EMIT_BF16(DM, o);
;                 ssq += h0 * h0 + h1 * h1 + h2 * h2 + h3 * h3;
;               }
.LBB0_330:
	s_and_b64 vcc, exec, s[10:11]
	v_mov_b32_e32 v160, v133
	s_cbranch_vccz .LBB0_333
	v_lshl_add_u64 v[130:131], v[138:139], 0, v[0:1]
	v_lshlrev_b64 v[124:125], 2, v[130:131]
	v_lshl_add_u64 v[126:127], v[148:149], 0, v[124:125]
	s_nop 0
	flat_load_dwordx4 v[126:129], v[126:127] offset:128
	v_lshl_add_u64 v[124:125], v[146:147], 0, v[124:125]
	s_andn2_b64 vcc, exec, s[42:43]
	v_mov_b32_e32 v160, v133
	s_waitcnt vmcnt(0) lgkmcnt(0)
	v_pk_add_f32 v[126:127], v[120:121], v[126:127]
	v_pk_add_f32 v[128:129], v[122:123], v[128:129]
	flat_store_dwordx4 v[124:125], v[126:129] offset:128
	v_mov_b32_e32 v125, v176
	v_mov_b32_e32 v124, v178
	s_cbranch_vccnz .LBB0_333
	v_lshl_add_u64 v[124:125], v[130:131], 2, s[30:31]
	global_load_dwordx4 v[180:183], v[124:125], off offset:128
	v_pk_mul_f32 v[124:125], v[126:127], v[126:127]
	v_pk_mul_f32 v[130:131], v[128:129], v[128:129]
	v_add_f32_e32 v2, v124, v125
	v_add_f32_e32 v2, v2, v130
	v_add_f32_e32 v2, v2, v131
	v_add_f32_e32 v160, v133, v2
	s_waitcnt vmcnt(0)
	v_pk_mul_f32 v[124:125], v[128:129], v[182:183]
	v_pk_mul_f32 v[126:127], v[126:127], v[180:181]
	v_cvt_pk_bf16_f32 v125, v124, v125
	v_cvt_pk_bf16_f32 v124, v126, v127

; __device__ __forceinline__ float b2f(u16 b) { return __uint_as_float(((uint32_t)b) << 16); }
; __device__ __forceinline__ float sigmoidf_(float x) { return 1.0f / (1.0f + __expf(-x)); }
; __device__ __forceinline__ void gemm_phase(const Ctx& cx, const GemmArgs& g_, char* shm) {
;     ...
;             } else {
;               const uint2 gv = *(const uint2*)(g.gate + (size_t)tok * NP + n0);
;               float v0 = sigmoidf_(b2f((u16)(gv.x & 0xffff))) * a[0], v1 = sigmoidf_(b2f((u16)(gv.x >> 16))) * a[1];
;               float v2 = sigmoidf_(b2f((u16)(gv.y & 0xffff))) * a[2], v3 = sigmoidf_(b2f((u16)(gv.y >> 16))) * a[3];
;               uint2* mp = (uint2*)(g.outb + (size_t)tok * DM + n0);
;               if (g.epi != EPI_BR0) {
;                 const uint2 pv = *mp;
;                 v0 += b2f((u16)(pv.x & 0xffff)); v1 += b2f((u16)(pv.x >> 16));
;                 v2 += b2f((u16)(pv.y & 0xffff)); v3 += b2f((u16)(pv.y >> 16));
;               }
;               uint2 o; o.x = pack2(v0, v1); o.y = pack2(v2, v3);
;               *mp = o;
;             }
.LBB0_335:
	v_lshl_add_u64 v[124:125], v[138:139], 0, v[0:1]
	v_lshlrev_b64 v[126:127], 1, v[124:125]
	v_lshl_add_u64 v[124:125], v[156:157], 0, v[126:127]
	s_nop 0
	flat_load_dwordx2 v[128:129], v[124:125] offset:64
	v_lshl_add_u64 v[126:127], v[134:135], 0, v[126:127]
	s_waitcnt vmcnt(0) lgkmcnt(0)
	v_lshlrev_b32_e32 v2, 16, v128
	v_mul_f32_e32 v2, 0xbfb8aa3b, v2
	v_exp_f32_e32 v124, v2
	v_and_b32_e32 v2, 0xffff0000, v128
	v_mul_f32_e32 v2, 0xbfb8aa3b, v2
	v_exp_f32_e32 v125, v2
	s_nop 0
	v_pk_add_f32 v[124:125], v[124:125], 1.0 op_sel_hi:[1,0]
	s_nop 0
	v_div_scale_f32 v2, s[2:3], v125, v125, 1.0
	v_rcp_f32_e32 v128, v2
	s_nop 0
	v_fma_f32 v130, -v2, v128, 1.0
	v_fmac_f32_e32 v128, v130, v128
	v_div_scale_f32 v130, vcc, 1.0, v125, 1.0
	v_mul_f32_e32 v131, v130, v128
	v_fma_f32 v160, -v2, v131, v130
	v_fmac_f32_e32 v131, v160, v128
	v_fma_f32 v2, -v2, v131, v130
	v_div_fmas_f32 v2, v2, v128, v131
	v_div_fixup_f32 v125, v2, v125, 1.0
	v_div_scale_f32 v2, s[2:3], v124, v124, 1.0
	v_rcp_f32_e32 v128, v2
	s_nop 0
	v_fma_f32 v130, -v2, v128, 1.0
	v_fmac_f32_e32 v128, v130, v128
	v_div_scale_f32 v130, vcc, 1.0, v124, 1.0
	v_mul_f32_e32 v131, v130, v128
	v_fma_f32 v160, -v2, v131, v130
	v_fmac_f32_e32 v131, v160, v128
	v_fma_f32 v2, -v2, v131, v130
	v_div_fmas_f32 v2, v2, v128, v131
	v_div_fixup_f32 v124, v2, v124, 1.0
	v_lshlrev_b32_e32 v2, 16, v129
	v_mul_f32_e32 v2, 0xbfb8aa3b, v2
	v_exp_f32_e32 v128, v2
	v_and_b32_e32 v2, 0xffff0000, v129
	v_mul_f32_e32 v2, 0xbfb8aa3b, v2
	v_exp_f32_e32 v129, v2
	v_pk_mul_f32 v[124:125], v[120:121], v[124:125]
	v_pk_add_f32 v[128:129], v[128:129], 1.0 op_sel_hi:[1,0]
	s_nop 0
	v_div_scale_f32 v2, s[2:3], v129, v129, 1.0
	v_rcp_f32_e32 v130, v2
	s_nop 0
	v_fma_f32 v131, -v2, v130, 1.0
	v_fmac_f32_e32 v130, v131, v130
	v_div_scale_f32 v131, vcc, 1.0, v129, 1.0
	v_mul_f32_e32 v160, v131, v130
	v_fma_f32 v161, -v2, v160, v131
	v_fmac_f32_e32 v160, v161, v130
	v_fma_f32 v2, -v2, v160, v131
	v_div_fmas_f32 v2, v2, v130, v160
	v_div_fixup_f32 v129, v2, v129, 1.0
	v_div_scale_f32 v2, s[2:3], v128, v128, 1.0
	v_rcp_f32_e32 v130, v2
	s_nop 0
	v_fma_f32 v131, -v2, v130, 1.0
	v_fmac_f32_e32 v130, v131, v130
	v_div_scale_f32 v131, vcc, 1.0, v128, 1.0
	v_mul_f32_e32 v160, v131, v130
	v_fma_f32 v161, -v2, v160, v131
	v_fmac_f32_e32 v160, v161, v130
	v_fma_f32 v2, -v2, v160, v131
	v_div_fmas_f32 v2, v2, v130, v160
	v_div_fixup_f32 v128, v2, v128, 1.0
	v_pk_mul_f32 v[128:129], v[122:123], v[128:129]
	s_and_b64 vcc, exec, s[4:5]
	s_cbranch_vccnz .LBB0_337
	flat_load_dwordx2 v[130:131], v[126:127] offset:64
	s_waitcnt vmcnt(0) lgkmcnt(0)
	v_lshlrev_b32_e32 v160, 16, v130
	v_and_b32_e32 v161, 0xffff0000, v130
	v_lshlrev_b32_e32 v130, 16, v131
	v_and_b32_e32 v131, 0xffff0000, v131
	v_pk_add_f32 v[124:125], v[124:125], v[160:161]
	v_pk_add_f32 v[128:129], v[128:129], v[130:131]

; __device__ __forceinline__ void gemm_phase(const Ctx& cx, const GemmArgs& g_, char* shm) {
;     ...
;               } else {
;                 float o0 = a[0], o1 = a[1], o2 = a[2], o3 = a[3];
;                 const bool r128 = (n0 >= C_DSAQ && n0 < C_HGQ) || (n0 >= C_DSAK && n0 < C_DSAV);
;                 const bool r64 = (n0 >= C_IDXQ && n0 < C_GLAA);
;                 if (r128 || r64) {
;                   float4 cs;
;                   float sc;
;                   if (r128) {
;                     cs = *(const float4*)(g.w + ((size_t)tok * 64 + ((n0 & 127) >> 1)) * 2);
;                     sc = (n0 < C_HGQ) ? 0.08838834764831845f : 1.0f;
;                   } else {
;                     cs = *(const float4*)(g.hout + ((size_t)tok * 32 + ((n0 & 63) >> 1)) * 2);
;                     sc = (n0 < C_IDXK) ? 0.125f : 1.0f;
;                   }
;                   o0 = (a[0] * cs.x - a[1] * cs.y) * sc; o1 = (a[1] * cs.x + a[0] * cs.y) * sc;
;                   o2 = (a[2] * cs.z - a[3] * cs.w) * sc; o3 = (a[3] * cs.z + a[2] * cs.w) * sc;
;                 }
.LBB0_338:
	v_or_b32_e32 v161, v138, v174
	s_movk_i32 s0, 0x5c00
	s_and_b64 vcc, exec, s[2:3]
	v_cmp_gt_i32_e64 s[6:7], s0, v161
	s_cbranch_vccz .LBB0_350
	s_and_saveexec_b64 s[2:3], s[6:7]
	s_xor_b64 s[2:3], exec, s[2:3]
	s_cbranch_execz .LBB0_347
	v_add_u32_e32 v2, 0xffffa700, v138
	v_cmp_gt_u32_e32 vcc, s77, v2
	s_or_b64 s[10:11], s[58:59], vcc
	s_and_saveexec_b64 s[6:7], s[10:11]
	s_cbranch_execz .LBB0_346
	s_and_saveexec_b64 s[10:11], s[56:57]
	s_xor_b64 s[10:11], exec, s[10:11]
	v_lshlrev_b32_e32 v2, 2, v0
	s_movk_i32 s0, 0x5b00
	v_lshl_add_u64 v[124:125], v[152:153], 0, v[2:3]
	v_cmp_gt_u32_e32 vcc, s0, v138
	v_lshl_add_u64 v[124:125], v[124:125], 0, s[70:71]
	s_nop 0
	v_cndmask_b32_e32 v2, 1.0, v166, vcc
	s_andn2_saveexec_b64 s[10:11], s[10:11]
	v_and_b32_e32 v2, 0x6c, v161
	v_lshlrev_b32_e32 v2, 2, v2
	v_cmp_gt_i32_e32 vcc, s81, v161
	v_lshl_add_u64 v[124:125], v[150:151], 0, v[2:3]
	s_nop 0
	v_cndmask_b32_e32 v2, 1.0, v167, vcc
	s_or_b64 exec, exec, s[10:11]
	s_nop 0
	flat_load_dwordx4 v[124:127], v[124:125]
	s_waitcnt vmcnt(0) lgkmcnt(0)
	v_pk_mul_f32 v[128:129], v[120:121], v[124:125] op_sel:[1,1] op_sel_hi:[1,0]
	s_nop 0
	v_pk_fma_f32 v[130:131], v[120:121], v[124:125], v[128:129] neg_lo:[0,0,1] neg_hi:[0,0,1]
	v_pk_fma_f32 v[120:121], v[120:121], v[124:125], v[128:129] op_sel_hi:[0,1,1]
	v_mov_b32_e32 v124, v123
	v_pk_mul_f32 v[124:125], v[124:125], v[126:127] op_sel:[0,1] op_sel_hi:[0,0]
	v_pk_fma_f32 v[128:129], v[122:123], v[126:127], v[124:125] neg_lo:[0,0,1] neg_hi:[0,0,1]
	v_pk_fma_f32 v[122:123], v[122:123], v[126:127], v[124:125] op_sel_hi:[0,1,1]
	v_mov_b32_e32 v131, v121
	v_mov_b32_e32 v129, v123
	v_pk_mul_f32 v[120:121], v[2:3], v[130:131] op_sel_hi:[0,1]
	v_pk_mul_f32 v[122:123], v[2:3], v[128:129] op_sel_hi:[0,1]

; __device__ __forceinline__ void gemm_phase(const Ctx& cx, const GemmArgs& g_, char* shm) {
;     ...
;               if (n0 >= C_GLAX) {
;                 const int i = n0 - C_GLAX;
;                 const float4 b4 = *(const float4*)(g.hin + i);
;                 float xs[4] = {a[0] + b4.x, a[1] + b4.y, a[2] + b4.z, a[3] + b4.w};
; #pragma unroll
;                 for (int j = 0; j < 4; ++j)
;                   xs[j] = (fminf(xs[j], 0.f) - __logf(1.0f + __expf(-fabsf(xs[j])))) * (1.0f / 16.0f);
;                 *(float4*)(g.f32buf + (size_t)tok * 1024 + i) = make_float4(xs[0], xs[1], xs[2], xs[3]);
.LBB0_347:
	s_andn2_saveexec_b64 s[2:3], s[2:3]
	s_cbranch_execz .LBB0_349
	v_add_u32_e32 v2, 0xffffa400, v161
	v_lshlrev_b64 v[128:129], 2, v[2:3]
	v_lshl_add_u64 v[124:125], s[26:27], 0, v[128:129]
	s_nop 0
	flat_load_dwordx4 v[124:127], v[124:125]
	s_mov_b32 s0, 0x3d800000
	v_lshl_add_u64 v[128:129], v[144:145], 0, v[128:129]
	s_waitcnt vmcnt(0) lgkmcnt(0)
	v_add_f32_e32 v2, v120, v124
	v_min_f32_e32 v120, 0, v2
	v_mul_f32_e64 v2, |v2|, s82
	v_exp_f32_e32 v2, v2
	v_add_f32_e32 v124, v121, v125
	v_add_f32_e32 v125, v122, v126
	v_add_f32_e32 v127, v123, v127
	v_add_f32_e32 v2, 1.0, v2
	v_cmp_gt_f32_e32 vcc, s83, v2
	s_nop 1
	v_cndmask_b32_e64 v121, 0, 32, vcc
	v_ldexp_f32 v2, v2, v121
	v_log_f32_e32 v2, v2
	s_nop 0
	v_mul_f32_e32 v121, 0x3f317217, v2
	v_fma_f32 v121, v2, s86, -v121
	v_fmac_f32_e32 v121, 0x3377d1cf, v2
	v_fmac_f32_e32 v121, 0x3f317217, v2
	v_cmp_lt_f32_e64 s[6:7], |v2|, s87
	s_nop 1
	v_cndmask_b32_e64 v2, v2, v121, s[6:7]
	v_cndmask_b32_e32 v121, 0, v165, vcc
	v_sub_f32_e32 v122, v2, v121
	v_mul_f32_e64 v2, |v124|, s82
	v_exp_f32_e32 v2, v2
	v_min_f32_e32 v121, 0, v124
	v_min_f32_e32 v124, 0, v125
	v_add_f32_e32 v2, 1.0, v2
	v_cmp_gt_f32_e32 vcc, s83, v2
	s_nop 1
	v_cndmask_b32_e64 v123, 0, 32, vcc
	v_ldexp_f32 v2, v2, v123
	v_log_f32_e32 v2, v2
	s_nop 0
	v_mul_f32_e32 v123, 0x3f317217, v2
	v_fma_f32 v123, v2, s86, -v123
	v_fmac_f32_e32 v123, 0x3377d1cf, v2
	v_fmac_f32_e32 v123, 0x3f317217, v2
	v_cmp_lt_f32_e64 s[6:7], |v2|, s87
	s_nop 1
	v_cndmask_b32_e64 v2, v2, v123, s[6:7]
	v_cndmask_b32_e32 v123, 0, v165, vcc
	v_sub_f32_e32 v123, v2, v123
	v_mul_f32_e64 v2, |v125|, s82
	v_exp_f32_e32 v2, v2
	v_pk_add_f32 v[120:121], v[120:121], v[122:123] neg_lo:[0,1] neg_hi:[0,1]
	v_add_f32_e32 v2, 1.0, v2
	v_cmp_gt_f32_e32 vcc, s83, v2
	v_pk_mul_f32 v[120:121], v[120:121], s[0:1] op_sel_hi:[1,0]
	s_nop 0
	v_cndmask_b32_e64 v125, 0, 32, vcc
	v_ldexp_f32 v2, v2, v125
	v_log_f32_e32 v2, v2
	s_nop 0
	v_mul_f32_e32 v125, 0x3f317217, v2
	v_fma_f32 v125, v2, s86, -v125
	v_fmac_f32_e32 v125, 0x3377d1cf, v2
	v_fmac_f32_e32 v125, 0x3f317217, v2
	v_cmp_lt_f32_e64 s[6:7], |v2|, s87
	s_nop 1
	v_cndmask_b32_e64 v2, v2, v125, s[6:7]
	v_cndmask_b32_e32 v125, 0, v165, vcc
	v_sub_f32_e32 v126, v2, v125
	v_mul_f32_e64 v2, |v127|, s82
	v_exp_f32_e32 v2, v2
	v_min_f32_e32 v125, 0, v127
	v_add_f32_e32 v2, 1.0, v2
	v_cmp_gt_f32_e32 vcc, s83, v2
	s_nop 1
	v_cndmask_b32_e64 v127, 0, 32, vcc
	v_ldexp_f32 v2, v2, v127
	v_log_f32_e32 v2, v2
	s_nop 0
	v_mul_f32_e32 v127, 0x3f317217, v2
	v_fma_f32 v127, v2, s86, -v127
	v_fmac_f32_e32 v127, 0x3377d1cf, v2
	v_fmac_f32_e32 v127, 0x3f317217, v2
	v_cmp_lt_f32_e64 s[6:7], |v2|, s87
	s_nop 1
	v_cndmask_b32_e64 v2, v2, v127, s[6:7]
	v_cndmask_b32_e32 v127, 0, v165, vcc
	v_sub_f32_e32 v127, v2, v127
	v_pk_add_f32 v[122:123], v[124:125], v[126:127] neg_lo:[0,1] neg_hi:[0,1]
	v_mov_b32_e32 v125, v176
	v_pk_mul_f32 v[122:123], v[122:123], s[0:1] op_sel_hi:[1,0]
	v_mov_b32_e32 v124, v178
	flat_store_dwordx4 v[128:129], v[120:123]

; __device__ __forceinline__ void gemm_phase(const Ctx& cx, const GemmArgs& g_, char* shm) {
;     ...
;             } else if (g.epi == EPI_RELU2) {
;               float r0 = fmaxf(a[0], 0.f), r1 = fmaxf(a[1], 0.f), r2 = fmaxf(a[2], 0.f), r3 = fmaxf(a[3], 0.f);
;               uint2 o; o.x = pack2(r0 * r0, r1 * r1); o.y = pack2(r2 * r2, r3 * r3);
;               EMIT_BF16(g.ldo, o);
.LBB0_359:
	s_cmp_gt_i32 s38, 4
	s_cbranch_scc0 .LBB0_363
	s_cmp_eq_u32 s38, 5
	s_mov_b64 s[6:7], -1
	s_cbranch_scc0 .LBB0_362
	v_max_f32_e32 v2, v118, v118
	v_max_f32_e32 v120, 0, v2
	v_max_f32_e32 v2, v119, v119
	v_max_f32_e32 v121, 0, v2
	v_pk_mul_f32 v[120:121], v[120:121], v[120:121]
	v_max_f32_e32 v2, v116, v116
	v_cvt_pk_bf16_f32 v123, v120, v121
	v_max_f32_e32 v120, 0, v2
	v_max_f32_e32 v2, v117, v117
	v_max_f32_e32 v121, 0, v2
	v_pk_mul_f32 v[120:121], v[120:121], v[120:121]
	v_ashrrev_i32_e32 v133, 31, v132
	v_cvt_pk_bf16_f32 v122, v120, v121
	v_mov_b32_e32 v120, v124
	v_mov_b32_e32 v121, v125
	s_nop 0
	v_permlane16_swap_b32_e32 v120, v122
	v_permlane16_swap_b32_e32 v121, v123
	v_lshl_add_u64 v[126:127], v[132:133], 1, v[158:159]
	s_nop 0
	flat_store_dwordx4 v[126:127], v[120:123] offset:96
	s_mov_b64 s[6:7], 0

; __device__ __forceinline__ void gemm_phase(const Ctx& cx, const GemmArgs& g_, char* shm) {
;     ...
;             } else if (g.epi == EPI_RES) {
;               const float4 hv = *(const float4*)(g.hin + (size_t)tok * DM + n0);
;               const float h0 = hv.x + a[0], h1 = hv.y + a[1], h2 = hv.z + a[2], h3 = hv.w + a[3];
;               *(float4*)(g.hout + (size_t)tok * DM + n0) = make_float4(h0, h1, h2, h3);
;               if (g.w != nullptr) {
;                 const float4 nw = *(const float4*)(g.w + n0);
;                 uint2 o; o.x = pack2(h0 * nw.x, h1 * nw.y); o.y = pack2(h2 * nw.z, h3 * nw.w);
;                 EMIT_BF16(DM, o);
;                 ssq += h0 * h0 + h1 * h1 + h2 * h2 + h3 * h3;
;               }
.LBB0_363:
	s_and_b64 vcc, exec, s[10:11]
	v_mov_b32_e32 v128, v160
	s_cbranch_vccz .LBB0_366
	v_lshl_add_u64 v[126:127], v[138:139], 0, v[0:1]
	v_lshlrev_b64 v[128:129], 2, v[126:127]
	v_lshl_add_u64 v[120:121], v[148:149], 0, v[128:129]
	s_nop 0
	flat_load_dwordx4 v[120:123], v[120:121] offset:192
	v_lshl_add_u64 v[128:129], v[146:147], 0, v[128:129]
	s_andn2_b64 vcc, exec, s[42:43]
	s_waitcnt vmcnt(0) lgkmcnt(0)
	v_pk_add_f32 v[120:121], v[116:117], v[120:121]
	v_pk_add_f32 v[122:123], v[118:119], v[122:123]
	flat_store_dwordx4 v[128:129], v[120:123] offset:192
	v_mov_b32_e32 v128, v160
	s_cbranch_vccnz .LBB0_366
	v_lshl_add_u64 v[126:127], v[126:127], 2, s[30:31]
	global_load_dwordx4 v[126:129], v[126:127], off offset:192
	v_ashrrev_i32_e32 v133, 31, v132
	v_lshl_add_u64 v[130:131], v[132:133], 1, v[134:135]
	s_waitcnt vmcnt(0)
	v_pk_mul_f32 v[126:127], v[120:121], v[126:127]
	v_pk_mul_f32 v[120:121], v[120:121], v[120:121]
	v_pk_mul_f32 v[128:129], v[122:123], v[128:129]
	v_pk_mul_f32 v[122:123], v[122:123], v[122:123]
	v_add_f32_e32 v2, v120, v121
	v_cvt_pk_bf16_f32 v129, v128, v129
	v_cvt_pk_bf16_f32 v128, v126, v127
	v_mov_b32_e32 v126, v124
	v_mov_b32_e32 v127, v125
	v_add_f32_e32 v2, v2, v122
	v_permlane16_swap_b32_e32 v126, v128
	v_permlane16_swap_b32_e32 v127, v129
	v_add_f32_e32 v2, v2, v123
	flat_store_dwordx4 v[130:131], v[126:129] offset:96
	s_nop 1
	v_add_f32_e32 v128, v160, v2

; __device__ __forceinline__ float b2f(u16 b) { return __uint_as_float(((uint32_t)b) << 16); }
; __device__ __forceinline__ float sigmoidf_(float x) { return 1.0f / (1.0f + __expf(-x)); }
; __device__ __forceinline__ void gemm_phase(const Ctx& cx, const GemmArgs& g_, char* shm) {
;     ...
;             } else {
;               const uint2 gv = *(const uint2*)(g.gate + (size_t)tok * NP + n0);
;               float v0 = sigmoidf_(b2f((u16)(gv.x & 0xffff))) * a[0], v1 = sigmoidf_(b2f((u16)(gv.x >> 16))) * a[1];
;               float v2 = sigmoidf_(b2f((u16)(gv.y & 0xffff))) * a[2], v3 = sigmoidf_(b2f((u16)(gv.y >> 16))) * a[3];
;               uint2* mp = (uint2*)(g.outb + (size_t)tok * DM + n0);
;               if (g.epi != EPI_BR0) {
;                 const uint2 pv = *mp;
;                 v0 += b2f((u16)(pv.x & 0xffff)); v1 += b2f((u16)(pv.x >> 16));
;                 v2 += b2f((u16)(pv.y & 0xffff)); v3 += b2f((u16)(pv.y >> 16));
;               }
;               uint2 o; o.x = pack2(v0, v1); o.y = pack2(v2, v3);
;               *mp = o;
;             }
.LBB0_368:
	v_lshl_add_u64 v[120:121], v[138:139], 0, v[0:1]
	v_lshlrev_b64 v[122:123], 1, v[120:121]
	v_lshl_add_u64 v[120:121], v[156:157], 0, v[122:123]
	s_nop 0
	flat_load_dwordx2 v[126:127], v[120:121] offset:96
	v_lshl_add_u64 v[122:123], v[134:135], 0, v[122:123]
	s_waitcnt vmcnt(0) lgkmcnt(0)
	v_lshlrev_b32_e32 v2, 16, v126
	v_mul_f32_e32 v2, 0xbfb8aa3b, v2
	v_exp_f32_e32 v120, v2
	v_and_b32_e32 v2, 0xffff0000, v126
	v_mul_f32_e32 v2, 0xbfb8aa3b, v2
	v_exp_f32_e32 v121, v2
	s_nop 0
	v_pk_add_f32 v[120:121], v[120:121], 1.0 op_sel_hi:[1,0]
	s_nop 0
	v_div_scale_f32 v2, s[2:3], v121, v121, 1.0
	v_rcp_f32_e32 v126, v2
	s_nop 0
	v_fma_f32 v128, -v2, v126, 1.0
	v_fmac_f32_e32 v126, v128, v126
	v_div_scale_f32 v128, vcc, 1.0, v121, 1.0
	v_mul_f32_e32 v129, v128, v126
	v_fma_f32 v130, -v2, v129, v128
	v_fmac_f32_e32 v129, v130, v126
	v_fma_f32 v2, -v2, v129, v128
	v_div_fmas_f32 v2, v2, v126, v129
	v_div_fixup_f32 v121, v2, v121, 1.0
	v_div_scale_f32 v2, s[2:3], v120, v120, 1.0
	v_rcp_f32_e32 v126, v2
	s_nop 0
	v_fma_f32 v128, -v2, v126, 1.0
	v_fmac_f32_e32 v126, v128, v126
	v_div_scale_f32 v128, vcc, 1.0, v120, 1.0
	v_mul_f32_e32 v129, v128, v126
	v_fma_f32 v130, -v2, v129, v128
	v_fmac_f32_e32 v129, v130, v126
	v_fma_f32 v2, -v2, v129, v128
	v_div_fmas_f32 v2, v2, v126, v129
	v_div_fixup_f32 v120, v2, v120, 1.0
	v_lshlrev_b32_e32 v2, 16, v127
	v_mul_f32_e32 v2, 0xbfb8aa3b, v2
	v_exp_f32_e32 v126, v2
	v_and_b32_e32 v2, 0xffff0000, v127
	v_mul_f32_e32 v2, 0xbfb8aa3b, v2
	v_exp_f32_e32 v127, v2
	v_pk_mul_f32 v[120:121], v[116:117], v[120:121]
	v_pk_add_f32 v[126:127], v[126:127], 1.0 op_sel_hi:[1,0]
	s_nop 0
	v_div_scale_f32 v2, s[2:3], v127, v127, 1.0
	v_rcp_f32_e32 v128, v2
	s_nop 0
	v_fma_f32 v129, -v2, v128, 1.0
	v_fmac_f32_e32 v128, v129, v128
	v_div_scale_f32 v129, vcc, 1.0, v127, 1.0
	v_mul_f32_e32 v130, v129, v128
	v_fma_f32 v131, -v2, v130, v129
	v_fmac_f32_e32 v130, v131, v128
	v_fma_f32 v2, -v2, v130, v129
	v_div_fmas_f32 v2, v2, v128, v130
	v_div_fixup_f32 v127, v2, v127, 1.0
	v_div_scale_f32 v2, s[2:3], v126, v126, 1.0
	v_rcp_f32_e32 v128, v2
	s_nop 0
	v_fma_f32 v129, -v2, v128, 1.0
	v_fmac_f32_e32 v128, v129, v128
	v_div_scale_f32 v129, vcc, 1.0, v126, 1.0
	v_mul_f32_e32 v130, v129, v128
	v_fma_f32 v131, -v2, v130, v129
	v_fmac_f32_e32 v130, v131, v128
	v_fma_f32 v2, -v2, v130, v129
	v_div_fmas_f32 v2, v2, v128, v130
	v_div_fixup_f32 v126, v2, v126, 1.0
	v_pk_mul_f32 v[126:127], v[118:119], v[126:127]
	s_and_b64 vcc, exec, s[4:5]
	s_cbranch_vccnz .LBB0_370
	flat_load_dwordx2 v[128:129], v[122:123] offset:96
	s_waitcnt vmcnt(0) lgkmcnt(0)
	v_lshlrev_b32_e32 v130, 16, v128
	v_and_b32_e32 v131, 0xffff0000, v128
	v_lshlrev_b32_e32 v128, 16, v129
	v_and_b32_e32 v129, 0xffff0000, v129
	v_pk_add_f32 v[120:121], v[120:121], v[130:131]
	v_pk_add_f32 v[126:127], v[126:127], v[128:129]

; __device__ __forceinline__ void gemm_phase(const Ctx& cx, const GemmArgs& g_, char* shm) {
;     ...
; #pragma unroll
;           for (int m = 0; m < 4; ++m) {
;             const int n0 = brow + ai * 128 + wr * 64 + m * 16 + fq * 4;
;             f32x4 a = acc[ai][bj][m][n];
;             if (g.epi == EPI_PROJ || g.epi == EPI_RELU2) { a[0] *= rs; a[1] *= rs; a[2] *= rs; a[3] *= rs; }
;             if (g.epi == EPI_PROJ) {
;               if (n0 >= C_GLAX) {
;                 const int i = n0 - C_GLAX;
;                 const float4 b4 = *(const float4*)(g.hin + i);
;                 float xs[4] = {a[0] + b4.x, a[1] + b4.y, a[2] + b4.z, a[3] + b4.w};
; #pragma unroll
;                 for (int j = 0; j < 4; ++j)
;                   xs[j] = (fminf(xs[j], 0.f) - __logf(1.0f + __expf(-fabsf(xs[j])))) * (1.0f / 16.0f);
;                 *(float4*)(g.f32buf + (size_t)tok * 1024 + i) = make_float4(xs[0], xs[1], xs[2], xs[3]);
;               } else {
;                 float o0 = a[0], o1 = a[1], o2 = a[2], o3 = a[3];
;                 const bool r128 = (n0 >= C_DSAQ && n0 < C_HGQ) || (n0 >= C_DSAK && n0 < C_DSAV);
;                 const bool r64 = (n0 >= C_IDXQ && n0 < C_GLAA);
;                 if (r128 || r64) {
;                   float4 cs;
;                   float sc;
;                   if (r128) {
;                     cs = *(const float4*)(g.w + ((size_t)tok * 64 + ((n0 & 127) >> 1)) * 2);
;                     sc = (n0 < C_HGQ) ? 0.08838834764831845f : 1.0f;
;                   } else {
;                     cs = *(const float4*)(g.hout + ((size_t)tok * 32 + ((n0 & 63) >> 1)) * 2);
;                     sc = (n0 < C_IDXK) ? 0.125f : 1.0f;
;                   }
;                   o0 = (a[0] * cs.x - a[1] * cs.y) * sc; o1 = (a[1] * cs.x + a[0] * cs.y) * sc;
;                   o2 = (a[2] * cs.z - a[3] * cs.w) * sc; o3 = (a[3] * cs.z + a[2] * cs.w) * sc;
;                 }
;                 uint2 o; o.x = pack2(o0, o1); o.y = pack2(o2, o3);
;                 EMIT_BF16(g.ldo, o);
.LBB0_371:
	v_or_b32_e32 v176, v138, v175
	s_movk_i32 s0, 0x5c00
	s_and_b64 vcc, exec, s[2:3]
	v_cmp_gt_i32_e64 s[6:7], s0, v176
	s_cbranch_vccz .LBB0_383
	s_and_saveexec_b64 s[2:3], s[6:7]
	s_xor_b64 s[2:3], exec, s[2:3]
	s_cbranch_execz .LBB0_380
	v_add_u32_e32 v2, 0xffffa700, v138
	v_cmp_gt_u32_e32 vcc, s77, v2
	s_or_b64 s[10:11], s[58:59], vcc
	s_and_saveexec_b64 s[6:7], s[10:11]
	s_cbranch_execz .LBB0_379
	s_and_saveexec_b64 s[10:11], s[56:57]
	s_xor_b64 s[10:11], exec, s[10:11]
	v_lshlrev_b32_e32 v2, 2, v0
	s_movk_i32 s0, 0x5b00
	v_lshl_add_u64 v[120:121], v[152:153], 0, v[2:3]
	s_mov_b64 s[52:53], 0xc0
	v_cmp_gt_u32_e32 vcc, s0, v138
	v_lshl_add_u64 v[120:121], v[120:121], 0, s[52:53]
	s_nop 0
	v_cndmask_b32_e32 v2, 1.0, v166, vcc
	s_andn2_saveexec_b64 s[10:11], s[10:11]
	v_and_b32_e32 v2, 0x7c, v176
	v_lshlrev_b32_e32 v2, 2, v2
	v_cmp_gt_i32_e32 vcc, s81, v176
	v_lshl_add_u64 v[120:121], v[150:151], 0, v[2:3]
	s_nop 0
	v_cndmask_b32_e32 v2, 1.0, v167, vcc
	s_or_b64 exec, exec, s[10:11]
	s_nop 0
	flat_load_dwordx4 v[120:123], v[120:121]
	s_waitcnt vmcnt(0) lgkmcnt(0)
	v_pk_mul_f32 v[126:127], v[116:117], v[120:121] op_sel:[1,1] op_sel_hi:[1,0]
	s_nop 0
	v_pk_fma_f32 v[128:129], v[116:117], v[120:121], v[126:127] neg_lo:[0,0,1] neg_hi:[0,0,1]
	v_pk_fma_f32 v[116:117], v[116:117], v[120:121], v[126:127] op_sel_hi:[0,1,1]
	v_mov_b32_e32 v120, v119
	v_pk_mul_f32 v[120:121], v[120:121], v[122:123] op_sel:[0,1] op_sel_hi:[0,0]
	v_pk_fma_f32 v[126:127], v[118:119], v[122:123], v[120:121] neg_lo:[0,0,1] neg_hi:[0,0,1]
	v_pk_fma_f32 v[118:119], v[118:119], v[122:123], v[120:121] op_sel_hi:[0,1,1]
	v_mov_b32_e32 v129, v117
	v_mov_b32_e32 v127, v119
	v_pk_mul_f32 v[116:117], v[2:3], v[128:129] op_sel_hi:[0,1]
	v_pk_mul_f32 v[118:119], v[2:3], v[126:127] op_sel_hi:[0,1]
.LBB0_379:
	s_or_b64 exec, exec, s[6:7]
	v_cvt_pk_bf16_f32 v2, v118, v119
	v_cvt_pk_bf16_f32 v118, v116, v117
	s_nop 1
	v_permlane16_swap_b32_e32 v124, v118
	v_permlane16_swap_b32_e32 v125, v2
	v_ashrrev_i32_e32 v133, 31, v132
	v_lshl_add_u64 v[116:117], v[132:133], 1, v[158:159]
	v_mov_b32_e32 v126, v118
	v_mov_b32_e32 v127, v2
	s_nop 0
	flat_store_dwordx4 v[116:117], v[124:127] offset:96
.LBB0_380:
	s_andn2_saveexec_b64 s[2:3], s[2:3]
	s_cbranch_execz .LBB0_382
	v_add_u32_e32 v2, 0xffffa400, v176
	v_lshlrev_b64 v[124:125], 2, v[2:3]
	v_lshl_add_u64 v[120:121], s[26:27], 0, v[124:125]
	s_nop 0
	flat_load_dwordx4 v[120:123], v[120:121]
	s_mov_b32 s0, 0x3d800000
	v_lshl_add_u64 v[124:125], v[144:145], 0, v[124:125]
	s_waitcnt vmcnt(0) lgkmcnt(0)
	v_add_f32_e32 v2, v116, v120
	v_min_f32_e32 v116, 0, v2
	v_mul_f32_e64 v2, |v2|, s82
	v_exp_f32_e32 v2, v2
	v_add_f32_e32 v120, v117, v121
	v_add_f32_e32 v121, v118, v122
	v_add_f32_e32 v123, v119, v123
	v_add_f32_e32 v2, 1.0, v2
	v_cmp_gt_f32_e32 vcc, s83, v2
	s_nop 1
	v_cndmask_b32_e64 v117, 0, 32, vcc
	v_ldexp_f32 v2, v2, v117
	v_log_f32_e32 v2, v2
	s_nop 0
	v_mul_f32_e32 v117, 0x3f317217, v2
	v_fma_f32 v117, v2, s86, -v117
	v_fmac_f32_e32 v117, 0x3377d1cf, v2
	v_fmac_f32_e32 v117, 0x3f317217, v2
	v_cmp_lt_f32_e64 s[6:7], |v2|, s87
	s_nop 1
	v_cndmask_b32_e64 v2, v2, v117, s[6:7]
	v_cndmask_b32_e32 v117, 0, v165, vcc
	v_sub_f32_e32 v118, v2, v117
	v_mul_f32_e64 v2, |v120|, s82
	v_exp_f32_e32 v2, v2
	v_min_f32_e32 v117, 0, v120
	v_min_f32_e32 v120, 0, v121
	v_add_f32_e32 v2, 1.0, v2
	v_cmp_gt_f32_e32 vcc, s83, v2
	s_nop 1
	v_cndmask_b32_e64 v119, 0, 32, vcc
	v_ldexp_f32 v2, v2, v119
	v_log_f32_e32 v2, v2
	s_nop 0
	v_mul_f32_e32 v119, 0x3f317217, v2
	v_fma_f32 v119, v2, s86, -v119
	v_fmac_f32_e32 v119, 0x3377d1cf, v2
	v_fmac_f32_e32 v119, 0x3f317217, v2
	v_cmp_lt_f32_e64 s[6:7], |v2|, s87
	s_nop 1
	v_cndmask_b32_e64 v2, v2, v119, s[6:7]
	v_cndmask_b32_e32 v119, 0, v165, vcc
	v_sub_f32_e32 v119, v2, v119
	v_mul_f32_e64 v2, |v121|, s82
	v_exp_f32_e32 v2, v2
	v_pk_add_f32 v[116:117], v[116:117], v[118:119] neg_lo:[0,1] neg_hi:[0,1]
	v_add_f32_e32 v2, 1.0, v2
	v_cmp_gt_f32_e32 vcc, s83, v2
	v_pk_mul_f32 v[116:117], v[116:117], s[0:1] op_sel_hi:[1,0]
	s_nop 0
	v_cndmask_b32_e64 v121, 0, 32, vcc
	v_ldexp_f32 v2, v2, v121
	v_log_f32_e32 v2, v2
	s_nop 0
	v_mul_f32_e32 v121, 0x3f317217, v2
	v_fma_f32 v121, v2, s86, -v121
	v_fmac_f32_e32 v121, 0x3377d1cf, v2
	v_fmac_f32_e32 v121, 0x3f317217, v2
	v_cmp_lt_f32_e64 s[6:7], |v2|, s87
	s_nop 1
	v_cndmask_b32_e64 v2, v2, v121, s[6:7]
	v_cndmask_b32_e32 v121, 0, v165, vcc
	v_sub_f32_e32 v122, v2, v121
	v_mul_f32_e64 v2, |v123|, s82
	v_exp_f32_e32 v2, v2
	v_min_f32_e32 v121, 0, v123
	v_add_f32_e32 v2, 1.0, v2
	v_cmp_gt_f32_e32 vcc, s83, v2
	s_nop 1
	v_cndmask_b32_e64 v123, 0, 32, vcc
	v_ldexp_f32 v2, v2, v123
	v_log_f32_e32 v2, v2
	s_nop 0
	v_mul_f32_e32 v123, 0x3f317217, v2
	v_fma_f32 v123, v2, s86, -v123
	v_fmac_f32_e32 v123, 0x3377d1cf, v2
	v_fmac_f32_e32 v123, 0x3f317217, v2
	v_cmp_lt_f32_e64 s[6:7], |v2|, s87
	s_nop 1
	v_cndmask_b32_e64 v2, v2, v123, s[6:7]
	v_cndmask_b32_e32 v123, 0, v165, vcc
	v_sub_f32_e32 v123, v2, v123
	v_pk_add_f32 v[118:119], v[120:121], v[122:123] neg_lo:[0,1] neg_hi:[0,1]
	s_nop 0
	v_pk_mul_f32 v[118:119], v[118:119], s[0:1] op_sel_hi:[1,0]
	flat_store_dwordx4 v[124:125], v[116:119]

; __device__ __forceinline__ void gemm_phase(const Ctx& cx, const GemmArgs& g_, char* shm) {
;     ...
;             } else if (g.epi == EPI_RES) {
;               const float4 hv = *(const float4*)(g.hin + (size_t)tok * DM + n0);
;               const float h0 = hv.x + a[0], h1 = hv.y + a[1], h2 = hv.z + a[2], h3 = hv.w + a[3];
;               *(float4*)(g.hout + (size_t)tok * DM + n0) = make_float4(h0, h1, h2, h3);
;               if (g.w != nullptr) {
;                 const float4 nw = *(const float4*)(g.w + n0);
;                 uint2 o; o.x = pack2(h0 * nw.x, h1 * nw.y); o.y = pack2(h2 * nw.z, h3 * nw.w);
;                 EMIT_BF16(DM, o);
;                 ssq += h0 * h0 + h1 * h1 + h2 * h2 + h3 * h3;
;               }
.LBB0_396:
	s_and_b64 vcc, exec, s[54:55]
	v_mov_b32_e32 v125, v128
	s_cbranch_vccz .LBB0_399
	v_ashrrev_i32_e32 v123, 31, v122
	v_lshlrev_b64 v[124:125], 2, v[122:123]
	v_lshl_add_u64 v[116:117], v[148:149], 0, v[124:125]
	s_nop 0
	flat_load_dwordx4 v[116:119], v[116:117]
	v_lshl_add_u64 v[124:125], v[146:147], 0, v[124:125]
	s_andn2_b64 vcc, exec, s[42:43]
	s_waitcnt vmcnt(0) lgkmcnt(0)
	v_pk_add_f32 v[116:117], v[112:113], v[116:117]
	v_pk_add_f32 v[118:119], v[114:115], v[118:119]
	flat_store_dwordx4 v[124:125], v[116:119]
	s_cbranch_vccnz .LBB0_535
	v_lshl_add_u64 v[124:125], v[122:123], 2, s[30:31]
	global_load_dwordx4 v[124:127], v[124:125], off
	s_waitcnt vmcnt(0)
	v_pk_mul_f32 v[124:125], v[116:117], v[124:125]
	v_pk_mul_f32 v[116:117], v[116:117], v[116:117]
	v_pk_mul_f32 v[126:127], v[118:119], v[126:127]
	v_pk_mul_f32 v[118:119], v[118:119], v[118:119]
	v_add_f32_e32 v2, v116, v117
	v_add_f32_e32 v2, v2, v118
	v_add_f32_e32 v2, v2, v119
	v_cvt_pk_bf16_f32 v126, v126, v127
	v_cvt_pk_bf16_f32 v124, v124, v125
	v_add_f32_e32 v125, v128, v2

; __device__ __forceinline__ float b2f(u16 b) { return __uint_as_float(((uint32_t)b) << 16); }
; __device__ __forceinline__ float sigmoidf_(float x) { return 1.0f / (1.0f + __expf(-x)); }
; __device__ __forceinline__ void gemm_phase(const Ctx& cx, const GemmArgs& g_, char* shm) {
;     ...
;             } else {
;               const uint2 gv = *(const uint2*)(g.gate + (size_t)tok * NP + n0);
;               float v0 = sigmoidf_(b2f((u16)(gv.x & 0xffff))) * a[0], v1 = sigmoidf_(b2f((u16)(gv.x >> 16))) * a[1];
;               float v2 = sigmoidf_(b2f((u16)(gv.y & 0xffff))) * a[2], v3 = sigmoidf_(b2f((u16)(gv.y >> 16))) * a[3];
;               uint2* mp = (uint2*)(g.outb + (size_t)tok * DM + n0);
;               if (g.epi != EPI_BR0) {
;                 const uint2 pv = *mp;
;                 v0 += b2f((u16)(pv.x & 0xffff)); v1 += b2f((u16)(pv.x >> 16));
;                 v2 += b2f((u16)(pv.y & 0xffff)); v3 += b2f((u16)(pv.y >> 16));
;               }
;               uint2 o; o.x = pack2(v0, v1); o.y = pack2(v2, v3);
;               *mp = o;
;             }
.LBB0_401:
	v_lshlrev_b64 v[118:119], 1, v[122:123]
	v_lshl_add_u64 v[116:117], v[156:157], 0, v[118:119]
	s_nop 0
	flat_load_dwordx2 v[124:125], v[116:117]
	v_lshl_add_u64 v[118:119], v[134:135], 0, v[118:119]
	s_waitcnt vmcnt(0) lgkmcnt(0)
	v_lshlrev_b32_e32 v2, 16, v124
	v_mul_f32_e32 v2, 0xbfb8aa3b, v2
	v_exp_f32_e32 v116, v2
	v_and_b32_e32 v2, 0xffff0000, v124
	v_mul_f32_e32 v2, 0xbfb8aa3b, v2
	v_exp_f32_e32 v117, v2
	s_nop 0
	v_pk_add_f32 v[116:117], v[116:117], 1.0 op_sel_hi:[1,0]
	s_nop 0
	v_div_scale_f32 v2, s[2:3], v117, v117, 1.0
	v_rcp_f32_e32 v121, v2
	s_nop 0
	v_fma_f32 v124, -v2, v121, 1.0
	v_fmac_f32_e32 v121, v124, v121
	v_div_scale_f32 v124, vcc, 1.0, v117, 1.0
	v_mul_f32_e32 v126, v124, v121
	v_fma_f32 v127, -v2, v126, v124
	v_fmac_f32_e32 v126, v127, v121
	v_fma_f32 v2, -v2, v126, v124
	v_div_fmas_f32 v2, v2, v121, v126
	v_div_fixup_f32 v117, v2, v117, 1.0
	v_div_scale_f32 v2, s[2:3], v116, v116, 1.0
	v_rcp_f32_e32 v121, v2
	s_nop 0
	v_fma_f32 v124, -v2, v121, 1.0
	v_fmac_f32_e32 v121, v124, v121
	v_div_scale_f32 v124, vcc, 1.0, v116, 1.0
	v_mul_f32_e32 v126, v124, v121
	v_fma_f32 v127, -v2, v126, v124
	v_fmac_f32_e32 v126, v127, v121
	v_fma_f32 v2, -v2, v126, v124
	v_div_fmas_f32 v2, v2, v121, v126
	v_div_fixup_f32 v116, v2, v116, 1.0
	v_lshlrev_b32_e32 v2, 16, v125
	v_mul_f32_e32 v2, 0xbfb8aa3b, v2
	v_exp_f32_e32 v124, v2
	v_and_b32_e32 v2, 0xffff0000, v125
	v_mul_f32_e32 v2, 0xbfb8aa3b, v2
	v_exp_f32_e32 v125, v2
	v_pk_mul_f32 v[116:117], v[112:113], v[116:117]
	v_pk_add_f32 v[124:125], v[124:125], 1.0 op_sel_hi:[1,0]
	s_nop 0
	v_div_scale_f32 v2, s[2:3], v125, v125, 1.0
	v_rcp_f32_e32 v121, v2
	s_nop 0
	v_fma_f32 v126, -v2, v121, 1.0
	v_fmac_f32_e32 v121, v126, v121
	v_div_scale_f32 v126, vcc, 1.0, v125, 1.0
	v_mul_f32_e32 v127, v126, v121
	v_fma_f32 v129, -v2, v127, v126
	v_fmac_f32_e32 v127, v129, v121
	v_fma_f32 v2, -v2, v127, v126
	v_div_fmas_f32 v2, v2, v121, v127
	v_div_fixup_f32 v125, v2, v125, 1.0
	v_div_scale_f32 v2, s[2:3], v124, v124, 1.0
	v_rcp_f32_e32 v121, v2
	s_nop 0
	v_fma_f32 v126, -v2, v121, 1.0
	v_fmac_f32_e32 v121, v126, v121
	v_div_scale_f32 v126, vcc, 1.0, v124, 1.0
	v_mul_f32_e32 v127, v126, v121
	v_fma_f32 v129, -v2, v127, v126
	v_fmac_f32_e32 v127, v129, v121
	v_fma_f32 v2, -v2, v127, v126
	v_div_fmas_f32 v2, v2, v121, v127
	v_div_fixup_f32 v124, v2, v124, 1.0
	v_pk_mul_f32 v[124:125], v[114:115], v[124:125]
	s_and_b64 vcc, exec, s[4:5]
	s_cbranch_vccnz .LBB0_403
	flat_load_dwordx2 v[126:127], v[118:119]
	s_waitcnt vmcnt(0) lgkmcnt(0)
	v_lshlrev_b32_e32 v130, 16, v126
	v_and_b32_e32 v131, 0xffff0000, v126
	v_lshlrev_b32_e32 v126, 16, v127
	v_and_b32_e32 v127, 0xffff0000, v127
	v_pk_add_f32 v[116:117], v[116:117], v[130:131]
	v_pk_add_f32 v[124:125], v[124:125], v[126:127]

; __device__ __forceinline__ void gemm_phase(const Ctx& cx, const GemmArgs& g_, char* shm) {
;     ...
;               } else {
;                 float o0 = a[0], o1 = a[1], o2 = a[2], o3 = a[3];
;                 const bool r128 = (n0 >= C_DSAQ && n0 < C_HGQ) || (n0 >= C_DSAK && n0 < C_DSAV);
;                 const bool r64 = (n0 >= C_IDXQ && n0 < C_GLAA);
;                 if (r128 || r64) {
;                   float4 cs;
;                   float sc;
;                   if (r128) {
;                     cs = *(const float4*)(g.w + ((size_t)tok * 64 + ((n0 & 127) >> 1)) * 2);
;                     sc = (n0 < C_HGQ) ? 0.08838834764831845f : 1.0f;
;                   } else {
;                     cs = *(const float4*)(g.hout + ((size_t)tok * 32 + ((n0 & 63) >> 1)) * 2);
;                     sc = (n0 < C_IDXK) ? 0.125f : 1.0f;
;                   }
;                   o0 = (a[0] * cs.x - a[1] * cs.y) * sc; o1 = (a[1] * cs.x + a[0] * cs.y) * sc;
;                   o2 = (a[2] * cs.z - a[3] * cs.w) * sc; o3 = (a[3] * cs.z + a[2] * cs.w) * sc;
;                 }
.LBB0_404:
	s_or_b64 s[54:55], s[6:7], s[10:11]
	s_movk_i32 s0, 0x5c00
	s_xor_b64 s[52:53], s[54:55], -1
	s_and_b64 vcc, exec, s[2:3]
	v_cmp_gt_i32_e64 s[6:7], s0, v122
	s_cbranch_vccz .LBB0_416
	s_and_saveexec_b64 s[2:3], s[6:7]
	s_xor_b64 s[2:3], exec, s[2:3]
	s_cbranch_execz .LBB0_413
	v_add_u32_e32 v2, 0xffffa780, v138
	v_cmp_gt_u32_e32 vcc, s77, v2
	s_or_b64 s[10:11], s[54:55], vcc
	s_and_saveexec_b64 s[6:7], s[10:11]
	s_cbranch_execz .LBB0_412
	s_and_saveexec_b64 s[10:11], s[52:53]
	s_xor_b64 s[10:11], exec, s[10:11]
	s_movk_i32 s0, 0x5b00
	v_lshlrev_b32_e32 v2, 2, v0
	v_cmp_gt_u32_e32 vcc, s0, v120
	v_lshl_add_u64 v[116:117], v[152:153], 0, v[2:3]
	s_nop 0
	v_cndmask_b32_e32 v2, 1.0, v166, vcc
	s_andn2_saveexec_b64 s[10:11], s[10:11]
	v_and_b32_e32 v2, 0x4c, v122
	v_lshlrev_b32_e32 v2, 2, v2
	v_cmp_gt_i32_e32 vcc, s81, v122
	v_lshl_add_u64 v[116:117], v[150:151], 0, v[2:3]
	s_nop 0
	v_cndmask_b32_e32 v2, 1.0, v167, vcc
	s_or_b64 exec, exec, s[10:11]
	s_nop 0
	flat_load_dwordx4 v[116:119], v[116:117]
	s_waitcnt vmcnt(0) lgkmcnt(0)
	v_pk_mul_f32 v[124:125], v[112:113], v[116:117] op_sel:[1,1] op_sel_hi:[1,0]
	s_nop 0
	v_pk_fma_f32 v[126:127], v[112:113], v[116:117], v[124:125] neg_lo:[0,0,1] neg_hi:[0,0,1]
	v_pk_fma_f32 v[112:113], v[112:113], v[116:117], v[124:125] op_sel_hi:[0,1,1]
	v_mov_b32_e32 v116, v115
	v_pk_mul_f32 v[116:117], v[116:117], v[118:119] op_sel:[0,1] op_sel_hi:[0,0]
	v_pk_fma_f32 v[124:125], v[114:115], v[118:119], v[116:117] neg_lo:[0,0,1] neg_hi:[0,0,1]
	v_pk_fma_f32 v[114:115], v[114:115], v[118:119], v[116:117] op_sel_hi:[0,1,1]
	v_mov_b32_e32 v127, v113
	v_mov_b32_e32 v125, v115
	v_pk_mul_f32 v[112:113], v[2:3], v[126:127] op_sel_hi:[0,1]
	v_pk_mul_f32 v[114:115], v[2:3], v[124:125] op_sel_hi:[0,1]

; __device__ __forceinline__ void gemm_phase(const Ctx& cx, const GemmArgs& g_, char* shm) {
;     ...
;               if (n0 >= C_GLAX) {
;                 const int i = n0 - C_GLAX;
;                 const float4 b4 = *(const float4*)(g.hin + i);
;                 float xs[4] = {a[0] + b4.x, a[1] + b4.y, a[2] + b4.z, a[3] + b4.w};
; #pragma unroll
;                 for (int j = 0; j < 4; ++j)
;                   xs[j] = (fminf(xs[j], 0.f) - __logf(1.0f + __expf(-fabsf(xs[j])))) * (1.0f / 16.0f);
;                 *(float4*)(g.f32buf + (size_t)tok * 1024 + i) = make_float4(xs[0], xs[1], xs[2], xs[3]);
.LBB0_413:
	s_andn2_saveexec_b64 s[2:3], s[2:3]
	s_cbranch_execz .LBB0_415
	v_add_u32_e32 v2, 0xffffa400, v122
	v_lshlrev_b64 v[124:125], 2, v[2:3]
	v_lshl_add_u64 v[116:117], s[26:27], 0, v[124:125]
	s_nop 0
	flat_load_dwordx4 v[116:119], v[116:117]
	s_mov_b32 s0, 0x3d800000
	v_lshl_add_u64 v[124:125], v[144:145], 0, v[124:125]
	v_mov_b32_e32 v126, 0
	s_waitcnt vmcnt(0) lgkmcnt(0)
	v_add_f32_e32 v2, v112, v116
	v_min_f32_e32 v112, 0, v2
	v_mul_f32_e64 v2, |v2|, s82
	v_exp_f32_e32 v2, v2
	v_add_f32_e32 v116, v113, v117
	v_add_f32_e32 v117, v114, v118
	v_add_f32_e32 v119, v115, v119
	v_add_f32_e32 v2, 1.0, v2
	v_cmp_gt_f32_e32 vcc, s83, v2
	s_nop 1
	v_cndmask_b32_e64 v113, 0, 32, vcc
	v_ldexp_f32 v2, v2, v113
	v_log_f32_e32 v2, v2
	s_nop 0
	v_mul_f32_e32 v113, 0x3f317217, v2
	v_fma_f32 v113, v2, s86, -v113
	v_fmac_f32_e32 v113, 0x3377d1cf, v2
	v_fmac_f32_e32 v113, 0x3f317217, v2
	v_cmp_lt_f32_e64 s[6:7], |v2|, s87
	s_nop 1
	v_cndmask_b32_e64 v2, v2, v113, s[6:7]
	v_cndmask_b32_e32 v113, 0, v165, vcc
	v_sub_f32_e32 v114, v2, v113
	v_mul_f32_e64 v2, |v116|, s82
	v_exp_f32_e32 v2, v2
	v_min_f32_e32 v113, 0, v116
	v_min_f32_e32 v116, 0, v117
	v_add_f32_e32 v2, 1.0, v2
	v_cmp_gt_f32_e32 vcc, s83, v2
	s_nop 1
	v_cndmask_b32_e64 v115, 0, 32, vcc
	v_ldexp_f32 v2, v2, v115
	v_log_f32_e32 v2, v2
	s_nop 0
	v_mul_f32_e32 v115, 0x3f317217, v2
	v_fma_f32 v115, v2, s86, -v115
	v_fmac_f32_e32 v115, 0x3377d1cf, v2
	v_fmac_f32_e32 v115, 0x3f317217, v2
	v_cmp_lt_f32_e64 s[6:7], |v2|, s87
	s_nop 1
	v_cndmask_b32_e64 v2, v2, v115, s[6:7]
	v_cndmask_b32_e32 v115, 0, v165, vcc
	v_sub_f32_e32 v115, v2, v115
	v_mul_f32_e64 v2, |v117|, s82
	v_exp_f32_e32 v2, v2
	v_pk_add_f32 v[112:113], v[112:113], v[114:115] neg_lo:[0,1] neg_hi:[0,1]
	v_add_f32_e32 v2, 1.0, v2
	v_cmp_gt_f32_e32 vcc, s83, v2
	v_pk_mul_f32 v[112:113], v[112:113], s[0:1] op_sel_hi:[1,0]
	s_nop 0
	v_cndmask_b32_e64 v117, 0, 32, vcc
	v_ldexp_f32 v2, v2, v117
	v_log_f32_e32 v2, v2
	s_nop 0
	v_mul_f32_e32 v117, 0x3f317217, v2
	v_fma_f32 v117, v2, s86, -v117
	v_fmac_f32_e32 v117, 0x3377d1cf, v2
	v_fmac_f32_e32 v117, 0x3f317217, v2
	v_cmp_lt_f32_e64 s[6:7], |v2|, s87
	s_nop 1
	v_cndmask_b32_e64 v2, v2, v117, s[6:7]
	v_cndmask_b32_e32 v117, 0, v165, vcc
	v_sub_f32_e32 v118, v2, v117
	v_mul_f32_e64 v2, |v119|, s82
	v_exp_f32_e32 v2, v2
	v_min_f32_e32 v117, 0, v119
	v_add_f32_e32 v2, 1.0, v2
	v_cmp_gt_f32_e32 vcc, s83, v2
	s_nop 1
	v_cndmask_b32_e64 v119, 0, 32, vcc
	v_ldexp_f32 v2, v2, v119
	v_log_f32_e32 v2, v2
	s_nop 0
	v_mul_f32_e32 v119, 0x3f317217, v2
	v_fma_f32 v119, v2, s86, -v119
	v_fmac_f32_e32 v119, 0x3377d1cf, v2
	v_fmac_f32_e32 v119, 0x3f317217, v2
	v_cmp_lt_f32_e64 s[6:7], |v2|, s87
	s_nop 1
	v_cndmask_b32_e64 v2, v2, v119, s[6:7]
	v_cndmask_b32_e32 v119, 0, v165, vcc
	v_sub_f32_e32 v119, v2, v119
	v_pk_add_f32 v[114:115], v[116:117], v[118:119] neg_lo:[0,1] neg_hi:[0,1]
	s_nop 0
	v_pk_mul_f32 v[114:115], v[114:115], s[0:1] op_sel_hi:[1,0]
	flat_store_dwordx4 v[124:125], v[112:115]
	v_mov_b32_e32 v124, 0

; __device__ __forceinline__ void gemm_phase(const Ctx& cx, const GemmArgs& g_, char* shm) {
;     ...
;             } else if (g.epi == EPI_RELU2) {
;               float r0 = fmaxf(a[0], 0.f), r1 = fmaxf(a[1], 0.f), r2 = fmaxf(a[2], 0.f), r3 = fmaxf(a[3], 0.f);
;               uint2 o; o.x = pack2(r0 * r0, r1 * r1); o.y = pack2(r2 * r2, r3 * r3);
;               EMIT_BF16(g.ldo, o);
.LBB0_425:
	s_cmp_gt_i32 s38, 4
	s_cbranch_scc0 .LBB0_429
	s_cmp_eq_u32 s38, 5
	s_mov_b64 s[6:7], -1
	s_cbranch_scc0 .LBB0_428
	v_max_f32_e32 v2, v110, v110
	v_max_f32_e32 v112, 0, v2
	v_max_f32_e32 v2, v111, v111
	v_max_f32_e32 v113, 0, v2
	v_pk_mul_f32 v[112:113], v[112:113], v[112:113]
	v_max_f32_e32 v2, v108, v108
	v_cvt_pk_bf16_f32 v115, v112, v113
	v_max_f32_e32 v112, 0, v2
	v_max_f32_e32 v2, v109, v109
	v_max_f32_e32 v113, 0, v2
	v_pk_mul_f32 v[112:113], v[112:113], v[112:113]
	v_ashrrev_i32_e32 v117, 31, v116
	v_cvt_pk_bf16_f32 v114, v112, v113
	v_mov_b32_e32 v112, v124
	v_mov_b32_e32 v113, v126
	s_nop 0
	v_permlane16_swap_b32_e32 v112, v114
	v_permlane16_swap_b32_e32 v113, v115
	v_lshl_add_u64 v[118:119], v[116:117], 1, v[158:159]
	s_nop 0
	flat_store_dwordx4 v[118:119], v[112:115] offset:32
	s_mov_b64 s[6:7], 0

; __device__ __forceinline__ void gemm_phase(const Ctx& cx, const GemmArgs& g_, char* shm) {
;     ...
;             } else if (g.epi == EPI_RES) {
;               const float4 hv = *(const float4*)(g.hin + (size_t)tok * DM + n0);
;               const float h0 = hv.x + a[0], h1 = hv.y + a[1], h2 = hv.z + a[2], h3 = hv.w + a[3];
;               *(float4*)(g.hout + (size_t)tok * DM + n0) = make_float4(h0, h1, h2, h3);
;               if (g.w != nullptr) {
;                 const float4 nw = *(const float4*)(g.w + n0);
;                 uint2 o; o.x = pack2(h0 * nw.x, h1 * nw.y); o.y = pack2(h2 * nw.z, h3 * nw.w);
;                 EMIT_BF16(DM, o);
;                 ssq += h0 * h0 + h1 * h1 + h2 * h2 + h3 * h3;
;               }
.LBB0_429:
	s_and_b64 vcc, exec, s[10:11]
	v_mov_b32_e32 v117, v125
	s_cbranch_vccz .LBB0_432
	v_ashrrev_i32_e32 v121, 31, v120
	v_lshl_add_u64 v[118:119], v[120:121], 0, v[0:1]
	v_lshlrev_b64 v[128:129], 2, v[118:119]
	v_lshl_add_u64 v[112:113], v[148:149], 0, v[128:129]
	s_nop 0
	flat_load_dwordx4 v[112:115], v[112:113] offset:64
	s_andn2_b64 vcc, exec, s[42:43]
	v_lshl_add_u64 v[128:129], v[146:147], 0, v[128:129]
	v_mov_b32_e32 v117, v125
	s_waitcnt vmcnt(0) lgkmcnt(0)
	v_pk_add_f32 v[112:113], v[108:109], v[112:113]
	v_pk_add_f32 v[114:115], v[110:111], v[114:115]
	flat_store_dwordx4 v[128:129], v[112:115] offset:64
	s_cbranch_vccnz .LBB0_432
	v_lshl_add_u64 v[118:119], v[118:119], 2, s[30:31]
	global_load_dwordx4 v[128:131], v[118:119], off offset:64
	v_ashrrev_i32_e32 v117, 31, v116
	s_waitcnt vmcnt(0)
	v_pk_mul_f32 v[118:119], v[114:115], v[130:131]
	s_nop 0
	v_cvt_pk_bf16_f32 v131, v118, v119
	v_pk_mul_f32 v[118:119], v[112:113], v[128:129]
	v_pk_mul_f32 v[112:113], v[112:113], v[112:113]
	v_pk_mul_f32 v[114:115], v[114:115], v[114:115]
	v_add_f32_e32 v2, v112, v113
	v_cvt_pk_bf16_f32 v130, v118, v119
	v_mov_b32_e32 v128, v124
	v_mov_b32_e32 v129, v126
	v_add_f32_e32 v2, v2, v114
	v_permlane16_swap_b32_e32 v128, v130
	v_permlane16_swap_b32_e32 v129, v131
	v_lshl_add_u64 v[118:119], v[116:117], 1, v[134:135]
	v_add_f32_e32 v2, v2, v115
	flat_store_dwordx4 v[118:119], v[128:131] offset:32
	v_add_f32_e32 v117, v125, v2

; __device__ __forceinline__ float b2f(u16 b) { return __uint_as_float(((uint32_t)b) << 16); }
; __device__ __forceinline__ float sigmoidf_(float x) { return 1.0f / (1.0f + __expf(-x)); }
; __device__ __forceinline__ void gemm_phase(const Ctx& cx, const GemmArgs& g_, char* shm) {
;     ...
;             } else {
;               const uint2 gv = *(const uint2*)(g.gate + (size_t)tok * NP + n0);
;               float v0 = sigmoidf_(b2f((u16)(gv.x & 0xffff))) * a[0], v1 = sigmoidf_(b2f((u16)(gv.x >> 16))) * a[1];
;               float v2 = sigmoidf_(b2f((u16)(gv.y & 0xffff))) * a[2], v3 = sigmoidf_(b2f((u16)(gv.y >> 16))) * a[3];
;               uint2* mp = (uint2*)(g.outb + (size_t)tok * DM + n0);
;               if (g.epi != EPI_BR0) {
;                 const uint2 pv = *mp;
;                 v0 += b2f((u16)(pv.x & 0xffff)); v1 += b2f((u16)(pv.x >> 16));
;                 v2 += b2f((u16)(pv.y & 0xffff)); v3 += b2f((u16)(pv.y >> 16));
;               }
;               uint2 o; o.x = pack2(v0, v1); o.y = pack2(v2, v3);
;               *mp = o;
;             }
.LBB0_434:
	v_lshl_add_u64 v[112:113], v[120:121], 0, v[0:1]
	v_lshlrev_b64 v[114:115], 1, v[112:113]
	v_lshl_add_u64 v[112:113], v[156:157], 0, v[114:115]
	s_nop 0
	flat_load_dwordx2 v[118:119], v[112:113] offset:32
	v_lshl_add_u64 v[114:115], v[134:135], 0, v[114:115]
	s_waitcnt vmcnt(0) lgkmcnt(0)
	v_lshlrev_b32_e32 v2, 16, v118
	v_mul_f32_e32 v2, 0xbfb8aa3b, v2
	v_exp_f32_e32 v112, v2
	v_and_b32_e32 v2, 0xffff0000, v118
	v_mul_f32_e32 v2, 0xbfb8aa3b, v2
	v_exp_f32_e32 v113, v2
	s_nop 0
	v_pk_add_f32 v[112:113], v[112:113], 1.0 op_sel_hi:[1,0]
	s_nop 0
	v_div_scale_f32 v2, s[2:3], v113, v113, 1.0
	v_rcp_f32_e32 v117, v2
	s_nop 0
	v_fma_f32 v118, -v2, v117, 1.0
	v_fmac_f32_e32 v117, v118, v117
	v_div_scale_f32 v118, vcc, 1.0, v113, 1.0
	v_mul_f32_e32 v127, v118, v117
	v_fma_f32 v128, -v2, v127, v118
	v_fmac_f32_e32 v127, v128, v117
	v_fma_f32 v2, -v2, v127, v118
	v_div_fmas_f32 v2, v2, v117, v127
	v_div_fixup_f32 v113, v2, v113, 1.0
	v_div_scale_f32 v2, s[2:3], v112, v112, 1.0
	v_rcp_f32_e32 v117, v2
	s_nop 0
	v_fma_f32 v118, -v2, v117, 1.0
	v_fmac_f32_e32 v117, v118, v117
	v_div_scale_f32 v118, vcc, 1.0, v112, 1.0
	v_mul_f32_e32 v127, v118, v117
	v_fma_f32 v128, -v2, v127, v118
	v_fmac_f32_e32 v127, v128, v117
	v_fma_f32 v2, -v2, v127, v118
	v_div_fmas_f32 v2, v2, v117, v127
	v_div_fixup_f32 v112, v2, v112, 1.0
	v_lshlrev_b32_e32 v2, 16, v119
	v_mul_f32_e32 v2, 0xbfb8aa3b, v2
	v_exp_f32_e32 v118, v2
	v_and_b32_e32 v2, 0xffff0000, v119
	v_mul_f32_e32 v2, 0xbfb8aa3b, v2
	v_exp_f32_e32 v119, v2
	v_pk_mul_f32 v[112:113], v[108:109], v[112:113]
	v_pk_add_f32 v[118:119], v[118:119], 1.0 op_sel_hi:[1,0]
	s_nop 0
	v_div_scale_f32 v2, s[2:3], v119, v119, 1.0
	v_rcp_f32_e32 v117, v2
	s_nop 0
	v_fma_f32 v127, -v2, v117, 1.0
	v_fmac_f32_e32 v117, v127, v117
	v_div_scale_f32 v127, vcc, 1.0, v119, 1.0
	v_mul_f32_e32 v128, v127, v117
	v_fma_f32 v129, -v2, v128, v127
	v_fmac_f32_e32 v128, v129, v117
	v_fma_f32 v2, -v2, v128, v127
	v_div_fmas_f32 v2, v2, v117, v128
	v_div_fixup_f32 v119, v2, v119, 1.0
	v_div_scale_f32 v2, s[2:3], v118, v118, 1.0
	v_rcp_f32_e32 v117, v2
	s_nop 0
	v_fma_f32 v127, -v2, v117, 1.0
	v_fmac_f32_e32 v117, v127, v117
	v_div_scale_f32 v127, vcc, 1.0, v118, 1.0
	v_mul_f32_e32 v128, v127, v117
	v_fma_f32 v129, -v2, v128, v127
	v_fmac_f32_e32 v128, v129, v117
	v_fma_f32 v2, -v2, v128, v127
	v_div_fmas_f32 v2, v2, v117, v128
	v_div_fixup_f32 v118, v2, v118, 1.0
	v_pk_mul_f32 v[118:119], v[110:111], v[118:119]
	s_and_b64 vcc, exec, s[4:5]
	s_cbranch_vccnz .LBB0_436
	flat_load_dwordx2 v[128:129], v[114:115] offset:32
	s_waitcnt vmcnt(0) lgkmcnt(0)
	v_lshlrev_b32_e32 v130, 16, v128
	v_and_b32_e32 v131, 0xffff0000, v128
	v_lshlrev_b32_e32 v128, 16, v129
	v_and_b32_e32 v129, 0xffff0000, v129
	v_pk_add_f32 v[112:113], v[112:113], v[130:131]
	v_pk_add_f32 v[118:119], v[118:119], v[128:129]

; __device__ __forceinline__ void gemm_phase(const Ctx& cx, const GemmArgs& g_, char* shm) {
;     ...
; #pragma unroll
;           for (int m = 0; m < 4; ++m) {
;             const int n0 = brow + ai * 128 + wr * 64 + m * 16 + fq * 4;
;             f32x4 a = acc[ai][bj][m][n];
;             if (g.epi == EPI_PROJ || g.epi == EPI_RELU2) { a[0] *= rs; a[1] *= rs; a[2] *= rs; a[3] *= rs; }
;             if (g.epi == EPI_PROJ) {
;               if (n0 >= C_GLAX) {
;                 const int i = n0 - C_GLAX;
;                 const float4 b4 = *(const float4*)(g.hin + i);
;                 float xs[4] = {a[0] + b4.x, a[1] + b4.y, a[2] + b4.z, a[3] + b4.w};
; #pragma unroll
;                 for (int j = 0; j < 4; ++j)
;                   xs[j] = (fminf(xs[j], 0.f) - __logf(1.0f + __expf(-fabsf(xs[j])))) * (1.0f / 16.0f);
;                 *(float4*)(g.f32buf + (size_t)tok * 1024 + i) = make_float4(xs[0], xs[1], xs[2], xs[3]);
;               } else {
;                 float o0 = a[0], o1 = a[1], o2 = a[2], o3 = a[3];
;                 const bool r128 = (n0 >= C_DSAQ && n0 < C_HGQ) || (n0 >= C_DSAK && n0 < C_DSAV);
;                 const bool r64 = (n0 >= C_IDXQ && n0 < C_GLAA);
;                 if (r128 || r64) {
;                   float4 cs;
;                   float sc;
;                   if (r128) {
;                     cs = *(const float4*)(g.w + ((size_t)tok * 64 + ((n0 & 127) >> 1)) * 2);
;                     sc = (n0 < C_HGQ) ? 0.08838834764831845f : 1.0f;
;                   } else {
;                     cs = *(const float4*)(g.hout + ((size_t)tok * 32 + ((n0 & 63) >> 1)) * 2);
;                     sc = (n0 < C_IDXK) ? 0.125f : 1.0f;
;                   }
;                   o0 = (a[0] * cs.x - a[1] * cs.y) * sc; o1 = (a[1] * cs.x + a[0] * cs.y) * sc;
;                   o2 = (a[2] * cs.z - a[3] * cs.w) * sc; o3 = (a[3] * cs.z + a[2] * cs.w) * sc;
;                 }
;                 uint2 o; o.x = pack2(o0, o1); o.y = pack2(o2, o3);
;                 EMIT_BF16(g.ldo, o);
.LBB0_437:
	v_or_b32_e32 v160, v120, v173
	s_movk_i32 s0, 0x5c00
	s_and_b64 vcc, exec, s[2:3]
	v_cmp_gt_i32_e64 s[6:7], s0, v160
	s_cbranch_vccz .LBB0_449
	s_and_saveexec_b64 s[2:3], s[6:7]
	s_xor_b64 s[2:3], exec, s[2:3]
	s_cbranch_execz .LBB0_446
	v_add_u32_e32 v2, 0xffffa780, v138
	v_cmp_gt_u32_e32 vcc, s77, v2
	s_or_b64 s[10:11], s[54:55], vcc
	s_and_saveexec_b64 s[6:7], s[10:11]
	s_cbranch_execz .LBB0_445
	s_and_saveexec_b64 s[10:11], s[52:53]
	s_xor_b64 s[10:11], exec, s[10:11]
	v_lshlrev_b32_e32 v2, 2, v0
	s_movk_i32 s0, 0x5b00
	v_lshl_add_u64 v[112:113], v[152:153], 0, v[2:3]
	v_cmp_gt_u32_e32 vcc, s0, v120
	v_lshl_add_u64 v[112:113], v[112:113], 0, 64
	s_nop 0
	v_cndmask_b32_e32 v2, 1.0, v166, vcc
	s_andn2_saveexec_b64 s[10:11], s[10:11]
	v_and_b32_e32 v2, 0x5c, v160
	v_lshlrev_b32_e32 v2, 2, v2
	v_cmp_gt_i32_e32 vcc, s81, v160
	v_lshl_add_u64 v[112:113], v[150:151], 0, v[2:3]
	s_nop 0
	v_cndmask_b32_e32 v2, 1.0, v167, vcc
	s_or_b64 exec, exec, s[10:11]
	s_nop 0
	flat_load_dwordx4 v[112:115], v[112:113]
	s_waitcnt vmcnt(0) lgkmcnt(0)
	v_pk_mul_f32 v[118:119], v[108:109], v[112:113] op_sel:[1,1] op_sel_hi:[1,0]
	s_nop 0
	v_pk_fma_f32 v[128:129], v[108:109], v[112:113], v[118:119] neg_lo:[0,0,1] neg_hi:[0,0,1]
	v_pk_fma_f32 v[108:109], v[108:109], v[112:113], v[118:119] op_sel_hi:[0,1,1]
	v_mov_b32_e32 v112, v111
	v_pk_mul_f32 v[112:113], v[112:113], v[114:115] op_sel:[0,1] op_sel_hi:[0,0]
	v_pk_fma_f32 v[118:119], v[110:111], v[114:115], v[112:113] neg_lo:[0,0,1] neg_hi:[0,0,1]
	v_pk_fma_f32 v[110:111], v[110:111], v[114:115], v[112:113] op_sel_hi:[0,1,1]
	v_mov_b32_e32 v129, v109
	v_mov_b32_e32 v119, v111
	v_pk_mul_f32 v[108:109], v[2:3], v[128:129] op_sel_hi:[0,1]
	v_pk_mul_f32 v[110:111], v[2:3], v[118:119] op_sel_hi:[0,1]
.LBB0_445:
	s_or_b64 exec, exec, s[6:7]
	v_cvt_pk_bf16_f32 v111, v110, v111
	v_cvt_pk_bf16_f32 v110, v108, v109
	v_mov_b32_e32 v108, v124
	v_mov_b32_e32 v109, v126
	v_ashrrev_i32_e32 v117, 31, v116
	v_permlane16_swap_b32_e32 v108, v110
	v_permlane16_swap_b32_e32 v109, v111
	v_lshl_add_u64 v[112:113], v[116:117], 1, v[158:159]
	s_nop 0
	flat_store_dwordx4 v[112:113], v[108:111] offset:32
.LBB0_446:
	s_andn2_saveexec_b64 s[2:3], s[2:3]
	s_cbranch_execz .LBB0_448
	v_add_u32_e32 v2, 0xffffa400, v160
	v_lshlrev_b64 v[118:119], 2, v[2:3]
	v_lshl_add_u64 v[112:113], s[26:27], 0, v[118:119]
	s_nop 0
	flat_load_dwordx4 v[112:115], v[112:113]
	s_mov_b32 s0, 0x3d800000
	v_lshl_add_u64 v[118:119], v[144:145], 0, v[118:119]
	s_waitcnt vmcnt(0) lgkmcnt(0)
	v_add_f32_e32 v2, v108, v112
	v_min_f32_e32 v108, 0, v2
	v_mul_f32_e64 v2, |v2|, s82
	v_exp_f32_e32 v2, v2
	v_add_f32_e32 v112, v109, v113
	v_add_f32_e32 v113, v110, v114
	v_add_f32_e32 v115, v111, v115
	v_add_f32_e32 v2, 1.0, v2
	v_cmp_gt_f32_e32 vcc, s83, v2
	s_nop 1
	v_cndmask_b32_e64 v109, 0, 32, vcc
	v_ldexp_f32 v2, v2, v109
	v_log_f32_e32 v2, v2
	s_nop 0
	v_mul_f32_e32 v109, 0x3f317217, v2
	v_fma_f32 v109, v2, s86, -v109
	v_fmac_f32_e32 v109, 0x3377d1cf, v2
	v_fmac_f32_e32 v109, 0x3f317217, v2
	v_cmp_lt_f32_e64 s[6:7], |v2|, s87
	s_nop 1
	v_cndmask_b32_e64 v2, v2, v109, s[6:7]
	v_cndmask_b32_e32 v109, 0, v165, vcc
	v_sub_f32_e32 v110, v2, v109
	v_mul_f32_e64 v2, |v112|, s82
	v_exp_f32_e32 v2, v2
	v_min_f32_e32 v109, 0, v112
	v_min_f32_e32 v112, 0, v113
	v_add_f32_e32 v2, 1.0, v2
	v_cmp_gt_f32_e32 vcc, s83, v2
	s_nop 1
	v_cndmask_b32_e64 v111, 0, 32, vcc
	v_ldexp_f32 v2, v2, v111
	v_log_f32_e32 v2, v2
	s_nop 0
	v_mul_f32_e32 v111, 0x3f317217, v2
	v_fma_f32 v111, v2, s86, -v111
	v_fmac_f32_e32 v111, 0x3377d1cf, v2
	v_fmac_f32_e32 v111, 0x3f317217, v2
	v_cmp_lt_f32_e64 s[6:7], |v2|, s87
	s_nop 1
	v_cndmask_b32_e64 v2, v2, v111, s[6:7]
	v_cndmask_b32_e32 v111, 0, v165, vcc
	v_sub_f32_e32 v111, v2, v111
	v_mul_f32_e64 v2, |v113|, s82
	v_exp_f32_e32 v2, v2
	v_pk_add_f32 v[108:109], v[108:109], v[110:111] neg_lo:[0,1] neg_hi:[0,1]
	v_add_f32_e32 v2, 1.0, v2
	v_cmp_gt_f32_e32 vcc, s83, v2
	v_pk_mul_f32 v[108:109], v[108:109], s[0:1] op_sel_hi:[1,0]
	s_nop 0
	v_cndmask_b32_e64 v113, 0, 32, vcc
	v_ldexp_f32 v2, v2, v113
	v_log_f32_e32 v2, v2
	s_nop 0
	v_mul_f32_e32 v113, 0x3f317217, v2
	v_fma_f32 v113, v2, s86, -v113
	v_fmac_f32_e32 v113, 0x3377d1cf, v2
	v_fmac_f32_e32 v113, 0x3f317217, v2
	v_cmp_lt_f32_e64 s[6:7], |v2|, s87
	s_nop 1
	v_cndmask_b32_e64 v2, v2, v113, s[6:7]
	v_cndmask_b32_e32 v113, 0, v165, vcc
	v_sub_f32_e32 v114, v2, v113
	v_mul_f32_e64 v2, |v115|, s82
	v_exp_f32_e32 v2, v2
	v_min_f32_e32 v113, 0, v115
	v_add_f32_e32 v2, 1.0, v2
	v_cmp_gt_f32_e32 vcc, s83, v2
	s_nop 1
	v_cndmask_b32_e64 v115, 0, 32, vcc
	v_ldexp_f32 v2, v2, v115
	v_log_f32_e32 v2, v2
	s_nop 0
	v_mul_f32_e32 v115, 0x3f317217, v2
	v_fma_f32 v115, v2, s86, -v115
	v_fmac_f32_e32 v115, 0x3377d1cf, v2
	v_fmac_f32_e32 v115, 0x3f317217, v2
	v_cmp_lt_f32_e64 s[6:7], |v2|, s87
	s_nop 1
	v_cndmask_b32_e64 v2, v2, v115, s[6:7]
	v_cndmask_b32_e32 v115, 0, v165, vcc
	v_sub_f32_e32 v115, v2, v115
	v_pk_add_f32 v[110:111], v[112:113], v[114:115] neg_lo:[0,1] neg_hi:[0,1]
	s_nop 0
	v_pk_mul_f32 v[110:111], v[110:111], s[0:1] op_sel_hi:[1,0]
	flat_store_dwordx4 v[118:119], v[108:111]

; __device__ __forceinline__ void gemm_phase(const Ctx& cx, const GemmArgs& g_, char* shm) {
;     ...
;             } else if (g.epi == EPI_RES) {
;               const float4 hv = *(const float4*)(g.hin + (size_t)tok * DM + n0);
;               const float h0 = hv.x + a[0], h1 = hv.y + a[1], h2 = hv.z + a[2], h3 = hv.w + a[3];
;               *(float4*)(g.hout + (size_t)tok * DM + n0) = make_float4(h0, h1, h2, h3);
;               if (g.w != nullptr) {
;                 const float4 nw = *(const float4*)(g.w + n0);
;                 uint2 o; o.x = pack2(h0 * nw.x, h1 * nw.y); o.y = pack2(h2 * nw.z, h3 * nw.w);
;                 EMIT_BF16(DM, o);
;                 ssq += h0 * h0 + h1 * h1 + h2 * h2 + h3 * h3;
;               }
.LBB0_462:
	s_and_b64 vcc, exec, s[10:11]
	v_mov_b32_e32 v118, v117
	s_cbranch_vccz .LBB0_465
	v_lshl_add_u64 v[114:115], v[120:121], 0, v[0:1]
	v_lshlrev_b64 v[108:109], 2, v[114:115]
	v_lshl_add_u64 v[110:111], v[148:149], 0, v[108:109]
	s_nop 0
	flat_load_dwordx4 v[110:113], v[110:111] offset:128
	v_lshl_add_u64 v[108:109], v[146:147], 0, v[108:109]
	s_andn2_b64 vcc, exec, s[42:43]
	v_mov_b32_e32 v118, v117
	s_waitcnt vmcnt(0) lgkmcnt(0)
	v_pk_add_f32 v[110:111], v[104:105], v[110:111]
	v_pk_add_f32 v[112:113], v[106:107], v[112:113]
	flat_store_dwordx4 v[108:109], v[110:113] offset:128
	v_mov_b32_e32 v109, v126
	v_mov_b32_e32 v108, v124
	s_cbranch_vccnz .LBB0_465
	v_lshl_add_u64 v[108:109], v[114:115], 2, s[30:31]
	global_load_dwordx4 v[128:131], v[108:109], off offset:128
	v_pk_mul_f32 v[108:109], v[110:111], v[110:111]
	v_pk_mul_f32 v[114:115], v[112:113], v[112:113]
	v_add_f32_e32 v2, v108, v109
	v_add_f32_e32 v2, v2, v114
	v_add_f32_e32 v2, v2, v115
	v_add_f32_e32 v118, v117, v2
	s_waitcnt vmcnt(0)
	v_pk_mul_f32 v[108:109], v[112:113], v[130:131]
	v_pk_mul_f32 v[110:111], v[110:111], v[128:129]
	v_cvt_pk_bf16_f32 v109, v108, v109
	v_cvt_pk_bf16_f32 v108, v110, v111

; __device__ __forceinline__ float b2f(u16 b) { return __uint_as_float(((uint32_t)b) << 16); }
; __device__ __forceinline__ float sigmoidf_(float x) { return 1.0f / (1.0f + __expf(-x)); }
; __device__ __forceinline__ void gemm_phase(const Ctx& cx, const GemmArgs& g_, char* shm) {
;     ...
;             } else {
;               const uint2 gv = *(const uint2*)(g.gate + (size_t)tok * NP + n0);
;               float v0 = sigmoidf_(b2f((u16)(gv.x & 0xffff))) * a[0], v1 = sigmoidf_(b2f((u16)(gv.x >> 16))) * a[1];
;               float v2 = sigmoidf_(b2f((u16)(gv.y & 0xffff))) * a[2], v3 = sigmoidf_(b2f((u16)(gv.y >> 16))) * a[3];
;               uint2* mp = (uint2*)(g.outb + (size_t)tok * DM + n0);
;               if (g.epi != EPI_BR0) {
;                 const uint2 pv = *mp;
;                 v0 += b2f((u16)(pv.x & 0xffff)); v1 += b2f((u16)(pv.x >> 16));
;                 v2 += b2f((u16)(pv.y & 0xffff)); v3 += b2f((u16)(pv.y >> 16));
;               }
;               uint2 o; o.x = pack2(v0, v1); o.y = pack2(v2, v3);
;               *mp = o;
;             }
.LBB0_467:
	v_lshl_add_u64 v[108:109], v[120:121], 0, v[0:1]
	v_lshlrev_b64 v[110:111], 1, v[108:109]
	v_lshl_add_u64 v[108:109], v[156:157], 0, v[110:111]
	s_nop 0
	flat_load_dwordx2 v[112:113], v[108:109] offset:64
	v_lshl_add_u64 v[110:111], v[134:135], 0, v[110:111]
	s_waitcnt vmcnt(0) lgkmcnt(0)
	v_lshlrev_b32_e32 v2, 16, v112
	v_mul_f32_e32 v2, 0xbfb8aa3b, v2
	v_exp_f32_e32 v108, v2
	v_and_b32_e32 v2, 0xffff0000, v112
	v_mul_f32_e32 v2, 0xbfb8aa3b, v2
	v_exp_f32_e32 v109, v2
	s_nop 0
	v_pk_add_f32 v[108:109], v[108:109], 1.0 op_sel_hi:[1,0]
	s_nop 0
	v_div_scale_f32 v2, s[2:3], v109, v109, 1.0
	v_rcp_f32_e32 v112, v2
	s_nop 0
	v_fma_f32 v114, -v2, v112, 1.0
	v_fmac_f32_e32 v112, v114, v112
	v_div_scale_f32 v114, vcc, 1.0, v109, 1.0
	v_mul_f32_e32 v115, v114, v112
	v_fma_f32 v118, -v2, v115, v114
	v_fmac_f32_e32 v115, v118, v112
	v_fma_f32 v2, -v2, v115, v114
	v_div_fmas_f32 v2, v2, v112, v115
	v_div_fixup_f32 v109, v2, v109, 1.0
	v_div_scale_f32 v2, s[2:3], v108, v108, 1.0
	v_rcp_f32_e32 v112, v2
	s_nop 0
	v_fma_f32 v114, -v2, v112, 1.0
	v_fmac_f32_e32 v112, v114, v112
	v_div_scale_f32 v114, vcc, 1.0, v108, 1.0
	v_mul_f32_e32 v115, v114, v112
	v_fma_f32 v118, -v2, v115, v114
	v_fmac_f32_e32 v115, v118, v112
	v_fma_f32 v2, -v2, v115, v114
	v_div_fmas_f32 v2, v2, v112, v115
	v_div_fixup_f32 v108, v2, v108, 1.0
	v_lshlrev_b32_e32 v2, 16, v113
	v_mul_f32_e32 v2, 0xbfb8aa3b, v2
	v_exp_f32_e32 v112, v2
	v_and_b32_e32 v2, 0xffff0000, v113
	v_mul_f32_e32 v2, 0xbfb8aa3b, v2
	v_exp_f32_e32 v113, v2
	v_pk_mul_f32 v[108:109], v[104:105], v[108:109]
	v_pk_add_f32 v[112:113], v[112:113], 1.0 op_sel_hi:[1,0]
	s_nop 0
	v_div_scale_f32 v2, s[2:3], v113, v113, 1.0
	v_rcp_f32_e32 v114, v2
	s_nop 0
	v_fma_f32 v115, -v2, v114, 1.0
	v_fmac_f32_e32 v114, v115, v114
	v_div_scale_f32 v115, vcc, 1.0, v113, 1.0
	v_mul_f32_e32 v118, v115, v114
	v_fma_f32 v119, -v2, v118, v115
	v_fmac_f32_e32 v118, v119, v114
	v_fma_f32 v2, -v2, v118, v115
	v_div_fmas_f32 v2, v2, v114, v118
	v_div_fixup_f32 v113, v2, v113, 1.0
	v_div_scale_f32 v2, s[2:3], v112, v112, 1.0
	v_rcp_f32_e32 v114, v2
	s_nop 0
	v_fma_f32 v115, -v2, v114, 1.0
	v_fmac_f32_e32 v114, v115, v114
	v_div_scale_f32 v115, vcc, 1.0, v112, 1.0
	v_mul_f32_e32 v118, v115, v114
	v_fma_f32 v119, -v2, v118, v115
	v_fmac_f32_e32 v118, v119, v114
	v_fma_f32 v2, -v2, v118, v115
	v_div_fmas_f32 v2, v2, v114, v118
	v_div_fixup_f32 v112, v2, v112, 1.0
	v_pk_mul_f32 v[112:113], v[106:107], v[112:113]
	s_and_b64 vcc, exec, s[4:5]
	s_cbranch_vccnz .LBB0_469
	flat_load_dwordx2 v[114:115], v[110:111] offset:64
	s_waitcnt vmcnt(0) lgkmcnt(0)
	v_lshlrev_b32_e32 v118, 16, v114
	v_and_b32_e32 v119, 0xffff0000, v114
	v_lshlrev_b32_e32 v114, 16, v115
	v_and_b32_e32 v115, 0xffff0000, v115
	v_pk_add_f32 v[108:109], v[108:109], v[118:119]
	v_pk_add_f32 v[112:113], v[112:113], v[114:115]

; __device__ __forceinline__ void gemm_phase(const Ctx& cx, const GemmArgs& g_, char* shm) {
;     ...
;               } else {
;                 float o0 = a[0], o1 = a[1], o2 = a[2], o3 = a[3];
;                 const bool r128 = (n0 >= C_DSAQ && n0 < C_HGQ) || (n0 >= C_DSAK && n0 < C_DSAV);
;                 const bool r64 = (n0 >= C_IDXQ && n0 < C_GLAA);
;                 if (r128 || r64) {
;                   float4 cs;
;                   float sc;
;                   if (r128) {
;                     cs = *(const float4*)(g.w + ((size_t)tok * 64 + ((n0 & 127) >> 1)) * 2);
;                     sc = (n0 < C_HGQ) ? 0.08838834764831845f : 1.0f;
;                   } else {
;                     cs = *(const float4*)(g.hout + ((size_t)tok * 32 + ((n0 & 63) >> 1)) * 2);
;                     sc = (n0 < C_IDXK) ? 0.125f : 1.0f;
;                   }
;                   o0 = (a[0] * cs.x - a[1] * cs.y) * sc; o1 = (a[1] * cs.x + a[0] * cs.y) * sc;
;                   o2 = (a[2] * cs.z - a[3] * cs.w) * sc; o3 = (a[3] * cs.z + a[2] * cs.w) * sc;
;                 }
.LBB0_470:
	v_or_b32_e32 v131, v120, v174
	s_movk_i32 s0, 0x5c00
	s_and_b64 vcc, exec, s[2:3]
	v_cmp_gt_i32_e64 s[6:7], s0, v131
	s_cbranch_vccz .LBB0_482
	s_and_saveexec_b64 s[2:3], s[6:7]
	s_xor_b64 s[2:3], exec, s[2:3]
	s_cbranch_execz .LBB0_479
	v_add_u32_e32 v2, 0xffffa780, v138
	v_cmp_gt_u32_e32 vcc, s77, v2
	s_or_b64 s[10:11], s[54:55], vcc
	s_and_saveexec_b64 s[6:7], s[10:11]
	s_cbranch_execz .LBB0_478
	s_and_saveexec_b64 s[10:11], s[52:53]
	s_xor_b64 s[10:11], exec, s[10:11]
	v_lshlrev_b32_e32 v2, 2, v0
	s_movk_i32 s0, 0x5b00
	v_lshl_add_u64 v[108:109], v[152:153], 0, v[2:3]
	v_cmp_gt_u32_e32 vcc, s0, v120
	v_lshl_add_u64 v[108:109], v[108:109], 0, s[70:71]
	s_nop 0
	v_cndmask_b32_e32 v2, 1.0, v166, vcc
	s_andn2_saveexec_b64 s[10:11], s[10:11]
	v_and_b32_e32 v2, 0x6c, v131
	v_lshlrev_b32_e32 v2, 2, v2
	v_cmp_gt_i32_e32 vcc, s81, v131
	v_lshl_add_u64 v[108:109], v[150:151], 0, v[2:3]
	s_nop 0
	v_cndmask_b32_e32 v2, 1.0, v167, vcc
	s_or_b64 exec, exec, s[10:11]
	s_nop 0
	flat_load_dwordx4 v[108:111], v[108:109]
	s_waitcnt vmcnt(0) lgkmcnt(0)
	v_pk_mul_f32 v[112:113], v[104:105], v[108:109] op_sel:[1,1] op_sel_hi:[1,0]
	s_nop 0
	v_pk_fma_f32 v[114:115], v[104:105], v[108:109], v[112:113] neg_lo:[0,0,1] neg_hi:[0,0,1]
	v_pk_fma_f32 v[104:105], v[104:105], v[108:109], v[112:113] op_sel_hi:[0,1,1]
	v_mov_b32_e32 v108, v107
	v_pk_mul_f32 v[108:109], v[108:109], v[110:111] op_sel:[0,1] op_sel_hi:[0,0]
	v_pk_fma_f32 v[112:113], v[106:107], v[110:111], v[108:109] neg_lo:[0,0,1] neg_hi:[0,0,1]
	v_pk_fma_f32 v[106:107], v[106:107], v[110:111], v[108:109] op_sel_hi:[0,1,1]
	v_mov_b32_e32 v115, v105
	v_mov_b32_e32 v113, v107
	v_pk_mul_f32 v[104:105], v[2:3], v[114:115] op_sel_hi:[0,1]
	v_pk_mul_f32 v[106:107], v[2:3], v[112:113] op_sel_hi:[0,1]

; __device__ __forceinline__ void gemm_phase(const Ctx& cx, const GemmArgs& g_, char* shm) {
;     ...
;               if (n0 >= C_GLAX) {
;                 const int i = n0 - C_GLAX;
;                 const float4 b4 = *(const float4*)(g.hin + i);
;                 float xs[4] = {a[0] + b4.x, a[1] + b4.y, a[2] + b4.z, a[3] + b4.w};
; #pragma unroll
;                 for (int j = 0; j < 4; ++j)
;                   xs[j] = (fminf(xs[j], 0.f) - __logf(1.0f + __expf(-fabsf(xs[j])))) * (1.0f / 16.0f);
;                 *(float4*)(g.f32buf + (size_t)tok * 1024 + i) = make_float4(xs[0], xs[1], xs[2], xs[3]);
.LBB0_479:
	s_andn2_saveexec_b64 s[2:3], s[2:3]
	s_cbranch_execz .LBB0_481
	v_add_u32_e32 v2, 0xffffa400, v131
	v_lshlrev_b64 v[112:113], 2, v[2:3]
	v_lshl_add_u64 v[108:109], s[26:27], 0, v[112:113]
	s_nop 0
	flat_load_dwordx4 v[108:111], v[108:109]
	s_mov_b32 s0, 0x3d800000
	v_lshl_add_u64 v[112:113], v[144:145], 0, v[112:113]
	s_waitcnt vmcnt(0) lgkmcnt(0)
	v_add_f32_e32 v2, v104, v108
	v_min_f32_e32 v104, 0, v2
	v_mul_f32_e64 v2, |v2|, s82
	v_exp_f32_e32 v2, v2
	v_add_f32_e32 v108, v105, v109
	v_add_f32_e32 v109, v106, v110
	v_add_f32_e32 v111, v107, v111
	v_add_f32_e32 v2, 1.0, v2
	v_cmp_gt_f32_e32 vcc, s83, v2
	s_nop 1
	v_cndmask_b32_e64 v105, 0, 32, vcc
	v_ldexp_f32 v2, v2, v105
	v_log_f32_e32 v2, v2
	s_nop 0
	v_mul_f32_e32 v105, 0x3f317217, v2
	v_fma_f32 v105, v2, s86, -v105
	v_fmac_f32_e32 v105, 0x3377d1cf, v2
	v_fmac_f32_e32 v105, 0x3f317217, v2
	v_cmp_lt_f32_e64 s[6:7], |v2|, s87
	s_nop 1
	v_cndmask_b32_e64 v2, v2, v105, s[6:7]
	v_cndmask_b32_e32 v105, 0, v165, vcc
	v_sub_f32_e32 v106, v2, v105
	v_mul_f32_e64 v2, |v108|, s82
	v_exp_f32_e32 v2, v2
	v_min_f32_e32 v105, 0, v108
	v_min_f32_e32 v108, 0, v109
	v_add_f32_e32 v2, 1.0, v2
	v_cmp_gt_f32_e32 vcc, s83, v2
	s_nop 1
	v_cndmask_b32_e64 v107, 0, 32, vcc
	v_ldexp_f32 v2, v2, v107
	v_log_f32_e32 v2, v2
	s_nop 0
	v_mul_f32_e32 v107, 0x3f317217, v2
	v_fma_f32 v107, v2, s86, -v107
	v_fmac_f32_e32 v107, 0x3377d1cf, v2
	v_fmac_f32_e32 v107, 0x3f317217, v2
	v_cmp_lt_f32_e64 s[6:7], |v2|, s87
	s_nop 1
	v_cndmask_b32_e64 v2, v2, v107, s[6:7]
	v_cndmask_b32_e32 v107, 0, v165, vcc
	v_sub_f32_e32 v107, v2, v107
	v_mul_f32_e64 v2, |v109|, s82
	v_exp_f32_e32 v2, v2
	v_pk_add_f32 v[104:105], v[104:105], v[106:107] neg_lo:[0,1] neg_hi:[0,1]
	v_add_f32_e32 v2, 1.0, v2
	v_cmp_gt_f32_e32 vcc, s83, v2
	v_pk_mul_f32 v[104:105], v[104:105], s[0:1] op_sel_hi:[1,0]
	s_nop 0
	v_cndmask_b32_e64 v109, 0, 32, vcc
	v_ldexp_f32 v2, v2, v109
	v_log_f32_e32 v2, v2
	s_nop 0
	v_mul_f32_e32 v109, 0x3f317217, v2
	v_fma_f32 v109, v2, s86, -v109
	v_fmac_f32_e32 v109, 0x3377d1cf, v2
	v_fmac_f32_e32 v109, 0x3f317217, v2
	v_cmp_lt_f32_e64 s[6:7], |v2|, s87
	s_nop 1
	v_cndmask_b32_e64 v2, v2, v109, s[6:7]
	v_cndmask_b32_e32 v109, 0, v165, vcc
	v_sub_f32_e32 v110, v2, v109
	v_mul_f32_e64 v2, |v111|, s82
	v_exp_f32_e32 v2, v2
	v_min_f32_e32 v109, 0, v111
	v_add_f32_e32 v2, 1.0, v2
	v_cmp_gt_f32_e32 vcc, s83, v2
	s_nop 1
	v_cndmask_b32_e64 v111, 0, 32, vcc
	v_ldexp_f32 v2, v2, v111
	v_log_f32_e32 v2, v2
	s_nop 0
	v_mul_f32_e32 v111, 0x3f317217, v2
	v_fma_f32 v111, v2, s86, -v111
	v_fmac_f32_e32 v111, 0x3377d1cf, v2
	v_fmac_f32_e32 v111, 0x3f317217, v2
	v_cmp_lt_f32_e64 s[6:7], |v2|, s87
	s_nop 1
	v_cndmask_b32_e64 v2, v2, v111, s[6:7]
	v_cndmask_b32_e32 v111, 0, v165, vcc
	v_sub_f32_e32 v111, v2, v111
	v_pk_add_f32 v[106:107], v[108:109], v[110:111] neg_lo:[0,1] neg_hi:[0,1]
	v_mov_b32_e32 v109, v126
	v_pk_mul_f32 v[106:107], v[106:107], s[0:1] op_sel_hi:[1,0]
	v_mov_b32_e32 v108, v124
	flat_store_dwordx4 v[112:113], v[104:107]

; __device__ __forceinline__ void gemm_phase(const Ctx& cx, const GemmArgs& g_, char* shm) {
;     ...
;             } else if (g.epi == EPI_RELU2) {
;               float r0 = fmaxf(a[0], 0.f), r1 = fmaxf(a[1], 0.f), r2 = fmaxf(a[2], 0.f), r3 = fmaxf(a[3], 0.f);
;               uint2 o; o.x = pack2(r0 * r0, r1 * r1); o.y = pack2(r2 * r2, r3 * r3);
;               EMIT_BF16(g.ldo, o);
.LBB0_491:
	s_cmp_gt_i32 s38, 4
	s_cbranch_scc0 .LBB0_495
	s_cmp_eq_u32 s38, 5
	s_mov_b64 s[6:7], -1
	s_cbranch_scc0 .LBB0_494
	v_max_f32_e32 v2, v102, v102
	v_max_f32_e32 v104, 0, v2
	v_max_f32_e32 v2, v103, v103
	v_max_f32_e32 v105, 0, v2
	v_pk_mul_f32 v[104:105], v[104:105], v[104:105]
	v_max_f32_e32 v2, v100, v100
	v_cvt_pk_bf16_f32 v107, v104, v105
	v_max_f32_e32 v104, 0, v2
	v_max_f32_e32 v2, v101, v101
	v_max_f32_e32 v105, 0, v2
	v_pk_mul_f32 v[104:105], v[104:105], v[104:105]
	v_ashrrev_i32_e32 v117, 31, v116
	v_cvt_pk_bf16_f32 v106, v104, v105
	v_mov_b32_e32 v104, v108
	v_mov_b32_e32 v105, v109
	s_nop 0
	v_permlane16_swap_b32_e32 v104, v106
	v_permlane16_swap_b32_e32 v105, v107
	v_lshl_add_u64 v[110:111], v[116:117], 1, v[158:159]
	s_nop 0
	flat_store_dwordx4 v[110:111], v[104:107] offset:96
	s_mov_b64 s[6:7], 0

; __device__ __forceinline__ void gemm_phase(const Ctx& cx, const GemmArgs& g_, char* shm) {
;     ...
;             } else if (g.epi == EPI_RES) {
;               const float4 hv = *(const float4*)(g.hin + (size_t)tok * DM + n0);
;               const float h0 = hv.x + a[0], h1 = hv.y + a[1], h2 = hv.z + a[2], h3 = hv.w + a[3];
;               *(float4*)(g.hout + (size_t)tok * DM + n0) = make_float4(h0, h1, h2, h3);
;               if (g.w != nullptr) {
;                 const float4 nw = *(const float4*)(g.w + n0);
;                 uint2 o; o.x = pack2(h0 * nw.x, h1 * nw.y); o.y = pack2(h2 * nw.z, h3 * nw.w);
;                 EMIT_BF16(DM, o);
;                 ssq += h0 * h0 + h1 * h1 + h2 * h2 + h3 * h3;
;               }
.LBB0_495:
	s_and_b64 vcc, exec, s[10:11]
	v_mov_b32_e32 v2, v118
	s_cbranch_vccz .LBB0_498
	v_lshl_add_u64 v[110:111], v[120:121], 0, v[0:1]
	v_lshlrev_b64 v[112:113], 2, v[110:111]
	v_lshl_add_u64 v[104:105], v[148:149], 0, v[112:113]
	s_nop 0
	flat_load_dwordx4 v[104:107], v[104:105] offset:192
	v_lshl_add_u64 v[112:113], v[146:147], 0, v[112:113]
	s_andn2_b64 vcc, exec, s[42:43]
	v_mov_b32_e32 v2, v118
	s_waitcnt vmcnt(0) lgkmcnt(0)
	v_pk_add_f32 v[104:105], v[100:101], v[104:105]
	v_pk_add_f32 v[106:107], v[102:103], v[106:107]
	flat_store_dwordx4 v[112:113], v[104:107] offset:192
	s_cbranch_vccnz .LBB0_498
	v_lshl_add_u64 v[110:111], v[110:111], 2, s[30:31]
	global_load_dwordx4 v[110:113], v[110:111], off offset:192
	v_ashrrev_i32_e32 v117, 31, v116
	v_lshl_add_u64 v[114:115], v[116:117], 1, v[134:135]
	s_waitcnt vmcnt(0)
	v_pk_mul_f32 v[110:111], v[104:105], v[110:111]
	v_pk_mul_f32 v[104:105], v[104:105], v[104:105]
	v_pk_mul_f32 v[112:113], v[106:107], v[112:113]
	v_pk_mul_f32 v[106:107], v[106:107], v[106:107]
	v_add_f32_e32 v2, v104, v105
	v_cvt_pk_bf16_f32 v113, v112, v113
	v_cvt_pk_bf16_f32 v112, v110, v111
	v_mov_b32_e32 v110, v108
	v_mov_b32_e32 v111, v109
	v_add_f32_e32 v2, v2, v106
	v_permlane16_swap_b32_e32 v110, v112
	v_permlane16_swap_b32_e32 v111, v113
	v_add_f32_e32 v2, v2, v107
	flat_store_dwordx4 v[114:115], v[110:113] offset:96
	v_add_f32_e32 v2, v118, v2

; __device__ __forceinline__ float b2f(u16 b) { return __uint_as_float(((uint32_t)b) << 16); }
; __device__ __forceinline__ float sigmoidf_(float x) { return 1.0f / (1.0f + __expf(-x)); }
; __device__ __forceinline__ void gemm_phase(const Ctx& cx, const GemmArgs& g_, char* shm) {
;     ...
;             } else {
;               const uint2 gv = *(const uint2*)(g.gate + (size_t)tok * NP + n0);
;               float v0 = sigmoidf_(b2f((u16)(gv.x & 0xffff))) * a[0], v1 = sigmoidf_(b2f((u16)(gv.x >> 16))) * a[1];
;               float v2 = sigmoidf_(b2f((u16)(gv.y & 0xffff))) * a[2], v3 = sigmoidf_(b2f((u16)(gv.y >> 16))) * a[3];
;               uint2* mp = (uint2*)(g.outb + (size_t)tok * DM + n0);
;               if (g.epi != EPI_BR0) {
;                 const uint2 pv = *mp;
;                 v0 += b2f((u16)(pv.x & 0xffff)); v1 += b2f((u16)(pv.x >> 16));
;                 v2 += b2f((u16)(pv.y & 0xffff)); v3 += b2f((u16)(pv.y >> 16));
;               }
;               uint2 o; o.x = pack2(v0, v1); o.y = pack2(v2, v3);
;               *mp = o;
;             }
.LBB0_500:
	v_lshl_add_u64 v[104:105], v[120:121], 0, v[0:1]
	v_lshlrev_b64 v[106:107], 1, v[104:105]
	v_lshl_add_u64 v[104:105], v[156:157], 0, v[106:107]
	s_nop 0
	flat_load_dwordx2 v[110:111], v[104:105] offset:96
	v_lshl_add_u64 v[106:107], v[134:135], 0, v[106:107]
	s_waitcnt vmcnt(0) lgkmcnt(0)
	v_lshlrev_b32_e32 v2, 16, v110
	v_mul_f32_e32 v2, 0xbfb8aa3b, v2
	v_exp_f32_e32 v104, v2
	v_and_b32_e32 v2, 0xffff0000, v110
	v_mul_f32_e32 v2, 0xbfb8aa3b, v2
	v_exp_f32_e32 v105, v2
	s_nop 0
	v_pk_add_f32 v[104:105], v[104:105], 1.0 op_sel_hi:[1,0]
	s_nop 0
	v_div_scale_f32 v2, s[2:3], v105, v105, 1.0
	v_rcp_f32_e32 v110, v2
	s_nop 0
	v_fma_f32 v112, -v2, v110, 1.0
	v_fmac_f32_e32 v110, v112, v110
	v_div_scale_f32 v112, vcc, 1.0, v105, 1.0
	v_mul_f32_e32 v113, v112, v110
	v_fma_f32 v114, -v2, v113, v112
	v_fmac_f32_e32 v113, v114, v110
	v_fma_f32 v2, -v2, v113, v112
	v_div_fmas_f32 v2, v2, v110, v113
	v_div_fixup_f32 v105, v2, v105, 1.0
	v_div_scale_f32 v2, s[2:3], v104, v104, 1.0
	v_rcp_f32_e32 v110, v2
	s_nop 0
	v_fma_f32 v112, -v2, v110, 1.0
	v_fmac_f32_e32 v110, v112, v110
	v_div_scale_f32 v112, vcc, 1.0, v104, 1.0
	v_mul_f32_e32 v113, v112, v110
	v_fma_f32 v114, -v2, v113, v112
	v_fmac_f32_e32 v113, v114, v110
	v_fma_f32 v2, -v2, v113, v112
	v_div_fmas_f32 v2, v2, v110, v113
	v_div_fixup_f32 v104, v2, v104, 1.0
	v_lshlrev_b32_e32 v2, 16, v111
	v_mul_f32_e32 v2, 0xbfb8aa3b, v2
	v_exp_f32_e32 v110, v2
	v_and_b32_e32 v2, 0xffff0000, v111
	v_mul_f32_e32 v2, 0xbfb8aa3b, v2
	v_exp_f32_e32 v111, v2
	v_pk_mul_f32 v[104:105], v[100:101], v[104:105]
	v_pk_add_f32 v[110:111], v[110:111], 1.0 op_sel_hi:[1,0]
	s_nop 0
	v_div_scale_f32 v2, s[2:3], v111, v111, 1.0
	v_rcp_f32_e32 v112, v2
	s_nop 0
	v_fma_f32 v113, -v2, v112, 1.0
	v_fmac_f32_e32 v112, v113, v112
	v_div_scale_f32 v113, vcc, 1.0, v111, 1.0
	v_mul_f32_e32 v114, v113, v112
	v_fma_f32 v115, -v2, v114, v113
	v_fmac_f32_e32 v114, v115, v112
	v_fma_f32 v2, -v2, v114, v113
	v_div_fmas_f32 v2, v2, v112, v114
	v_div_fixup_f32 v111, v2, v111, 1.0
	v_div_scale_f32 v2, s[2:3], v110, v110, 1.0
	v_rcp_f32_e32 v112, v2
	s_nop 0
	v_fma_f32 v113, -v2, v112, 1.0
	v_fmac_f32_e32 v112, v113, v112
	v_div_scale_f32 v113, vcc, 1.0, v110, 1.0
	v_mul_f32_e32 v114, v113, v112
	v_fma_f32 v115, -v2, v114, v113
	v_fmac_f32_e32 v114, v115, v112
	v_fma_f32 v2, -v2, v114, v113
	v_div_fmas_f32 v2, v2, v112, v114
	v_div_fixup_f32 v110, v2, v110, 1.0
	v_pk_mul_f32 v[110:111], v[102:103], v[110:111]
	s_and_b64 vcc, exec, s[4:5]
	s_cbranch_vccnz .LBB0_502
	flat_load_dwordx2 v[112:113], v[106:107] offset:96
	s_waitcnt vmcnt(0) lgkmcnt(0)
	v_lshlrev_b32_e32 v114, 16, v112
	v_and_b32_e32 v115, 0xffff0000, v112
	v_lshlrev_b32_e32 v112, 16, v113
	v_and_b32_e32 v113, 0xffff0000, v113
	v_pk_add_f32 v[104:105], v[104:105], v[114:115]
	v_pk_add_f32 v[110:111], v[110:111], v[112:113]

; __device__ __forceinline__ void gemm_phase(const Ctx& cx, const GemmArgs& g_, char* shm) {
;     ...
; #pragma unroll
;           for (int m = 0; m < 4; ++m) {
;             const int n0 = brow + ai * 128 + wr * 64 + m * 16 + fq * 4;
;             f32x4 a = acc[ai][bj][m][n];
;             if (g.epi == EPI_PROJ || g.epi == EPI_RELU2) { a[0] *= rs; a[1] *= rs; a[2] *= rs; a[3] *= rs; }
;             if (g.epi == EPI_PROJ) {
;               if (n0 >= C_GLAX) {
;                 const int i = n0 - C_GLAX;
;                 const float4 b4 = *(const float4*)(g.hin + i);
;                 float xs[4] = {a[0] + b4.x, a[1] + b4.y, a[2] + b4.z, a[3] + b4.w};
; #pragma unroll
;                 for (int j = 0; j < 4; ++j)
;                   xs[j] = (fminf(xs[j], 0.f) - __logf(1.0f + __expf(-fabsf(xs[j])))) * (1.0f / 16.0f);
;                 *(float4*)(g.f32buf + (size_t)tok * 1024 + i) = make_float4(xs[0], xs[1], xs[2], xs[3]);
;               } else {
;                 float o0 = a[0], o1 = a[1], o2 = a[2], o3 = a[3];
;                 const bool r128 = (n0 >= C_DSAQ && n0 < C_HGQ) || (n0 >= C_DSAK && n0 < C_DSAV);
;                 const bool r64 = (n0 >= C_IDXQ && n0 < C_GLAA);
;                 if (r128 || r64) {
;                   float4 cs;
;                   float sc;
;                   if (r128) {
;                     cs = *(const float4*)(g.w + ((size_t)tok * 64 + ((n0 & 127) >> 1)) * 2);
;                     sc = (n0 < C_HGQ) ? 0.08838834764831845f : 1.0f;
;                   } else {
;                     cs = *(const float4*)(g.hout + ((size_t)tok * 32 + ((n0 & 63) >> 1)) * 2);
;                     sc = (n0 < C_IDXK) ? 0.125f : 1.0f;
;                   }
;                   o0 = (a[0] * cs.x - a[1] * cs.y) * sc; o1 = (a[1] * cs.x + a[0] * cs.y) * sc;
;                   o2 = (a[2] * cs.z - a[3] * cs.w) * sc; o3 = (a[3] * cs.z + a[2] * cs.w) * sc;
;                 }
;                 uint2 o; o.x = pack2(o0, o1); o.y = pack2(o2, o3);
;                 EMIT_BF16(g.ldo, o);
.LBB0_508:
	s_and_saveexec_b64 s[2:3], s[6:7]
	s_xor_b64 s[2:3], exec, s[2:3]
	s_cbranch_execz .LBB0_516
	v_add_u32_e32 v2, 0xffffa780, v138
	v_cmp_gt_u32_e32 vcc, s77, v2
	s_or_b64 s[10:11], s[54:55], vcc
	s_and_saveexec_b64 s[6:7], s[10:11]
	s_cbranch_execz .LBB0_515
	s_and_saveexec_b64 s[10:11], s[52:53]
	s_xor_b64 s[10:11], exec, s[10:11]
	v_lshlrev_b32_e32 v2, 2, v0
	s_movk_i32 s0, 0x5b00
	v_lshl_add_u64 v[104:105], v[152:153], 0, v[2:3]
	s_mov_b64 s[60:61], 0xc0
	v_cmp_gt_u32_e32 vcc, s0, v120
	v_lshl_add_u64 v[104:105], v[104:105], 0, s[60:61]
	s_nop 0
	v_cndmask_b32_e32 v2, 1.0, v166, vcc
	s_andn2_saveexec_b64 s[10:11], s[10:11]
	v_and_b32_e32 v2, 0x7c, v130
	v_lshlrev_b32_e32 v2, 2, v2
	v_cmp_gt_i32_e32 vcc, s81, v130
	v_lshl_add_u64 v[104:105], v[150:151], 0, v[2:3]
	s_nop 0
	v_cndmask_b32_e32 v2, 1.0, v167, vcc
	s_or_b64 exec, exec, s[10:11]
	s_nop 0
	flat_load_dwordx4 v[104:107], v[104:105]
	s_waitcnt vmcnt(0) lgkmcnt(0)
	v_pk_mul_f32 v[110:111], v[100:101], v[104:105] op_sel:[1,1] op_sel_hi:[1,0]
	s_nop 0
	v_pk_fma_f32 v[112:113], v[100:101], v[104:105], v[110:111] neg_lo:[0,0,1] neg_hi:[0,0,1]
	v_pk_fma_f32 v[100:101], v[100:101], v[104:105], v[110:111] op_sel_hi:[0,1,1]
	v_mov_b32_e32 v104, v103
	v_pk_mul_f32 v[104:105], v[104:105], v[106:107] op_sel:[0,1] op_sel_hi:[0,0]
	v_pk_fma_f32 v[110:111], v[102:103], v[106:107], v[104:105] neg_lo:[0,0,1] neg_hi:[0,0,1]
	v_pk_fma_f32 v[102:103], v[102:103], v[106:107], v[104:105] op_sel_hi:[0,1,1]
	v_mov_b32_e32 v113, v101
	v_mov_b32_e32 v111, v103
	v_pk_mul_f32 v[100:101], v[2:3], v[112:113] op_sel_hi:[0,1]
	v_pk_mul_f32 v[102:103], v[2:3], v[110:111] op_sel_hi:[0,1]
.LBB0_515:
	s_or_b64 exec, exec, s[6:7]
	v_cvt_pk_bf16_f32 v2, v102, v103
	v_cvt_pk_bf16_f32 v102, v100, v101
	s_nop 1
	v_permlane16_swap_b32_e32 v108, v102
	v_permlane16_swap_b32_e32 v109, v2
	v_ashrrev_i32_e32 v117, 31, v116
	v_lshl_add_u64 v[100:101], v[116:117], 1, v[158:159]
	v_mov_b32_e32 v110, v102
	v_mov_b32_e32 v111, v2
	s_nop 0
	flat_store_dwordx4 v[100:101], v[108:111] offset:96
.LBB0_516:
	s_andn2_saveexec_b64 s[2:3], s[2:3]
	s_cbranch_execz .LBB0_518
	v_add_u32_e32 v2, 0xffffa400, v130
	v_lshlrev_b64 v[108:109], 2, v[2:3]
	v_lshl_add_u64 v[104:105], s[26:27], 0, v[108:109]
	s_nop 0
	flat_load_dwordx4 v[104:107], v[104:105]
	s_mov_b32 s0, 0x3d800000
	v_lshl_add_u64 v[108:109], v[144:145], 0, v[108:109]
	s_waitcnt vmcnt(0) lgkmcnt(0)
	v_add_f32_e32 v2, v100, v104
	v_min_f32_e32 v100, 0, v2
	v_mul_f32_e64 v2, |v2|, s82
	v_exp_f32_e32 v2, v2
	v_add_f32_e32 v104, v101, v105
	v_add_f32_e32 v105, v102, v106
	v_add_f32_e32 v107, v103, v107
	v_add_f32_e32 v2, 1.0, v2
	v_cmp_gt_f32_e32 vcc, s83, v2
	s_nop 1
	v_cndmask_b32_e64 v101, 0, 32, vcc
	v_ldexp_f32 v2, v2, v101
	v_log_f32_e32 v2, v2
	s_nop 0
	v_mul_f32_e32 v101, 0x3f317217, v2
	v_fma_f32 v101, v2, s86, -v101
	v_fmac_f32_e32 v101, 0x3377d1cf, v2
	v_fmac_f32_e32 v101, 0x3f317217, v2
	v_cmp_lt_f32_e64 s[6:7], |v2|, s87
	s_nop 1
	v_cndmask_b32_e64 v2, v2, v101, s[6:7]
	v_cndmask_b32_e32 v101, 0, v165, vcc
	v_sub_f32_e32 v102, v2, v101
	v_mul_f32_e64 v2, |v104|, s82
	v_exp_f32_e32 v2, v2
	v_min_f32_e32 v101, 0, v104
	v_min_f32_e32 v104, 0, v105
	v_add_f32_e32 v2, 1.0, v2
	v_cmp_gt_f32_e32 vcc, s83, v2
	s_nop 1
	v_cndmask_b32_e64 v103, 0, 32, vcc
	v_ldexp_f32 v2, v2, v103
	v_log_f32_e32 v2, v2
	s_nop 0
	v_mul_f32_e32 v103, 0x3f317217, v2
	v_fma_f32 v103, v2, s86, -v103
	v_fmac_f32_e32 v103, 0x3377d1cf, v2
	v_fmac_f32_e32 v103, 0x3f317217, v2
	v_cmp_lt_f32_e64 s[6:7], |v2|, s87
	s_nop 1
	v_cndmask_b32_e64 v2, v2, v103, s[6:7]
	v_cndmask_b32_e32 v103, 0, v165, vcc
	v_sub_f32_e32 v103, v2, v103
	v_mul_f32_e64 v2, |v105|, s82
	v_exp_f32_e32 v2, v2
	v_pk_add_f32 v[100:101], v[100:101], v[102:103] neg_lo:[0,1] neg_hi:[0,1]
	v_add_f32_e32 v2, 1.0, v2
	v_cmp_gt_f32_e32 vcc, s83, v2
	v_pk_mul_f32 v[100:101], v[100:101], s[0:1] op_sel_hi:[1,0]
	s_nop 0
	v_cndmask_b32_e64 v105, 0, 32, vcc
	v_ldexp_f32 v2, v2, v105
	v_log_f32_e32 v2, v2
	s_nop 0
	v_mul_f32_e32 v105, 0x3f317217, v2
	v_fma_f32 v105, v2, s86, -v105
	v_fmac_f32_e32 v105, 0x3377d1cf, v2
	v_fmac_f32_e32 v105, 0x3f317217, v2
	v_cmp_lt_f32_e64 s[6:7], |v2|, s87
	s_nop 1
	v_cndmask_b32_e64 v2, v2, v105, s[6:7]
	v_cndmask_b32_e32 v105, 0, v165, vcc
	v_sub_f32_e32 v106, v2, v105
	v_mul_f32_e64 v2, |v107|, s82
	v_exp_f32_e32 v2, v2
	v_min_f32_e32 v105, 0, v107
	v_add_f32_e32 v2, 1.0, v2
	v_cmp_gt_f32_e32 vcc, s83, v2
	s_nop 1
	v_cndmask_b32_e64 v107, 0, 32, vcc
	v_ldexp_f32 v2, v2, v107
	v_log_f32_e32 v2, v2
	s_nop 0
	v_mul_f32_e32 v107, 0x3f317217, v2
	v_fma_f32 v107, v2, s86, -v107
	v_fmac_f32_e32 v107, 0x3377d1cf, v2
	v_fmac_f32_e32 v107, 0x3f317217, v2
	v_cmp_lt_f32_e64 s[6:7], |v2|, s87
	s_nop 1
	v_cndmask_b32_e64 v2, v2, v107, s[6:7]
	v_cndmask_b32_e32 v107, 0, v165, vcc
	v_sub_f32_e32 v107, v2, v107
	v_pk_add_f32 v[102:103], v[104:105], v[106:107] neg_lo:[0,1] neg_hi:[0,1]
	s_nop 0
	v_pk_mul_f32 v[102:103], v[102:103], s[0:1] op_sel_hi:[1,0]
	flat_store_dwordx4 v[108:109], v[100:103]

; __device__ __forceinline__ void gemm_phase(const Ctx& cx, const GemmArgs& g_, char* shm) {
;     ...
;         if (g.epi == EPI_RES && g.w != nullptr) {
;           float v2 = ssq;
;           v2 += shx(lane, v2, 16);
;           v2 += shx(lane, v2, 32);
;           if (fq == 0) __hip_atomic_fetch_add(g.f32buf + tok, v2, __ATOMIC_RELAXED, __HIP_MEMORY_SCOPE_AGENT);
;         }
.LBB0_519:
	ds_bpermute_b32 v100, v171, v2
	s_waitcnt lgkmcnt(0)
	v_add_f32_e32 v2, v2, v100
	ds_bpermute_b32 v100, v172, v2
	s_and_saveexec_b64 s[2:3], s[12:13]
	s_cbranch_execz .LBB0_521
	s_waitcnt lgkmcnt(0)
	v_add_f32_e32 v2, v2, v100
	v_lshl_add_u64 v[100:101], v[136:137], 2, s[24:25]
	s_nop 0
	flat_atomic_add_f32 v[100:101], v2

; __device__ __forceinline__ void gemm_phase(const Ctx& cx, const GemmArgs& g_, char* shm) {
;     ...
;             } else if (g.epi == EPI_RES) {
;               const float4 hv = *(const float4*)(g.hin + (size_t)tok * DM + n0);
;               const float h0 = hv.x + a[0], h1 = hv.y + a[1], h2 = hv.z + a[2], h3 = hv.w + a[3];
;               *(float4*)(g.hout + (size_t)tok * DM + n0) = make_float4(h0, h1, h2, h3);
;               if (g.w != nullptr) {
;                 const float4 nw = *(const float4*)(g.w + n0);
;                 uint2 o; o.x = pack2(h0 * nw.x, h1 * nw.y); o.y = pack2(h2 * nw.z, h3 * nw.w);
;                 EMIT_BF16(DM, o);
;                 ssq += h0 * h0 + h1 * h1 + h2 * h2 + h3 * h3;
;               }
.LBB0_532:
	v_mov_b32_e32 v126, 0
	s_and_b64 vcc, exec, s[60:61]
	s_cbranch_vccz .LBB0_537
	v_lshlrev_b64 v[110:111], 2, v[140:141]
	v_lshl_add_u64 v[100:101], v[106:107], 0, v[110:111]
	s_nop 0
	flat_load_dwordx4 v[100:103], v[100:101]
	v_lshl_add_u64 v[110:111], v[104:105], 0, v[110:111]
	s_andn2_b64 vcc, exec, s[42:43]
	s_waitcnt vmcnt(0) lgkmcnt(0)
	v_pk_add_f32 v[100:101], v[96:97], v[100:101]
	v_pk_add_f32 v[102:103], v[98:99], v[102:103]
	flat_store_dwordx4 v[110:111], v[100:103]
	s_cbranch_vccnz .LBB0_536
	v_lshl_add_u64 v[110:111], v[140:141], 2, s[30:31]
	global_load_dwordx4 v[110:113], v[110:111], off
	s_waitcnt vmcnt(0)
	v_pk_mul_f32 v[110:111], v[100:101], v[110:111]
	v_pk_mul_f32 v[100:101], v[100:101], v[100:101]
	v_pk_mul_f32 v[112:113], v[102:103], v[112:113]
	v_pk_mul_f32 v[102:103], v[102:103], v[102:103]
	v_add_f32_e32 v2, v100, v101
	v_add_f32_e32 v2, v2, v102
	v_cvt_pk_bf16_f32 v109, v112, v113
	v_cvt_pk_bf16_f32 v117, v110, v111
	v_add_f32_e32 v126, v2, v103
	s_branch .LBB0_537

; __device__ __forceinline__ float b2f(u16 b) { return __uint_as_float(((uint32_t)b) << 16); }
; __device__ __forceinline__ float sigmoidf_(float x) { return 1.0f / (1.0f + __expf(-x)); }
; __device__ __forceinline__ void gemm_phase(const Ctx& cx, const GemmArgs& g_, char* shm) {
;     ...
;             } else {
;               const uint2 gv = *(const uint2*)(g.gate + (size_t)tok * NP + n0);
;               float v0 = sigmoidf_(b2f((u16)(gv.x & 0xffff))) * a[0], v1 = sigmoidf_(b2f((u16)(gv.x >> 16))) * a[1];
;               float v2 = sigmoidf_(b2f((u16)(gv.y & 0xffff))) * a[2], v3 = sigmoidf_(b2f((u16)(gv.y >> 16))) * a[3];
;               uint2* mp = (uint2*)(g.outb + (size_t)tok * DM + n0);
;               if (g.epi != EPI_BR0) {
;                 const uint2 pv = *mp;
;                 v0 += b2f((u16)(pv.x & 0xffff)); v1 += b2f((u16)(pv.x >> 16));
;                 v2 += b2f((u16)(pv.y & 0xffff)); v3 += b2f((u16)(pv.y >> 16));
;               }
;               uint2 o; o.x = pack2(v0, v1); o.y = pack2(v2, v3);
;               *mp = o;
;             }
.LBB0_540:
	v_lshlrev_b64 v[102:103], 12, v[118:119]
	v_mov_b64_e32 v[110:111], s[22:23]
	v_lshl_add_u64 v[100:101], s[20:21], 0, v[102:103]
	s_andn2_b64 vcc, exec, s[10:11]
	v_mad_i64_i32 v[114:115], s[10:11], v118, s76, v[110:111]
	s_cbranch_vccnz .LBB0_544
	v_lshlrev_b64 v[112:113], 1, v[140:141]
	v_lshl_add_u64 v[110:111], v[114:115], 0, v[112:113]
	s_nop 0
	flat_load_dwordx2 v[124:125], v[110:111]
	v_lshl_add_u64 v[112:113], v[100:101], 0, v[112:113]
	s_waitcnt vmcnt(0) lgkmcnt(0)
	v_lshlrev_b32_e32 v2, 16, v124
	v_mul_f32_e32 v2, 0xbfb8aa3b, v2
	v_exp_f32_e32 v110, v2
	v_and_b32_e32 v2, 0xffff0000, v124
	v_mul_f32_e32 v2, 0xbfb8aa3b, v2
	v_exp_f32_e32 v111, v2
	s_nop 0
	v_pk_add_f32 v[110:111], v[110:111], 1.0 op_sel_hi:[1,0]
	s_nop 0
	v_div_scale_f32 v2, s[2:3], v111, v111, 1.0
	v_rcp_f32_e32 v109, v2
	s_nop 0
	v_fma_f32 v117, -v2, v109, 1.0
	v_fmac_f32_e32 v109, v117, v109
	v_div_scale_f32 v117, vcc, 1.0, v111, 1.0
	v_mul_f32_e32 v124, v117, v109
	v_fma_f32 v126, -v2, v124, v117
	v_fmac_f32_e32 v124, v126, v109
	v_fma_f32 v2, -v2, v124, v117
	v_div_fmas_f32 v2, v2, v109, v124
	v_div_fixup_f32 v111, v2, v111, 1.0
	v_div_scale_f32 v2, s[2:3], v110, v110, 1.0
	v_rcp_f32_e32 v109, v2
	s_nop 0
	v_fma_f32 v117, -v2, v109, 1.0
	v_fmac_f32_e32 v109, v117, v109
	v_div_scale_f32 v117, vcc, 1.0, v110, 1.0
	v_mul_f32_e32 v124, v117, v109
	v_fma_f32 v126, -v2, v124, v117
	v_fmac_f32_e32 v124, v126, v109
	v_fma_f32 v2, -v2, v124, v117
	v_div_fmas_f32 v2, v2, v109, v124
	v_div_fixup_f32 v110, v2, v110, 1.0
	v_lshlrev_b32_e32 v2, 16, v125
	v_mul_f32_e32 v2, 0xbfb8aa3b, v2
	v_exp_f32_e32 v124, v2
	v_and_b32_e32 v2, 0xffff0000, v125
	v_mul_f32_e32 v2, 0xbfb8aa3b, v2
	v_exp_f32_e32 v125, v2
	v_pk_mul_f32 v[110:111], v[96:97], v[110:111]
	v_pk_add_f32 v[124:125], v[124:125], 1.0 op_sel_hi:[1,0]
	s_nop 0
	v_div_scale_f32 v2, s[2:3], v125, v125, 1.0
	v_rcp_f32_e32 v109, v2
	s_nop 0
	v_fma_f32 v117, -v2, v109, 1.0
	v_fmac_f32_e32 v109, v117, v109
	v_div_scale_f32 v117, vcc, 1.0, v125, 1.0
	v_mul_f32_e32 v126, v117, v109
	v_fma_f32 v127, -v2, v126, v117
	v_fmac_f32_e32 v126, v127, v109
	v_fma_f32 v2, -v2, v126, v117
	v_div_fmas_f32 v2, v2, v109, v126
	v_div_fixup_f32 v125, v2, v125, 1.0
	v_div_scale_f32 v2, s[2:3], v124, v124, 1.0
	v_rcp_f32_e32 v109, v2
	s_nop 0
	v_fma_f32 v117, -v2, v109, 1.0
	v_fmac_f32_e32 v109, v117, v109
	v_div_scale_f32 v117, vcc, 1.0, v124, 1.0
	v_mul_f32_e32 v126, v117, v109
	v_fma_f32 v127, -v2, v126, v117
	v_fmac_f32_e32 v126, v127, v109
	v_fma_f32 v2, -v2, v126, v117
	v_div_fmas_f32 v2, v2, v109, v126
	v_div_fixup_f32 v124, v2, v124, 1.0
	v_pk_mul_f32 v[124:125], v[98:99], v[124:125]
	s_and_b64 vcc, exec, s[4:5]
	s_cbranch_vccnz .LBB0_543
	flat_load_dwordx2 v[126:127], v[112:113]
	s_waitcnt vmcnt(0) lgkmcnt(0)
	v_lshlrev_b32_e32 v128, 16, v126
	v_and_b32_e32 v129, 0xffff0000, v126
	v_lshlrev_b32_e32 v126, 16, v127
	v_and_b32_e32 v127, 0xffff0000, v127
	v_pk_add_f32 v[110:111], v[110:111], v[128:129]
	v_pk_add_f32 v[124:125], v[124:125], v[126:127]

; __device__ __forceinline__ void gemm_phase(const Ctx& cx, const GemmArgs& g_, char* shm) {
;     ...
;             const int n0 = brow + ai * 128 + wr * 64 + m * 16 + fq * 4;
;             f32x4 a = acc[ai][bj][m][n];
;             if (g.epi == EPI_PROJ || g.epi == EPI_RELU2) { a[0] *= rs; a[1] *= rs; a[2] *= rs; a[3] *= rs; }
;             if (g.epi == EPI_PROJ) {
;               if (n0 >= C_GLAX) {
;                 const int i = n0 - C_GLAX;
;                 const float4 b4 = *(const float4*)(g.hin + i);
;                 float xs[4] = {a[0] + b4.x, a[1] + b4.y, a[2] + b4.z, a[3] + b4.w};
; #pragma unroll
;                 for (int j = 0; j < 4; ++j)
;                   xs[j] = (fminf(xs[j], 0.f) - __logf(1.0f + __expf(-fabsf(xs[j])))) * (1.0f / 16.0f);
;                 *(float4*)(g.f32buf + (size_t)tok * 1024 + i) = make_float4(xs[0], xs[1], xs[2], xs[3]);
;               } else {
;                 float o0 = a[0], o1 = a[1], o2 = a[2], o3 = a[3];
;                 const bool r128 = (n0 >= C_DSAQ && n0 < C_HGQ) || (n0 >= C_DSAK && n0 < C_DSAV);
;                 const bool r64 = (n0 >= C_IDXQ && n0 < C_GLAA);
;                 if (r128 || r64) {
;                   float4 cs;
;                   float sc;
;                   if (r128) {
;                     cs = *(const float4*)(g.w + ((size_t)tok * 64 + ((n0 & 127) >> 1)) * 2);
;                     sc = (n0 < C_HGQ) ? 0.08838834764831845f : 1.0f;
;                   } else {
;                     cs = *(const float4*)(g.hout + ((size_t)tok * 32 + ((n0 & 63) >> 1)) * 2);
;                     sc = (n0 < C_IDXK) ? 0.125f : 1.0f;
;                   }
;                   o0 = (a[0] * cs.x - a[1] * cs.y) * sc; o1 = (a[1] * cs.x + a[0] * cs.y) * sc;
;                   o2 = (a[2] * cs.z - a[3] * cs.w) * sc; o3 = (a[3] * cs.z + a[2] * cs.w) * sc;
;                 }
.LBB0_544:
	s_movk_i32 s0, 0xe100
	v_lshlrev_b64 v[110:111], 9, v[118:119]
	v_mad_i64_i32 v[112:113], s[10:11], v118, s0, v[104:105]
	v_lshl_add_u64 v[110:111], s[30:31], 0, v[110:111]
	v_lshl_add_u64 v[102:103], s[24:25], 0, v[102:103]
	s_and_b64 vcc, exec, s[2:3]
	s_cbranch_vccz .LBB0_556
	s_movk_i32 s0, 0x5c00
	v_cmp_gt_i32_e32 vcc, s0, v140
	s_and_saveexec_b64 s[2:3], vcc
	s_xor_b64 s[2:3], exec, s[2:3]
	s_cbranch_execz .LBB0_553
	v_add_u32_e32 v2, 0xffffa700, v138
	v_cmp_gt_u32_e32 vcc, s77, v2
	s_or_b64 s[60:61], s[58:59], vcc
	s_and_saveexec_b64 s[10:11], s[60:61]
	s_cbranch_execz .LBB0_552
	s_and_saveexec_b64 s[60:61], s[56:57]
	s_xor_b64 s[60:61], exec, s[60:61]
	s_movk_i32 s0, 0x5b00
	v_lshlrev_b32_e32 v2, 2, v0
	v_cmp_gt_u32_e32 vcc, s0, v138
	v_lshl_add_u64 v[124:125], v[112:113], 0, v[2:3]
	s_nop 0
	v_cndmask_b32_e32 v2, 1.0, v166, vcc
	s_andn2_saveexec_b64 s[60:61], s[60:61]
	v_and_b32_e32 v2, 0x4c, v140
	v_lshlrev_b32_e32 v2, 2, v2
	v_cmp_gt_i32_e32 vcc, s81, v140
	v_lshl_add_u64 v[124:125], v[110:111], 0, v[2:3]
	s_nop 0
	v_cndmask_b32_e32 v2, 1.0, v167, vcc
	s_or_b64 exec, exec, s[60:61]
	s_nop 0
	flat_load_dwordx4 v[124:127], v[124:125]
	s_waitcnt vmcnt(0) lgkmcnt(0)
	v_pk_mul_f32 v[128:129], v[96:97], v[124:125] op_sel:[1,1] op_sel_hi:[1,0]
	s_nop 0
	v_pk_fma_f32 v[134:135], v[96:97], v[124:125], v[128:129] neg_lo:[0,0,1] neg_hi:[0,0,1]
	v_pk_fma_f32 v[96:97], v[96:97], v[124:125], v[128:129] op_sel_hi:[0,1,1]
	v_mov_b32_e32 v124, v99
	v_pk_mul_f32 v[124:125], v[124:125], v[126:127] op_sel:[0,1] op_sel_hi:[0,0]
	v_pk_fma_f32 v[128:129], v[98:99], v[126:127], v[124:125] neg_lo:[0,0,1] neg_hi:[0,0,1]
	v_pk_fma_f32 v[98:99], v[98:99], v[126:127], v[124:125] op_sel_hi:[0,1,1]
	v_mov_b32_e32 v135, v97
	v_mov_b32_e32 v129, v99
	v_pk_mul_f32 v[96:97], v[2:3], v[134:135] op_sel_hi:[0,1]
	v_pk_mul_f32 v[98:99], v[2:3], v[128:129] op_sel_hi:[0,1]

; __device__ __forceinline__ void gemm_phase(const Ctx& cx, const GemmArgs& g_, char* shm) {
;     ...
;               if (n0 >= C_GLAX) {
;                 const int i = n0 - C_GLAX;
;                 const float4 b4 = *(const float4*)(g.hin + i);
;                 float xs[4] = {a[0] + b4.x, a[1] + b4.y, a[2] + b4.z, a[3] + b4.w};
; #pragma unroll
;                 for (int j = 0; j < 4; ++j)
;                   xs[j] = (fminf(xs[j], 0.f) - __logf(1.0f + __expf(-fabsf(xs[j])))) * (1.0f / 16.0f);
;                 *(float4*)(g.f32buf + (size_t)tok * 1024 + i) = make_float4(xs[0], xs[1], xs[2], xs[3]);
.LBB0_553:
	s_andn2_saveexec_b64 s[2:3], s[2:3]
	s_cbranch_execz .LBB0_555
	v_add_u32_e32 v2, 0xffffa400, v140
	v_lshlrev_b64 v[128:129], 2, v[2:3]
	v_lshl_add_u64 v[124:125], s[26:27], 0, v[128:129]
	s_nop 0
	flat_load_dwordx4 v[124:127], v[124:125]
	s_mov_b32 s0, 0x3d800000
	v_mov_b32_e32 v109, 0
	v_lshl_add_u64 v[128:129], v[102:103], 0, v[128:129]
	s_waitcnt vmcnt(0) lgkmcnt(0)
	v_add_f32_e32 v2, v96, v124
	v_min_f32_e32 v96, 0, v2
	v_mul_f32_e64 v2, |v2|, s82
	v_exp_f32_e32 v2, v2
	v_add_f32_e32 v117, v97, v125
	v_add_f32_e32 v119, v98, v126
	v_add_f32_e32 v127, v99, v127
	v_add_f32_e32 v2, 1.0, v2
	v_cmp_gt_f32_e32 vcc, s83, v2
	v_min_f32_e32 v124, 0, v119
	v_min_f32_e32 v125, 0, v127
	v_cndmask_b32_e64 v97, 0, 32, vcc
	v_ldexp_f32 v2, v2, v97
	v_log_f32_e32 v2, v2
	s_nop 0
	v_mul_f32_e32 v97, 0x3f317217, v2
	v_fma_f32 v97, v2, s86, -v97
	v_fmac_f32_e32 v97, 0x3377d1cf, v2
	v_fmac_f32_e32 v97, 0x3f317217, v2
	v_cmp_lt_f32_e64 s[10:11], |v2|, s87
	s_nop 1
	v_cndmask_b32_e64 v2, v2, v97, s[10:11]
	v_cndmask_b32_e32 v97, 0, v165, vcc
	v_sub_f32_e32 v98, v2, v97
	v_mul_f32_e64 v2, |v117|, s82
	v_exp_f32_e32 v2, v2
	v_min_f32_e32 v97, 0, v117
	v_add_f32_e32 v2, 1.0, v2
	v_cmp_gt_f32_e32 vcc, s83, v2
	s_nop 1
	v_cndmask_b32_e64 v99, 0, 32, vcc
	v_ldexp_f32 v2, v2, v99
	v_log_f32_e32 v2, v2
	s_nop 0
	v_mul_f32_e32 v99, 0x3f317217, v2
	v_fma_f32 v99, v2, s86, -v99
	v_fmac_f32_e32 v99, 0x3377d1cf, v2
	v_fmac_f32_e32 v99, 0x3f317217, v2
	v_cmp_lt_f32_e64 s[10:11], |v2|, s87
	s_nop 1
	v_cndmask_b32_e64 v2, v2, v99, s[10:11]
	v_cndmask_b32_e32 v99, 0, v165, vcc
	v_sub_f32_e32 v99, v2, v99
	v_mul_f32_e64 v2, |v119|, s82
	v_exp_f32_e32 v2, v2
	v_pk_add_f32 v[96:97], v[96:97], v[98:99] neg_lo:[0,1] neg_hi:[0,1]
	v_add_f32_e32 v2, 1.0, v2
	v_cmp_gt_f32_e32 vcc, s83, v2
	v_pk_mul_f32 v[96:97], v[96:97], s[0:1] op_sel_hi:[1,0]
	s_nop 0
	v_cndmask_b32_e64 v117, 0, 32, vcc
	v_ldexp_f32 v2, v2, v117
	v_log_f32_e32 v2, v2
	s_nop 0
	v_mul_f32_e32 v117, 0x3f317217, v2
	v_fma_f32 v117, v2, s86, -v117
	v_fmac_f32_e32 v117, 0x3377d1cf, v2
	v_fmac_f32_e32 v117, 0x3f317217, v2
	v_cmp_lt_f32_e64 s[10:11], |v2|, s87
	s_nop 1
	v_cndmask_b32_e64 v2, v2, v117, s[10:11]
	v_cndmask_b32_e32 v117, 0, v165, vcc
	v_sub_f32_e32 v126, v2, v117
	v_mul_f32_e64 v2, |v127|, s82
	v_exp_f32_e32 v2, v2
	s_nop 0
	v_add_f32_e32 v2, 1.0, v2
	v_cmp_gt_f32_e32 vcc, s83, v2
	s_nop 1
	v_cndmask_b32_e64 v117, 0, 32, vcc
	v_ldexp_f32 v2, v2, v117
	v_log_f32_e32 v2, v2
	s_nop 0
	v_mul_f32_e32 v117, 0x3f317217, v2
	v_fma_f32 v117, v2, s86, -v117
	v_fmac_f32_e32 v117, 0x3377d1cf, v2
	v_fmac_f32_e32 v117, 0x3f317217, v2
	v_cmp_lt_f32_e64 s[10:11], |v2|, s87
	s_nop 1
	v_cndmask_b32_e64 v2, v2, v117, s[10:11]
	v_cndmask_b32_e32 v117, 0, v165, vcc
	v_sub_f32_e32 v127, v2, v117
	v_pk_add_f32 v[98:99], v[124:125], v[126:127] neg_lo:[0,1] neg_hi:[0,1]
	v_mov_b32_e32 v117, 0
	v_pk_mul_f32 v[98:99], v[98:99], s[0:1] op_sel_hi:[1,0]
	flat_store_dwordx4 v[128:129], v[96:99]

; __device__ __forceinline__ void gemm_phase(const Ctx& cx, const GemmArgs& g_, char* shm) {
;     ...
;             } else if (g.epi == EPI_RELU2) {
;               float r0 = fmaxf(a[0], 0.f), r1 = fmaxf(a[1], 0.f), r2 = fmaxf(a[2], 0.f), r3 = fmaxf(a[3], 0.f);
;               uint2 o; o.x = pack2(r0 * r0, r1 * r1); o.y = pack2(r2 * r2, r3 * r3);
;               EMIT_BF16(g.ldo, o);
.LBB0_568:
	s_cmp_gt_i32 s38, 4
	s_cbranch_scc0 .LBB0_572
	s_cmp_eq_u32 s38, 5
	s_mov_b64 s[10:11], -1
	s_cbranch_scc0 .LBB0_571
	v_max_f32_e32 v2, v94, v94
	v_max_f32_e32 v96, 0, v2
	v_max_f32_e32 v2, v95, v95
	v_max_f32_e32 v97, 0, v2
	v_pk_mul_f32 v[96:97], v[96:97], v[96:97]
	v_max_f32_e32 v2, v92, v92
	v_cvt_pk_bf16_f32 v99, v96, v97
	v_max_f32_e32 v96, 0, v2
	v_max_f32_e32 v2, v93, v93
	v_max_f32_e32 v97, 0, v2
	v_pk_mul_f32 v[96:97], v[96:97], v[96:97]
	v_ashrrev_i32_e32 v133, 31, v132
	v_cvt_pk_bf16_f32 v98, v96, v97
	v_mov_b32_e32 v96, v117
	v_mov_b32_e32 v97, v109
	s_nop 0
	v_permlane16_swap_b32_e32 v96, v98
	v_permlane16_swap_b32_e32 v97, v99
	v_lshl_add_u64 v[124:125], v[132:133], 1, v[118:119]
	s_nop 0
	flat_store_dwordx4 v[124:125], v[96:99] offset:32
	s_mov_b64 s[10:11], 0

; __device__ __forceinline__ void gemm_phase(const Ctx& cx, const GemmArgs& g_, char* shm) {
;     ...
;             } else if (g.epi == EPI_RES) {
;               const float4 hv = *(const float4*)(g.hin + (size_t)tok * DM + n0);
;               const float h0 = hv.x + a[0], h1 = hv.y + a[1], h2 = hv.z + a[2], h3 = hv.w + a[3];
;               *(float4*)(g.hout + (size_t)tok * DM + n0) = make_float4(h0, h1, h2, h3);
;               if (g.w != nullptr) {
;                 const float4 nw = *(const float4*)(g.w + n0);
;                 uint2 o; o.x = pack2(h0 * nw.x, h1 * nw.y); o.y = pack2(h2 * nw.z, h3 * nw.w);
;                 EMIT_BF16(DM, o);
;                 ssq += h0 * h0 + h1 * h1 + h2 * h2 + h3 * h3;
;               }
.LBB0_572:
	s_and_b64 vcc, exec, s[60:61]
	v_mov_b32_e32 v127, v126
	s_cbranch_vccz .LBB0_575
	v_lshl_add_u64 v[124:125], v[138:139], 0, v[0:1]
	v_lshlrev_b64 v[128:129], 2, v[124:125]
	v_lshl_add_u64 v[96:97], v[106:107], 0, v[128:129]
	s_nop 0
	flat_load_dwordx4 v[96:99], v[96:97] offset:64
	v_lshl_add_u64 v[128:129], v[104:105], 0, v[128:129]
	s_andn2_b64 vcc, exec, s[42:43]
	v_mov_b32_e32 v127, v126
	s_waitcnt vmcnt(0) lgkmcnt(0)
	v_pk_add_f32 v[96:97], v[92:93], v[96:97]
	v_pk_add_f32 v[98:99], v[94:95], v[98:99]
	flat_store_dwordx4 v[128:129], v[96:99] offset:64
	s_cbranch_vccnz .LBB0_575
	v_lshl_add_u64 v[124:125], v[124:125], 2, s[30:31]
	global_load_dwordx4 v[144:147], v[124:125], off offset:64
	v_ashrrev_i32_e32 v133, 31, v132
	s_waitcnt vmcnt(0)
	v_pk_mul_f32 v[124:125], v[98:99], v[146:147]
	s_nop 0
	v_cvt_pk_bf16_f32 v147, v124, v125
	v_pk_mul_f32 v[124:125], v[96:97], v[144:145]
	v_pk_mul_f32 v[96:97], v[96:97], v[96:97]
	v_pk_mul_f32 v[98:99], v[98:99], v[98:99]
	v_add_f32_e32 v2, v96, v97
	v_cvt_pk_bf16_f32 v146, v124, v125
	v_mov_b32_e32 v144, v117
	v_mov_b32_e32 v145, v109
	v_add_f32_e32 v2, v2, v98
	v_permlane16_swap_b32_e32 v144, v146
	v_permlane16_swap_b32_e32 v145, v147
	v_lshl_add_u64 v[124:125], v[132:133], 1, v[100:101]
	v_add_f32_e32 v2, v2, v99
	flat_store_dwordx4 v[124:125], v[144:147] offset:32
	v_add_f32_e32 v127, v126, v2

; __device__ __forceinline__ float b2f(u16 b) { return __uint_as_float(((uint32_t)b) << 16); }
; __device__ __forceinline__ float sigmoidf_(float x) { return 1.0f / (1.0f + __expf(-x)); }
; __device__ __forceinline__ void gemm_phase(const Ctx& cx, const GemmArgs& g_, char* shm) {
;     ...
;               const uint2 gv = *(const uint2*)(g.gate + (size_t)tok * NP + n0);
;               float v0 = sigmoidf_(b2f((u16)(gv.x & 0xffff))) * a[0], v1 = sigmoidf_(b2f((u16)(gv.x >> 16))) * a[1];
;               float v2 = sigmoidf_(b2f((u16)(gv.y & 0xffff))) * a[2], v3 = sigmoidf_(b2f((u16)(gv.y >> 16))) * a[3];
;               uint2* mp = (uint2*)(g.outb + (size_t)tok * DM + n0);
;               if (g.epi != EPI_BR0) {
;                 const uint2 pv = *mp;
;                 v0 += b2f((u16)(pv.x & 0xffff)); v1 += b2f((u16)(pv.x >> 16));
;                 v2 += b2f((u16)(pv.y & 0xffff)); v3 += b2f((u16)(pv.y >> 16));
;               }
.LBB0_577:
	v_lshl_add_u64 v[96:97], v[138:139], 0, v[0:1]
	v_lshlrev_b64 v[98:99], 1, v[96:97]
	v_lshl_add_u64 v[96:97], v[114:115], 0, v[98:99]
	s_nop 0
	flat_load_dwordx2 v[124:125], v[96:97] offset:32
	v_lshl_add_u64 v[98:99], v[100:101], 0, v[98:99]
	s_waitcnt vmcnt(0) lgkmcnt(0)
	v_lshlrev_b32_e32 v2, 16, v124
	v_mul_f32_e32 v2, 0xbfb8aa3b, v2
	v_exp_f32_e32 v96, v2
	v_and_b32_e32 v2, 0xffff0000, v124
	v_mul_f32_e32 v2, 0xbfb8aa3b, v2
	v_exp_f32_e32 v97, v2
	s_nop 0
	v_pk_add_f32 v[96:97], v[96:97], 1.0 op_sel_hi:[1,0]
	s_nop 0
	v_div_scale_f32 v2, s[2:3], v97, v97, 1.0
	v_rcp_f32_e32 v124, v2
	s_nop 0
	v_fma_f32 v127, -v2, v124, 1.0
	v_fmac_f32_e32 v124, v127, v124
	v_div_scale_f32 v127, vcc, 1.0, v97, 1.0
	v_mul_f32_e32 v128, v127, v124
	v_fma_f32 v129, -v2, v128, v127
	v_fmac_f32_e32 v128, v129, v124
	v_fma_f32 v2, -v2, v128, v127
	v_div_fmas_f32 v2, v2, v124, v128
	v_div_fixup_f32 v97, v2, v97, 1.0
	v_div_scale_f32 v2, s[2:3], v96, v96, 1.0
	v_rcp_f32_e32 v124, v2
	s_nop 0
	v_fma_f32 v127, -v2, v124, 1.0
	v_fmac_f32_e32 v124, v127, v124
	v_div_scale_f32 v127, vcc, 1.0, v96, 1.0
	v_mul_f32_e32 v128, v127, v124
	v_fma_f32 v129, -v2, v128, v127
	v_fmac_f32_e32 v128, v129, v124
	v_fma_f32 v2, -v2, v128, v127
	v_div_fmas_f32 v2, v2, v124, v128
	v_div_fixup_f32 v96, v2, v96, 1.0
	v_lshlrev_b32_e32 v2, 16, v125
	v_mul_f32_e32 v2, 0xbfb8aa3b, v2
	v_exp_f32_e32 v124, v2
	v_and_b32_e32 v2, 0xffff0000, v125
	v_mul_f32_e32 v2, 0xbfb8aa3b, v2
	v_exp_f32_e32 v125, v2
	v_pk_mul_f32 v[96:97], v[92:93], v[96:97]
	v_pk_add_f32 v[124:125], v[124:125], 1.0 op_sel_hi:[1,0]
	s_nop 0
	v_div_scale_f32 v2, s[2:3], v125, v125, 1.0
	v_rcp_f32_e32 v127, v2
	s_nop 0
	v_fma_f32 v128, -v2, v127, 1.0
	v_fmac_f32_e32 v127, v128, v127
	v_div_scale_f32 v128, vcc, 1.0, v125, 1.0
	v_mul_f32_e32 v129, v128, v127
	v_fma_f32 v133, -v2, v129, v128
	v_fmac_f32_e32 v129, v133, v127
	v_fma_f32 v2, -v2, v129, v128
	v_div_fmas_f32 v2, v2, v127, v129
	v_div_fixup_f32 v125, v2, v125, 1.0
	v_div_scale_f32 v2, s[2:3], v124, v124, 1.0
	v_rcp_f32_e32 v127, v2
	s_nop 0
	v_fma_f32 v128, -v2, v127, 1.0
	v_fmac_f32_e32 v127, v128, v127
	v_div_scale_f32 v128, vcc, 1.0, v124, 1.0
	v_mul_f32_e32 v129, v128, v127
	v_fma_f32 v133, -v2, v129, v128
	v_fmac_f32_e32 v129, v133, v127
	v_fma_f32 v2, -v2, v129, v128
	v_div_fmas_f32 v2, v2, v127, v129
	v_div_fixup_f32 v124, v2, v124, 1.0
	v_pk_mul_f32 v[124:125], v[94:95], v[124:125]
	s_and_b64 vcc, exec, s[4:5]
	s_cbranch_vccnz .LBB0_579
	flat_load_dwordx2 v[128:129], v[98:99] offset:32
	s_waitcnt vmcnt(0) lgkmcnt(0)
	v_lshlrev_b32_e32 v134, 16, v128
	v_and_b32_e32 v135, 0xffff0000, v128
	v_lshlrev_b32_e32 v128, 16, v129
	v_and_b32_e32 v129, 0xffff0000, v129
	v_pk_add_f32 v[96:97], v[96:97], v[134:135]
	v_pk_add_f32 v[124:125], v[124:125], v[128:129]

; __device__ __forceinline__ void gemm_phase(const Ctx& cx, const GemmArgs& g_, char* shm) {
;     ...
;             const int n0 = brow + ai * 128 + wr * 64 + m * 16 + fq * 4;
;             f32x4 a = acc[ai][bj][m][n];
;             if (g.epi == EPI_PROJ || g.epi == EPI_RELU2) { a[0] *= rs; a[1] *= rs; a[2] *= rs; a[3] *= rs; }
;             if (g.epi == EPI_PROJ) {
;               if (n0 >= C_GLAX) {
;                 const int i = n0 - C_GLAX;
;                 const float4 b4 = *(const float4*)(g.hin + i);
;                 float xs[4] = {a[0] + b4.x, a[1] + b4.y, a[2] + b4.z, a[3] + b4.w};
; #pragma unroll
;                 for (int j = 0; j < 4; ++j)
;                   xs[j] = (fminf(xs[j], 0.f) - __logf(1.0f + __expf(-fabsf(xs[j])))) * (1.0f / 16.0f);
;                 *(float4*)(g.f32buf + (size_t)tok * 1024 + i) = make_float4(xs[0], xs[1], xs[2], xs[3]);
;               } else {
;                 float o0 = a[0], o1 = a[1], o2 = a[2], o3 = a[3];
;                 const bool r128 = (n0 >= C_DSAQ && n0 < C_HGQ) || (n0 >= C_DSAK && n0 < C_DSAV);
;                 const bool r64 = (n0 >= C_IDXQ && n0 < C_GLAA);
;                 if (r128 || r64) {
;                   float4 cs;
;                   float sc;
;                   if (r128) {
;                     cs = *(const float4*)(g.w + ((size_t)tok * 64 + ((n0 & 127) >> 1)) * 2);
;                     sc = (n0 < C_HGQ) ? 0.08838834764831845f : 1.0f;
;                   } else {
;                     cs = *(const float4*)(g.hout + ((size_t)tok * 32 + ((n0 & 63) >> 1)) * 2);
;                     sc = (n0 < C_IDXK) ? 0.125f : 1.0f;
;                   }
;                   o0 = (a[0] * cs.x - a[1] * cs.y) * sc; o1 = (a[1] * cs.x + a[0] * cs.y) * sc;
;                   o2 = (a[2] * cs.z - a[3] * cs.w) * sc; o3 = (a[3] * cs.z + a[2] * cs.w) * sc;
;                 }
;                 uint2 o; o.x = pack2(o0, o1); o.y = pack2(o2, o3);
;                 EMIT_BF16(g.ldo, o);
.LBB0_580:
	s_movk_i32 s0, 0x5c00
	v_cmp_gt_i32_e32 vcc, s0, v177
	s_and_saveexec_b64 s[2:3], vcc
	s_xor_b64 s[2:3], exec, s[2:3]
	s_cbranch_execz .LBB0_588
	v_add_u32_e32 v2, 0xffffa700, v138
	v_cmp_gt_u32_e32 vcc, s77, v2
	s_or_b64 s[60:61], s[58:59], vcc
	s_and_saveexec_b64 s[10:11], s[60:61]
	s_cbranch_execz .LBB0_587
	s_and_saveexec_b64 s[60:61], s[56:57]
	s_xor_b64 s[60:61], exec, s[60:61]
	v_lshlrev_b32_e32 v2, 2, v0
	s_movk_i32 s0, 0x5b00
	v_lshl_add_u64 v[96:97], v[112:113], 0, v[2:3]
	v_cmp_gt_u32_e32 vcc, s0, v138
	v_lshl_add_u64 v[96:97], v[96:97], 0, 64
	s_nop 0
	v_cndmask_b32_e32 v2, 1.0, v166, vcc
	s_andn2_saveexec_b64 s[60:61], s[60:61]
	v_and_b32_e32 v2, 0x5c, v177
	v_lshlrev_b32_e32 v2, 2, v2
	v_cmp_gt_i32_e32 vcc, s81, v177
	v_lshl_add_u64 v[96:97], v[110:111], 0, v[2:3]
	s_nop 0
	v_cndmask_b32_e32 v2, 1.0, v167, vcc
	s_or_b64 exec, exec, s[60:61]
	s_nop 0
	flat_load_dwordx4 v[96:99], v[96:97]
	s_waitcnt vmcnt(0) lgkmcnt(0)
	v_pk_mul_f32 v[124:125], v[92:93], v[96:97] op_sel:[1,1] op_sel_hi:[1,0]
	s_nop 0
	v_pk_fma_f32 v[128:129], v[92:93], v[96:97], v[124:125] neg_lo:[0,0,1] neg_hi:[0,0,1]
	v_pk_fma_f32 v[92:93], v[92:93], v[96:97], v[124:125] op_sel_hi:[0,1,1]
	v_mov_b32_e32 v96, v95
	v_pk_mul_f32 v[96:97], v[96:97], v[98:99] op_sel:[0,1] op_sel_hi:[0,0]
	v_pk_fma_f32 v[124:125], v[94:95], v[98:99], v[96:97] neg_lo:[0,0,1] neg_hi:[0,0,1]
	v_pk_fma_f32 v[94:95], v[94:95], v[98:99], v[96:97] op_sel_hi:[0,1,1]
	v_mov_b32_e32 v129, v93
	v_mov_b32_e32 v125, v95
	v_pk_mul_f32 v[92:93], v[2:3], v[128:129] op_sel_hi:[0,1]
	v_pk_mul_f32 v[94:95], v[2:3], v[124:125] op_sel_hi:[0,1]
.LBB0_587:
	s_or_b64 exec, exec, s[10:11]
	v_cvt_pk_bf16_f32 v95, v94, v95
	v_cvt_pk_bf16_f32 v94, v92, v93
	v_mov_b32_e32 v92, v117
	v_mov_b32_e32 v93, v109
	v_ashrrev_i32_e32 v133, 31, v132
	v_permlane16_swap_b32_e32 v92, v94
	v_permlane16_swap_b32_e32 v93, v95
	v_lshl_add_u64 v[96:97], v[132:133], 1, v[118:119]
	s_nop 0
	flat_store_dwordx4 v[96:97], v[92:95] offset:32
.LBB0_588:
	s_andn2_saveexec_b64 s[2:3], s[2:3]
	s_cbranch_execz .LBB0_590
	v_add_u32_e32 v2, 0xffffa400, v177
	v_lshlrev_b64 v[124:125], 2, v[2:3]
	v_lshl_add_u64 v[96:97], s[26:27], 0, v[124:125]
	s_nop 0
	flat_load_dwordx4 v[96:99], v[96:97]
	s_mov_b32 s0, 0x3d800000
	v_lshl_add_u64 v[124:125], v[102:103], 0, v[124:125]
	s_waitcnt vmcnt(0) lgkmcnt(0)
	v_add_f32_e32 v2, v92, v96
	v_min_f32_e32 v92, 0, v2
	v_mul_f32_e64 v2, |v2|, s82
	v_exp_f32_e32 v2, v2
	v_add_f32_e32 v96, v93, v97
	v_add_f32_e32 v97, v94, v98
	v_add_f32_e32 v99, v95, v99
	v_add_f32_e32 v2, 1.0, v2
	v_cmp_gt_f32_e32 vcc, s83, v2
	s_nop 1
	v_cndmask_b32_e64 v93, 0, 32, vcc
	v_ldexp_f32 v2, v2, v93
	v_log_f32_e32 v2, v2
	s_nop 0
	v_mul_f32_e32 v93, 0x3f317217, v2
	v_fma_f32 v93, v2, s86, -v93
	v_fmac_f32_e32 v93, 0x3377d1cf, v2
	v_fmac_f32_e32 v93, 0x3f317217, v2
	v_cmp_lt_f32_e64 s[10:11], |v2|, s87
	s_nop 1
	v_cndmask_b32_e64 v2, v2, v93, s[10:11]
	v_cndmask_b32_e32 v93, 0, v165, vcc
	v_sub_f32_e32 v94, v2, v93
	v_mul_f32_e64 v2, |v96|, s82
	v_exp_f32_e32 v2, v2
	v_min_f32_e32 v93, 0, v96
	v_min_f32_e32 v96, 0, v97
	v_add_f32_e32 v2, 1.0, v2
	v_cmp_gt_f32_e32 vcc, s83, v2
	s_nop 1
	v_cndmask_b32_e64 v95, 0, 32, vcc
	v_ldexp_f32 v2, v2, v95
	v_log_f32_e32 v2, v2
	s_nop 0
	v_mul_f32_e32 v95, 0x3f317217, v2
	v_fma_f32 v95, v2, s86, -v95
	v_fmac_f32_e32 v95, 0x3377d1cf, v2
	v_fmac_f32_e32 v95, 0x3f317217, v2
	v_cmp_lt_f32_e64 s[10:11], |v2|, s87
	s_nop 1
	v_cndmask_b32_e64 v2, v2, v95, s[10:11]
	v_cndmask_b32_e32 v95, 0, v165, vcc
	v_sub_f32_e32 v95, v2, v95
	v_mul_f32_e64 v2, |v97|, s82
	v_exp_f32_e32 v2, v2
	v_pk_add_f32 v[92:93], v[92:93], v[94:95] neg_lo:[0,1] neg_hi:[0,1]
	v_add_f32_e32 v2, 1.0, v2
	v_cmp_gt_f32_e32 vcc, s83, v2
	v_pk_mul_f32 v[92:93], v[92:93], s[0:1] op_sel_hi:[1,0]
	s_nop 0
	v_cndmask_b32_e64 v97, 0, 32, vcc
	v_ldexp_f32 v2, v2, v97
	v_log_f32_e32 v2, v2
	s_nop 0
	v_mul_f32_e32 v97, 0x3f317217, v2
	v_fma_f32 v97, v2, s86, -v97
	v_fmac_f32_e32 v97, 0x3377d1cf, v2
	v_fmac_f32_e32 v97, 0x3f317217, v2
	v_cmp_lt_f32_e64 s[10:11], |v2|, s87
	s_nop 1
	v_cndmask_b32_e64 v2, v2, v97, s[10:11]
	v_cndmask_b32_e32 v97, 0, v165, vcc
	v_sub_f32_e32 v98, v2, v97
	v_mul_f32_e64 v2, |v99|, s82
	v_exp_f32_e32 v2, v2
	v_min_f32_e32 v97, 0, v99
	v_add_f32_e32 v2, 1.0, v2
	v_cmp_gt_f32_e32 vcc, s83, v2
	s_nop 1
	v_cndmask_b32_e64 v99, 0, 32, vcc
	v_ldexp_f32 v2, v2, v99
	v_log_f32_e32 v2, v2
	s_nop 0
	v_mul_f32_e32 v99, 0x3f317217, v2
	v_fma_f32 v99, v2, s86, -v99
	v_fmac_f32_e32 v99, 0x3377d1cf, v2
	v_fmac_f32_e32 v99, 0x3f317217, v2
	v_cmp_lt_f32_e64 s[10:11], |v2|, s87
	s_nop 1
	v_cndmask_b32_e64 v2, v2, v99, s[10:11]
	v_cndmask_b32_e32 v99, 0, v165, vcc
	v_sub_f32_e32 v99, v2, v99
	v_pk_add_f32 v[94:95], v[96:97], v[98:99] neg_lo:[0,1] neg_hi:[0,1]
	s_nop 0
	v_pk_mul_f32 v[94:95], v[94:95], s[0:1] op_sel_hi:[1,0]
	flat_store_dwordx4 v[124:125], v[92:95]

; __device__ __forceinline__ void gemm_phase(const Ctx& cx, const GemmArgs& g_, char* shm) {
;     ...
;             } else if (g.epi == EPI_RES) {
;               const float4 hv = *(const float4*)(g.hin + (size_t)tok * DM + n0);
;               const float h0 = hv.x + a[0], h1 = hv.y + a[1], h2 = hv.z + a[2], h3 = hv.w + a[3];
;               *(float4*)(g.hout + (size_t)tok * DM + n0) = make_float4(h0, h1, h2, h3);
;               if (g.w != nullptr) {
;                 const float4 nw = *(const float4*)(g.w + n0);
;                 uint2 o; o.x = pack2(h0 * nw.x, h1 * nw.y); o.y = pack2(h2 * nw.z, h3 * nw.w);
;                 EMIT_BF16(DM, o);
;                 ssq += h0 * h0 + h1 * h1 + h2 * h2 + h3 * h3;
;               }
.LBB0_605:
	s_and_b64 vcc, exec, s[60:61]
	v_mov_b32_e32 v124, v127
	s_cbranch_vccz .LBB0_608
	v_lshl_add_u64 v[98:99], v[138:139], 0, v[0:1]
	v_lshlrev_b64 v[92:93], 2, v[98:99]
	v_lshl_add_u64 v[94:95], v[106:107], 0, v[92:93]
	s_nop 0
	flat_load_dwordx4 v[94:97], v[94:95] offset:128
	v_lshl_add_u64 v[92:93], v[104:105], 0, v[92:93]
	s_andn2_b64 vcc, exec, s[42:43]
	v_mov_b32_e32 v124, v127
	s_waitcnt vmcnt(0) lgkmcnt(0)
	v_pk_add_f32 v[94:95], v[88:89], v[94:95]
	v_pk_add_f32 v[96:97], v[90:91], v[96:97]
	flat_store_dwordx4 v[92:93], v[94:97] offset:128
	v_mov_b32_e32 v93, v109
	v_mov_b32_e32 v92, v117
	s_cbranch_vccnz .LBB0_608
	v_lshl_add_u64 v[92:93], v[98:99], 2, s[30:31]
	global_load_dwordx4 v[144:147], v[92:93], off offset:128
	v_pk_mul_f32 v[92:93], v[94:95], v[94:95]
	v_pk_mul_f32 v[98:99], v[96:97], v[96:97]
	v_add_f32_e32 v2, v92, v93
	v_add_f32_e32 v2, v2, v98
	v_add_f32_e32 v2, v2, v99
	v_add_f32_e32 v124, v127, v2
	s_waitcnt vmcnt(0)
	v_pk_mul_f32 v[92:93], v[96:97], v[146:147]
	v_pk_mul_f32 v[94:95], v[94:95], v[144:145]
	v_cvt_pk_bf16_f32 v93, v92, v93
	v_cvt_pk_bf16_f32 v92, v94, v95

; __device__ __forceinline__ float b2f(u16 b) { return __uint_as_float(((uint32_t)b) << 16); }
; __device__ __forceinline__ float sigmoidf_(float x) { return 1.0f / (1.0f + __expf(-x)); }
; __device__ __forceinline__ void gemm_phase(const Ctx& cx, const GemmArgs& g_, char* shm) {
;     ...
;               const uint2 gv = *(const uint2*)(g.gate + (size_t)tok * NP + n0);
;               float v0 = sigmoidf_(b2f((u16)(gv.x & 0xffff))) * a[0], v1 = sigmoidf_(b2f((u16)(gv.x >> 16))) * a[1];
;               float v2 = sigmoidf_(b2f((u16)(gv.y & 0xffff))) * a[2], v3 = sigmoidf_(b2f((u16)(gv.y >> 16))) * a[3];
;               uint2* mp = (uint2*)(g.outb + (size_t)tok * DM + n0);
;               if (g.epi != EPI_BR0) {
;                 const uint2 pv = *mp;
;                 v0 += b2f((u16)(pv.x & 0xffff)); v1 += b2f((u16)(pv.x >> 16));
;                 v2 += b2f((u16)(pv.y & 0xffff)); v3 += b2f((u16)(pv.y >> 16));
;               }
.LBB0_610:
	v_lshl_add_u64 v[92:93], v[138:139], 0, v[0:1]
	v_lshlrev_b64 v[94:95], 1, v[92:93]
	v_lshl_add_u64 v[92:93], v[114:115], 0, v[94:95]
	s_nop 0
	flat_load_dwordx2 v[96:97], v[92:93] offset:64
	v_lshl_add_u64 v[94:95], v[100:101], 0, v[94:95]
	s_waitcnt vmcnt(0) lgkmcnt(0)
	v_lshlrev_b32_e32 v2, 16, v96
	v_mul_f32_e32 v2, 0xbfb8aa3b, v2
	v_exp_f32_e32 v92, v2
	v_and_b32_e32 v2, 0xffff0000, v96
	v_mul_f32_e32 v2, 0xbfb8aa3b, v2
	v_exp_f32_e32 v93, v2
	s_nop 0
	v_pk_add_f32 v[92:93], v[92:93], 1.0 op_sel_hi:[1,0]
	s_nop 0
	v_div_scale_f32 v2, s[2:3], v93, v93, 1.0
	v_rcp_f32_e32 v96, v2
	s_nop 0
	v_fma_f32 v98, -v2, v96, 1.0
	v_fmac_f32_e32 v96, v98, v96
	v_div_scale_f32 v98, vcc, 1.0, v93, 1.0
	v_mul_f32_e32 v99, v98, v96
	v_fma_f32 v124, -v2, v99, v98
	v_fmac_f32_e32 v99, v124, v96
	v_fma_f32 v2, -v2, v99, v98
	v_div_fmas_f32 v2, v2, v96, v99
	v_div_fixup_f32 v93, v2, v93, 1.0
	v_div_scale_f32 v2, s[2:3], v92, v92, 1.0
	v_rcp_f32_e32 v96, v2
	s_nop 0
	v_fma_f32 v98, -v2, v96, 1.0
	v_fmac_f32_e32 v96, v98, v96
	v_div_scale_f32 v98, vcc, 1.0, v92, 1.0
	v_mul_f32_e32 v99, v98, v96
	v_fma_f32 v124, -v2, v99, v98
	v_fmac_f32_e32 v99, v124, v96
	v_fma_f32 v2, -v2, v99, v98
	v_div_fmas_f32 v2, v2, v96, v99
	v_div_fixup_f32 v92, v2, v92, 1.0
	v_lshlrev_b32_e32 v2, 16, v97
	v_mul_f32_e32 v2, 0xbfb8aa3b, v2
	v_exp_f32_e32 v96, v2
	v_and_b32_e32 v2, 0xffff0000, v97
	v_mul_f32_e32 v2, 0xbfb8aa3b, v2
	v_exp_f32_e32 v97, v2
	v_pk_mul_f32 v[92:93], v[88:89], v[92:93]
	v_pk_add_f32 v[96:97], v[96:97], 1.0 op_sel_hi:[1,0]
	s_nop 0
	v_div_scale_f32 v2, s[2:3], v97, v97, 1.0
	v_rcp_f32_e32 v98, v2
	s_nop 0
	v_fma_f32 v99, -v2, v98, 1.0
	v_fmac_f32_e32 v98, v99, v98
	v_div_scale_f32 v99, vcc, 1.0, v97, 1.0
	v_mul_f32_e32 v124, v99, v98
	v_fma_f32 v125, -v2, v124, v99
	v_fmac_f32_e32 v124, v125, v98
	v_fma_f32 v2, -v2, v124, v99
	v_div_fmas_f32 v2, v2, v98, v124
	v_div_fixup_f32 v97, v2, v97, 1.0
	v_div_scale_f32 v2, s[2:3], v96, v96, 1.0
	v_rcp_f32_e32 v98, v2
	s_nop 0
	v_fma_f32 v99, -v2, v98, 1.0
	v_fmac_f32_e32 v98, v99, v98
	v_div_scale_f32 v99, vcc, 1.0, v96, 1.0
	v_mul_f32_e32 v124, v99, v98
	v_fma_f32 v125, -v2, v124, v99
	v_fmac_f32_e32 v124, v125, v98
	v_fma_f32 v2, -v2, v124, v99
	v_div_fmas_f32 v2, v2, v98, v124
	v_div_fixup_f32 v96, v2, v96, 1.0
	v_pk_mul_f32 v[96:97], v[90:91], v[96:97]
	s_and_b64 vcc, exec, s[4:5]
	s_cbranch_vccnz .LBB0_612
	flat_load_dwordx2 v[98:99], v[94:95] offset:64
	s_waitcnt vmcnt(0) lgkmcnt(0)
	v_lshlrev_b32_e32 v124, 16, v98
	v_and_b32_e32 v125, 0xffff0000, v98
	v_lshlrev_b32_e32 v98, 16, v99
	v_and_b32_e32 v99, 0xffff0000, v99
	v_pk_add_f32 v[92:93], v[92:93], v[124:125]
	v_pk_add_f32 v[96:97], v[96:97], v[98:99]

; __device__ __forceinline__ void gemm_phase(const Ctx& cx, const GemmArgs& g_, char* shm) {
;     ...
;                 const bool r128 = (n0 >= C_DSAQ && n0 < C_HGQ) || (n0 >= C_DSAK && n0 < C_DSAV);
;                 const bool r64 = (n0 >= C_IDXQ && n0 < C_GLAA);
;                 if (r128 || r64) {
;                   float4 cs;
;                   float sc;
;                   if (r128) {
;                     cs = *(const float4*)(g.w + ((size_t)tok * 64 + ((n0 & 127) >> 1)) * 2);
;                     sc = (n0 < C_HGQ) ? 0.08838834764831845f : 1.0f;
;                   } else {
;                     cs = *(const float4*)(g.hout + ((size_t)tok * 32 + ((n0 & 63) >> 1)) * 2);
;                     sc = (n0 < C_IDXK) ? 0.125f : 1.0f;
;                   }
;                   o0 = (a[0] * cs.x - a[1] * cs.y) * sc; o1 = (a[1] * cs.x + a[0] * cs.y) * sc;
;                   o2 = (a[2] * cs.z - a[3] * cs.w) * sc; o3 = (a[3] * cs.z + a[2] * cs.w) * sc;
;                 }
.LBB0_613:
	s_movk_i32 s0, 0x5c00
	v_cmp_gt_i32_e32 vcc, s0, v161
	s_and_saveexec_b64 s[2:3], vcc
	s_xor_b64 s[2:3], exec, s[2:3]
	s_cbranch_execz .LBB0_621
	v_add_u32_e32 v2, 0xffffa700, v138
	v_cmp_gt_u32_e32 vcc, s77, v2
	s_or_b64 s[60:61], s[58:59], vcc
	s_and_saveexec_b64 s[10:11], s[60:61]
	s_cbranch_execz .LBB0_620
	s_and_saveexec_b64 s[60:61], s[56:57]
	s_xor_b64 s[60:61], exec, s[60:61]
	v_lshlrev_b32_e32 v2, 2, v0
	s_movk_i32 s0, 0x5b00
	v_lshl_add_u64 v[92:93], v[112:113], 0, v[2:3]
	v_cmp_gt_u32_e32 vcc, s0, v138
	v_lshl_add_u64 v[92:93], v[92:93], 0, s[70:71]
	s_nop 0
	v_cndmask_b32_e32 v2, 1.0, v166, vcc
	s_andn2_saveexec_b64 s[60:61], s[60:61]
	v_and_b32_e32 v2, 0x6c, v161
	v_lshlrev_b32_e32 v2, 2, v2
	v_cmp_gt_i32_e32 vcc, s81, v161
	v_lshl_add_u64 v[92:93], v[110:111], 0, v[2:3]
	s_nop 0
	v_cndmask_b32_e32 v2, 1.0, v167, vcc
	s_or_b64 exec, exec, s[60:61]
	s_nop 0
	flat_load_dwordx4 v[92:95], v[92:93]
	s_waitcnt vmcnt(0) lgkmcnt(0)
	v_pk_mul_f32 v[96:97], v[88:89], v[92:93] op_sel:[1,1] op_sel_hi:[1,0]
	s_nop 0
	v_pk_fma_f32 v[98:99], v[88:89], v[92:93], v[96:97] neg_lo:[0,0,1] neg_hi:[0,0,1]
	v_pk_fma_f32 v[88:89], v[88:89], v[92:93], v[96:97] op_sel_hi:[0,1,1]
	v_mov_b32_e32 v92, v91
	v_pk_mul_f32 v[92:93], v[92:93], v[94:95] op_sel:[0,1] op_sel_hi:[0,0]
	v_pk_fma_f32 v[96:97], v[90:91], v[94:95], v[92:93] neg_lo:[0,0,1] neg_hi:[0,0,1]
	v_pk_fma_f32 v[90:91], v[90:91], v[94:95], v[92:93] op_sel_hi:[0,1,1]
	v_mov_b32_e32 v99, v89
	v_mov_b32_e32 v97, v91
	v_pk_mul_f32 v[88:89], v[2:3], v[98:99] op_sel_hi:[0,1]
	v_pk_mul_f32 v[90:91], v[2:3], v[96:97] op_sel_hi:[0,1]

; __device__ __forceinline__ void gemm_phase(const Ctx& cx, const GemmArgs& g_, char* shm) {
;     ...
;               if (n0 >= C_GLAX) {
;                 const int i = n0 - C_GLAX;
;                 const float4 b4 = *(const float4*)(g.hin + i);
;                 float xs[4] = {a[0] + b4.x, a[1] + b4.y, a[2] + b4.z, a[3] + b4.w};
; #pragma unroll
;                 for (int j = 0; j < 4; ++j)
;                   xs[j] = (fminf(xs[j], 0.f) - __logf(1.0f + __expf(-fabsf(xs[j])))) * (1.0f / 16.0f);
;                 *(float4*)(g.f32buf + (size_t)tok * 1024 + i) = make_float4(xs[0], xs[1], xs[2], xs[3]);
.LBB0_621:
	s_andn2_saveexec_b64 s[2:3], s[2:3]
	s_cbranch_execz .LBB0_623
	v_add_u32_e32 v2, 0xffffa400, v161
	v_lshlrev_b64 v[96:97], 2, v[2:3]
	v_lshl_add_u64 v[92:93], s[26:27], 0, v[96:97]
	s_nop 0
	flat_load_dwordx4 v[92:95], v[92:93]
	s_mov_b32 s0, 0x3d800000
	v_lshl_add_u64 v[96:97], v[102:103], 0, v[96:97]
	s_waitcnt vmcnt(0) lgkmcnt(0)
	v_add_f32_e32 v2, v88, v92
	v_min_f32_e32 v88, 0, v2
	v_mul_f32_e64 v2, |v2|, s82
	v_exp_f32_e32 v2, v2
	v_add_f32_e32 v92, v89, v93
	v_add_f32_e32 v93, v90, v94
	v_add_f32_e32 v95, v91, v95
	v_add_f32_e32 v2, 1.0, v2
	v_cmp_gt_f32_e32 vcc, s83, v2
	s_nop 1
	v_cndmask_b32_e64 v89, 0, 32, vcc
	v_ldexp_f32 v2, v2, v89
	v_log_f32_e32 v2, v2
	s_nop 0
	v_mul_f32_e32 v89, 0x3f317217, v2
	v_fma_f32 v89, v2, s86, -v89
	v_fmac_f32_e32 v89, 0x3377d1cf, v2
	v_fmac_f32_e32 v89, 0x3f317217, v2
	v_cmp_lt_f32_e64 s[10:11], |v2|, s87
	s_nop 1
	v_cndmask_b32_e64 v2, v2, v89, s[10:11]
	v_cndmask_b32_e32 v89, 0, v165, vcc
	v_sub_f32_e32 v90, v2, v89
	v_mul_f32_e64 v2, |v92|, s82
	v_exp_f32_e32 v2, v2
	v_min_f32_e32 v89, 0, v92
	v_min_f32_e32 v92, 0, v93
	v_add_f32_e32 v2, 1.0, v2
	v_cmp_gt_f32_e32 vcc, s83, v2
	s_nop 1
	v_cndmask_b32_e64 v91, 0, 32, vcc
	v_ldexp_f32 v2, v2, v91
	v_log_f32_e32 v2, v2
	s_nop 0
	v_mul_f32_e32 v91, 0x3f317217, v2
	v_fma_f32 v91, v2, s86, -v91
	v_fmac_f32_e32 v91, 0x3377d1cf, v2
	v_fmac_f32_e32 v91, 0x3f317217, v2
	v_cmp_lt_f32_e64 s[10:11], |v2|, s87
	s_nop 1
	v_cndmask_b32_e64 v2, v2, v91, s[10:11]
	v_cndmask_b32_e32 v91, 0, v165, vcc
	v_sub_f32_e32 v91, v2, v91
	v_mul_f32_e64 v2, |v93|, s82
	v_exp_f32_e32 v2, v2
	v_pk_add_f32 v[88:89], v[88:89], v[90:91] neg_lo:[0,1] neg_hi:[0,1]
	v_add_f32_e32 v2, 1.0, v2
	v_cmp_gt_f32_e32 vcc, s83, v2
	v_pk_mul_f32 v[88:89], v[88:89], s[0:1] op_sel_hi:[1,0]
	s_nop 0
	v_cndmask_b32_e64 v93, 0, 32, vcc
	v_ldexp_f32 v2, v2, v93
	v_log_f32_e32 v2, v2
	s_nop 0
	v_mul_f32_e32 v93, 0x3f317217, v2
	v_fma_f32 v93, v2, s86, -v93
	v_fmac_f32_e32 v93, 0x3377d1cf, v2
	v_fmac_f32_e32 v93, 0x3f317217, v2
	v_cmp_lt_f32_e64 s[10:11], |v2|, s87
	s_nop 1
	v_cndmask_b32_e64 v2, v2, v93, s[10:11]
	v_cndmask_b32_e32 v93, 0, v165, vcc
	v_sub_f32_e32 v94, v2, v93
	v_mul_f32_e64 v2, |v95|, s82
	v_exp_f32_e32 v2, v2
	v_min_f32_e32 v93, 0, v95
	v_add_f32_e32 v2, 1.0, v2
	v_cmp_gt_f32_e32 vcc, s83, v2
	s_nop 1
	v_cndmask_b32_e64 v95, 0, 32, vcc
	v_ldexp_f32 v2, v2, v95
	v_log_f32_e32 v2, v2
	s_nop 0
	v_mul_f32_e32 v95, 0x3f317217, v2
	v_fma_f32 v95, v2, s86, -v95
	v_fmac_f32_e32 v95, 0x3377d1cf, v2
	v_fmac_f32_e32 v95, 0x3f317217, v2
	v_cmp_lt_f32_e64 s[10:11], |v2|, s87
	s_nop 1
	v_cndmask_b32_e64 v2, v2, v95, s[10:11]
	v_cndmask_b32_e32 v95, 0, v165, vcc
	v_sub_f32_e32 v95, v2, v95
	v_pk_add_f32 v[90:91], v[92:93], v[94:95] neg_lo:[0,1] neg_hi:[0,1]
	v_mov_b32_e32 v93, v109
	v_pk_mul_f32 v[90:91], v[90:91], s[0:1] op_sel_hi:[1,0]
	v_mov_b32_e32 v92, v117
	flat_store_dwordx4 v[96:97], v[88:91]

; __device__ __forceinline__ void gemm_phase(const Ctx& cx, const GemmArgs& g_, char* shm) {
;     ...
;             } else if (g.epi == EPI_RELU2) {
;               float r0 = fmaxf(a[0], 0.f), r1 = fmaxf(a[1], 0.f), r2 = fmaxf(a[2], 0.f), r3 = fmaxf(a[3], 0.f);
;               uint2 o; o.x = pack2(r0 * r0, r1 * r1); o.y = pack2(r2 * r2, r3 * r3);
;               EMIT_BF16(g.ldo, o);
.LBB0_634:
	s_cmp_gt_i32 s38, 4
	s_cbranch_scc0 .LBB0_638
	s_cmp_eq_u32 s38, 5
	s_mov_b64 s[10:11], -1
	s_cbranch_scc0 .LBB0_637
	v_max_f32_e32 v2, v86, v86
	v_max_f32_e32 v88, 0, v2
	v_max_f32_e32 v2, v87, v87
	v_max_f32_e32 v89, 0, v2
	v_pk_mul_f32 v[88:89], v[88:89], v[88:89]
	v_max_f32_e32 v2, v84, v84
	v_cvt_pk_bf16_f32 v91, v88, v89
	v_max_f32_e32 v88, 0, v2
	v_max_f32_e32 v2, v85, v85
	v_max_f32_e32 v89, 0, v2
	v_pk_mul_f32 v[88:89], v[88:89], v[88:89]
	v_ashrrev_i32_e32 v133, 31, v132
	v_cvt_pk_bf16_f32 v90, v88, v89
	v_mov_b32_e32 v88, v92
	v_mov_b32_e32 v89, v93
	s_nop 0
	v_permlane16_swap_b32_e32 v88, v90
	v_permlane16_swap_b32_e32 v89, v91
	v_lshl_add_u64 v[94:95], v[132:133], 1, v[118:119]
	s_nop 0
	flat_store_dwordx4 v[94:95], v[88:91] offset:96
	s_mov_b64 s[10:11], 0

; __device__ __forceinline__ void gemm_phase(const Ctx& cx, const GemmArgs& g_, char* shm) {
;     ...
;             } else if (g.epi == EPI_RES) {
;               const float4 hv = *(const float4*)(g.hin + (size_t)tok * DM + n0);
;               const float h0 = hv.x + a[0], h1 = hv.y + a[1], h2 = hv.z + a[2], h3 = hv.w + a[3];
;               *(float4*)(g.hout + (size_t)tok * DM + n0) = make_float4(h0, h1, h2, h3);
;               if (g.w != nullptr) {
;                 const float4 nw = *(const float4*)(g.w + n0);
;                 uint2 o; o.x = pack2(h0 * nw.x, h1 * nw.y); o.y = pack2(h2 * nw.z, h3 * nw.w);
;                 EMIT_BF16(DM, o);
;                 ssq += h0 * h0 + h1 * h1 + h2 * h2 + h3 * h3;
;               }
.LBB0_638:
	s_and_b64 vcc, exec, s[60:61]
	v_mov_b32_e32 v96, v124
	s_cbranch_vccz .LBB0_641
	v_lshl_add_u64 v[94:95], v[138:139], 0, v[0:1]
	v_lshlrev_b64 v[96:97], 2, v[94:95]
	v_lshl_add_u64 v[88:89], v[106:107], 0, v[96:97]
	s_nop 0
	flat_load_dwordx4 v[88:91], v[88:89] offset:192
	v_lshl_add_u64 v[96:97], v[104:105], 0, v[96:97]
	s_andn2_b64 vcc, exec, s[42:43]
	s_waitcnt vmcnt(0) lgkmcnt(0)
	v_pk_add_f32 v[88:89], v[84:85], v[88:89]
	v_pk_add_f32 v[90:91], v[86:87], v[90:91]
	flat_store_dwordx4 v[96:97], v[88:91] offset:192
	v_mov_b32_e32 v96, v124
	s_cbranch_vccnz .LBB0_641
	v_lshl_add_u64 v[94:95], v[94:95], 2, s[30:31]
	global_load_dwordx4 v[94:97], v[94:95], off offset:192
	v_ashrrev_i32_e32 v133, 31, v132
	v_lshl_add_u64 v[98:99], v[132:133], 1, v[100:101]
	s_waitcnt vmcnt(0)
	v_pk_mul_f32 v[94:95], v[88:89], v[94:95]
	v_pk_mul_f32 v[88:89], v[88:89], v[88:89]
	v_pk_mul_f32 v[96:97], v[90:91], v[96:97]
	v_pk_mul_f32 v[90:91], v[90:91], v[90:91]
	v_add_f32_e32 v2, v88, v89
	v_cvt_pk_bf16_f32 v97, v96, v97
	v_cvt_pk_bf16_f32 v96, v94, v95
	v_mov_b32_e32 v94, v92
	v_mov_b32_e32 v95, v93
	v_add_f32_e32 v2, v2, v90
	v_permlane16_swap_b32_e32 v94, v96
	v_permlane16_swap_b32_e32 v95, v97
	v_add_f32_e32 v2, v2, v91
	flat_store_dwordx4 v[98:99], v[94:97] offset:96
	s_nop 1
	v_add_f32_e32 v96, v124, v2

; __device__ __forceinline__ float b2f(u16 b) { return __uint_as_float(((uint32_t)b) << 16); }
; __device__ __forceinline__ float sigmoidf_(float x) { return 1.0f / (1.0f + __expf(-x)); }
; __device__ __forceinline__ void gemm_phase(const Ctx& cx, const GemmArgs& g_, char* shm) {
;     ...
;               const uint2 gv = *(const uint2*)(g.gate + (size_t)tok * NP + n0);
;               float v0 = sigmoidf_(b2f((u16)(gv.x & 0xffff))) * a[0], v1 = sigmoidf_(b2f((u16)(gv.x >> 16))) * a[1];
;               float v2 = sigmoidf_(b2f((u16)(gv.y & 0xffff))) * a[2], v3 = sigmoidf_(b2f((u16)(gv.y >> 16))) * a[3];
;               uint2* mp = (uint2*)(g.outb + (size_t)tok * DM + n0);
;               if (g.epi != EPI_BR0) {
;                 const uint2 pv = *mp;
;                 v0 += b2f((u16)(pv.x & 0xffff)); v1 += b2f((u16)(pv.x >> 16));
;                 v2 += b2f((u16)(pv.y & 0xffff)); v3 += b2f((u16)(pv.y >> 16));
;               }
.LBB0_643:
	v_lshl_add_u64 v[88:89], v[138:139], 0, v[0:1]
	v_lshlrev_b64 v[90:91], 1, v[88:89]
	v_lshl_add_u64 v[88:89], v[114:115], 0, v[90:91]
	s_nop 0
	flat_load_dwordx2 v[94:95], v[88:89] offset:96
	v_lshl_add_u64 v[90:91], v[100:101], 0, v[90:91]
	s_waitcnt vmcnt(0) lgkmcnt(0)
	v_lshlrev_b32_e32 v2, 16, v94
	v_mul_f32_e32 v2, 0xbfb8aa3b, v2
	v_exp_f32_e32 v88, v2
	v_and_b32_e32 v2, 0xffff0000, v94
	v_mul_f32_e32 v2, 0xbfb8aa3b, v2
	v_exp_f32_e32 v89, v2
	s_nop 0
	v_pk_add_f32 v[88:89], v[88:89], 1.0 op_sel_hi:[1,0]
	s_nop 0
	v_div_scale_f32 v2, s[2:3], v89, v89, 1.0
	v_rcp_f32_e32 v94, v2
	s_nop 0
	v_fma_f32 v96, -v2, v94, 1.0
	v_fmac_f32_e32 v94, v96, v94
	v_div_scale_f32 v96, vcc, 1.0, v89, 1.0
	v_mul_f32_e32 v97, v96, v94
	v_fma_f32 v98, -v2, v97, v96
	v_fmac_f32_e32 v97, v98, v94
	v_fma_f32 v2, -v2, v97, v96
	v_div_fmas_f32 v2, v2, v94, v97
	v_div_fixup_f32 v89, v2, v89, 1.0
	v_div_scale_f32 v2, s[2:3], v88, v88, 1.0
	v_rcp_f32_e32 v94, v2
	s_nop 0
	v_fma_f32 v96, -v2, v94, 1.0
	v_fmac_f32_e32 v94, v96, v94
	v_div_scale_f32 v96, vcc, 1.0, v88, 1.0
	v_mul_f32_e32 v97, v96, v94
	v_fma_f32 v98, -v2, v97, v96
	v_fmac_f32_e32 v97, v98, v94
	v_fma_f32 v2, -v2, v97, v96
	v_div_fmas_f32 v2, v2, v94, v97
	v_div_fixup_f32 v88, v2, v88, 1.0
	v_lshlrev_b32_e32 v2, 16, v95
	v_mul_f32_e32 v2, 0xbfb8aa3b, v2
	v_exp_f32_e32 v94, v2
	v_and_b32_e32 v2, 0xffff0000, v95
	v_mul_f32_e32 v2, 0xbfb8aa3b, v2
	v_exp_f32_e32 v95, v2
	v_pk_mul_f32 v[88:89], v[84:85], v[88:89]
	v_pk_add_f32 v[94:95], v[94:95], 1.0 op_sel_hi:[1,0]
	s_nop 0
	v_div_scale_f32 v2, s[2:3], v95, v95, 1.0
	v_rcp_f32_e32 v96, v2
	s_nop 0
	v_fma_f32 v97, -v2, v96, 1.0
	v_fmac_f32_e32 v96, v97, v96
	v_div_scale_f32 v97, vcc, 1.0, v95, 1.0
	v_mul_f32_e32 v98, v97, v96
	v_fma_f32 v99, -v2, v98, v97
	v_fmac_f32_e32 v98, v99, v96
	v_fma_f32 v2, -v2, v98, v97
	v_div_fmas_f32 v2, v2, v96, v98
	v_div_fixup_f32 v95, v2, v95, 1.0
	v_div_scale_f32 v2, s[2:3], v94, v94, 1.0
	v_rcp_f32_e32 v96, v2
	s_nop 0
	v_fma_f32 v97, -v2, v96, 1.0
	v_fmac_f32_e32 v96, v97, v96
	v_div_scale_f32 v97, vcc, 1.0, v94, 1.0
	v_mul_f32_e32 v98, v97, v96
	v_fma_f32 v99, -v2, v98, v97
	v_fmac_f32_e32 v98, v99, v96
	v_fma_f32 v2, -v2, v98, v97
	v_div_fmas_f32 v2, v2, v96, v98
	v_div_fixup_f32 v94, v2, v94, 1.0
	v_pk_mul_f32 v[94:95], v[86:87], v[94:95]
	s_and_b64 vcc, exec, s[4:5]
	s_cbranch_vccnz .LBB0_645
	flat_load_dwordx2 v[96:97], v[90:91] offset:96
	s_waitcnt vmcnt(0) lgkmcnt(0)
	v_lshlrev_b32_e32 v98, 16, v96
	v_and_b32_e32 v99, 0xffff0000, v96
	v_lshlrev_b32_e32 v96, 16, v97
	v_and_b32_e32 v97, 0xffff0000, v97
	v_pk_add_f32 v[88:89], v[88:89], v[98:99]
	v_pk_add_f32 v[94:95], v[94:95], v[96:97]

; __device__ __forceinline__ void gemm_phase(const Ctx& cx, const GemmArgs& g_, char* shm) {
;     ...
;             const int n0 = brow + ai * 128 + wr * 64 + m * 16 + fq * 4;
;             f32x4 a = acc[ai][bj][m][n];
;             if (g.epi == EPI_PROJ || g.epi == EPI_RELU2) { a[0] *= rs; a[1] *= rs; a[2] *= rs; a[3] *= rs; }
;             if (g.epi == EPI_PROJ) {
;               if (n0 >= C_GLAX) {
;                 const int i = n0 - C_GLAX;
;                 const float4 b4 = *(const float4*)(g.hin + i);
;                 float xs[4] = {a[0] + b4.x, a[1] + b4.y, a[2] + b4.z, a[3] + b4.w};
; #pragma unroll
;                 for (int j = 0; j < 4; ++j)
;                   xs[j] = (fminf(xs[j], 0.f) - __logf(1.0f + __expf(-fabsf(xs[j])))) * (1.0f / 16.0f);
;                 *(float4*)(g.f32buf + (size_t)tok * 1024 + i) = make_float4(xs[0], xs[1], xs[2], xs[3]);
;               } else {
;                 float o0 = a[0], o1 = a[1], o2 = a[2], o3 = a[3];
;                 const bool r128 = (n0 >= C_DSAQ && n0 < C_HGQ) || (n0 >= C_DSAK && n0 < C_DSAV);
;                 const bool r64 = (n0 >= C_IDXQ && n0 < C_GLAA);
;                 if (r128 || r64) {
;                   float4 cs;
;                   float sc;
;                   if (r128) {
;                     cs = *(const float4*)(g.w + ((size_t)tok * 64 + ((n0 & 127) >> 1)) * 2);
;                     sc = (n0 < C_HGQ) ? 0.08838834764831845f : 1.0f;
;                   } else {
;                     cs = *(const float4*)(g.hout + ((size_t)tok * 32 + ((n0 & 63) >> 1)) * 2);
;                     sc = (n0 < C_IDXK) ? 0.125f : 1.0f;
;                   }
;                   o0 = (a[0] * cs.x - a[1] * cs.y) * sc; o1 = (a[1] * cs.x + a[0] * cs.y) * sc;
;                   o2 = (a[2] * cs.z - a[3] * cs.w) * sc; o3 = (a[3] * cs.z + a[2] * cs.w) * sc;
;                 }
;                 uint2 o; o.x = pack2(o0, o1); o.y = pack2(o2, o3);
;                 EMIT_BF16(g.ldo, o);
.LBB0_646:
	s_movk_i32 s0, 0x5c00
	v_cmp_gt_i32_e32 vcc, s0, v176
	s_and_saveexec_b64 s[2:3], vcc
	s_xor_b64 s[2:3], exec, s[2:3]
	s_cbranch_execz .LBB0_654
	v_add_u32_e32 v2, 0xffffa700, v138
	v_cmp_gt_u32_e32 vcc, s77, v2
	s_or_b64 s[60:61], s[58:59], vcc
	s_and_saveexec_b64 s[10:11], s[60:61]
	s_cbranch_execz .LBB0_653
	s_and_saveexec_b64 s[60:61], s[56:57]
	s_xor_b64 s[60:61], exec, s[60:61]
	v_lshlrev_b32_e32 v2, 2, v0
	s_movk_i32 s0, 0x5b00
	v_lshl_add_u64 v[88:89], v[112:113], 0, v[2:3]
	s_mov_b64 s[68:69], 0xc0
	v_cmp_gt_u32_e32 vcc, s0, v138
	v_lshl_add_u64 v[88:89], v[88:89], 0, s[68:69]
	s_nop 0
	v_cndmask_b32_e32 v2, 1.0, v166, vcc
	s_andn2_saveexec_b64 s[60:61], s[60:61]
	v_and_b32_e32 v2, 0x7c, v176
	v_lshlrev_b32_e32 v2, 2, v2
	v_cmp_gt_i32_e32 vcc, s81, v176
	v_lshl_add_u64 v[88:89], v[110:111], 0, v[2:3]
	s_nop 0
	v_cndmask_b32_e32 v2, 1.0, v167, vcc
	s_or_b64 exec, exec, s[60:61]
	s_nop 0
	flat_load_dwordx4 v[88:91], v[88:89]
	s_waitcnt vmcnt(0) lgkmcnt(0)
	v_pk_mul_f32 v[94:95], v[84:85], v[88:89] op_sel:[1,1] op_sel_hi:[1,0]
	s_nop 0
	v_pk_fma_f32 v[96:97], v[84:85], v[88:89], v[94:95] neg_lo:[0,0,1] neg_hi:[0,0,1]
	v_pk_fma_f32 v[84:85], v[84:85], v[88:89], v[94:95] op_sel_hi:[0,1,1]
	v_mov_b32_e32 v88, v87
	v_pk_mul_f32 v[88:89], v[88:89], v[90:91] op_sel:[0,1] op_sel_hi:[0,0]
	v_pk_fma_f32 v[94:95], v[86:87], v[90:91], v[88:89] neg_lo:[0,0,1] neg_hi:[0,0,1]
	v_pk_fma_f32 v[86:87], v[86:87], v[90:91], v[88:89] op_sel_hi:[0,1,1]
	v_mov_b32_e32 v97, v85
	v_mov_b32_e32 v95, v87
	v_pk_mul_f32 v[84:85], v[2:3], v[96:97] op_sel_hi:[0,1]
	v_pk_mul_f32 v[86:87], v[2:3], v[94:95] op_sel_hi:[0,1]
.LBB0_653:
	s_or_b64 exec, exec, s[10:11]
	v_cvt_pk_bf16_f32 v2, v86, v87
	v_cvt_pk_bf16_f32 v86, v84, v85
	s_nop 1
	v_permlane16_swap_b32_e32 v92, v86
	v_permlane16_swap_b32_e32 v93, v2
	v_ashrrev_i32_e32 v133, 31, v132
	v_lshl_add_u64 v[84:85], v[132:133], 1, v[118:119]
	v_mov_b32_e32 v94, v86
	v_mov_b32_e32 v95, v2
	s_nop 0
	flat_store_dwordx4 v[84:85], v[92:95] offset:96
.LBB0_654:
	s_andn2_saveexec_b64 s[2:3], s[2:3]
	s_cbranch_execz .LBB0_656
	v_add_u32_e32 v2, 0xffffa400, v176
	v_lshlrev_b64 v[92:93], 2, v[2:3]
	v_lshl_add_u64 v[88:89], s[26:27], 0, v[92:93]
	s_nop 0
	flat_load_dwordx4 v[88:91], v[88:89]
	s_mov_b32 s0, 0x3d800000
	v_lshl_add_u64 v[92:93], v[102:103], 0, v[92:93]
	s_waitcnt vmcnt(0) lgkmcnt(0)
	v_add_f32_e32 v2, v84, v88
	v_min_f32_e32 v84, 0, v2
	v_mul_f32_e64 v2, |v2|, s82
	v_exp_f32_e32 v2, v2
	v_add_f32_e32 v88, v85, v89
	v_add_f32_e32 v89, v86, v90
	v_add_f32_e32 v91, v87, v91
	v_add_f32_e32 v2, 1.0, v2
	v_cmp_gt_f32_e32 vcc, s83, v2
	s_nop 1
	v_cndmask_b32_e64 v85, 0, 32, vcc
	v_ldexp_f32 v2, v2, v85
	v_log_f32_e32 v2, v2
	s_nop 0
	v_mul_f32_e32 v85, 0x3f317217, v2
	v_fma_f32 v85, v2, s86, -v85
	v_fmac_f32_e32 v85, 0x3377d1cf, v2
	v_fmac_f32_e32 v85, 0x3f317217, v2
	v_cmp_lt_f32_e64 s[10:11], |v2|, s87
	s_nop 1
	v_cndmask_b32_e64 v2, v2, v85, s[10:11]
	v_cndmask_b32_e32 v85, 0, v165, vcc
	v_sub_f32_e32 v86, v2, v85
	v_mul_f32_e64 v2, |v88|, s82
	v_exp_f32_e32 v2, v2
	v_min_f32_e32 v85, 0, v88
	v_min_f32_e32 v88, 0, v89
	v_add_f32_e32 v2, 1.0, v2
	v_cmp_gt_f32_e32 vcc, s83, v2
	s_nop 1
	v_cndmask_b32_e64 v87, 0, 32, vcc
	v_ldexp_f32 v2, v2, v87
	v_log_f32_e32 v2, v2
	s_nop 0
	v_mul_f32_e32 v87, 0x3f317217, v2
	v_fma_f32 v87, v2, s86, -v87
	v_fmac_f32_e32 v87, 0x3377d1cf, v2
	v_fmac_f32_e32 v87, 0x3f317217, v2
	v_cmp_lt_f32_e64 s[10:11], |v2|, s87
	s_nop 1
	v_cndmask_b32_e64 v2, v2, v87, s[10:11]
	v_cndmask_b32_e32 v87, 0, v165, vcc
	v_sub_f32_e32 v87, v2, v87
	v_mul_f32_e64 v2, |v89|, s82
	v_exp_f32_e32 v2, v2
	v_pk_add_f32 v[84:85], v[84:85], v[86:87] neg_lo:[0,1] neg_hi:[0,1]
	v_add_f32_e32 v2, 1.0, v2
	v_cmp_gt_f32_e32 vcc, s83, v2
	v_pk_mul_f32 v[84:85], v[84:85], s[0:1] op_sel_hi:[1,0]
	s_nop 0
	v_cndmask_b32_e64 v89, 0, 32, vcc
	v_ldexp_f32 v2, v2, v89
	v_log_f32_e32 v2, v2
	s_nop 0
	v_mul_f32_e32 v89, 0x3f317217, v2
	v_fma_f32 v89, v2, s86, -v89
	v_fmac_f32_e32 v89, 0x3377d1cf, v2
	v_fmac_f32_e32 v89, 0x3f317217, v2
	v_cmp_lt_f32_e64 s[10:11], |v2|, s87
	s_nop 1
	v_cndmask_b32_e64 v2, v2, v89, s[10:11]
	v_cndmask_b32_e32 v89, 0, v165, vcc
	v_sub_f32_e32 v90, v2, v89
	v_mul_f32_e64 v2, |v91|, s82
	v_exp_f32_e32 v2, v2
	v_min_f32_e32 v89, 0, v91
	v_add_f32_e32 v2, 1.0, v2
	v_cmp_gt_f32_e32 vcc, s83, v2
	s_nop 1
	v_cndmask_b32_e64 v91, 0, 32, vcc
	v_ldexp_f32 v2, v2, v91
	v_log_f32_e32 v2, v2
	s_nop 0
	v_mul_f32_e32 v91, 0x3f317217, v2
	v_fma_f32 v91, v2, s86, -v91
	v_fmac_f32_e32 v91, 0x3377d1cf, v2
	v_fmac_f32_e32 v91, 0x3f317217, v2
	v_cmp_lt_f32_e64 s[10:11], |v2|, s87
	s_nop 1
	v_cndmask_b32_e64 v2, v2, v91, s[10:11]
	v_cndmask_b32_e32 v91, 0, v165, vcc
	v_sub_f32_e32 v91, v2, v91
	v_pk_add_f32 v[86:87], v[88:89], v[90:91] neg_lo:[0,1] neg_hi:[0,1]
	s_nop 0
	v_pk_mul_f32 v[86:87], v[86:87], s[0:1] op_sel_hi:[1,0]
	flat_store_dwordx4 v[92:93], v[84:87]

; __device__ __forceinline__ void gemm_phase(const Ctx& cx, const GemmArgs& g_, char* shm) {
;     ...
;             } else if (g.epi == EPI_RES) {
;               const float4 hv = *(const float4*)(g.hin + (size_t)tok * DM + n0);
;               const float h0 = hv.x + a[0], h1 = hv.y + a[1], h2 = hv.z + a[2], h3 = hv.w + a[3];
;               *(float4*)(g.hout + (size_t)tok * DM + n0) = make_float4(h0, h1, h2, h3);
;               if (g.w != nullptr) {
;                 const float4 nw = *(const float4*)(g.w + n0);
;                 uint2 o; o.x = pack2(h0 * nw.x, h1 * nw.y); o.y = pack2(h2 * nw.z, h3 * nw.w);
;                 EMIT_BF16(DM, o);
;                 ssq += h0 * h0 + h1 * h1 + h2 * h2 + h3 * h3;
;               }
.LBB0_671:
	s_and_b64 vcc, exec, s[60:61]
	v_mov_b32_e32 v87, v96
	s_cbranch_vccz .LBB0_674
	v_lshlrev_b64 v[88:89], 2, v[122:123]
	v_lshl_add_u64 v[84:85], v[106:107], 0, v[88:89]
	s_nop 0
	flat_load_dwordx4 v[84:87], v[84:85]
	v_lshl_add_u64 v[88:89], v[104:105], 0, v[88:89]
	s_andn2_b64 vcc, exec, s[42:43]
	s_waitcnt vmcnt(0) lgkmcnt(0)
	v_pk_add_f32 v[84:85], v[80:81], v[84:85]
	v_pk_add_f32 v[86:87], v[82:83], v[86:87]
	flat_store_dwordx4 v[88:89], v[84:87]
	s_cbranch_vccnz .LBB0_807
	v_lshl_add_u64 v[88:89], v[122:123], 2, s[30:31]
	global_load_dwordx4 v[88:91], v[88:89], off
	s_waitcnt vmcnt(0)
	v_pk_mul_f32 v[88:89], v[84:85], v[88:89]
	v_pk_mul_f32 v[84:85], v[84:85], v[84:85]
	v_pk_mul_f32 v[90:91], v[86:87], v[90:91]
	v_pk_mul_f32 v[86:87], v[86:87], v[86:87]
	v_add_f32_e32 v2, v84, v85
	v_add_f32_e32 v2, v2, v86
	v_add_f32_e32 v2, v2, v87
	v_cvt_pk_bf16_f32 v90, v90, v91
	v_cvt_pk_bf16_f32 v88, v88, v89
	v_add_f32_e32 v87, v96, v2

; __device__ __forceinline__ float b2f(u16 b) { return __uint_as_float(((uint32_t)b) << 16); }
; __device__ __forceinline__ float sigmoidf_(float x) { return 1.0f / (1.0f + __expf(-x)); }
; __device__ __forceinline__ void gemm_phase(const Ctx& cx, const GemmArgs& g_, char* shm) {
;     ...
;               const uint2 gv = *(const uint2*)(g.gate + (size_t)tok * NP + n0);
;               float v0 = sigmoidf_(b2f((u16)(gv.x & 0xffff))) * a[0], v1 = sigmoidf_(b2f((u16)(gv.x >> 16))) * a[1];
;               float v2 = sigmoidf_(b2f((u16)(gv.y & 0xffff))) * a[2], v3 = sigmoidf_(b2f((u16)(gv.y >> 16))) * a[3];
;               uint2* mp = (uint2*)(g.outb + (size_t)tok * DM + n0);
;               if (g.epi != EPI_BR0) {
;                 const uint2 pv = *mp;
;                 v0 += b2f((u16)(pv.x & 0xffff)); v1 += b2f((u16)(pv.x >> 16));
;                 v2 += b2f((u16)(pv.y & 0xffff)); v3 += b2f((u16)(pv.y >> 16));
;               }
.LBB0_676:
	v_lshlrev_b64 v[86:87], 1, v[122:123]
	v_lshl_add_u64 v[84:85], v[114:115], 0, v[86:87]
	s_nop 0
	flat_load_dwordx2 v[88:89], v[84:85]
	v_lshl_add_u64 v[86:87], v[100:101], 0, v[86:87]
	s_waitcnt vmcnt(0) lgkmcnt(0)
	v_lshlrev_b32_e32 v2, 16, v88
	v_mul_f32_e32 v2, 0xbfb8aa3b, v2
	v_exp_f32_e32 v84, v2
	v_and_b32_e32 v2, 0xffff0000, v88
	v_mul_f32_e32 v2, 0xbfb8aa3b, v2
	v_exp_f32_e32 v85, v2
	s_nop 0
	v_pk_add_f32 v[84:85], v[84:85], 1.0 op_sel_hi:[1,0]
	s_nop 0
	v_div_scale_f32 v2, s[2:3], v85, v85, 1.0
	v_rcp_f32_e32 v88, v2
	s_nop 0
	v_fma_f32 v90, -v2, v88, 1.0
	v_fmac_f32_e32 v88, v90, v88
	v_div_scale_f32 v90, vcc, 1.0, v85, 1.0
	v_mul_f32_e32 v91, v90, v88
	v_fma_f32 v92, -v2, v91, v90
	v_fmac_f32_e32 v91, v92, v88
	v_fma_f32 v2, -v2, v91, v90
	v_div_fmas_f32 v2, v2, v88, v91
	v_div_fixup_f32 v85, v2, v85, 1.0
	v_div_scale_f32 v2, s[2:3], v84, v84, 1.0
	v_rcp_f32_e32 v88, v2
	s_nop 0
	v_fma_f32 v90, -v2, v88, 1.0
	v_fmac_f32_e32 v88, v90, v88
	v_div_scale_f32 v90, vcc, 1.0, v84, 1.0
	v_mul_f32_e32 v91, v90, v88
	v_fma_f32 v92, -v2, v91, v90
	v_fmac_f32_e32 v91, v92, v88
	v_fma_f32 v2, -v2, v91, v90
	v_div_fmas_f32 v2, v2, v88, v91
	v_div_fixup_f32 v84, v2, v84, 1.0
	v_lshlrev_b32_e32 v2, 16, v89
	v_mul_f32_e32 v2, 0xbfb8aa3b, v2
	v_exp_f32_e32 v88, v2
	v_and_b32_e32 v2, 0xffff0000, v89
	v_mul_f32_e32 v2, 0xbfb8aa3b, v2
	v_exp_f32_e32 v89, v2
	v_pk_mul_f32 v[84:85], v[80:81], v[84:85]
	v_pk_add_f32 v[88:89], v[88:89], 1.0 op_sel_hi:[1,0]
	s_nop 0
	v_div_scale_f32 v2, s[2:3], v89, v89, 1.0
	v_rcp_f32_e32 v90, v2
	s_nop 0
	v_fma_f32 v91, -v2, v90, 1.0
	v_fmac_f32_e32 v90, v91, v90
	v_div_scale_f32 v91, vcc, 1.0, v89, 1.0
	v_mul_f32_e32 v92, v91, v90
	v_fma_f32 v93, -v2, v92, v91
	v_fmac_f32_e32 v92, v93, v90
	v_fma_f32 v2, -v2, v92, v91
	v_div_fmas_f32 v2, v2, v90, v92
	v_div_fixup_f32 v89, v2, v89, 1.0
	v_div_scale_f32 v2, s[2:3], v88, v88, 1.0
	v_rcp_f32_e32 v90, v2
	s_nop 0
	v_fma_f32 v91, -v2, v90, 1.0
	v_fmac_f32_e32 v90, v91, v90
	v_div_scale_f32 v91, vcc, 1.0, v88, 1.0
	v_mul_f32_e32 v92, v91, v90
	v_fma_f32 v93, -v2, v92, v91
	v_fmac_f32_e32 v92, v93, v90
	v_fma_f32 v2, -v2, v92, v91
	v_div_fmas_f32 v2, v2, v90, v92
	v_div_fixup_f32 v88, v2, v88, 1.0
	v_pk_mul_f32 v[88:89], v[82:83], v[88:89]
	s_and_b64 vcc, exec, s[4:5]
	s_cbranch_vccnz .LBB0_678
	flat_load_dwordx2 v[90:91], v[86:87]
	s_waitcnt vmcnt(0) lgkmcnt(0)
	v_lshlrev_b32_e32 v92, 16, v90
	v_and_b32_e32 v93, 0xffff0000, v90
	v_lshlrev_b32_e32 v90, 16, v91
	v_and_b32_e32 v91, 0xffff0000, v91
	v_pk_add_f32 v[84:85], v[84:85], v[92:93]
	v_pk_add_f32 v[88:89], v[88:89], v[90:91]

; __device__ __forceinline__ void gemm_phase(const Ctx& cx, const GemmArgs& g_, char* shm) {
;     ...
;                 const bool r128 = (n0 >= C_DSAQ && n0 < C_HGQ) || (n0 >= C_DSAK && n0 < C_DSAV);
;                 const bool r64 = (n0 >= C_IDXQ && n0 < C_GLAA);
;                 if (r128 || r64) {
;                   float4 cs;
;                   float sc;
;                   if (r128) {
;                     cs = *(const float4*)(g.w + ((size_t)tok * 64 + ((n0 & 127) >> 1)) * 2);
;                     sc = (n0 < C_HGQ) ? 0.08838834764831845f : 1.0f;
;                   } else {
;                     cs = *(const float4*)(g.hout + ((size_t)tok * 32 + ((n0 & 63) >> 1)) * 2);
;                     sc = (n0 < C_IDXK) ? 0.125f : 1.0f;
;                   }
;                   o0 = (a[0] * cs.x - a[1] * cs.y) * sc; o1 = (a[1] * cs.x + a[0] * cs.y) * sc;
;                   o2 = (a[2] * cs.z - a[3] * cs.w) * sc; o3 = (a[3] * cs.z + a[2] * cs.w) * sc;
;                 }
.LBB0_679:
	s_movk_i32 s0, 0x5c00
	v_cmp_gt_i32_e32 vcc, s0, v122
	s_and_saveexec_b64 s[2:3], vcc
	s_xor_b64 s[2:3], exec, s[2:3]
	s_cbranch_execz .LBB0_687
	v_add_u32_e32 v2, 0xffffa780, v138
	v_cmp_gt_u32_e32 vcc, s77, v2
	s_or_b64 s[60:61], s[54:55], vcc
	s_and_saveexec_b64 s[10:11], s[60:61]
	s_cbranch_execz .LBB0_686
	s_and_saveexec_b64 s[60:61], s[52:53]
	s_xor_b64 s[60:61], exec, s[60:61]
	s_movk_i32 s0, 0x5b00
	v_lshlrev_b32_e32 v2, 2, v0
	v_cmp_gt_u32_e32 vcc, s0, v120
	v_lshl_add_u64 v[84:85], v[112:113], 0, v[2:3]
	s_nop 0
	v_cndmask_b32_e32 v2, 1.0, v166, vcc
	s_andn2_saveexec_b64 s[60:61], s[60:61]
	v_and_b32_e32 v2, 0x4c, v122
	v_lshlrev_b32_e32 v2, 2, v2
	v_cmp_gt_i32_e32 vcc, s81, v122
	v_lshl_add_u64 v[84:85], v[110:111], 0, v[2:3]
	s_nop 0
	v_cndmask_b32_e32 v2, 1.0, v167, vcc
	s_or_b64 exec, exec, s[60:61]
	s_nop 0
	flat_load_dwordx4 v[84:87], v[84:85]
	s_waitcnt vmcnt(0) lgkmcnt(0)
	v_pk_mul_f32 v[88:89], v[80:81], v[84:85] op_sel:[1,1] op_sel_hi:[1,0]
	s_nop 0
	v_pk_fma_f32 v[90:91], v[80:81], v[84:85], v[88:89] neg_lo:[0,0,1] neg_hi:[0,0,1]
	v_pk_fma_f32 v[80:81], v[80:81], v[84:85], v[88:89] op_sel_hi:[0,1,1]
	v_mov_b32_e32 v84, v83
	v_pk_mul_f32 v[84:85], v[84:85], v[86:87] op_sel:[0,1] op_sel_hi:[0,0]
	v_pk_fma_f32 v[88:89], v[82:83], v[86:87], v[84:85] neg_lo:[0,0,1] neg_hi:[0,0,1]
	v_pk_fma_f32 v[82:83], v[82:83], v[86:87], v[84:85] op_sel_hi:[0,1,1]
	v_mov_b32_e32 v91, v81
	v_mov_b32_e32 v89, v83
	v_pk_mul_f32 v[80:81], v[2:3], v[90:91] op_sel_hi:[0,1]
	v_pk_mul_f32 v[82:83], v[2:3], v[88:89] op_sel_hi:[0,1]

; __device__ __forceinline__ void gemm_phase(const Ctx& cx, const GemmArgs& g_, char* shm) {
;     ...
;               if (n0 >= C_GLAX) {
;                 const int i = n0 - C_GLAX;
;                 const float4 b4 = *(const float4*)(g.hin + i);
;                 float xs[4] = {a[0] + b4.x, a[1] + b4.y, a[2] + b4.z, a[3] + b4.w};
; #pragma unroll
;                 for (int j = 0; j < 4; ++j)
;                   xs[j] = (fminf(xs[j], 0.f) - __logf(1.0f + __expf(-fabsf(xs[j])))) * (1.0f / 16.0f);
;                 *(float4*)(g.f32buf + (size_t)tok * 1024 + i) = make_float4(xs[0], xs[1], xs[2], xs[3]);
.LBB0_687:
	s_andn2_saveexec_b64 s[2:3], s[2:3]
	s_cbranch_execz .LBB0_689
	v_add_u32_e32 v2, 0xffffa400, v122
	v_lshlrev_b64 v[88:89], 2, v[2:3]
	v_lshl_add_u64 v[84:85], s[26:27], 0, v[88:89]
	s_nop 0
	flat_load_dwordx4 v[84:87], v[84:85]
	s_mov_b32 s0, 0x3d800000
	v_lshl_add_u64 v[88:89], v[102:103], 0, v[88:89]
	v_mov_b32_e32 v90, 0
	s_waitcnt vmcnt(0) lgkmcnt(0)
	v_add_f32_e32 v2, v80, v84
	v_min_f32_e32 v80, 0, v2
	v_mul_f32_e64 v2, |v2|, s82
	v_exp_f32_e32 v2, v2
	v_add_f32_e32 v84, v81, v85
	v_add_f32_e32 v85, v82, v86
	v_add_f32_e32 v87, v83, v87
	v_add_f32_e32 v2, 1.0, v2
	v_cmp_gt_f32_e32 vcc, s83, v2
	s_nop 1
	v_cndmask_b32_e64 v81, 0, 32, vcc
	v_ldexp_f32 v2, v2, v81
	v_log_f32_e32 v2, v2
	s_nop 0
	v_mul_f32_e32 v81, 0x3f317217, v2
	v_fma_f32 v81, v2, s86, -v81
	v_fmac_f32_e32 v81, 0x3377d1cf, v2
	v_fmac_f32_e32 v81, 0x3f317217, v2
	v_cmp_lt_f32_e64 s[10:11], |v2|, s87
	s_nop 1
	v_cndmask_b32_e64 v2, v2, v81, s[10:11]
	v_cndmask_b32_e32 v81, 0, v165, vcc
	v_sub_f32_e32 v82, v2, v81
	v_mul_f32_e64 v2, |v84|, s82
	v_exp_f32_e32 v2, v2
	v_min_f32_e32 v81, 0, v84
	v_min_f32_e32 v84, 0, v85
	v_add_f32_e32 v2, 1.0, v2
	v_cmp_gt_f32_e32 vcc, s83, v2
	s_nop 1
	v_cndmask_b32_e64 v83, 0, 32, vcc
	v_ldexp_f32 v2, v2, v83
	v_log_f32_e32 v2, v2
	s_nop 0
	v_mul_f32_e32 v83, 0x3f317217, v2
	v_fma_f32 v83, v2, s86, -v83
	v_fmac_f32_e32 v83, 0x3377d1cf, v2
	v_fmac_f32_e32 v83, 0x3f317217, v2
	v_cmp_lt_f32_e64 s[10:11], |v2|, s87
	s_nop 1
	v_cndmask_b32_e64 v2, v2, v83, s[10:11]
	v_cndmask_b32_e32 v83, 0, v165, vcc
	v_sub_f32_e32 v83, v2, v83
	v_mul_f32_e64 v2, |v85|, s82
	v_exp_f32_e32 v2, v2
	v_pk_add_f32 v[80:81], v[80:81], v[82:83] neg_lo:[0,1] neg_hi:[0,1]
	v_add_f32_e32 v2, 1.0, v2
	v_cmp_gt_f32_e32 vcc, s83, v2
	v_pk_mul_f32 v[80:81], v[80:81], s[0:1] op_sel_hi:[1,0]
	s_nop 0
	v_cndmask_b32_e64 v85, 0, 32, vcc
	v_ldexp_f32 v2, v2, v85
	v_log_f32_e32 v2, v2
	s_nop 0
	v_mul_f32_e32 v85, 0x3f317217, v2
	v_fma_f32 v85, v2, s86, -v85
	v_fmac_f32_e32 v85, 0x3377d1cf, v2
	v_fmac_f32_e32 v85, 0x3f317217, v2
	v_cmp_lt_f32_e64 s[10:11], |v2|, s87
	s_nop 1
	v_cndmask_b32_e64 v2, v2, v85, s[10:11]
	v_cndmask_b32_e32 v85, 0, v165, vcc
	v_sub_f32_e32 v86, v2, v85
	v_mul_f32_e64 v2, |v87|, s82
	v_exp_f32_e32 v2, v2
	v_min_f32_e32 v85, 0, v87
	v_add_f32_e32 v2, 1.0, v2
	v_cmp_gt_f32_e32 vcc, s83, v2
	s_nop 1
	v_cndmask_b32_e64 v87, 0, 32, vcc
	v_ldexp_f32 v2, v2, v87
	v_log_f32_e32 v2, v2
	s_nop 0
	v_mul_f32_e32 v87, 0x3f317217, v2
	v_fma_f32 v87, v2, s86, -v87
	v_fmac_f32_e32 v87, 0x3377d1cf, v2
	v_fmac_f32_e32 v87, 0x3f317217, v2
	v_cmp_lt_f32_e64 s[10:11], |v2|, s87
	s_nop 1
	v_cndmask_b32_e64 v2, v2, v87, s[10:11]
	v_cndmask_b32_e32 v87, 0, v165, vcc
	v_sub_f32_e32 v87, v2, v87
	v_pk_add_f32 v[82:83], v[84:85], v[86:87] neg_lo:[0,1] neg_hi:[0,1]
	s_nop 0
	v_pk_mul_f32 v[82:83], v[82:83], s[0:1] op_sel_hi:[1,0]
	flat_store_dwordx4 v[88:89], v[80:83]
	v_mov_b32_e32 v88, 0

; __device__ __forceinline__ void gemm_phase(const Ctx& cx, const GemmArgs& g_, char* shm) {
;     ...
;             } else if (g.epi == EPI_RELU2) {
;               float r0 = fmaxf(a[0], 0.f), r1 = fmaxf(a[1], 0.f), r2 = fmaxf(a[2], 0.f), r3 = fmaxf(a[3], 0.f);
;               uint2 o; o.x = pack2(r0 * r0, r1 * r1); o.y = pack2(r2 * r2, r3 * r3);
;               EMIT_BF16(g.ldo, o);
.LBB0_700:
	s_cmp_gt_i32 s38, 4
	s_cbranch_scc0 .LBB0_704
	s_cmp_eq_u32 s38, 5
	s_mov_b64 s[10:11], -1
	s_cbranch_scc0 .LBB0_703
	v_max_f32_e32 v2, v78, v78
	v_max_f32_e32 v80, 0, v2
	v_max_f32_e32 v2, v79, v79
	v_max_f32_e32 v81, 0, v2
	v_pk_mul_f32 v[80:81], v[80:81], v[80:81]
	v_max_f32_e32 v2, v76, v76
	v_cvt_pk_bf16_f32 v83, v80, v81
	v_max_f32_e32 v80, 0, v2
	v_max_f32_e32 v2, v77, v77
	v_max_f32_e32 v81, 0, v2
	v_pk_mul_f32 v[80:81], v[80:81], v[80:81]
	v_ashrrev_i32_e32 v117, 31, v116
	v_cvt_pk_bf16_f32 v82, v80, v81
	v_mov_b32_e32 v80, v88
	v_mov_b32_e32 v81, v90
	s_nop 0
	v_permlane16_swap_b32_e32 v80, v82
	v_permlane16_swap_b32_e32 v81, v83
	v_lshl_add_u64 v[84:85], v[116:117], 1, v[118:119]
	s_nop 0
	flat_store_dwordx4 v[84:85], v[80:83] offset:32
	s_mov_b64 s[10:11], 0

; __device__ __forceinline__ void gemm_phase(const Ctx& cx, const GemmArgs& g_, char* shm) {
;     ...
;             } else if (g.epi == EPI_RES) {
;               const float4 hv = *(const float4*)(g.hin + (size_t)tok * DM + n0);
;               const float h0 = hv.x + a[0], h1 = hv.y + a[1], h2 = hv.z + a[2], h3 = hv.w + a[3];
;               *(float4*)(g.hout + (size_t)tok * DM + n0) = make_float4(h0, h1, h2, h3);
;               if (g.w != nullptr) {
;                 const float4 nw = *(const float4*)(g.w + n0);
;                 uint2 o; o.x = pack2(h0 * nw.x, h1 * nw.y); o.y = pack2(h2 * nw.z, h3 * nw.w);
;                 EMIT_BF16(DM, o);
;                 ssq += h0 * h0 + h1 * h1 + h2 * h2 + h3 * h3;
;               }
.LBB0_704:
	s_and_b64 vcc, exec, s[60:61]
	v_mov_b32_e32 v86, v87
	s_cbranch_vccz .LBB0_707
	v_lshl_add_u64 v[84:85], v[120:121], 0, v[0:1]
	v_lshlrev_b64 v[92:93], 2, v[84:85]
	v_lshl_add_u64 v[80:81], v[106:107], 0, v[92:93]
	s_nop 0
	flat_load_dwordx4 v[80:83], v[80:81] offset:64
	v_lshl_add_u64 v[92:93], v[104:105], 0, v[92:93]
	s_andn2_b64 vcc, exec, s[42:43]
	v_mov_b32_e32 v86, v87
	s_waitcnt vmcnt(0) lgkmcnt(0)
	v_pk_add_f32 v[80:81], v[76:77], v[80:81]
	v_pk_add_f32 v[82:83], v[78:79], v[82:83]
	flat_store_dwordx4 v[92:93], v[80:83] offset:64
	s_cbranch_vccnz .LBB0_707
	v_lshl_add_u64 v[84:85], v[84:85], 2, s[30:31]
	global_load_dwordx4 v[92:95], v[84:85], off offset:64
	v_ashrrev_i32_e32 v117, 31, v116
	s_waitcnt vmcnt(0)
	v_pk_mul_f32 v[84:85], v[82:83], v[94:95]
	s_nop 0
	v_cvt_pk_bf16_f32 v95, v84, v85
	v_pk_mul_f32 v[84:85], v[80:81], v[92:93]
	v_pk_mul_f32 v[80:81], v[80:81], v[80:81]
	v_pk_mul_f32 v[82:83], v[82:83], v[82:83]
	v_add_f32_e32 v2, v80, v81
	v_cvt_pk_bf16_f32 v94, v84, v85
	v_mov_b32_e32 v92, v88
	v_mov_b32_e32 v93, v90
	v_add_f32_e32 v2, v2, v82
	v_permlane16_swap_b32_e32 v92, v94
	v_permlane16_swap_b32_e32 v93, v95
	v_lshl_add_u64 v[84:85], v[116:117], 1, v[100:101]
	v_add_f32_e32 v2, v2, v83
	flat_store_dwordx4 v[84:85], v[92:95] offset:32
	v_add_f32_e32 v86, v87, v2

; __device__ __forceinline__ float b2f(u16 b) { return __uint_as_float(((uint32_t)b) << 16); }
; __device__ __forceinline__ float sigmoidf_(float x) { return 1.0f / (1.0f + __expf(-x)); }
; __device__ __forceinline__ void gemm_phase(const Ctx& cx, const GemmArgs& g_, char* shm) {
;     ...
;               const uint2 gv = *(const uint2*)(g.gate + (size_t)tok * NP + n0);
;               float v0 = sigmoidf_(b2f((u16)(gv.x & 0xffff))) * a[0], v1 = sigmoidf_(b2f((u16)(gv.x >> 16))) * a[1];
;               float v2 = sigmoidf_(b2f((u16)(gv.y & 0xffff))) * a[2], v3 = sigmoidf_(b2f((u16)(gv.y >> 16))) * a[3];
;               uint2* mp = (uint2*)(g.outb + (size_t)tok * DM + n0);
;               if (g.epi != EPI_BR0) {
;                 const uint2 pv = *mp;
;                 v0 += b2f((u16)(pv.x & 0xffff)); v1 += b2f((u16)(pv.x >> 16));
;                 v2 += b2f((u16)(pv.y & 0xffff)); v3 += b2f((u16)(pv.y >> 16));
;               }
.LBB0_709:
	v_lshl_add_u64 v[80:81], v[120:121], 0, v[0:1]
	v_lshlrev_b64 v[82:83], 1, v[80:81]
	v_lshl_add_u64 v[80:81], v[114:115], 0, v[82:83]
	s_nop 0
	flat_load_dwordx2 v[84:85], v[80:81] offset:32
	v_lshl_add_u64 v[82:83], v[100:101], 0, v[82:83]
	s_waitcnt vmcnt(0) lgkmcnt(0)
	v_lshlrev_b32_e32 v2, 16, v84
	v_mul_f32_e32 v2, 0xbfb8aa3b, v2
	v_exp_f32_e32 v80, v2
	v_and_b32_e32 v2, 0xffff0000, v84
	v_mul_f32_e32 v2, 0xbfb8aa3b, v2
	v_exp_f32_e32 v81, v2
	s_nop 0
	v_pk_add_f32 v[80:81], v[80:81], 1.0 op_sel_hi:[1,0]
	s_nop 0
	v_div_scale_f32 v2, s[2:3], v81, v81, 1.0
	v_rcp_f32_e32 v84, v2
	s_nop 0
	v_fma_f32 v86, -v2, v84, 1.0
	v_fmac_f32_e32 v84, v86, v84
	v_div_scale_f32 v86, vcc, 1.0, v81, 1.0
	v_mul_f32_e32 v89, v86, v84
	v_fma_f32 v91, -v2, v89, v86
	v_fmac_f32_e32 v89, v91, v84
	v_fma_f32 v2, -v2, v89, v86
	v_div_fmas_f32 v2, v2, v84, v89
	v_div_fixup_f32 v81, v2, v81, 1.0
	v_div_scale_f32 v2, s[2:3], v80, v80, 1.0
	v_rcp_f32_e32 v84, v2
	s_nop 0
	v_fma_f32 v86, -v2, v84, 1.0
	v_fmac_f32_e32 v84, v86, v84
	v_div_scale_f32 v86, vcc, 1.0, v80, 1.0
	v_mul_f32_e32 v89, v86, v84
	v_fma_f32 v91, -v2, v89, v86
	v_fmac_f32_e32 v89, v91, v84
	v_fma_f32 v2, -v2, v89, v86
	v_div_fmas_f32 v2, v2, v84, v89
	v_div_fixup_f32 v80, v2, v80, 1.0
	v_lshlrev_b32_e32 v2, 16, v85
	v_mul_f32_e32 v2, 0xbfb8aa3b, v2
	v_exp_f32_e32 v84, v2
	v_and_b32_e32 v2, 0xffff0000, v85
	v_mul_f32_e32 v2, 0xbfb8aa3b, v2
	v_exp_f32_e32 v85, v2
	v_pk_mul_f32 v[80:81], v[76:77], v[80:81]
	v_pk_add_f32 v[84:85], v[84:85], 1.0 op_sel_hi:[1,0]
	s_nop 0
	v_div_scale_f32 v2, s[2:3], v85, v85, 1.0
	v_rcp_f32_e32 v86, v2
	s_nop 0
	v_fma_f32 v89, -v2, v86, 1.0
	v_fmac_f32_e32 v86, v89, v86
	v_div_scale_f32 v89, vcc, 1.0, v85, 1.0
	v_mul_f32_e32 v91, v89, v86
	v_fma_f32 v92, -v2, v91, v89
	v_fmac_f32_e32 v91, v92, v86
	v_fma_f32 v2, -v2, v91, v89
	v_div_fmas_f32 v2, v2, v86, v91
	v_div_fixup_f32 v85, v2, v85, 1.0
	v_div_scale_f32 v2, s[2:3], v84, v84, 1.0
	v_rcp_f32_e32 v86, v2
	s_nop 0
	v_fma_f32 v89, -v2, v86, 1.0
	v_fmac_f32_e32 v86, v89, v86
	v_div_scale_f32 v89, vcc, 1.0, v84, 1.0
	v_mul_f32_e32 v91, v89, v86
	v_fma_f32 v92, -v2, v91, v89
	v_fmac_f32_e32 v91, v92, v86
	v_fma_f32 v2, -v2, v91, v89
	v_div_fmas_f32 v2, v2, v86, v91
	v_div_fixup_f32 v84, v2, v84, 1.0
	v_pk_mul_f32 v[84:85], v[78:79], v[84:85]
	s_and_b64 vcc, exec, s[4:5]
	s_cbranch_vccnz .LBB0_711
	flat_load_dwordx2 v[92:93], v[82:83] offset:32
	s_waitcnt vmcnt(0) lgkmcnt(0)
	v_lshlrev_b32_e32 v94, 16, v92
	v_and_b32_e32 v95, 0xffff0000, v92
	v_lshlrev_b32_e32 v92, 16, v93
	v_and_b32_e32 v93, 0xffff0000, v93
	v_pk_add_f32 v[80:81], v[80:81], v[94:95]
	v_pk_add_f32 v[84:85], v[84:85], v[92:93]

; __device__ __forceinline__ void gemm_phase(const Ctx& cx, const GemmArgs& g_, char* shm) {
;     ...
;             const int n0 = brow + ai * 128 + wr * 64 + m * 16 + fq * 4;
;             f32x4 a = acc[ai][bj][m][n];
;             if (g.epi == EPI_PROJ || g.epi == EPI_RELU2) { a[0] *= rs; a[1] *= rs; a[2] *= rs; a[3] *= rs; }
;             if (g.epi == EPI_PROJ) {
;               if (n0 >= C_GLAX) {
;                 const int i = n0 - C_GLAX;
;                 const float4 b4 = *(const float4*)(g.hin + i);
;                 float xs[4] = {a[0] + b4.x, a[1] + b4.y, a[2] + b4.z, a[3] + b4.w};
; #pragma unroll
;                 for (int j = 0; j < 4; ++j)
;                   xs[j] = (fminf(xs[j], 0.f) - __logf(1.0f + __expf(-fabsf(xs[j])))) * (1.0f / 16.0f);
;                 *(float4*)(g.f32buf + (size_t)tok * 1024 + i) = make_float4(xs[0], xs[1], xs[2], xs[3]);
;               } else {
;                 float o0 = a[0], o1 = a[1], o2 = a[2], o3 = a[3];
;                 const bool r128 = (n0 >= C_DSAQ && n0 < C_HGQ) || (n0 >= C_DSAK && n0 < C_DSAV);
;                 const bool r64 = (n0 >= C_IDXQ && n0 < C_GLAA);
;                 if (r128 || r64) {
;                   float4 cs;
;                   float sc;
;                   if (r128) {
;                     cs = *(const float4*)(g.w + ((size_t)tok * 64 + ((n0 & 127) >> 1)) * 2);
;                     sc = (n0 < C_HGQ) ? 0.08838834764831845f : 1.0f;
;                   } else {
;                     cs = *(const float4*)(g.hout + ((size_t)tok * 32 + ((n0 & 63) >> 1)) * 2);
;                     sc = (n0 < C_IDXK) ? 0.125f : 1.0f;
;                   }
;                   o0 = (a[0] * cs.x - a[1] * cs.y) * sc; o1 = (a[1] * cs.x + a[0] * cs.y) * sc;
;                   o2 = (a[2] * cs.z - a[3] * cs.w) * sc; o3 = (a[3] * cs.z + a[2] * cs.w) * sc;
;                 }
;                 uint2 o; o.x = pack2(o0, o1); o.y = pack2(o2, o3);
;                 EMIT_BF16(g.ldo, o);
.LBB0_712:
	s_movk_i32 s0, 0x5c00
	v_cmp_gt_i32_e32 vcc, s0, v160
	s_and_saveexec_b64 s[2:3], vcc
	s_xor_b64 s[2:3], exec, s[2:3]
	s_cbranch_execz .LBB0_720
	v_add_u32_e32 v2, 0xffffa780, v138
	v_cmp_gt_u32_e32 vcc, s77, v2
	s_or_b64 s[60:61], s[54:55], vcc
	s_and_saveexec_b64 s[10:11], s[60:61]
	s_cbranch_execz .LBB0_719
	s_and_saveexec_b64 s[60:61], s[52:53]
	s_xor_b64 s[60:61], exec, s[60:61]
	v_lshlrev_b32_e32 v2, 2, v0
	s_movk_i32 s0, 0x5b00
	v_lshl_add_u64 v[80:81], v[112:113], 0, v[2:3]
	v_cmp_gt_u32_e32 vcc, s0, v120
	v_lshl_add_u64 v[80:81], v[80:81], 0, 64
	s_nop 0
	v_cndmask_b32_e32 v2, 1.0, v166, vcc
	s_andn2_saveexec_b64 s[60:61], s[60:61]
	v_and_b32_e32 v2, 0x5c, v160
	v_lshlrev_b32_e32 v2, 2, v2
	v_cmp_gt_i32_e32 vcc, s81, v160
	v_lshl_add_u64 v[80:81], v[110:111], 0, v[2:3]
	s_nop 0
	v_cndmask_b32_e32 v2, 1.0, v167, vcc
	s_or_b64 exec, exec, s[60:61]
	s_nop 0
	flat_load_dwordx4 v[80:83], v[80:81]
	s_waitcnt vmcnt(0) lgkmcnt(0)
	v_pk_mul_f32 v[84:85], v[76:77], v[80:81] op_sel:[1,1] op_sel_hi:[1,0]
	s_nop 0
	v_pk_fma_f32 v[92:93], v[76:77], v[80:81], v[84:85] neg_lo:[0,0,1] neg_hi:[0,0,1]
	v_pk_fma_f32 v[76:77], v[76:77], v[80:81], v[84:85] op_sel_hi:[0,1,1]
	v_mov_b32_e32 v80, v79
	v_pk_mul_f32 v[80:81], v[80:81], v[82:83] op_sel:[0,1] op_sel_hi:[0,0]
	v_pk_fma_f32 v[84:85], v[78:79], v[82:83], v[80:81] neg_lo:[0,0,1] neg_hi:[0,0,1]
	v_pk_fma_f32 v[78:79], v[78:79], v[82:83], v[80:81] op_sel_hi:[0,1,1]
	v_mov_b32_e32 v93, v77
	v_mov_b32_e32 v85, v79
	v_pk_mul_f32 v[76:77], v[2:3], v[92:93] op_sel_hi:[0,1]
	v_pk_mul_f32 v[78:79], v[2:3], v[84:85] op_sel_hi:[0,1]
.LBB0_719:
	s_or_b64 exec, exec, s[10:11]
	v_cvt_pk_bf16_f32 v79, v78, v79
	v_cvt_pk_bf16_f32 v78, v76, v77
	v_mov_b32_e32 v76, v88
	v_mov_b32_e32 v77, v90
	v_ashrrev_i32_e32 v117, 31, v116
	v_permlane16_swap_b32_e32 v76, v78
	v_permlane16_swap_b32_e32 v77, v79
	v_lshl_add_u64 v[80:81], v[116:117], 1, v[118:119]
	s_nop 0
	flat_store_dwordx4 v[80:81], v[76:79] offset:32
.LBB0_720:
	s_andn2_saveexec_b64 s[2:3], s[2:3]
	s_cbranch_execz .LBB0_722
	v_add_u32_e32 v2, 0xffffa400, v160
	v_lshlrev_b64 v[84:85], 2, v[2:3]
	v_lshl_add_u64 v[80:81], s[26:27], 0, v[84:85]
	s_nop 0
	flat_load_dwordx4 v[80:83], v[80:81]
	s_mov_b32 s0, 0x3d800000
	v_lshl_add_u64 v[84:85], v[102:103], 0, v[84:85]
	s_waitcnt vmcnt(0) lgkmcnt(0)
	v_add_f32_e32 v2, v76, v80
	v_min_f32_e32 v76, 0, v2
	v_mul_f32_e64 v2, |v2|, s82
	v_exp_f32_e32 v2, v2
	v_add_f32_e32 v80, v77, v81
	v_add_f32_e32 v81, v78, v82
	v_add_f32_e32 v83, v79, v83
	v_add_f32_e32 v2, 1.0, v2
	v_cmp_gt_f32_e32 vcc, s83, v2
	s_nop 1
	v_cndmask_b32_e64 v77, 0, 32, vcc
	v_ldexp_f32 v2, v2, v77
	v_log_f32_e32 v2, v2
	s_nop 0
	v_mul_f32_e32 v77, 0x3f317217, v2
	v_fma_f32 v77, v2, s86, -v77
	v_fmac_f32_e32 v77, 0x3377d1cf, v2
	v_fmac_f32_e32 v77, 0x3f317217, v2
	v_cmp_lt_f32_e64 s[10:11], |v2|, s87
	s_nop 1
	v_cndmask_b32_e64 v2, v2, v77, s[10:11]
	v_cndmask_b32_e32 v77, 0, v165, vcc
	v_sub_f32_e32 v78, v2, v77
	v_mul_f32_e64 v2, |v80|, s82
	v_exp_f32_e32 v2, v2
	v_min_f32_e32 v77, 0, v80
	v_min_f32_e32 v80, 0, v81
	v_add_f32_e32 v2, 1.0, v2
	v_cmp_gt_f32_e32 vcc, s83, v2
	s_nop 1
	v_cndmask_b32_e64 v79, 0, 32, vcc
	v_ldexp_f32 v2, v2, v79
	v_log_f32_e32 v2, v2
	s_nop 0
	v_mul_f32_e32 v79, 0x3f317217, v2
	v_fma_f32 v79, v2, s86, -v79
	v_fmac_f32_e32 v79, 0x3377d1cf, v2
	v_fmac_f32_e32 v79, 0x3f317217, v2
	v_cmp_lt_f32_e64 s[10:11], |v2|, s87
	s_nop 1
	v_cndmask_b32_e64 v2, v2, v79, s[10:11]
	v_cndmask_b32_e32 v79, 0, v165, vcc
	v_sub_f32_e32 v79, v2, v79
	v_mul_f32_e64 v2, |v81|, s82
	v_exp_f32_e32 v2, v2
	v_pk_add_f32 v[76:77], v[76:77], v[78:79] neg_lo:[0,1] neg_hi:[0,1]
	v_add_f32_e32 v2, 1.0, v2
	v_cmp_gt_f32_e32 vcc, s83, v2
	v_pk_mul_f32 v[76:77], v[76:77], s[0:1] op_sel_hi:[1,0]
	s_nop 0
	v_cndmask_b32_e64 v81, 0, 32, vcc
	v_ldexp_f32 v2, v2, v81
	v_log_f32_e32 v2, v2
	s_nop 0
	v_mul_f32_e32 v81, 0x3f317217, v2
	v_fma_f32 v81, v2, s86, -v81
	v_fmac_f32_e32 v81, 0x3377d1cf, v2
	v_fmac_f32_e32 v81, 0x3f317217, v2
	v_cmp_lt_f32_e64 s[10:11], |v2|, s87
	s_nop 1
	v_cndmask_b32_e64 v2, v2, v81, s[10:11]
	v_cndmask_b32_e32 v81, 0, v165, vcc
	v_sub_f32_e32 v82, v2, v81
	v_mul_f32_e64 v2, |v83|, s82
	v_exp_f32_e32 v2, v2
	v_min_f32_e32 v81, 0, v83
	v_add_f32_e32 v2, 1.0, v2
	v_cmp_gt_f32_e32 vcc, s83, v2
	s_nop 1
	v_cndmask_b32_e64 v83, 0, 32, vcc
	v_ldexp_f32 v2, v2, v83
	v_log_f32_e32 v2, v2
	s_nop 0
	v_mul_f32_e32 v83, 0x3f317217, v2
	v_fma_f32 v83, v2, s86, -v83
	v_fmac_f32_e32 v83, 0x3377d1cf, v2
	v_fmac_f32_e32 v83, 0x3f317217, v2
	v_cmp_lt_f32_e64 s[10:11], |v2|, s87
	s_nop 1
	v_cndmask_b32_e64 v2, v2, v83, s[10:11]
	v_cndmask_b32_e32 v83, 0, v165, vcc
	v_sub_f32_e32 v83, v2, v83
	v_pk_add_f32 v[78:79], v[80:81], v[82:83] neg_lo:[0,1] neg_hi:[0,1]
	s_nop 0
	v_pk_mul_f32 v[78:79], v[78:79], s[0:1] op_sel_hi:[1,0]
	flat_store_dwordx4 v[84:85], v[76:79]

; __device__ __forceinline__ void gemm_phase(const Ctx& cx, const GemmArgs& g_, char* shm) {
;     ...
;             } else if (g.epi == EPI_RES) {
;               const float4 hv = *(const float4*)(g.hin + (size_t)tok * DM + n0);
;               const float h0 = hv.x + a[0], h1 = hv.y + a[1], h2 = hv.z + a[2], h3 = hv.w + a[3];
;               *(float4*)(g.hout + (size_t)tok * DM + n0) = make_float4(h0, h1, h2, h3);
;               if (g.w != nullptr) {
;                 const float4 nw = *(const float4*)(g.w + n0);
;                 uint2 o; o.x = pack2(h0 * nw.x, h1 * nw.y); o.y = pack2(h2 * nw.z, h3 * nw.w);
;                 EMIT_BF16(DM, o);
;                 ssq += h0 * h0 + h1 * h1 + h2 * h2 + h3 * h3;
;               }
.LBB0_737:
	s_and_b64 vcc, exec, s[60:61]
	v_mov_b32_e32 v84, v86
	s_cbranch_vccz .LBB0_740
	v_lshl_add_u64 v[82:83], v[120:121], 0, v[0:1]
	v_lshlrev_b64 v[76:77], 2, v[82:83]
	v_lshl_add_u64 v[78:79], v[106:107], 0, v[76:77]
	s_nop 0
	flat_load_dwordx4 v[78:81], v[78:79] offset:128
	v_lshl_add_u64 v[76:77], v[104:105], 0, v[76:77]
	s_andn2_b64 vcc, exec, s[42:43]
	v_mov_b32_e32 v84, v86
	s_waitcnt vmcnt(0) lgkmcnt(0)
	v_pk_add_f32 v[78:79], v[72:73], v[78:79]
	v_pk_add_f32 v[80:81], v[74:75], v[80:81]
	flat_store_dwordx4 v[76:77], v[78:81] offset:128
	v_mov_b32_e32 v77, v90
	v_mov_b32_e32 v76, v88
	s_cbranch_vccnz .LBB0_740
	v_lshl_add_u64 v[76:77], v[82:83], 2, s[30:31]
	global_load_dwordx4 v[82:85], v[76:77], off offset:128
	v_pk_mul_f32 v[76:77], v[78:79], v[78:79]
	v_pk_mul_f32 v[92:93], v[80:81], v[80:81]
	v_add_f32_e32 v2, v76, v77
	v_add_f32_e32 v2, v2, v92
	v_add_f32_e32 v2, v2, v93
	s_waitcnt vmcnt(0)
	v_pk_mul_f32 v[76:77], v[80:81], v[84:85]
	v_pk_mul_f32 v[78:79], v[78:79], v[82:83]
	v_cvt_pk_bf16_f32 v77, v76, v77
	v_cvt_pk_bf16_f32 v76, v78, v79
	v_add_f32_e32 v84, v86, v2

; __device__ __forceinline__ float b2f(u16 b) { return __uint_as_float(((uint32_t)b) << 16); }
; __device__ __forceinline__ float sigmoidf_(float x) { return 1.0f / (1.0f + __expf(-x)); }
; __device__ __forceinline__ void gemm_phase(const Ctx& cx, const GemmArgs& g_, char* shm) {
;     ...
;               const uint2 gv = *(const uint2*)(g.gate + (size_t)tok * NP + n0);
;               float v0 = sigmoidf_(b2f((u16)(gv.x & 0xffff))) * a[0], v1 = sigmoidf_(b2f((u16)(gv.x >> 16))) * a[1];
;               float v2 = sigmoidf_(b2f((u16)(gv.y & 0xffff))) * a[2], v3 = sigmoidf_(b2f((u16)(gv.y >> 16))) * a[3];
;               uint2* mp = (uint2*)(g.outb + (size_t)tok * DM + n0);
;               if (g.epi != EPI_BR0) {
;                 const uint2 pv = *mp;
;                 v0 += b2f((u16)(pv.x & 0xffff)); v1 += b2f((u16)(pv.x >> 16));
;                 v2 += b2f((u16)(pv.y & 0xffff)); v3 += b2f((u16)(pv.y >> 16));
;               }
.LBB0_742:
	v_lshl_add_u64 v[76:77], v[120:121], 0, v[0:1]
	v_lshlrev_b64 v[78:79], 1, v[76:77]
	v_lshl_add_u64 v[76:77], v[114:115], 0, v[78:79]
	s_nop 0
	flat_load_dwordx2 v[80:81], v[76:77] offset:64
	v_lshl_add_u64 v[78:79], v[100:101], 0, v[78:79]
	s_waitcnt vmcnt(0) lgkmcnt(0)
	v_lshlrev_b32_e32 v2, 16, v80
	v_mul_f32_e32 v2, 0xbfb8aa3b, v2
	v_exp_f32_e32 v76, v2
	v_and_b32_e32 v2, 0xffff0000, v80
	v_mul_f32_e32 v2, 0xbfb8aa3b, v2
	v_exp_f32_e32 v77, v2
	s_nop 0
	v_pk_add_f32 v[76:77], v[76:77], 1.0 op_sel_hi:[1,0]
	s_nop 0
	v_div_scale_f32 v2, s[2:3], v77, v77, 1.0
	v_rcp_f32_e32 v80, v2
	s_nop 0
	v_fma_f32 v82, -v2, v80, 1.0
	v_fmac_f32_e32 v80, v82, v80
	v_div_scale_f32 v82, vcc, 1.0, v77, 1.0
	v_mul_f32_e32 v83, v82, v80
	v_fma_f32 v84, -v2, v83, v82
	v_fmac_f32_e32 v83, v84, v80
	v_fma_f32 v2, -v2, v83, v82
	v_div_fmas_f32 v2, v2, v80, v83
	v_div_fixup_f32 v77, v2, v77, 1.0
	v_div_scale_f32 v2, s[2:3], v76, v76, 1.0
	v_rcp_f32_e32 v80, v2
	s_nop 0
	v_fma_f32 v82, -v2, v80, 1.0
	v_fmac_f32_e32 v80, v82, v80
	v_div_scale_f32 v82, vcc, 1.0, v76, 1.0
	v_mul_f32_e32 v83, v82, v80
	v_fma_f32 v84, -v2, v83, v82
	v_fmac_f32_e32 v83, v84, v80
	v_fma_f32 v2, -v2, v83, v82
	v_div_fmas_f32 v2, v2, v80, v83
	v_div_fixup_f32 v76, v2, v76, 1.0
	v_lshlrev_b32_e32 v2, 16, v81
	v_mul_f32_e32 v2, 0xbfb8aa3b, v2
	v_exp_f32_e32 v80, v2
	v_and_b32_e32 v2, 0xffff0000, v81
	v_mul_f32_e32 v2, 0xbfb8aa3b, v2
	v_exp_f32_e32 v81, v2
	v_pk_mul_f32 v[76:77], v[72:73], v[76:77]
	v_pk_add_f32 v[80:81], v[80:81], 1.0 op_sel_hi:[1,0]
	s_nop 0
	v_div_scale_f32 v2, s[2:3], v81, v81, 1.0
	v_rcp_f32_e32 v82, v2
	s_nop 0
	v_fma_f32 v83, -v2, v82, 1.0
	v_fmac_f32_e32 v82, v83, v82
	v_div_scale_f32 v83, vcc, 1.0, v81, 1.0
	v_mul_f32_e32 v84, v83, v82
	v_fma_f32 v85, -v2, v84, v83
	v_fmac_f32_e32 v84, v85, v82
	v_fma_f32 v2, -v2, v84, v83
	v_div_fmas_f32 v2, v2, v82, v84
	v_div_fixup_f32 v81, v2, v81, 1.0
	v_div_scale_f32 v2, s[2:3], v80, v80, 1.0
	v_rcp_f32_e32 v82, v2
	s_nop 0
	v_fma_f32 v83, -v2, v82, 1.0
	v_fmac_f32_e32 v82, v83, v82
	v_div_scale_f32 v83, vcc, 1.0, v80, 1.0
	v_mul_f32_e32 v84, v83, v82
	v_fma_f32 v85, -v2, v84, v83
	v_fmac_f32_e32 v84, v85, v82
	v_fma_f32 v2, -v2, v84, v83
	v_div_fmas_f32 v2, v2, v82, v84
	v_div_fixup_f32 v80, v2, v80, 1.0
	v_pk_mul_f32 v[80:81], v[74:75], v[80:81]
	s_and_b64 vcc, exec, s[4:5]
	s_cbranch_vccnz .LBB0_744
	flat_load_dwordx2 v[82:83], v[78:79] offset:64
	s_waitcnt vmcnt(0) lgkmcnt(0)
	v_lshlrev_b32_e32 v84, 16, v82
	v_and_b32_e32 v85, 0xffff0000, v82
	v_lshlrev_b32_e32 v82, 16, v83
	v_and_b32_e32 v83, 0xffff0000, v83
	v_pk_add_f32 v[76:77], v[76:77], v[84:85]
	v_pk_add_f32 v[80:81], v[80:81], v[82:83]

; __device__ __forceinline__ void gemm_phase(const Ctx& cx, const GemmArgs& g_, char* shm) {
;     ...
;                 const bool r128 = (n0 >= C_DSAQ && n0 < C_HGQ) || (n0 >= C_DSAK && n0 < C_DSAV);
;                 const bool r64 = (n0 >= C_IDXQ && n0 < C_GLAA);
;                 if (r128 || r64) {
;                   float4 cs;
;                   float sc;
;                   if (r128) {
;                     cs = *(const float4*)(g.w + ((size_t)tok * 64 + ((n0 & 127) >> 1)) * 2);
;                     sc = (n0 < C_HGQ) ? 0.08838834764831845f : 1.0f;
;                   } else {
;                     cs = *(const float4*)(g.hout + ((size_t)tok * 32 + ((n0 & 63) >> 1)) * 2);
;                     sc = (n0 < C_IDXK) ? 0.125f : 1.0f;
;                   }
;                   o0 = (a[0] * cs.x - a[1] * cs.y) * sc; o1 = (a[1] * cs.x + a[0] * cs.y) * sc;
;                   o2 = (a[2] * cs.z - a[3] * cs.w) * sc; o3 = (a[3] * cs.z + a[2] * cs.w) * sc;
;                 }
.LBB0_745:
	s_movk_i32 s0, 0x5c00
	v_cmp_gt_i32_e32 vcc, s0, v131
	s_and_saveexec_b64 s[2:3], vcc
	s_xor_b64 s[2:3], exec, s[2:3]
	s_cbranch_execz .LBB0_753
	v_add_u32_e32 v2, 0xffffa780, v138
	v_cmp_gt_u32_e32 vcc, s77, v2
	s_or_b64 s[60:61], s[54:55], vcc
	s_and_saveexec_b64 s[10:11], s[60:61]
	s_cbranch_execz .LBB0_752
	s_and_saveexec_b64 s[60:61], s[52:53]
	s_xor_b64 s[60:61], exec, s[60:61]
	v_lshlrev_b32_e32 v2, 2, v0
	s_movk_i32 s0, 0x5b00
	v_lshl_add_u64 v[76:77], v[112:113], 0, v[2:3]
	v_cmp_gt_u32_e32 vcc, s0, v120
	v_lshl_add_u64 v[76:77], v[76:77], 0, s[70:71]
	s_nop 0
	v_cndmask_b32_e32 v2, 1.0, v166, vcc
	s_andn2_saveexec_b64 s[60:61], s[60:61]
	v_and_b32_e32 v2, 0x6c, v131
	v_lshlrev_b32_e32 v2, 2, v2
	v_cmp_gt_i32_e32 vcc, s81, v131
	v_lshl_add_u64 v[76:77], v[110:111], 0, v[2:3]
	s_nop 0
	v_cndmask_b32_e32 v2, 1.0, v167, vcc
	s_or_b64 exec, exec, s[60:61]
	s_nop 0
	flat_load_dwordx4 v[76:79], v[76:77]
	s_waitcnt vmcnt(0) lgkmcnt(0)
	v_pk_mul_f32 v[80:81], v[72:73], v[76:77] op_sel:[1,1] op_sel_hi:[1,0]
	s_nop 0
	v_pk_fma_f32 v[82:83], v[72:73], v[76:77], v[80:81] neg_lo:[0,0,1] neg_hi:[0,0,1]
	v_pk_fma_f32 v[72:73], v[72:73], v[76:77], v[80:81] op_sel_hi:[0,1,1]
	v_mov_b32_e32 v76, v75
	v_pk_mul_f32 v[76:77], v[76:77], v[78:79] op_sel:[0,1] op_sel_hi:[0,0]
	v_pk_fma_f32 v[80:81], v[74:75], v[78:79], v[76:77] neg_lo:[0,0,1] neg_hi:[0,0,1]
	v_pk_fma_f32 v[74:75], v[74:75], v[78:79], v[76:77] op_sel_hi:[0,1,1]
	v_mov_b32_e32 v83, v73
	v_mov_b32_e32 v81, v75
	v_pk_mul_f32 v[72:73], v[2:3], v[82:83] op_sel_hi:[0,1]
	v_pk_mul_f32 v[74:75], v[2:3], v[80:81] op_sel_hi:[0,1]

; __device__ __forceinline__ void gemm_phase(const Ctx& cx, const GemmArgs& g_, char* shm) {
;     ...
;               if (n0 >= C_GLAX) {
;                 const int i = n0 - C_GLAX;
;                 const float4 b4 = *(const float4*)(g.hin + i);
;                 float xs[4] = {a[0] + b4.x, a[1] + b4.y, a[2] + b4.z, a[3] + b4.w};
; #pragma unroll
;                 for (int j = 0; j < 4; ++j)
;                   xs[j] = (fminf(xs[j], 0.f) - __logf(1.0f + __expf(-fabsf(xs[j])))) * (1.0f / 16.0f);
;                 *(float4*)(g.f32buf + (size_t)tok * 1024 + i) = make_float4(xs[0], xs[1], xs[2], xs[3]);
.LBB0_753:
	s_andn2_saveexec_b64 s[2:3], s[2:3]
	s_cbranch_execz .LBB0_755
	v_add_u32_e32 v2, 0xffffa400, v131
	v_lshlrev_b64 v[80:81], 2, v[2:3]
	v_lshl_add_u64 v[76:77], s[26:27], 0, v[80:81]
	s_nop 0
	flat_load_dwordx4 v[76:79], v[76:77]
	s_mov_b32 s0, 0x3d800000
	v_lshl_add_u64 v[80:81], v[102:103], 0, v[80:81]
	s_waitcnt vmcnt(0) lgkmcnt(0)
	v_add_f32_e32 v2, v72, v76
	v_min_f32_e32 v72, 0, v2
	v_mul_f32_e64 v2, |v2|, s82
	v_exp_f32_e32 v2, v2
	v_add_f32_e32 v76, v73, v77
	v_add_f32_e32 v77, v74, v78
	v_add_f32_e32 v79, v75, v79
	v_add_f32_e32 v2, 1.0, v2
	v_cmp_gt_f32_e32 vcc, s83, v2
	s_nop 1
	v_cndmask_b32_e64 v73, 0, 32, vcc
	v_ldexp_f32 v2, v2, v73
	v_log_f32_e32 v2, v2
	s_nop 0
	v_mul_f32_e32 v73, 0x3f317217, v2
	v_fma_f32 v73, v2, s86, -v73
	v_fmac_f32_e32 v73, 0x3377d1cf, v2
	v_fmac_f32_e32 v73, 0x3f317217, v2
	v_cmp_lt_f32_e64 s[10:11], |v2|, s87
	s_nop 1
	v_cndmask_b32_e64 v2, v2, v73, s[10:11]
	v_cndmask_b32_e32 v73, 0, v165, vcc
	v_sub_f32_e32 v74, v2, v73
	v_mul_f32_e64 v2, |v76|, s82
	v_exp_f32_e32 v2, v2
	v_min_f32_e32 v73, 0, v76
	v_min_f32_e32 v76, 0, v77
	v_add_f32_e32 v2, 1.0, v2
	v_cmp_gt_f32_e32 vcc, s83, v2
	s_nop 1
	v_cndmask_b32_e64 v75, 0, 32, vcc
	v_ldexp_f32 v2, v2, v75
	v_log_f32_e32 v2, v2
	s_nop 0
	v_mul_f32_e32 v75, 0x3f317217, v2
	v_fma_f32 v75, v2, s86, -v75
	v_fmac_f32_e32 v75, 0x3377d1cf, v2
	v_fmac_f32_e32 v75, 0x3f317217, v2
	v_cmp_lt_f32_e64 s[10:11], |v2|, s87
	s_nop 1
	v_cndmask_b32_e64 v2, v2, v75, s[10:11]
	v_cndmask_b32_e32 v75, 0, v165, vcc
	v_sub_f32_e32 v75, v2, v75
	v_mul_f32_e64 v2, |v77|, s82
	v_exp_f32_e32 v2, v2
	v_pk_add_f32 v[72:73], v[72:73], v[74:75] neg_lo:[0,1] neg_hi:[0,1]
	v_add_f32_e32 v2, 1.0, v2
	v_cmp_gt_f32_e32 vcc, s83, v2
	v_pk_mul_f32 v[72:73], v[72:73], s[0:1] op_sel_hi:[1,0]
	s_nop 0
	v_cndmask_b32_e64 v77, 0, 32, vcc
	v_ldexp_f32 v2, v2, v77
	v_log_f32_e32 v2, v2
	s_nop 0
	v_mul_f32_e32 v77, 0x3f317217, v2
	v_fma_f32 v77, v2, s86, -v77
	v_fmac_f32_e32 v77, 0x3377d1cf, v2
	v_fmac_f32_e32 v77, 0x3f317217, v2
	v_cmp_lt_f32_e64 s[10:11], |v2|, s87
	s_nop 1
	v_cndmask_b32_e64 v2, v2, v77, s[10:11]
	v_cndmask_b32_e32 v77, 0, v165, vcc
	v_sub_f32_e32 v78, v2, v77
	v_mul_f32_e64 v2, |v79|, s82
	v_exp_f32_e32 v2, v2
	v_min_f32_e32 v77, 0, v79
	v_add_f32_e32 v2, 1.0, v2
	v_cmp_gt_f32_e32 vcc, s83, v2
	s_nop 1
	v_cndmask_b32_e64 v79, 0, 32, vcc
	v_ldexp_f32 v2, v2, v79
	v_log_f32_e32 v2, v2
	s_nop 0
	v_mul_f32_e32 v79, 0x3f317217, v2
	v_fma_f32 v79, v2, s86, -v79
	v_fmac_f32_e32 v79, 0x3377d1cf, v2
	v_fmac_f32_e32 v79, 0x3f317217, v2
	v_cmp_lt_f32_e64 s[10:11], |v2|, s87
	s_nop 1
	v_cndmask_b32_e64 v2, v2, v79, s[10:11]
	v_cndmask_b32_e32 v79, 0, v165, vcc
	v_sub_f32_e32 v79, v2, v79
	v_pk_add_f32 v[74:75], v[76:77], v[78:79] neg_lo:[0,1] neg_hi:[0,1]
	v_mov_b32_e32 v77, v90
	v_pk_mul_f32 v[74:75], v[74:75], s[0:1] op_sel_hi:[1,0]
	v_mov_b32_e32 v76, v88
	flat_store_dwordx4 v[80:81], v[72:75]

; __device__ __forceinline__ void gemm_phase(const Ctx& cx, const GemmArgs& g_, char* shm) {
;     ...
;             } else if (g.epi == EPI_RELU2) {
;               float r0 = fmaxf(a[0], 0.f), r1 = fmaxf(a[1], 0.f), r2 = fmaxf(a[2], 0.f), r3 = fmaxf(a[3], 0.f);
;               uint2 o; o.x = pack2(r0 * r0, r1 * r1); o.y = pack2(r2 * r2, r3 * r3);
;               EMIT_BF16(g.ldo, o);
.LBB0_768:
	s_cmp_gt_i32 s38, 4
	s_cbranch_scc0 .LBB0_772
	s_cmp_eq_u32 s38, 5
	s_mov_b64 s[10:11], -1
	s_cbranch_scc0 .LBB0_771
	v_max_f32_e32 v2, v70, v70
	v_max_f32_e32 v72, 0, v2
	v_max_f32_e32 v2, v71, v71
	v_max_f32_e32 v73, 0, v2
	v_pk_mul_f32 v[72:73], v[72:73], v[72:73]
	v_max_f32_e32 v2, v68, v68
	v_cvt_pk_bf16_f32 v75, v72, v73
	v_max_f32_e32 v72, 0, v2
	v_max_f32_e32 v2, v69, v69
	v_max_f32_e32 v73, 0, v2
	v_pk_mul_f32 v[72:73], v[72:73], v[72:73]
	v_ashrrev_i32_e32 v117, 31, v116
	v_cvt_pk_bf16_f32 v74, v72, v73
	v_mov_b32_e32 v72, v76
	v_mov_b32_e32 v73, v77
	s_nop 0
	v_permlane16_swap_b32_e32 v72, v74
	v_permlane16_swap_b32_e32 v73, v75
	v_lshl_add_u64 v[78:79], v[116:117], 1, v[118:119]
	s_nop 0
	flat_store_dwordx4 v[78:79], v[72:75] offset:96
	s_mov_b64 s[10:11], 0

; __device__ __forceinline__ void gemm_phase(const Ctx& cx, const GemmArgs& g_, char* shm) {
;     ...
;             } else if (g.epi == EPI_RES) {
;               const float4 hv = *(const float4*)(g.hin + (size_t)tok * DM + n0);
;               const float h0 = hv.x + a[0], h1 = hv.y + a[1], h2 = hv.z + a[2], h3 = hv.w + a[3];
;               *(float4*)(g.hout + (size_t)tok * DM + n0) = make_float4(h0, h1, h2, h3);
;               if (g.w != nullptr) {
;                 const float4 nw = *(const float4*)(g.w + n0);
;                 uint2 o; o.x = pack2(h0 * nw.x, h1 * nw.y); o.y = pack2(h2 * nw.z, h3 * nw.w);
;                 EMIT_BF16(DM, o);
;                 ssq += h0 * h0 + h1 * h1 + h2 * h2 + h3 * h3;
;               }
.LBB0_772:
	s_and_b64 vcc, exec, s[60:61]
	v_mov_b32_e32 v2, v84
	s_cbranch_vccz .LBB0_775
	v_lshl_add_u64 v[78:79], v[120:121], 0, v[0:1]
	v_lshlrev_b64 v[80:81], 2, v[78:79]
	v_lshl_add_u64 v[72:73], v[106:107], 0, v[80:81]
	s_nop 0
	flat_load_dwordx4 v[72:75], v[72:73] offset:192
	v_lshl_add_u64 v[80:81], v[104:105], 0, v[80:81]
	s_andn2_b64 vcc, exec, s[42:43]
	v_mov_b32_e32 v2, v84
	s_waitcnt vmcnt(0) lgkmcnt(0)
	v_pk_add_f32 v[72:73], v[68:69], v[72:73]
	v_pk_add_f32 v[74:75], v[70:71], v[74:75]
	flat_store_dwordx4 v[80:81], v[72:75] offset:192
	s_cbranch_vccnz .LBB0_775
	v_lshl_add_u64 v[78:79], v[78:79], 2, s[30:31]
	global_load_dwordx4 v[78:81], v[78:79], off offset:192
	v_ashrrev_i32_e32 v117, 31, v116
	v_lshl_add_u64 v[82:83], v[116:117], 1, v[100:101]
	s_waitcnt vmcnt(0)
	v_pk_mul_f32 v[78:79], v[72:73], v[78:79]
	v_pk_mul_f32 v[72:73], v[72:73], v[72:73]
	v_pk_mul_f32 v[80:81], v[74:75], v[80:81]
	v_pk_mul_f32 v[74:75], v[74:75], v[74:75]
	v_add_f32_e32 v2, v72, v73
	v_cvt_pk_bf16_f32 v81, v80, v81
	v_cvt_pk_bf16_f32 v80, v78, v79
	v_mov_b32_e32 v78, v76
	v_mov_b32_e32 v79, v77
	v_add_f32_e32 v2, v2, v74
	v_permlane16_swap_b32_e32 v78, v80
	v_permlane16_swap_b32_e32 v79, v81
	v_add_f32_e32 v2, v2, v75
	flat_store_dwordx4 v[82:83], v[78:81] offset:96
	v_add_f32_e32 v2, v84, v2

; __device__ __forceinline__ float b2f(u16 b) { return __uint_as_float(((uint32_t)b) << 16); }
; __device__ __forceinline__ float sigmoidf_(float x) { return 1.0f / (1.0f + __expf(-x)); }
; __device__ __forceinline__ void gemm_phase(const Ctx& cx, const GemmArgs& g_, char* shm) {
;     ...
;               const uint2 gv = *(const uint2*)(g.gate + (size_t)tok * NP + n0);
;               float v0 = sigmoidf_(b2f((u16)(gv.x & 0xffff))) * a[0], v1 = sigmoidf_(b2f((u16)(gv.x >> 16))) * a[1];
;               float v2 = sigmoidf_(b2f((u16)(gv.y & 0xffff))) * a[2], v3 = sigmoidf_(b2f((u16)(gv.y >> 16))) * a[3];
;               uint2* mp = (uint2*)(g.outb + (size_t)tok * DM + n0);
;               if (g.epi != EPI_BR0) {
;                 const uint2 pv = *mp;
;                 v0 += b2f((u16)(pv.x & 0xffff)); v1 += b2f((u16)(pv.x >> 16));
;                 v2 += b2f((u16)(pv.y & 0xffff)); v3 += b2f((u16)(pv.y >> 16));
;               }
.LBB0_777:
	v_lshl_add_u64 v[72:73], v[120:121], 0, v[0:1]
	v_lshlrev_b64 v[74:75], 1, v[72:73]
	v_lshl_add_u64 v[72:73], v[114:115], 0, v[74:75]
	s_nop 0
	flat_load_dwordx2 v[78:79], v[72:73] offset:96
	v_lshl_add_u64 v[74:75], v[100:101], 0, v[74:75]
	s_waitcnt vmcnt(0) lgkmcnt(0)
	v_lshlrev_b32_e32 v2, 16, v78
	v_mul_f32_e32 v2, 0xbfb8aa3b, v2
	v_exp_f32_e32 v72, v2
	v_and_b32_e32 v2, 0xffff0000, v78
	v_mul_f32_e32 v2, 0xbfb8aa3b, v2
	v_exp_f32_e32 v73, v2
	s_nop 0
	v_pk_add_f32 v[72:73], v[72:73], 1.0 op_sel_hi:[1,0]
	s_nop 0
	v_div_scale_f32 v2, s[2:3], v73, v73, 1.0
	v_rcp_f32_e32 v78, v2
	s_nop 0
	v_fma_f32 v80, -v2, v78, 1.0
	v_fmac_f32_e32 v78, v80, v78
	v_div_scale_f32 v80, vcc, 1.0, v73, 1.0
	v_mul_f32_e32 v81, v80, v78
	v_fma_f32 v82, -v2, v81, v80
	v_fmac_f32_e32 v81, v82, v78
	v_fma_f32 v2, -v2, v81, v80
	v_div_fmas_f32 v2, v2, v78, v81
	v_div_fixup_f32 v73, v2, v73, 1.0
	v_div_scale_f32 v2, s[2:3], v72, v72, 1.0
	v_rcp_f32_e32 v78, v2
	s_nop 0
	v_fma_f32 v80, -v2, v78, 1.0
	v_fmac_f32_e32 v78, v80, v78
	v_div_scale_f32 v80, vcc, 1.0, v72, 1.0
	v_mul_f32_e32 v81, v80, v78
	v_fma_f32 v82, -v2, v81, v80
	v_fmac_f32_e32 v81, v82, v78
	v_fma_f32 v2, -v2, v81, v80
	v_div_fmas_f32 v2, v2, v78, v81
	v_div_fixup_f32 v72, v2, v72, 1.0
	v_lshlrev_b32_e32 v2, 16, v79
	v_mul_f32_e32 v2, 0xbfb8aa3b, v2
	v_exp_f32_e32 v78, v2
	v_and_b32_e32 v2, 0xffff0000, v79
	v_mul_f32_e32 v2, 0xbfb8aa3b, v2
	v_exp_f32_e32 v79, v2
	v_pk_mul_f32 v[72:73], v[68:69], v[72:73]
	v_pk_add_f32 v[78:79], v[78:79], 1.0 op_sel_hi:[1,0]
	s_nop 0
	v_div_scale_f32 v2, s[2:3], v79, v79, 1.0
	v_rcp_f32_e32 v80, v2
	s_nop 0
	v_fma_f32 v81, -v2, v80, 1.0
	v_fmac_f32_e32 v80, v81, v80
	v_div_scale_f32 v81, vcc, 1.0, v79, 1.0
	v_mul_f32_e32 v82, v81, v80
	v_fma_f32 v83, -v2, v82, v81
	v_fmac_f32_e32 v82, v83, v80
	v_fma_f32 v2, -v2, v82, v81
	v_div_fmas_f32 v2, v2, v80, v82
	v_div_fixup_f32 v79, v2, v79, 1.0
	v_div_scale_f32 v2, s[2:3], v78, v78, 1.0
	v_rcp_f32_e32 v80, v2
	s_nop 0
	v_fma_f32 v81, -v2, v80, 1.0
	v_fmac_f32_e32 v80, v81, v80
	v_div_scale_f32 v81, vcc, 1.0, v78, 1.0
	v_mul_f32_e32 v82, v81, v80
	v_fma_f32 v83, -v2, v82, v81
	v_fmac_f32_e32 v82, v83, v80
	v_fma_f32 v2, -v2, v82, v81
	v_div_fmas_f32 v2, v2, v80, v82
	v_div_fixup_f32 v78, v2, v78, 1.0
	v_pk_mul_f32 v[78:79], v[70:71], v[78:79]
	s_and_b64 vcc, exec, s[4:5]
	s_cbranch_vccnz .LBB0_779
	flat_load_dwordx2 v[80:81], v[74:75] offset:96
	s_waitcnt vmcnt(0) lgkmcnt(0)
	v_lshlrev_b32_e32 v82, 16, v80
	v_and_b32_e32 v83, 0xffff0000, v80
	v_lshlrev_b32_e32 v80, 16, v81
	v_and_b32_e32 v81, 0xffff0000, v81
	v_pk_add_f32 v[72:73], v[72:73], v[82:83]
	v_pk_add_f32 v[78:79], v[78:79], v[80:81]

; __device__ __forceinline__ void gemm_phase(const Ctx& cx, const GemmArgs& g_, char* shm) {
;     ...
;             const int n0 = brow + ai * 128 + wr * 64 + m * 16 + fq * 4;
;             f32x4 a = acc[ai][bj][m][n];
;             if (g.epi == EPI_PROJ || g.epi == EPI_RELU2) { a[0] *= rs; a[1] *= rs; a[2] *= rs; a[3] *= rs; }
;             if (g.epi == EPI_PROJ) {
;               if (n0 >= C_GLAX) {
;                 const int i = n0 - C_GLAX;
;                 const float4 b4 = *(const float4*)(g.hin + i);
;                 float xs[4] = {a[0] + b4.x, a[1] + b4.y, a[2] + b4.z, a[3] + b4.w};
; #pragma unroll
;                 for (int j = 0; j < 4; ++j)
;                   xs[j] = (fminf(xs[j], 0.f) - __logf(1.0f + __expf(-fabsf(xs[j])))) * (1.0f / 16.0f);
;                 *(float4*)(g.f32buf + (size_t)tok * 1024 + i) = make_float4(xs[0], xs[1], xs[2], xs[3]);
;               } else {
;                 float o0 = a[0], o1 = a[1], o2 = a[2], o3 = a[3];
;                 const bool r128 = (n0 >= C_DSAQ && n0 < C_HGQ) || (n0 >= C_DSAK && n0 < C_DSAV);
;                 const bool r64 = (n0 >= C_IDXQ && n0 < C_GLAA);
;                 if (r128 || r64) {
;                   float4 cs;
;                   float sc;
;                   if (r128) {
;                     cs = *(const float4*)(g.w + ((size_t)tok * 64 + ((n0 & 127) >> 1)) * 2);
;                     sc = (n0 < C_HGQ) ? 0.08838834764831845f : 1.0f;
;                   } else {
;                     cs = *(const float4*)(g.hout + ((size_t)tok * 32 + ((n0 & 63) >> 1)) * 2);
;                     sc = (n0 < C_IDXK) ? 0.125f : 1.0f;
;                   }
;                   o0 = (a[0] * cs.x - a[1] * cs.y) * sc; o1 = (a[1] * cs.x + a[0] * cs.y) * sc;
;                   o2 = (a[2] * cs.z - a[3] * cs.w) * sc; o3 = (a[3] * cs.z + a[2] * cs.w) * sc;
;                 }
;                 uint2 o; o.x = pack2(o0, o1); o.y = pack2(o2, o3);
;                 EMIT_BF16(g.ldo, o);
.LBB0_780:
	s_movk_i32 s0, 0x5c00
	v_cmp_gt_i32_e32 vcc, s0, v130
	s_and_saveexec_b64 s[2:3], vcc
	s_xor_b64 s[2:3], exec, s[2:3]
	s_cbranch_execz .LBB0_788
	v_add_u32_e32 v2, 0xffffa780, v138
	v_cmp_gt_u32_e32 vcc, s77, v2
	s_or_b64 s[60:61], s[54:55], vcc
	s_and_saveexec_b64 s[10:11], s[60:61]
	s_cbranch_execz .LBB0_787
	s_and_saveexec_b64 s[60:61], s[52:53]
	s_xor_b64 s[60:61], exec, s[60:61]
	v_lshlrev_b32_e32 v2, 2, v0
	s_movk_i32 s0, 0x5b00
	v_lshl_add_u64 v[72:73], v[112:113], 0, v[2:3]
	s_mov_b64 s[68:69], 0xc0
	v_cmp_gt_u32_e32 vcc, s0, v120
	v_lshl_add_u64 v[72:73], v[72:73], 0, s[68:69]
	s_nop 0
	v_cndmask_b32_e32 v2, 1.0, v166, vcc
	s_andn2_saveexec_b64 s[60:61], s[60:61]
	v_and_b32_e32 v2, 0x7c, v130
	v_lshlrev_b32_e32 v2, 2, v2
	v_cmp_gt_i32_e32 vcc, s81, v130
	v_lshl_add_u64 v[72:73], v[110:111], 0, v[2:3]
	s_nop 0
	v_cndmask_b32_e32 v2, 1.0, v167, vcc
	s_or_b64 exec, exec, s[60:61]
	s_nop 0
	flat_load_dwordx4 v[72:75], v[72:73]
	s_waitcnt vmcnt(0) lgkmcnt(0)
	v_pk_mul_f32 v[78:79], v[68:69], v[72:73] op_sel:[1,1] op_sel_hi:[1,0]
	s_nop 0
	v_pk_fma_f32 v[80:81], v[68:69], v[72:73], v[78:79] neg_lo:[0,0,1] neg_hi:[0,0,1]
	v_pk_fma_f32 v[68:69], v[68:69], v[72:73], v[78:79] op_sel_hi:[0,1,1]
	v_mov_b32_e32 v72, v71
	v_pk_mul_f32 v[72:73], v[72:73], v[74:75] op_sel:[0,1] op_sel_hi:[0,0]
	v_pk_fma_f32 v[78:79], v[70:71], v[74:75], v[72:73] neg_lo:[0,0,1] neg_hi:[0,0,1]
	v_pk_fma_f32 v[70:71], v[70:71], v[74:75], v[72:73] op_sel_hi:[0,1,1]
	v_mov_b32_e32 v81, v69
	v_mov_b32_e32 v79, v71
	v_pk_mul_f32 v[68:69], v[2:3], v[80:81] op_sel_hi:[0,1]
	v_pk_mul_f32 v[70:71], v[2:3], v[78:79] op_sel_hi:[0,1]
.LBB0_787:
	s_or_b64 exec, exec, s[10:11]
	v_cvt_pk_bf16_f32 v2, v70, v71
	v_cvt_pk_bf16_f32 v70, v68, v69
	s_nop 1
	v_permlane16_swap_b32_e32 v76, v70
	v_permlane16_swap_b32_e32 v77, v2
	v_ashrrev_i32_e32 v117, 31, v116
	v_lshl_add_u64 v[68:69], v[116:117], 1, v[118:119]
	v_mov_b32_e32 v78, v70
	v_mov_b32_e32 v79, v2
	s_nop 0
	flat_store_dwordx4 v[68:69], v[76:79] offset:96
.LBB0_788:
	s_andn2_saveexec_b64 s[2:3], s[2:3]
	s_cbranch_execz .LBB0_790
	v_add_u32_e32 v2, 0xffffa400, v130
	v_lshlrev_b64 v[76:77], 2, v[2:3]
	v_lshl_add_u64 v[72:73], s[26:27], 0, v[76:77]
	s_nop 0
	flat_load_dwordx4 v[72:75], v[72:73]
	s_mov_b32 s0, 0x3d800000
	v_lshl_add_u64 v[76:77], v[102:103], 0, v[76:77]
	s_waitcnt vmcnt(0) lgkmcnt(0)
	v_add_f32_e32 v2, v68, v72
	v_min_f32_e32 v68, 0, v2
	v_mul_f32_e64 v2, |v2|, s82
	v_exp_f32_e32 v2, v2
	v_add_f32_e32 v72, v69, v73
	v_add_f32_e32 v73, v70, v74
	v_add_f32_e32 v75, v71, v75
	v_add_f32_e32 v2, 1.0, v2
	v_cmp_gt_f32_e32 vcc, s83, v2
	s_nop 1
	v_cndmask_b32_e64 v69, 0, 32, vcc
	v_ldexp_f32 v2, v2, v69
	v_log_f32_e32 v2, v2
	s_nop 0
	v_mul_f32_e32 v69, 0x3f317217, v2
	v_fma_f32 v69, v2, s86, -v69
	v_fmac_f32_e32 v69, 0x3377d1cf, v2
	v_fmac_f32_e32 v69, 0x3f317217, v2
	v_cmp_lt_f32_e64 s[10:11], |v2|, s87
	s_nop 1
	v_cndmask_b32_e64 v2, v2, v69, s[10:11]
	v_cndmask_b32_e32 v69, 0, v165, vcc
	v_sub_f32_e32 v70, v2, v69
	v_mul_f32_e64 v2, |v72|, s82
	v_exp_f32_e32 v2, v2
	v_min_f32_e32 v69, 0, v72
	v_min_f32_e32 v72, 0, v73
	v_add_f32_e32 v2, 1.0, v2
	v_cmp_gt_f32_e32 vcc, s83, v2
	s_nop 1
	v_cndmask_b32_e64 v71, 0, 32, vcc
	v_ldexp_f32 v2, v2, v71
	v_log_f32_e32 v2, v2
	s_nop 0
	v_mul_f32_e32 v71, 0x3f317217, v2
	v_fma_f32 v71, v2, s86, -v71
	v_fmac_f32_e32 v71, 0x3377d1cf, v2
	v_fmac_f32_e32 v71, 0x3f317217, v2
	v_cmp_lt_f32_e64 s[10:11], |v2|, s87
	s_nop 1
	v_cndmask_b32_e64 v2, v2, v71, s[10:11]
	v_cndmask_b32_e32 v71, 0, v165, vcc
	v_sub_f32_e32 v71, v2, v71
	v_mul_f32_e64 v2, |v73|, s82
	v_exp_f32_e32 v2, v2
	v_pk_add_f32 v[68:69], v[68:69], v[70:71] neg_lo:[0,1] neg_hi:[0,1]
	v_add_f32_e32 v2, 1.0, v2
	v_cmp_gt_f32_e32 vcc, s83, v2
	v_pk_mul_f32 v[68:69], v[68:69], s[0:1] op_sel_hi:[1,0]
	s_nop 0
	v_cndmask_b32_e64 v73, 0, 32, vcc
	v_ldexp_f32 v2, v2, v73
	v_log_f32_e32 v2, v2
	s_nop 0
	v_mul_f32_e32 v73, 0x3f317217, v2
	v_fma_f32 v73, v2, s86, -v73
	v_fmac_f32_e32 v73, 0x3377d1cf, v2
	v_fmac_f32_e32 v73, 0x3f317217, v2
	v_cmp_lt_f32_e64 s[10:11], |v2|, s87
	s_nop 1
	v_cndmask_b32_e64 v2, v2, v73, s[10:11]
	v_cndmask_b32_e32 v73, 0, v165, vcc
	v_sub_f32_e32 v74, v2, v73
	v_mul_f32_e64 v2, |v75|, s82
	v_exp_f32_e32 v2, v2
	v_min_f32_e32 v73, 0, v75
	v_add_f32_e32 v2, 1.0, v2
	v_cmp_gt_f32_e32 vcc, s83, v2
	s_nop 1
	v_cndmask_b32_e64 v75, 0, 32, vcc
	v_ldexp_f32 v2, v2, v75
	v_log_f32_e32 v2, v2
	s_nop 0
	v_mul_f32_e32 v75, 0x3f317217, v2
	v_fma_f32 v75, v2, s86, -v75
	v_fmac_f32_e32 v75, 0x3377d1cf, v2
	v_fmac_f32_e32 v75, 0x3f317217, v2
	v_cmp_lt_f32_e64 s[10:11], |v2|, s87
	s_nop 1
	v_cndmask_b32_e64 v2, v2, v75, s[10:11]
	v_cndmask_b32_e32 v75, 0, v165, vcc
	v_sub_f32_e32 v75, v2, v75
	v_pk_add_f32 v[70:71], v[72:73], v[74:75] neg_lo:[0,1] neg_hi:[0,1]
	s_nop 0
	v_pk_mul_f32 v[70:71], v[70:71], s[0:1] op_sel_hi:[1,0]
	flat_store_dwordx4 v[76:77], v[68:71]

; __device__ __forceinline__ void gemm_phase(const Ctx& cx, const GemmArgs& g_, char* shm) {
;     ...
;         if (g.epi == EPI_RES && g.w != nullptr) {
;           float v2 = ssq;
;           v2 += shx(lane, v2, 16);
;           v2 += shx(lane, v2, 32);
;           if (fq == 0) __hip_atomic_fetch_add(g.f32buf + tok, v2, __ATOMIC_RELAXED, __HIP_MEMORY_SCOPE_AGENT);
.LBB0_791:
	ds_bpermute_b32 v68, v171, v2
	s_waitcnt lgkmcnt(0)
	v_add_f32_e32 v2, v2, v68
	ds_bpermute_b32 v68, v172, v2
	s_and_saveexec_b64 s[2:3], s[12:13]
	s_cbranch_execz .LBB0_793
	s_waitcnt lgkmcnt(0)
	v_add_f32_e32 v2, v2, v68
	v_lshl_add_u64 v[68:69], v[136:137], 2, s[24:25]
	s_nop 0
	flat_atomic_add_f32 v[68:69], v2 offset:64

; __device__ __forceinline__ void gemm_phase(const Ctx& cx, const GemmArgs& g_, char* shm) {
;     ...
;             } else if (g.epi == EPI_RES) {
;               const float4 hv = *(const float4*)(g.hin + (size_t)tok * DM + n0);
;               const float h0 = hv.x + a[0], h1 = hv.y + a[1], h2 = hv.z + a[2], h3 = hv.w + a[3];
;               *(float4*)(g.hout + (size_t)tok * DM + n0) = make_float4(h0, h1, h2, h3);
;               if (g.w != nullptr) {
;                 const float4 nw = *(const float4*)(g.w + n0);
;                 uint2 o; o.x = pack2(h0 * nw.x, h1 * nw.y); o.y = pack2(h2 * nw.z, h3 * nw.w);
;                 EMIT_BF16(DM, o);
;                 ssq += h0 * h0 + h1 * h1 + h2 * h2 + h3 * h3;
;               }
.LBB0_804:
	v_mov_b32_e32 v89, 0
	s_and_b64 vcc, exec, s[60:61]
	s_cbranch_vccz .LBB0_809
	v_lshlrev_b64 v[78:79], 2, v[140:141]
	v_lshl_add_u64 v[68:69], v[74:75], 0, v[78:79]
	s_nop 0
	flat_load_dwordx4 v[68:71], v[68:69]
	v_lshl_add_u64 v[78:79], v[72:73], 0, v[78:79]
	s_andn2_b64 vcc, exec, s[42:43]
	s_waitcnt vmcnt(0) lgkmcnt(0)
	v_pk_add_f32 v[68:69], v[64:65], v[68:69]
	v_pk_add_f32 v[70:71], v[66:67], v[70:71]
	flat_store_dwordx4 v[78:79], v[68:71]
	s_cbranch_vccnz .LBB0_808
	v_lshl_add_u64 v[78:79], v[140:141], 2, s[30:31]
	global_load_dwordx4 v[78:81], v[78:79], off
	s_waitcnt vmcnt(0)
	v_pk_mul_f32 v[78:79], v[68:69], v[78:79]
	v_pk_mul_f32 v[68:69], v[68:69], v[68:69]
	v_pk_mul_f32 v[80:81], v[70:71], v[80:81]
	v_pk_mul_f32 v[70:71], v[70:71], v[70:71]
	v_add_f32_e32 v2, v68, v69
	v_add_f32_e32 v2, v2, v70
	v_cvt_pk_bf16_f32 v77, v80, v81
	v_cvt_pk_bf16_f32 v88, v78, v79
	v_add_f32_e32 v89, v2, v71
	s_branch .LBB0_809

; __device__ __forceinline__ float b2f(u16 b) { return __uint_as_float(((uint32_t)b) << 16); }
; __device__ __forceinline__ float sigmoidf_(float x) { return 1.0f / (1.0f + __expf(-x)); }
; __device__ __forceinline__ void gemm_phase(const Ctx& cx, const GemmArgs& g_, char* shm) {
;     ...
;         const int tok = bcol + bj * 128 + wc * 32 + n * 16 + fr;
;     ...
;               const uint2 gv = *(const uint2*)(g.gate + (size_t)tok * NP + n0);
;               float v0 = sigmoidf_(b2f((u16)(gv.x & 0xffff))) * a[0], v1 = sigmoidf_(b2f((u16)(gv.x >> 16))) * a[1];
;               float v2 = sigmoidf_(b2f((u16)(gv.y & 0xffff))) * a[2], v3 = sigmoidf_(b2f((u16)(gv.y >> 16))) * a[3];
;               uint2* mp = (uint2*)(g.outb + (size_t)tok * DM + n0);
;               if (g.epi != EPI_BR0) {
;                 const uint2 pv = *mp;
;                 v0 += b2f((u16)(pv.x & 0xffff)); v1 += b2f((u16)(pv.x >> 16));
;                 v2 += b2f((u16)(pv.y & 0xffff)); v3 += b2f((u16)(pv.y >> 16));
;               }
.LBB0_812:
	v_lshlrev_b64 v[70:71], 12, v[84:85]
	v_mov_b64_e32 v[78:79], s[22:23]
	v_lshl_add_u64 v[68:69], s[20:21], 0, v[70:71]
	s_andn2_b64 vcc, exec, s[10:11]
	v_mad_i64_i32 v[82:83], s[10:11], v84, s76, v[78:79]
	s_cbranch_vccnz .LBB0_816
	v_lshlrev_b64 v[80:81], 1, v[140:141]
	v_lshl_add_u64 v[78:79], v[82:83], 0, v[80:81]
	s_nop 0
	flat_load_dwordx2 v[86:87], v[78:79]
	v_lshl_add_u64 v[80:81], v[68:69], 0, v[80:81]
	s_waitcnt vmcnt(0) lgkmcnt(0)
	v_lshlrev_b32_e32 v2, 16, v86
	v_mul_f32_e32 v2, 0xbfb8aa3b, v2
	v_exp_f32_e32 v78, v2
	v_and_b32_e32 v2, 0xffff0000, v86
	v_mul_f32_e32 v2, 0xbfb8aa3b, v2
	v_exp_f32_e32 v79, v2
	s_nop 0
	v_pk_add_f32 v[78:79], v[78:79], 1.0 op_sel_hi:[1,0]
	s_nop 0
	v_div_scale_f32 v2, s[2:3], v79, v79, 1.0
	v_rcp_f32_e32 v77, v2
	s_nop 0
	v_fma_f32 v86, -v2, v77, 1.0
	v_fmac_f32_e32 v77, v86, v77
	v_div_scale_f32 v86, vcc, 1.0, v79, 1.0
	v_mul_f32_e32 v88, v86, v77
	v_fma_f32 v89, -v2, v88, v86
	v_fmac_f32_e32 v88, v89, v77
	v_fma_f32 v2, -v2, v88, v86
	v_div_fmas_f32 v2, v2, v77, v88
	v_div_fixup_f32 v79, v2, v79, 1.0
	v_div_scale_f32 v2, s[2:3], v78, v78, 1.0
	v_rcp_f32_e32 v77, v2
	s_nop 0
	v_fma_f32 v86, -v2, v77, 1.0
	v_fmac_f32_e32 v77, v86, v77
	v_div_scale_f32 v86, vcc, 1.0, v78, 1.0
	v_mul_f32_e32 v88, v86, v77
	v_fma_f32 v89, -v2, v88, v86
	v_fmac_f32_e32 v88, v89, v77
	v_fma_f32 v2, -v2, v88, v86
	v_div_fmas_f32 v2, v2, v77, v88
	v_div_fixup_f32 v78, v2, v78, 1.0
	v_lshlrev_b32_e32 v2, 16, v87
	v_mul_f32_e32 v2, 0xbfb8aa3b, v2
	v_exp_f32_e32 v86, v2
	v_and_b32_e32 v2, 0xffff0000, v87
	v_mul_f32_e32 v2, 0xbfb8aa3b, v2
	v_exp_f32_e32 v87, v2
	v_pk_mul_f32 v[78:79], v[64:65], v[78:79]
	v_pk_add_f32 v[86:87], v[86:87], 1.0 op_sel_hi:[1,0]
	s_nop 0
	v_div_scale_f32 v2, s[2:3], v87, v87, 1.0
	v_rcp_f32_e32 v77, v2
	s_nop 0
	v_fma_f32 v88, -v2, v77, 1.0
	v_fmac_f32_e32 v77, v88, v77
	v_div_scale_f32 v88, vcc, 1.0, v87, 1.0
	v_mul_f32_e32 v89, v88, v77
	v_fma_f32 v90, -v2, v89, v88
	v_fmac_f32_e32 v89, v90, v77
	v_fma_f32 v2, -v2, v89, v88
	v_div_fmas_f32 v2, v2, v77, v89
	v_div_fixup_f32 v87, v2, v87, 1.0
	v_div_scale_f32 v2, s[2:3], v86, v86, 1.0
	v_rcp_f32_e32 v77, v2
	s_nop 0
	v_fma_f32 v88, -v2, v77, 1.0
	v_fmac_f32_e32 v77, v88, v77
	v_div_scale_f32 v88, vcc, 1.0, v86, 1.0
	v_mul_f32_e32 v89, v88, v77
	v_fma_f32 v90, -v2, v89, v88
	v_fmac_f32_e32 v89, v90, v77
	v_fma_f32 v2, -v2, v89, v88
	v_div_fmas_f32 v2, v2, v77, v89
	v_div_fixup_f32 v86, v2, v86, 1.0
	v_pk_mul_f32 v[86:87], v[66:67], v[86:87]
	s_and_b64 vcc, exec, s[4:5]
	s_cbranch_vccnz .LBB0_815
	flat_load_dwordx2 v[88:89], v[80:81]
	s_waitcnt vmcnt(0) lgkmcnt(0)
	v_lshlrev_b32_e32 v90, 16, v88
	v_and_b32_e32 v91, 0xffff0000, v88
	v_lshlrev_b32_e32 v88, 16, v89
	v_and_b32_e32 v89, 0xffff0000, v89
	v_pk_add_f32 v[78:79], v[78:79], v[90:91]
	v_pk_add_f32 v[86:87], v[86:87], v[88:89]

; __device__ __forceinline__ void gemm_phase(const Ctx& cx, const GemmArgs& g_, char* shm) {
;     ...
;             const int n0 = brow + ai * 128 + wr * 64 + m * 16 + fq * 4;
;             f32x4 a = acc[ai][bj][m][n];
;             if (g.epi == EPI_PROJ || g.epi == EPI_RELU2) { a[0] *= rs; a[1] *= rs; a[2] *= rs; a[3] *= rs; }
;             if (g.epi == EPI_PROJ) {
;               if (n0 >= C_GLAX) {
;                 const int i = n0 - C_GLAX;
;                 const float4 b4 = *(const float4*)(g.hin + i);
;                 float xs[4] = {a[0] + b4.x, a[1] + b4.y, a[2] + b4.z, a[3] + b4.w};
; #pragma unroll
;                 for (int j = 0; j < 4; ++j)
;                   xs[j] = (fminf(xs[j], 0.f) - __logf(1.0f + __expf(-fabsf(xs[j])))) * (1.0f / 16.0f);
;                 *(float4*)(g.f32buf + (size_t)tok * 1024 + i) = make_float4(xs[0], xs[1], xs[2], xs[3]);
;               } else {
;                 float o0 = a[0], o1 = a[1], o2 = a[2], o3 = a[3];
;                 const bool r128 = (n0 >= C_DSAQ && n0 < C_HGQ) || (n0 >= C_DSAK && n0 < C_DSAV);
;                 const bool r64 = (n0 >= C_IDXQ && n0 < C_GLAA);
;                 if (r128 || r64) {
;                   float4 cs;
;                   float sc;
;                   if (r128) {
;                     cs = *(const float4*)(g.w + ((size_t)tok * 64 + ((n0 & 127) >> 1)) * 2);
;                     sc = (n0 < C_HGQ) ? 0.08838834764831845f : 1.0f;
;                   } else {
;                     cs = *(const float4*)(g.hout + ((size_t)tok * 32 + ((n0 & 63) >> 1)) * 2);
;                     sc = (n0 < C_IDXK) ? 0.125f : 1.0f;
;                   }
;                   o0 = (a[0] * cs.x - a[1] * cs.y) * sc; o1 = (a[1] * cs.x + a[0] * cs.y) * sc;
;                   o2 = (a[2] * cs.z - a[3] * cs.w) * sc; o3 = (a[3] * cs.z + a[2] * cs.w) * sc;
;                 }
.LBB0_816:
	s_movk_i32 s0, 0xe100
	v_lshlrev_b64 v[78:79], 9, v[84:85]
	v_mad_i64_i32 v[80:81], s[10:11], v84, s0, v[72:73]
	v_lshl_add_u64 v[78:79], s[30:31], 0, v[78:79]
	v_lshl_add_u64 v[70:71], s[24:25], 0, v[70:71]
	s_and_b64 vcc, exec, s[2:3]
	s_cbranch_vccz .LBB0_828
	s_movk_i32 s0, 0x5c00
	v_cmp_gt_i32_e32 vcc, s0, v140
	s_and_saveexec_b64 s[2:3], vcc
	s_xor_b64 s[2:3], exec, s[2:3]
	s_cbranch_execz .LBB0_825
	v_add_u32_e32 v2, 0xffffa700, v138
	v_cmp_gt_u32_e32 vcc, s77, v2
	s_or_b64 s[60:61], s[58:59], vcc
	s_and_saveexec_b64 s[10:11], s[60:61]
	s_cbranch_execz .LBB0_824
	s_and_saveexec_b64 s[60:61], s[56:57]
	s_xor_b64 s[60:61], exec, s[60:61]
	s_movk_i32 s0, 0x5b00
	v_lshlrev_b32_e32 v2, 2, v0
	v_cmp_gt_u32_e32 vcc, s0, v138
	v_lshl_add_u64 v[86:87], v[80:81], 0, v[2:3]
	s_nop 0
	v_cndmask_b32_e32 v2, 1.0, v166, vcc
	s_andn2_saveexec_b64 s[60:61], s[60:61]
	v_and_b32_e32 v2, 0x4c, v140
	v_lshlrev_b32_e32 v2, 2, v2
	v_cmp_gt_i32_e32 vcc, s81, v140
	v_lshl_add_u64 v[86:87], v[78:79], 0, v[2:3]
	s_nop 0
	v_cndmask_b32_e32 v2, 1.0, v167, vcc
	s_or_b64 exec, exec, s[60:61]
	s_nop 0
	flat_load_dwordx4 v[86:89], v[86:87]
	s_waitcnt vmcnt(0) lgkmcnt(0)
	v_pk_mul_f32 v[90:91], v[64:65], v[86:87] op_sel:[1,1] op_sel_hi:[1,0]
	s_nop 0
	v_pk_fma_f32 v[92:93], v[64:65], v[86:87], v[90:91] neg_lo:[0,0,1] neg_hi:[0,0,1]
	v_pk_fma_f32 v[64:65], v[64:65], v[86:87], v[90:91] op_sel_hi:[0,1,1]
	v_mov_b32_e32 v86, v67
	v_pk_mul_f32 v[86:87], v[86:87], v[88:89] op_sel:[0,1] op_sel_hi:[0,0]
	v_pk_fma_f32 v[90:91], v[66:67], v[88:89], v[86:87] neg_lo:[0,0,1] neg_hi:[0,0,1]
	v_pk_fma_f32 v[66:67], v[66:67], v[88:89], v[86:87] op_sel_hi:[0,1,1]
	v_mov_b32_e32 v93, v65
	v_mov_b32_e32 v91, v67
	v_pk_mul_f32 v[64:65], v[2:3], v[92:93] op_sel_hi:[0,1]
	v_pk_mul_f32 v[66:67], v[2:3], v[90:91] op_sel_hi:[0,1]

; __device__ __forceinline__ void gemm_phase(const Ctx& cx, const GemmArgs& g_, char* shm) {
;     ...
;               if (n0 >= C_GLAX) {
;                 const int i = n0 - C_GLAX;
;                 const float4 b4 = *(const float4*)(g.hin + i);
;                 float xs[4] = {a[0] + b4.x, a[1] + b4.y, a[2] + b4.z, a[3] + b4.w};
; #pragma unroll
;                 for (int j = 0; j < 4; ++j)
;                   xs[j] = (fminf(xs[j], 0.f) - __logf(1.0f + __expf(-fabsf(xs[j])))) * (1.0f / 16.0f);
;                 *(float4*)(g.f32buf + (size_t)tok * 1024 + i) = make_float4(xs[0], xs[1], xs[2], xs[3]);
.LBB0_825:
	s_andn2_saveexec_b64 s[2:3], s[2:3]
	s_cbranch_execz .LBB0_827
	v_add_u32_e32 v2, 0xffffa400, v140
	v_lshlrev_b64 v[90:91], 2, v[2:3]
	v_lshl_add_u64 v[86:87], s[26:27], 0, v[90:91]
	s_nop 0
	flat_load_dwordx4 v[86:89], v[86:87]
	s_mov_b32 s0, 0x3d800000
	v_mov_b32_e32 v77, 0
	v_lshl_add_u64 v[90:91], v[70:71], 0, v[90:91]
	s_waitcnt vmcnt(0) lgkmcnt(0)
	v_add_f32_e32 v2, v64, v86
	v_min_f32_e32 v64, 0, v2
	v_mul_f32_e64 v2, |v2|, s82
	v_exp_f32_e32 v2, v2
	v_add_f32_e32 v85, v65, v87
	v_add_f32_e32 v87, v66, v88
	v_add_f32_e32 v89, v67, v89
	v_add_f32_e32 v2, 1.0, v2
	v_cmp_gt_f32_e32 vcc, s83, v2
	v_min_f32_e32 v86, 0, v87
	s_nop 0
	v_cndmask_b32_e64 v65, 0, 32, vcc
	v_ldexp_f32 v2, v2, v65
	v_log_f32_e32 v2, v2
	s_nop 0
	v_mul_f32_e32 v65, 0x3f317217, v2
	v_fma_f32 v65, v2, s86, -v65
	v_fmac_f32_e32 v65, 0x3377d1cf, v2
	v_fmac_f32_e32 v65, 0x3f317217, v2
	v_cmp_lt_f32_e64 s[10:11], |v2|, s87
	s_nop 1
	v_cndmask_b32_e64 v2, v2, v65, s[10:11]
	v_cndmask_b32_e32 v65, 0, v165, vcc
	v_sub_f32_e32 v66, v2, v65
	v_mul_f32_e64 v2, |v85|, s82
	v_exp_f32_e32 v2, v2
	v_min_f32_e32 v65, 0, v85
	v_add_f32_e32 v2, 1.0, v2
	v_cmp_gt_f32_e32 vcc, s83, v2
	s_nop 1
	v_cndmask_b32_e64 v67, 0, 32, vcc
	v_ldexp_f32 v2, v2, v67
	v_log_f32_e32 v2, v2
	s_nop 0
	v_mul_f32_e32 v67, 0x3f317217, v2
	v_fma_f32 v67, v2, s86, -v67
	v_fmac_f32_e32 v67, 0x3377d1cf, v2
	v_fmac_f32_e32 v67, 0x3f317217, v2
	v_cmp_lt_f32_e64 s[10:11], |v2|, s87
	s_nop 1
	v_cndmask_b32_e64 v2, v2, v67, s[10:11]
	v_cndmask_b32_e32 v67, 0, v165, vcc
	v_sub_f32_e32 v67, v2, v67
	v_mul_f32_e64 v2, |v87|, s82
	v_exp_f32_e32 v2, v2
	v_min_f32_e32 v87, 0, v89
	v_pk_add_f32 v[64:65], v[64:65], v[66:67] neg_lo:[0,1] neg_hi:[0,1]
	v_add_f32_e32 v2, 1.0, v2
	v_cmp_gt_f32_e32 vcc, s83, v2
	v_pk_mul_f32 v[64:65], v[64:65], s[0:1] op_sel_hi:[1,0]
	s_nop 0
	v_cndmask_b32_e64 v85, 0, 32, vcc
	v_ldexp_f32 v2, v2, v85
	v_log_f32_e32 v2, v2
	s_nop 0
	v_mul_f32_e32 v85, 0x3f317217, v2
	v_fma_f32 v85, v2, s86, -v85
	v_fmac_f32_e32 v85, 0x3377d1cf, v2
	v_fmac_f32_e32 v85, 0x3f317217, v2
	v_cmp_lt_f32_e64 s[10:11], |v2|, s87
	s_nop 1
	v_cndmask_b32_e64 v2, v2, v85, s[10:11]
	v_cndmask_b32_e32 v85, 0, v165, vcc
	v_sub_f32_e32 v88, v2, v85
	v_mul_f32_e64 v2, |v89|, s82
	v_exp_f32_e32 v2, v2
	s_nop 0
	v_add_f32_e32 v2, 1.0, v2
	v_cmp_gt_f32_e32 vcc, s83, v2
	s_nop 1
	v_cndmask_b32_e64 v85, 0, 32, vcc
	v_ldexp_f32 v2, v2, v85
	v_log_f32_e32 v2, v2
	s_nop 0
	v_mul_f32_e32 v85, 0x3f317217, v2
	v_fma_f32 v85, v2, s86, -v85
	v_fmac_f32_e32 v85, 0x3377d1cf, v2
	v_fmac_f32_e32 v85, 0x3f317217, v2
	v_cmp_lt_f32_e64 s[10:11], |v2|, s87
	s_nop 1
	v_cndmask_b32_e64 v2, v2, v85, s[10:11]
	v_cndmask_b32_e32 v85, 0, v165, vcc
	v_sub_f32_e32 v89, v2, v85
	v_pk_add_f32 v[66:67], v[86:87], v[88:89] neg_lo:[0,1] neg_hi:[0,1]
	v_mov_b32_e32 v88, 0
	v_pk_mul_f32 v[66:67], v[66:67], s[0:1] op_sel_hi:[1,0]
	flat_store_dwordx4 v[90:91], v[64:67]

; __device__ __forceinline__ void gemm_phase(const Ctx& cx, const GemmArgs& g_, char* shm) {
;     ...
;             } else if (g.epi == EPI_RELU2) {
;               float r0 = fmaxf(a[0], 0.f), r1 = fmaxf(a[1], 0.f), r2 = fmaxf(a[2], 0.f), r3 = fmaxf(a[3], 0.f);
;               uint2 o; o.x = pack2(r0 * r0, r1 * r1); o.y = pack2(r2 * r2, r3 * r3);
;               EMIT_BF16(g.ldo, o);
.LBB0_840:
	s_cmp_gt_i32 s38, 4
	s_cbranch_scc0 .LBB0_844
	s_cmp_eq_u32 s38, 5
	s_mov_b64 s[10:11], -1
	s_cbranch_scc0 .LBB0_843
	v_max_f32_e32 v2, v62, v62
	v_max_f32_e32 v64, 0, v2
	v_max_f32_e32 v2, v63, v63
	v_max_f32_e32 v65, 0, v2
	v_pk_mul_f32 v[64:65], v[64:65], v[64:65]
	v_max_f32_e32 v2, v60, v60
	v_cvt_pk_bf16_f32 v67, v64, v65
	v_max_f32_e32 v64, 0, v2
	v_max_f32_e32 v2, v61, v61
	v_max_f32_e32 v65, 0, v2
	v_pk_mul_f32 v[64:65], v[64:65], v[64:65]
	v_ashrrev_i32_e32 v133, 31, v132
	v_cvt_pk_bf16_f32 v66, v64, v65
	v_mov_b32_e32 v64, v88
	v_mov_b32_e32 v65, v77
	s_nop 0
	v_permlane16_swap_b32_e32 v64, v66
	v_permlane16_swap_b32_e32 v65, v67
	v_lshl_add_u64 v[86:87], v[132:133], 1, v[84:85]
	s_nop 0
	flat_store_dwordx4 v[86:87], v[64:67] offset:32
	s_mov_b64 s[10:11], 0

; __device__ __forceinline__ void gemm_phase(const Ctx& cx, const GemmArgs& g_, char* shm) {
;     ...
;             } else if (g.epi == EPI_RES) {
;               const float4 hv = *(const float4*)(g.hin + (size_t)tok * DM + n0);
;               const float h0 = hv.x + a[0], h1 = hv.y + a[1], h2 = hv.z + a[2], h3 = hv.w + a[3];
;               *(float4*)(g.hout + (size_t)tok * DM + n0) = make_float4(h0, h1, h2, h3);
;               if (g.w != nullptr) {
;                 const float4 nw = *(const float4*)(g.w + n0);
;                 uint2 o; o.x = pack2(h0 * nw.x, h1 * nw.y); o.y = pack2(h2 * nw.z, h3 * nw.w);
;                 EMIT_BF16(DM, o);
;                 ssq += h0 * h0 + h1 * h1 + h2 * h2 + h3 * h3;
;               }
.LBB0_844:
	s_and_b64 vcc, exec, s[60:61]
	v_mov_b32_e32 v90, v89
	s_cbranch_vccz .LBB0_847
	v_lshl_add_u64 v[86:87], v[138:139], 0, v[0:1]
	v_lshlrev_b64 v[90:91], 2, v[86:87]
	v_lshl_add_u64 v[64:65], v[74:75], 0, v[90:91]
	s_nop 0
	flat_load_dwordx4 v[64:67], v[64:65] offset:64
	v_lshl_add_u64 v[90:91], v[72:73], 0, v[90:91]
	s_andn2_b64 vcc, exec, s[42:43]
	s_waitcnt vmcnt(0) lgkmcnt(0)
	v_pk_add_f32 v[64:65], v[60:61], v[64:65]
	v_pk_add_f32 v[66:67], v[62:63], v[66:67]
	flat_store_dwordx4 v[90:91], v[64:67] offset:64
	v_mov_b32_e32 v90, v89
	s_cbranch_vccnz .LBB0_847
	v_lshl_add_u64 v[86:87], v[86:87], 2, s[30:31]
	global_load_dwordx4 v[90:93], v[86:87], off offset:64
	v_ashrrev_i32_e32 v133, 31, v132
	s_waitcnt vmcnt(0)
	v_pk_mul_f32 v[86:87], v[66:67], v[92:93]
	s_nop 0
	v_cvt_pk_bf16_f32 v93, v86, v87
	v_pk_mul_f32 v[86:87], v[64:65], v[90:91]
	v_pk_mul_f32 v[64:65], v[64:65], v[64:65]
	v_pk_mul_f32 v[66:67], v[66:67], v[66:67]
	v_add_f32_e32 v2, v64, v65
	v_cvt_pk_bf16_f32 v92, v86, v87
	v_mov_b32_e32 v90, v88
	v_mov_b32_e32 v91, v77
	v_add_f32_e32 v2, v2, v66
	v_permlane16_swap_b32_e32 v90, v92
	v_permlane16_swap_b32_e32 v91, v93
	v_lshl_add_u64 v[86:87], v[132:133], 1, v[68:69]
	v_add_f32_e32 v2, v2, v67
	flat_store_dwordx4 v[86:87], v[90:93] offset:32
	s_nop 1
	v_add_f32_e32 v90, v89, v2

; __device__ __forceinline__ float b2f(u16 b) { return __uint_as_float(((uint32_t)b) << 16); }
; __device__ __forceinline__ float sigmoidf_(float x) { return 1.0f / (1.0f + __expf(-x)); }
; __device__ __forceinline__ void gemm_phase(const Ctx& cx, const GemmArgs& g_, char* shm) {
;     ...
;               const uint2 gv = *(const uint2*)(g.gate + (size_t)tok * NP + n0);
;               float v0 = sigmoidf_(b2f((u16)(gv.x & 0xffff))) * a[0], v1 = sigmoidf_(b2f((u16)(gv.x >> 16))) * a[1];
;               float v2 = sigmoidf_(b2f((u16)(gv.y & 0xffff))) * a[2], v3 = sigmoidf_(b2f((u16)(gv.y >> 16))) * a[3];
;               uint2* mp = (uint2*)(g.outb + (size_t)tok * DM + n0);
;               if (g.epi != EPI_BR0) {
;                 const uint2 pv = *mp;
;                 v0 += b2f((u16)(pv.x & 0xffff)); v1 += b2f((u16)(pv.x >> 16));
;                 v2 += b2f((u16)(pv.y & 0xffff)); v3 += b2f((u16)(pv.y >> 16));
;               }
.LBB0_849:
	v_lshl_add_u64 v[64:65], v[138:139], 0, v[0:1]
	v_lshlrev_b64 v[66:67], 1, v[64:65]
	v_lshl_add_u64 v[64:65], v[82:83], 0, v[66:67]
	s_nop 0
	flat_load_dwordx2 v[86:87], v[64:65] offset:32
	v_lshl_add_u64 v[66:67], v[68:69], 0, v[66:67]
	s_waitcnt vmcnt(0) lgkmcnt(0)
	v_lshlrev_b32_e32 v2, 16, v86
	v_mul_f32_e32 v2, 0xbfb8aa3b, v2
	v_exp_f32_e32 v64, v2
	v_and_b32_e32 v2, 0xffff0000, v86
	v_mul_f32_e32 v2, 0xbfb8aa3b, v2
	v_exp_f32_e32 v65, v2
	s_nop 0
	v_pk_add_f32 v[64:65], v[64:65], 1.0 op_sel_hi:[1,0]
	s_nop 0
	v_div_scale_f32 v2, s[2:3], v65, v65, 1.0
	v_rcp_f32_e32 v86, v2
	s_nop 0
	v_fma_f32 v90, -v2, v86, 1.0
	v_fmac_f32_e32 v86, v90, v86
	v_div_scale_f32 v90, vcc, 1.0, v65, 1.0
	v_mul_f32_e32 v91, v90, v86
	v_fma_f32 v92, -v2, v91, v90
	v_fmac_f32_e32 v91, v92, v86
	v_fma_f32 v2, -v2, v91, v90
	v_div_fmas_f32 v2, v2, v86, v91
	v_div_fixup_f32 v65, v2, v65, 1.0
	v_div_scale_f32 v2, s[2:3], v64, v64, 1.0
	v_rcp_f32_e32 v86, v2
	s_nop 0
	v_fma_f32 v90, -v2, v86, 1.0
	v_fmac_f32_e32 v86, v90, v86
	v_div_scale_f32 v90, vcc, 1.0, v64, 1.0
	v_mul_f32_e32 v91, v90, v86
	v_fma_f32 v92, -v2, v91, v90
	v_fmac_f32_e32 v91, v92, v86
	v_fma_f32 v2, -v2, v91, v90
	v_div_fmas_f32 v2, v2, v86, v91
	v_div_fixup_f32 v64, v2, v64, 1.0
	v_lshlrev_b32_e32 v2, 16, v87
	v_mul_f32_e32 v2, 0xbfb8aa3b, v2
	v_exp_f32_e32 v86, v2
	v_and_b32_e32 v2, 0xffff0000, v87
	v_mul_f32_e32 v2, 0xbfb8aa3b, v2
	v_exp_f32_e32 v87, v2
	v_pk_mul_f32 v[64:65], v[60:61], v[64:65]
	v_pk_add_f32 v[86:87], v[86:87], 1.0 op_sel_hi:[1,0]
	s_nop 0
	v_div_scale_f32 v2, s[2:3], v87, v87, 1.0
	v_rcp_f32_e32 v90, v2
	s_nop 0
	v_fma_f32 v91, -v2, v90, 1.0
	v_fmac_f32_e32 v90, v91, v90
	v_div_scale_f32 v91, vcc, 1.0, v87, 1.0
	v_mul_f32_e32 v92, v91, v90
	v_fma_f32 v93, -v2, v92, v91
	v_fmac_f32_e32 v92, v93, v90
	v_fma_f32 v2, -v2, v92, v91
	v_div_fmas_f32 v2, v2, v90, v92
	v_div_fixup_f32 v87, v2, v87, 1.0
	v_div_scale_f32 v2, s[2:3], v86, v86, 1.0
	v_rcp_f32_e32 v90, v2
	s_nop 0
	v_fma_f32 v91, -v2, v90, 1.0
	v_fmac_f32_e32 v90, v91, v90
	v_div_scale_f32 v91, vcc, 1.0, v86, 1.0
	v_mul_f32_e32 v92, v91, v90
	v_fma_f32 v93, -v2, v92, v91
	v_fmac_f32_e32 v92, v93, v90
	v_fma_f32 v2, -v2, v92, v91
	v_div_fmas_f32 v2, v2, v90, v92
	v_div_fixup_f32 v86, v2, v86, 1.0
	v_pk_mul_f32 v[86:87], v[62:63], v[86:87]
	s_and_b64 vcc, exec, s[4:5]
	s_cbranch_vccnz .LBB0_851
	flat_load_dwordx2 v[90:91], v[66:67] offset:32
	s_waitcnt vmcnt(0) lgkmcnt(0)
	v_lshlrev_b32_e32 v92, 16, v90
	v_and_b32_e32 v93, 0xffff0000, v90
	v_lshlrev_b32_e32 v90, 16, v91
	v_and_b32_e32 v91, 0xffff0000, v91
	v_pk_add_f32 v[64:65], v[64:65], v[92:93]
	v_pk_add_f32 v[86:87], v[86:87], v[90:91]

; __device__ __forceinline__ void gemm_phase(const Ctx& cx, const GemmArgs& g_, char* shm) {
;     ...
;             const int n0 = brow + ai * 128 + wr * 64 + m * 16 + fq * 4;
;             f32x4 a = acc[ai][bj][m][n];
;             if (g.epi == EPI_PROJ || g.epi == EPI_RELU2) { a[0] *= rs; a[1] *= rs; a[2] *= rs; a[3] *= rs; }
;             if (g.epi == EPI_PROJ) {
;               if (n0 >= C_GLAX) {
;                 const int i = n0 - C_GLAX;
;                 const float4 b4 = *(const float4*)(g.hin + i);
;                 float xs[4] = {a[0] + b4.x, a[1] + b4.y, a[2] + b4.z, a[3] + b4.w};
; #pragma unroll
;                 for (int j = 0; j < 4; ++j)
;                   xs[j] = (fminf(xs[j], 0.f) - __logf(1.0f + __expf(-fabsf(xs[j])))) * (1.0f / 16.0f);
;                 *(float4*)(g.f32buf + (size_t)tok * 1024 + i) = make_float4(xs[0], xs[1], xs[2], xs[3]);
;               } else {
;                 float o0 = a[0], o1 = a[1], o2 = a[2], o3 = a[3];
;                 const bool r128 = (n0 >= C_DSAQ && n0 < C_HGQ) || (n0 >= C_DSAK && n0 < C_DSAV);
;                 const bool r64 = (n0 >= C_IDXQ && n0 < C_GLAA);
;                 if (r128 || r64) {
;                   float4 cs;
;                   float sc;
;                   if (r128) {
;                     cs = *(const float4*)(g.w + ((size_t)tok * 64 + ((n0 & 127) >> 1)) * 2);
;                     sc = (n0 < C_HGQ) ? 0.08838834764831845f : 1.0f;
;                   } else {
;                     cs = *(const float4*)(g.hout + ((size_t)tok * 32 + ((n0 & 63) >> 1)) * 2);
;                     sc = (n0 < C_IDXK) ? 0.125f : 1.0f;
;                   }
;                   o0 = (a[0] * cs.x - a[1] * cs.y) * sc; o1 = (a[1] * cs.x + a[0] * cs.y) * sc;
;                   o2 = (a[2] * cs.z - a[3] * cs.w) * sc; o3 = (a[3] * cs.z + a[2] * cs.w) * sc;
;                 }
;                 uint2 o; o.x = pack2(o0, o1); o.y = pack2(o2, o3);
;                 EMIT_BF16(g.ldo, o);
.LBB0_852:
	s_movk_i32 s0, 0x5c00
	v_cmp_gt_i32_e32 vcc, s0, v177
	s_and_saveexec_b64 s[2:3], vcc
	s_xor_b64 s[2:3], exec, s[2:3]
	s_cbranch_execz .LBB0_860
	v_add_u32_e32 v2, 0xffffa700, v138
	v_cmp_gt_u32_e32 vcc, s77, v2
	s_or_b64 s[60:61], s[58:59], vcc
	s_and_saveexec_b64 s[10:11], s[60:61]
	s_cbranch_execz .LBB0_859
	s_and_saveexec_b64 s[60:61], s[56:57]
	s_xor_b64 s[60:61], exec, s[60:61]
	v_lshlrev_b32_e32 v2, 2, v0
	s_movk_i32 s0, 0x5b00
	v_lshl_add_u64 v[64:65], v[80:81], 0, v[2:3]
	v_cmp_gt_u32_e32 vcc, s0, v138
	v_lshl_add_u64 v[64:65], v[64:65], 0, 64
	s_nop 0
	v_cndmask_b32_e32 v2, 1.0, v166, vcc
	s_andn2_saveexec_b64 s[60:61], s[60:61]
	v_and_b32_e32 v2, 0x5c, v177
	v_lshlrev_b32_e32 v2, 2, v2
	v_cmp_gt_i32_e32 vcc, s81, v177
	v_lshl_add_u64 v[64:65], v[78:79], 0, v[2:3]
	s_nop 0
	v_cndmask_b32_e32 v2, 1.0, v167, vcc
	s_or_b64 exec, exec, s[60:61]
	s_nop 0
	flat_load_dwordx4 v[64:67], v[64:65]
	s_waitcnt vmcnt(0) lgkmcnt(0)
	v_pk_mul_f32 v[86:87], v[60:61], v[64:65] op_sel:[1,1] op_sel_hi:[1,0]
	s_nop 0
	v_pk_fma_f32 v[90:91], v[60:61], v[64:65], v[86:87] neg_lo:[0,0,1] neg_hi:[0,0,1]
	v_pk_fma_f32 v[60:61], v[60:61], v[64:65], v[86:87] op_sel_hi:[0,1,1]
	v_mov_b32_e32 v64, v63
	v_pk_mul_f32 v[64:65], v[64:65], v[66:67] op_sel:[0,1] op_sel_hi:[0,0]
	v_pk_fma_f32 v[86:87], v[62:63], v[66:67], v[64:65] neg_lo:[0,0,1] neg_hi:[0,0,1]
	v_pk_fma_f32 v[62:63], v[62:63], v[66:67], v[64:65] op_sel_hi:[0,1,1]
	v_mov_b32_e32 v91, v61
	v_mov_b32_e32 v87, v63
	v_pk_mul_f32 v[60:61], v[2:3], v[90:91] op_sel_hi:[0,1]
	v_pk_mul_f32 v[62:63], v[2:3], v[86:87] op_sel_hi:[0,1]
.LBB0_859:
	s_or_b64 exec, exec, s[10:11]
	v_cvt_pk_bf16_f32 v63, v62, v63
	v_cvt_pk_bf16_f32 v62, v60, v61
	v_mov_b32_e32 v60, v88
	v_mov_b32_e32 v61, v77
	v_ashrrev_i32_e32 v133, 31, v132
	v_permlane16_swap_b32_e32 v60, v62
	v_permlane16_swap_b32_e32 v61, v63
	v_lshl_add_u64 v[64:65], v[132:133], 1, v[84:85]
	s_nop 0
	flat_store_dwordx4 v[64:65], v[60:63] offset:32
.LBB0_860:
	s_andn2_saveexec_b64 s[2:3], s[2:3]
	s_cbranch_execz .LBB0_862
	v_add_u32_e32 v2, 0xffffa400, v177
	v_lshlrev_b64 v[86:87], 2, v[2:3]
	v_lshl_add_u64 v[64:65], s[26:27], 0, v[86:87]
	s_nop 0
	flat_load_dwordx4 v[64:67], v[64:65]
	s_mov_b32 s0, 0x3d800000
	v_lshl_add_u64 v[86:87], v[70:71], 0, v[86:87]
	s_waitcnt vmcnt(0) lgkmcnt(0)
	v_add_f32_e32 v2, v60, v64
	v_min_f32_e32 v60, 0, v2
	v_mul_f32_e64 v2, |v2|, s82
	v_exp_f32_e32 v2, v2
	v_add_f32_e32 v64, v61, v65
	v_add_f32_e32 v65, v62, v66
	v_add_f32_e32 v67, v63, v67
	v_add_f32_e32 v2, 1.0, v2
	v_cmp_gt_f32_e32 vcc, s83, v2
	s_nop 1
	v_cndmask_b32_e64 v61, 0, 32, vcc
	v_ldexp_f32 v2, v2, v61
	v_log_f32_e32 v2, v2
	s_nop 0
	v_mul_f32_e32 v61, 0x3f317217, v2
	v_fma_f32 v61, v2, s86, -v61
	v_fmac_f32_e32 v61, 0x3377d1cf, v2
	v_fmac_f32_e32 v61, 0x3f317217, v2
	v_cmp_lt_f32_e64 s[10:11], |v2|, s87
	s_nop 1
	v_cndmask_b32_e64 v2, v2, v61, s[10:11]
	v_cndmask_b32_e32 v61, 0, v165, vcc
	v_sub_f32_e32 v62, v2, v61
	v_mul_f32_e64 v2, |v64|, s82
	v_exp_f32_e32 v2, v2
	v_min_f32_e32 v61, 0, v64
	v_min_f32_e32 v64, 0, v65
	v_add_f32_e32 v2, 1.0, v2
	v_cmp_gt_f32_e32 vcc, s83, v2
	s_nop 1
	v_cndmask_b32_e64 v63, 0, 32, vcc
	v_ldexp_f32 v2, v2, v63
	v_log_f32_e32 v2, v2
	s_nop 0
	v_mul_f32_e32 v63, 0x3f317217, v2
	v_fma_f32 v63, v2, s86, -v63
	v_fmac_f32_e32 v63, 0x3377d1cf, v2
	v_fmac_f32_e32 v63, 0x3f317217, v2
	v_cmp_lt_f32_e64 s[10:11], |v2|, s87
	s_nop 1
	v_cndmask_b32_e64 v2, v2, v63, s[10:11]
	v_cndmask_b32_e32 v63, 0, v165, vcc
	v_sub_f32_e32 v63, v2, v63
	v_mul_f32_e64 v2, |v65|, s82
	v_exp_f32_e32 v2, v2
	v_pk_add_f32 v[60:61], v[60:61], v[62:63] neg_lo:[0,1] neg_hi:[0,1]
	v_add_f32_e32 v2, 1.0, v2
	v_cmp_gt_f32_e32 vcc, s83, v2
	v_pk_mul_f32 v[60:61], v[60:61], s[0:1] op_sel_hi:[1,0]
	s_nop 0
	v_cndmask_b32_e64 v65, 0, 32, vcc
	v_ldexp_f32 v2, v2, v65
	v_log_f32_e32 v2, v2
	s_nop 0
	v_mul_f32_e32 v65, 0x3f317217, v2
	v_fma_f32 v65, v2, s86, -v65
	v_fmac_f32_e32 v65, 0x3377d1cf, v2
	v_fmac_f32_e32 v65, 0x3f317217, v2
	v_cmp_lt_f32_e64 s[10:11], |v2|, s87
	s_nop 1
	v_cndmask_b32_e64 v2, v2, v65, s[10:11]
	v_cndmask_b32_e32 v65, 0, v165, vcc
	v_sub_f32_e32 v66, v2, v65
	v_mul_f32_e64 v2, |v67|, s82
	v_exp_f32_e32 v2, v2
	v_min_f32_e32 v65, 0, v67
	v_add_f32_e32 v2, 1.0, v2
	v_cmp_gt_f32_e32 vcc, s83, v2
	s_nop 1
	v_cndmask_b32_e64 v67, 0, 32, vcc
	v_ldexp_f32 v2, v2, v67
	v_log_f32_e32 v2, v2
	s_nop 0
	v_mul_f32_e32 v67, 0x3f317217, v2
	v_fma_f32 v67, v2, s86, -v67
	v_fmac_f32_e32 v67, 0x3377d1cf, v2
	v_fmac_f32_e32 v67, 0x3f317217, v2
	v_cmp_lt_f32_e64 s[10:11], |v2|, s87
	s_nop 1
	v_cndmask_b32_e64 v2, v2, v67, s[10:11]
	v_cndmask_b32_e32 v67, 0, v165, vcc
	v_sub_f32_e32 v67, v2, v67
	v_pk_add_f32 v[62:63], v[64:65], v[66:67] neg_lo:[0,1] neg_hi:[0,1]
	s_nop 0
	v_pk_mul_f32 v[62:63], v[62:63], s[0:1] op_sel_hi:[1,0]
	flat_store_dwordx4 v[86:87], v[60:63]

; __device__ __forceinline__ void gemm_phase(const Ctx& cx, const GemmArgs& g_, char* shm) {
;     ...
;             } else if (g.epi == EPI_RES) {
;               const float4 hv = *(const float4*)(g.hin + (size_t)tok * DM + n0);
;               const float h0 = hv.x + a[0], h1 = hv.y + a[1], h2 = hv.z + a[2], h3 = hv.w + a[3];
;               *(float4*)(g.hout + (size_t)tok * DM + n0) = make_float4(h0, h1, h2, h3);
;               if (g.w != nullptr) {
;                 const float4 nw = *(const float4*)(g.w + n0);
;                 uint2 o; o.x = pack2(h0 * nw.x, h1 * nw.y); o.y = pack2(h2 * nw.z, h3 * nw.w);
;                 EMIT_BF16(DM, o);
;                 ssq += h0 * h0 + h1 * h1 + h2 * h2 + h3 * h3;
;               }
.LBB0_877:
	s_and_b64 vcc, exec, s[60:61]
	v_mov_b32_e32 v86, v90
	s_cbranch_vccz .LBB0_880
	v_lshl_add_u64 v[66:67], v[138:139], 0, v[0:1]
	v_lshlrev_b64 v[60:61], 2, v[66:67]
	v_lshl_add_u64 v[62:63], v[74:75], 0, v[60:61]
	s_nop 0
	flat_load_dwordx4 v[62:65], v[62:63] offset:128
	v_lshl_add_u64 v[60:61], v[72:73], 0, v[60:61]
	s_andn2_b64 vcc, exec, s[42:43]
	v_mov_b32_e32 v86, v90
	s_waitcnt vmcnt(0) lgkmcnt(0)
	v_pk_add_f32 v[62:63], v[56:57], v[62:63]
	v_pk_add_f32 v[64:65], v[58:59], v[64:65]
	flat_store_dwordx4 v[60:61], v[62:65] offset:128
	v_mov_b32_e32 v61, v77
	v_mov_b32_e32 v60, v88
	s_cbranch_vccnz .LBB0_880
	v_lshl_add_u64 v[60:61], v[66:67], 2, s[30:31]
	global_load_dwordx4 v[92:95], v[60:61], off offset:128
	v_pk_mul_f32 v[60:61], v[62:63], v[62:63]
	v_pk_mul_f32 v[66:67], v[64:65], v[64:65]
	v_add_f32_e32 v2, v60, v61
	v_add_f32_e32 v2, v2, v66
	v_add_f32_e32 v2, v2, v67
	v_add_f32_e32 v86, v90, v2
	s_waitcnt vmcnt(0)
	v_pk_mul_f32 v[60:61], v[64:65], v[94:95]
	v_pk_mul_f32 v[62:63], v[62:63], v[92:93]
	v_cvt_pk_bf16_f32 v61, v60, v61
	v_cvt_pk_bf16_f32 v60, v62, v63

; __device__ __forceinline__ float b2f(u16 b) { return __uint_as_float(((uint32_t)b) << 16); }
; __device__ __forceinline__ float sigmoidf_(float x) { return 1.0f / (1.0f + __expf(-x)); }
; __device__ __forceinline__ void gemm_phase(const Ctx& cx, const GemmArgs& g_, char* shm) {
;     ...
;               const uint2 gv = *(const uint2*)(g.gate + (size_t)tok * NP + n0);
;               float v0 = sigmoidf_(b2f((u16)(gv.x & 0xffff))) * a[0], v1 = sigmoidf_(b2f((u16)(gv.x >> 16))) * a[1];
;               float v2 = sigmoidf_(b2f((u16)(gv.y & 0xffff))) * a[2], v3 = sigmoidf_(b2f((u16)(gv.y >> 16))) * a[3];
;               uint2* mp = (uint2*)(g.outb + (size_t)tok * DM + n0);
;               if (g.epi != EPI_BR0) {
;                 const uint2 pv = *mp;
;                 v0 += b2f((u16)(pv.x & 0xffff)); v1 += b2f((u16)(pv.x >> 16));
;                 v2 += b2f((u16)(pv.y & 0xffff)); v3 += b2f((u16)(pv.y >> 16));
;               }
.LBB0_882:
	v_lshl_add_u64 v[60:61], v[138:139], 0, v[0:1]
	v_lshlrev_b64 v[62:63], 1, v[60:61]
	v_lshl_add_u64 v[60:61], v[82:83], 0, v[62:63]
	s_nop 0
	flat_load_dwordx2 v[64:65], v[60:61] offset:64
	v_lshl_add_u64 v[62:63], v[68:69], 0, v[62:63]
	s_waitcnt vmcnt(0) lgkmcnt(0)
	v_lshlrev_b32_e32 v2, 16, v64
	v_mul_f32_e32 v2, 0xbfb8aa3b, v2
	v_exp_f32_e32 v60, v2
	v_and_b32_e32 v2, 0xffff0000, v64
	v_mul_f32_e32 v2, 0xbfb8aa3b, v2
	v_exp_f32_e32 v61, v2
	s_nop 0
	v_pk_add_f32 v[60:61], v[60:61], 1.0 op_sel_hi:[1,0]
	s_nop 0
	v_div_scale_f32 v2, s[2:3], v61, v61, 1.0
	v_rcp_f32_e32 v64, v2
	s_nop 0
	v_fma_f32 v66, -v2, v64, 1.0
	v_fmac_f32_e32 v64, v66, v64
	v_div_scale_f32 v66, vcc, 1.0, v61, 1.0
	v_mul_f32_e32 v67, v66, v64
	v_fma_f32 v86, -v2, v67, v66
	v_fmac_f32_e32 v67, v86, v64
	v_fma_f32 v2, -v2, v67, v66
	v_div_fmas_f32 v2, v2, v64, v67
	v_div_fixup_f32 v61, v2, v61, 1.0
	v_div_scale_f32 v2, s[2:3], v60, v60, 1.0
	v_rcp_f32_e32 v64, v2
	s_nop 0
	v_fma_f32 v66, -v2, v64, 1.0
	v_fmac_f32_e32 v64, v66, v64
	v_div_scale_f32 v66, vcc, 1.0, v60, 1.0
	v_mul_f32_e32 v67, v66, v64
	v_fma_f32 v86, -v2, v67, v66
	v_fmac_f32_e32 v67, v86, v64
	v_fma_f32 v2, -v2, v67, v66
	v_div_fmas_f32 v2, v2, v64, v67
	v_div_fixup_f32 v60, v2, v60, 1.0
	v_lshlrev_b32_e32 v2, 16, v65
	v_mul_f32_e32 v2, 0xbfb8aa3b, v2
	v_exp_f32_e32 v64, v2
	v_and_b32_e32 v2, 0xffff0000, v65
	v_mul_f32_e32 v2, 0xbfb8aa3b, v2
	v_exp_f32_e32 v65, v2
	v_pk_mul_f32 v[60:61], v[56:57], v[60:61]
	v_pk_add_f32 v[64:65], v[64:65], 1.0 op_sel_hi:[1,0]
	s_nop 0
	v_div_scale_f32 v2, s[2:3], v65, v65, 1.0
	v_rcp_f32_e32 v66, v2
	s_nop 0
	v_fma_f32 v67, -v2, v66, 1.0
	v_fmac_f32_e32 v66, v67, v66
	v_div_scale_f32 v67, vcc, 1.0, v65, 1.0
	v_mul_f32_e32 v86, v67, v66
	v_fma_f32 v87, -v2, v86, v67
	v_fmac_f32_e32 v86, v87, v66
	v_fma_f32 v2, -v2, v86, v67
	v_div_fmas_f32 v2, v2, v66, v86
	v_div_fixup_f32 v65, v2, v65, 1.0
	v_div_scale_f32 v2, s[2:3], v64, v64, 1.0
	v_rcp_f32_e32 v66, v2
	s_nop 0
	v_fma_f32 v67, -v2, v66, 1.0
	v_fmac_f32_e32 v66, v67, v66
	v_div_scale_f32 v67, vcc, 1.0, v64, 1.0
	v_mul_f32_e32 v86, v67, v66
	v_fma_f32 v87, -v2, v86, v67
	v_fmac_f32_e32 v86, v87, v66
	v_fma_f32 v2, -v2, v86, v67
	v_div_fmas_f32 v2, v2, v66, v86
	v_div_fixup_f32 v64, v2, v64, 1.0
	v_pk_mul_f32 v[64:65], v[58:59], v[64:65]
	s_and_b64 vcc, exec, s[4:5]
	s_cbranch_vccnz .LBB0_884
	flat_load_dwordx2 v[66:67], v[62:63] offset:64
	s_waitcnt vmcnt(0) lgkmcnt(0)
	v_lshlrev_b32_e32 v86, 16, v66
	v_and_b32_e32 v87, 0xffff0000, v66
	v_lshlrev_b32_e32 v66, 16, v67
	v_and_b32_e32 v67, 0xffff0000, v67
	v_pk_add_f32 v[60:61], v[60:61], v[86:87]
	v_pk_add_f32 v[64:65], v[64:65], v[66:67]

; __device__ __forceinline__ void gemm_phase(const Ctx& cx, const GemmArgs& g_, char* shm) {
;     ...
;                 const bool r128 = (n0 >= C_DSAQ && n0 < C_HGQ) || (n0 >= C_DSAK && n0 < C_DSAV);
;                 const bool r64 = (n0 >= C_IDXQ && n0 < C_GLAA);
;                 if (r128 || r64) {
;                   float4 cs;
;                   float sc;
;                   if (r128) {
;                     cs = *(const float4*)(g.w + ((size_t)tok * 64 + ((n0 & 127) >> 1)) * 2);
;                     sc = (n0 < C_HGQ) ? 0.08838834764831845f : 1.0f;
;                   } else {
;                     cs = *(const float4*)(g.hout + ((size_t)tok * 32 + ((n0 & 63) >> 1)) * 2);
;                     sc = (n0 < C_IDXK) ? 0.125f : 1.0f;
;                   }
;                   o0 = (a[0] * cs.x - a[1] * cs.y) * sc; o1 = (a[1] * cs.x + a[0] * cs.y) * sc;
;                   o2 = (a[2] * cs.z - a[3] * cs.w) * sc; o3 = (a[3] * cs.z + a[2] * cs.w) * sc;
;                 }
.LBB0_885:
	s_movk_i32 s0, 0x5c00
	v_cmp_gt_i32_e32 vcc, s0, v161
	s_and_saveexec_b64 s[2:3], vcc
	s_xor_b64 s[2:3], exec, s[2:3]
	s_cbranch_execz .LBB0_893
	v_add_u32_e32 v2, 0xffffa700, v138
	v_cmp_gt_u32_e32 vcc, s77, v2
	s_or_b64 s[60:61], s[58:59], vcc
	s_and_saveexec_b64 s[10:11], s[60:61]
	s_cbranch_execz .LBB0_892
	s_and_saveexec_b64 s[60:61], s[56:57]
	s_xor_b64 s[60:61], exec, s[60:61]
	v_lshlrev_b32_e32 v2, 2, v0
	s_movk_i32 s0, 0x5b00
	v_lshl_add_u64 v[60:61], v[80:81], 0, v[2:3]
	v_cmp_gt_u32_e32 vcc, s0, v138
	v_lshl_add_u64 v[60:61], v[60:61], 0, s[70:71]
	s_nop 0
	v_cndmask_b32_e32 v2, 1.0, v166, vcc
	s_andn2_saveexec_b64 s[60:61], s[60:61]
	v_and_b32_e32 v2, 0x6c, v161
	v_lshlrev_b32_e32 v2, 2, v2
	v_cmp_gt_i32_e32 vcc, s81, v161
	v_lshl_add_u64 v[60:61], v[78:79], 0, v[2:3]
	s_nop 0
	v_cndmask_b32_e32 v2, 1.0, v167, vcc
	s_or_b64 exec, exec, s[60:61]
	s_nop 0
	flat_load_dwordx4 v[60:63], v[60:61]
	s_waitcnt vmcnt(0) lgkmcnt(0)
	v_pk_mul_f32 v[64:65], v[56:57], v[60:61] op_sel:[1,1] op_sel_hi:[1,0]
	s_nop 0
	v_pk_fma_f32 v[66:67], v[56:57], v[60:61], v[64:65] neg_lo:[0,0,1] neg_hi:[0,0,1]
	v_pk_fma_f32 v[56:57], v[56:57], v[60:61], v[64:65] op_sel_hi:[0,1,1]
	v_mov_b32_e32 v60, v59
	v_pk_mul_f32 v[60:61], v[60:61], v[62:63] op_sel:[0,1] op_sel_hi:[0,0]
	v_pk_fma_f32 v[64:65], v[58:59], v[62:63], v[60:61] neg_lo:[0,0,1] neg_hi:[0,0,1]
	v_pk_fma_f32 v[58:59], v[58:59], v[62:63], v[60:61] op_sel_hi:[0,1,1]
	v_mov_b32_e32 v67, v57
	v_mov_b32_e32 v65, v59
	v_pk_mul_f32 v[56:57], v[2:3], v[66:67] op_sel_hi:[0,1]
	v_pk_mul_f32 v[58:59], v[2:3], v[64:65] op_sel_hi:[0,1]

; __device__ __forceinline__ void gemm_phase(const Ctx& cx, const GemmArgs& g_, char* shm) {
;     ...
;               if (n0 >= C_GLAX) {
;                 const int i = n0 - C_GLAX;
;                 const float4 b4 = *(const float4*)(g.hin + i);
;                 float xs[4] = {a[0] + b4.x, a[1] + b4.y, a[2] + b4.z, a[3] + b4.w};
; #pragma unroll
;                 for (int j = 0; j < 4; ++j)
;                   xs[j] = (fminf(xs[j], 0.f) - __logf(1.0f + __expf(-fabsf(xs[j])))) * (1.0f / 16.0f);
;                 *(float4*)(g.f32buf + (size_t)tok * 1024 + i) = make_float4(xs[0], xs[1], xs[2], xs[3]);
.LBB0_893:
	s_andn2_saveexec_b64 s[2:3], s[2:3]
	s_cbranch_execz .LBB0_895
	v_add_u32_e32 v2, 0xffffa400, v161
	v_lshlrev_b64 v[64:65], 2, v[2:3]
	v_lshl_add_u64 v[60:61], s[26:27], 0, v[64:65]
	s_nop 0
	flat_load_dwordx4 v[60:63], v[60:61]
	s_mov_b32 s0, 0x3d800000
	v_lshl_add_u64 v[64:65], v[70:71], 0, v[64:65]
	s_waitcnt vmcnt(0) lgkmcnt(0)
	v_add_f32_e32 v2, v56, v60
	v_min_f32_e32 v56, 0, v2
	v_mul_f32_e64 v2, |v2|, s82
	v_exp_f32_e32 v2, v2
	v_add_f32_e32 v60, v57, v61
	v_add_f32_e32 v61, v58, v62
	v_add_f32_e32 v63, v59, v63
	v_add_f32_e32 v2, 1.0, v2
	v_cmp_gt_f32_e32 vcc, s83, v2
	s_nop 1
	v_cndmask_b32_e64 v57, 0, 32, vcc
	v_ldexp_f32 v2, v2, v57
	v_log_f32_e32 v2, v2
	s_nop 0
	v_mul_f32_e32 v57, 0x3f317217, v2
	v_fma_f32 v57, v2, s86, -v57
	v_fmac_f32_e32 v57, 0x3377d1cf, v2
	v_fmac_f32_e32 v57, 0x3f317217, v2
	v_cmp_lt_f32_e64 s[10:11], |v2|, s87
	s_nop 1
	v_cndmask_b32_e64 v2, v2, v57, s[10:11]
	v_cndmask_b32_e32 v57, 0, v165, vcc
	v_sub_f32_e32 v58, v2, v57
	v_mul_f32_e64 v2, |v60|, s82
	v_exp_f32_e32 v2, v2
	v_min_f32_e32 v57, 0, v60
	v_min_f32_e32 v60, 0, v61
	v_add_f32_e32 v2, 1.0, v2
	v_cmp_gt_f32_e32 vcc, s83, v2
	s_nop 1
	v_cndmask_b32_e64 v59, 0, 32, vcc
	v_ldexp_f32 v2, v2, v59
	v_log_f32_e32 v2, v2
	s_nop 0
	v_mul_f32_e32 v59, 0x3f317217, v2
	v_fma_f32 v59, v2, s86, -v59
	v_fmac_f32_e32 v59, 0x3377d1cf, v2
	v_fmac_f32_e32 v59, 0x3f317217, v2
	v_cmp_lt_f32_e64 s[10:11], |v2|, s87
	s_nop 1
	v_cndmask_b32_e64 v2, v2, v59, s[10:11]
	v_cndmask_b32_e32 v59, 0, v165, vcc
	v_sub_f32_e32 v59, v2, v59
	v_mul_f32_e64 v2, |v61|, s82
	v_exp_f32_e32 v2, v2
	v_pk_add_f32 v[56:57], v[56:57], v[58:59] neg_lo:[0,1] neg_hi:[0,1]
	v_add_f32_e32 v2, 1.0, v2
	v_cmp_gt_f32_e32 vcc, s83, v2
	v_pk_mul_f32 v[56:57], v[56:57], s[0:1] op_sel_hi:[1,0]
	s_nop 0
	v_cndmask_b32_e64 v61, 0, 32, vcc
	v_ldexp_f32 v2, v2, v61
	v_log_f32_e32 v2, v2
	s_nop 0
	v_mul_f32_e32 v61, 0x3f317217, v2
	v_fma_f32 v61, v2, s86, -v61
	v_fmac_f32_e32 v61, 0x3377d1cf, v2
	v_fmac_f32_e32 v61, 0x3f317217, v2
	v_cmp_lt_f32_e64 s[10:11], |v2|, s87
	s_nop 1
	v_cndmask_b32_e64 v2, v2, v61, s[10:11]
	v_cndmask_b32_e32 v61, 0, v165, vcc
	v_sub_f32_e32 v62, v2, v61
	v_mul_f32_e64 v2, |v63|, s82
	v_exp_f32_e32 v2, v2
	v_min_f32_e32 v61, 0, v63
	v_add_f32_e32 v2, 1.0, v2
	v_cmp_gt_f32_e32 vcc, s83, v2
	s_nop 1
	v_cndmask_b32_e64 v63, 0, 32, vcc
	v_ldexp_f32 v2, v2, v63
	v_log_f32_e32 v2, v2
	s_nop 0
	v_mul_f32_e32 v63, 0x3f317217, v2
	v_fma_f32 v63, v2, s86, -v63
	v_fmac_f32_e32 v63, 0x3377d1cf, v2
	v_fmac_f32_e32 v63, 0x3f317217, v2
	v_cmp_lt_f32_e64 s[10:11], |v2|, s87
	s_nop 1
	v_cndmask_b32_e64 v2, v2, v63, s[10:11]
	v_cndmask_b32_e32 v63, 0, v165, vcc
	v_sub_f32_e32 v63, v2, v63
	v_pk_add_f32 v[58:59], v[60:61], v[62:63] neg_lo:[0,1] neg_hi:[0,1]
	v_mov_b32_e32 v61, v77
	v_pk_mul_f32 v[58:59], v[58:59], s[0:1] op_sel_hi:[1,0]
	v_mov_b32_e32 v60, v88
	flat_store_dwordx4 v[64:65], v[56:59]

; __device__ __forceinline__ void gemm_phase(const Ctx& cx, const GemmArgs& g_, char* shm) {
;     ...
;             } else if (g.epi == EPI_RELU2) {
;               float r0 = fmaxf(a[0], 0.f), r1 = fmaxf(a[1], 0.f), r2 = fmaxf(a[2], 0.f), r3 = fmaxf(a[3], 0.f);
;               uint2 o; o.x = pack2(r0 * r0, r1 * r1); o.y = pack2(r2 * r2, r3 * r3);
;               EMIT_BF16(g.ldo, o);
.LBB0_906:
	s_cmp_gt_i32 s38, 4
	s_cbranch_scc0 .LBB0_910
	s_cmp_eq_u32 s38, 5
	s_mov_b64 s[10:11], -1
	s_cbranch_scc0 .LBB0_909
	v_max_f32_e32 v2, v54, v54
	v_max_f32_e32 v56, 0, v2
	v_max_f32_e32 v2, v55, v55
	v_max_f32_e32 v57, 0, v2
	v_pk_mul_f32 v[56:57], v[56:57], v[56:57]
	v_max_f32_e32 v2, v52, v52
	v_cvt_pk_bf16_f32 v59, v56, v57
	v_max_f32_e32 v56, 0, v2
	v_max_f32_e32 v2, v53, v53
	v_max_f32_e32 v57, 0, v2
	v_pk_mul_f32 v[56:57], v[56:57], v[56:57]
	v_ashrrev_i32_e32 v133, 31, v132
	v_cvt_pk_bf16_f32 v58, v56, v57
	v_mov_b32_e32 v56, v60
	v_mov_b32_e32 v57, v61
	s_nop 0
	v_permlane16_swap_b32_e32 v56, v58
	v_permlane16_swap_b32_e32 v57, v59
	v_lshl_add_u64 v[62:63], v[132:133], 1, v[84:85]
	s_nop 0
	flat_store_dwordx4 v[62:63], v[56:59] offset:96
	s_mov_b64 s[10:11], 0

; __device__ __forceinline__ void gemm_phase(const Ctx& cx, const GemmArgs& g_, char* shm) {
;     ...
;             } else if (g.epi == EPI_RES) {
;               const float4 hv = *(const float4*)(g.hin + (size_t)tok * DM + n0);
;               const float h0 = hv.x + a[0], h1 = hv.y + a[1], h2 = hv.z + a[2], h3 = hv.w + a[3];
;               *(float4*)(g.hout + (size_t)tok * DM + n0) = make_float4(h0, h1, h2, h3);
;               if (g.w != nullptr) {
;                 const float4 nw = *(const float4*)(g.w + n0);
;                 uint2 o; o.x = pack2(h0 * nw.x, h1 * nw.y); o.y = pack2(h2 * nw.z, h3 * nw.w);
;                 EMIT_BF16(DM, o);
;                 ssq += h0 * h0 + h1 * h1 + h2 * h2 + h3 * h3;
;               }
.LBB0_910:
	s_and_b64 vcc, exec, s[60:61]
	v_mov_b32_e32 v64, v86
	s_cbranch_vccz .LBB0_913
	v_lshl_add_u64 v[62:63], v[138:139], 0, v[0:1]
	v_lshlrev_b64 v[64:65], 2, v[62:63]
	v_lshl_add_u64 v[56:57], v[74:75], 0, v[64:65]
	s_nop 0
	flat_load_dwordx4 v[56:59], v[56:57] offset:192
	v_lshl_add_u64 v[64:65], v[72:73], 0, v[64:65]
	s_andn2_b64 vcc, exec, s[42:43]
	s_waitcnt vmcnt(0) lgkmcnt(0)
	v_pk_add_f32 v[56:57], v[52:53], v[56:57]
	v_pk_add_f32 v[58:59], v[54:55], v[58:59]
	flat_store_dwordx4 v[64:65], v[56:59] offset:192
	v_mov_b32_e32 v64, v86
	s_cbranch_vccnz .LBB0_913
	v_lshl_add_u64 v[62:63], v[62:63], 2, s[30:31]
	global_load_dwordx4 v[62:65], v[62:63], off offset:192
	v_ashrrev_i32_e32 v133, 31, v132
	v_lshl_add_u64 v[66:67], v[132:133], 1, v[68:69]
	s_waitcnt vmcnt(0)
	v_pk_mul_f32 v[62:63], v[56:57], v[62:63]
	v_pk_mul_f32 v[56:57], v[56:57], v[56:57]
	v_pk_mul_f32 v[64:65], v[58:59], v[64:65]
	v_pk_mul_f32 v[58:59], v[58:59], v[58:59]
	v_add_f32_e32 v2, v56, v57
	v_cvt_pk_bf16_f32 v65, v64, v65
	v_cvt_pk_bf16_f32 v64, v62, v63
	v_mov_b32_e32 v62, v60
	v_mov_b32_e32 v63, v61
	v_add_f32_e32 v2, v2, v58
	v_permlane16_swap_b32_e32 v62, v64
	v_permlane16_swap_b32_e32 v63, v65
	v_add_f32_e32 v2, v2, v59
	flat_store_dwordx4 v[66:67], v[62:65] offset:96
	s_nop 1
	v_add_f32_e32 v64, v86, v2

; __device__ __forceinline__ float b2f(u16 b) { return __uint_as_float(((uint32_t)b) << 16); }
; __device__ __forceinline__ float sigmoidf_(float x) { return 1.0f / (1.0f + __expf(-x)); }
; __device__ __forceinline__ void gemm_phase(const Ctx& cx, const GemmArgs& g_, char* shm) {
;     ...
;               const uint2 gv = *(const uint2*)(g.gate + (size_t)tok * NP + n0);
;               float v0 = sigmoidf_(b2f((u16)(gv.x & 0xffff))) * a[0], v1 = sigmoidf_(b2f((u16)(gv.x >> 16))) * a[1];
;               float v2 = sigmoidf_(b2f((u16)(gv.y & 0xffff))) * a[2], v3 = sigmoidf_(b2f((u16)(gv.y >> 16))) * a[3];
;               uint2* mp = (uint2*)(g.outb + (size_t)tok * DM + n0);
;               if (g.epi != EPI_BR0) {
;                 const uint2 pv = *mp;
;                 v0 += b2f((u16)(pv.x & 0xffff)); v1 += b2f((u16)(pv.x >> 16));
;                 v2 += b2f((u16)(pv.y & 0xffff)); v3 += b2f((u16)(pv.y >> 16));
;               }
.LBB0_915:
	v_lshl_add_u64 v[56:57], v[138:139], 0, v[0:1]
	v_lshlrev_b64 v[58:59], 1, v[56:57]
	v_lshl_add_u64 v[56:57], v[82:83], 0, v[58:59]
	s_nop 0
	flat_load_dwordx2 v[62:63], v[56:57] offset:96
	v_lshl_add_u64 v[58:59], v[68:69], 0, v[58:59]
	s_waitcnt vmcnt(0) lgkmcnt(0)
	v_lshlrev_b32_e32 v2, 16, v62
	v_mul_f32_e32 v2, 0xbfb8aa3b, v2
	v_exp_f32_e32 v56, v2
	v_and_b32_e32 v2, 0xffff0000, v62
	v_mul_f32_e32 v2, 0xbfb8aa3b, v2
	v_exp_f32_e32 v57, v2
	s_nop 0
	v_pk_add_f32 v[56:57], v[56:57], 1.0 op_sel_hi:[1,0]
	s_nop 0
	v_div_scale_f32 v2, s[2:3], v57, v57, 1.0
	v_rcp_f32_e32 v62, v2
	s_nop 0
	v_fma_f32 v64, -v2, v62, 1.0
	v_fmac_f32_e32 v62, v64, v62
	v_div_scale_f32 v64, vcc, 1.0, v57, 1.0
	v_mul_f32_e32 v65, v64, v62
	v_fma_f32 v66, -v2, v65, v64
	v_fmac_f32_e32 v65, v66, v62
	v_fma_f32 v2, -v2, v65, v64
	v_div_fmas_f32 v2, v2, v62, v65
	v_div_fixup_f32 v57, v2, v57, 1.0
	v_div_scale_f32 v2, s[2:3], v56, v56, 1.0
	v_rcp_f32_e32 v62, v2
	s_nop 0
	v_fma_f32 v64, -v2, v62, 1.0
	v_fmac_f32_e32 v62, v64, v62
	v_div_scale_f32 v64, vcc, 1.0, v56, 1.0
	v_mul_f32_e32 v65, v64, v62
	v_fma_f32 v66, -v2, v65, v64
	v_fmac_f32_e32 v65, v66, v62
	v_fma_f32 v2, -v2, v65, v64
	v_div_fmas_f32 v2, v2, v62, v65
	v_div_fixup_f32 v56, v2, v56, 1.0
	v_lshlrev_b32_e32 v2, 16, v63
	v_mul_f32_e32 v2, 0xbfb8aa3b, v2
	v_exp_f32_e32 v62, v2
	v_and_b32_e32 v2, 0xffff0000, v63
	v_mul_f32_e32 v2, 0xbfb8aa3b, v2
	v_exp_f32_e32 v63, v2
	v_pk_mul_f32 v[56:57], v[52:53], v[56:57]
	v_pk_add_f32 v[62:63], v[62:63], 1.0 op_sel_hi:[1,0]
	s_nop 0
	v_div_scale_f32 v2, s[2:3], v63, v63, 1.0
	v_rcp_f32_e32 v64, v2
	s_nop 0
	v_fma_f32 v65, -v2, v64, 1.0
	v_fmac_f32_e32 v64, v65, v64
	v_div_scale_f32 v65, vcc, 1.0, v63, 1.0
	v_mul_f32_e32 v66, v65, v64
	v_fma_f32 v67, -v2, v66, v65
	v_fmac_f32_e32 v66, v67, v64
	v_fma_f32 v2, -v2, v66, v65
	v_div_fmas_f32 v2, v2, v64, v66
	v_div_fixup_f32 v63, v2, v63, 1.0
	v_div_scale_f32 v2, s[2:3], v62, v62, 1.0
	v_rcp_f32_e32 v64, v2
	s_nop 0
	v_fma_f32 v65, -v2, v64, 1.0
	v_fmac_f32_e32 v64, v65, v64
	v_div_scale_f32 v65, vcc, 1.0, v62, 1.0
	v_mul_f32_e32 v66, v65, v64
	v_fma_f32 v67, -v2, v66, v65
	v_fmac_f32_e32 v66, v67, v64
	v_fma_f32 v2, -v2, v66, v65
	v_div_fmas_f32 v2, v2, v64, v66
	v_div_fixup_f32 v62, v2, v62, 1.0
	v_pk_mul_f32 v[62:63], v[54:55], v[62:63]
	s_and_b64 vcc, exec, s[4:5]
	s_cbranch_vccnz .LBB0_917
	flat_load_dwordx2 v[64:65], v[58:59] offset:96
	s_waitcnt vmcnt(0) lgkmcnt(0)
	v_lshlrev_b32_e32 v66, 16, v64
	v_and_b32_e32 v67, 0xffff0000, v64
	v_lshlrev_b32_e32 v64, 16, v65
	v_and_b32_e32 v65, 0xffff0000, v65
	v_pk_add_f32 v[56:57], v[56:57], v[66:67]
	v_pk_add_f32 v[62:63], v[62:63], v[64:65]

; __device__ __forceinline__ void gemm_phase(const Ctx& cx, const GemmArgs& g_, char* shm) {
;     ...
;             const int n0 = brow + ai * 128 + wr * 64 + m * 16 + fq * 4;
;             f32x4 a = acc[ai][bj][m][n];
;             if (g.epi == EPI_PROJ || g.epi == EPI_RELU2) { a[0] *= rs; a[1] *= rs; a[2] *= rs; a[3] *= rs; }
;             if (g.epi == EPI_PROJ) {
;               if (n0 >= C_GLAX) {
;                 const int i = n0 - C_GLAX;
;                 const float4 b4 = *(const float4*)(g.hin + i);
;                 float xs[4] = {a[0] + b4.x, a[1] + b4.y, a[2] + b4.z, a[3] + b4.w};
; #pragma unroll
;                 for (int j = 0; j < 4; ++j)
;                   xs[j] = (fminf(xs[j], 0.f) - __logf(1.0f + __expf(-fabsf(xs[j])))) * (1.0f / 16.0f);
;                 *(float4*)(g.f32buf + (size_t)tok * 1024 + i) = make_float4(xs[0], xs[1], xs[2], xs[3]);
;               } else {
;                 float o0 = a[0], o1 = a[1], o2 = a[2], o3 = a[3];
;                 const bool r128 = (n0 >= C_DSAQ && n0 < C_HGQ) || (n0 >= C_DSAK && n0 < C_DSAV);
;                 const bool r64 = (n0 >= C_IDXQ && n0 < C_GLAA);
;                 if (r128 || r64) {
;                   float4 cs;
;                   float sc;
;                   if (r128) {
;                     cs = *(const float4*)(g.w + ((size_t)tok * 64 + ((n0 & 127) >> 1)) * 2);
;                     sc = (n0 < C_HGQ) ? 0.08838834764831845f : 1.0f;
;                   } else {
;                     cs = *(const float4*)(g.hout + ((size_t)tok * 32 + ((n0 & 63) >> 1)) * 2);
;                     sc = (n0 < C_IDXK) ? 0.125f : 1.0f;
;                   }
;                   o0 = (a[0] * cs.x - a[1] * cs.y) * sc; o1 = (a[1] * cs.x + a[0] * cs.y) * sc;
;                   o2 = (a[2] * cs.z - a[3] * cs.w) * sc; o3 = (a[3] * cs.z + a[2] * cs.w) * sc;
;                 }
;                 uint2 o; o.x = pack2(o0, o1); o.y = pack2(o2, o3);
;                 EMIT_BF16(g.ldo, o);
.LBB0_918:
	s_movk_i32 s0, 0x5c00
	v_cmp_gt_i32_e32 vcc, s0, v176
	s_and_saveexec_b64 s[2:3], vcc
	s_xor_b64 s[2:3], exec, s[2:3]
	s_cbranch_execz .LBB0_926
	v_add_u32_e32 v2, 0xffffa700, v138
	v_cmp_gt_u32_e32 vcc, s77, v2
	s_or_b64 s[60:61], s[58:59], vcc
	s_and_saveexec_b64 s[10:11], s[60:61]
	s_cbranch_execz .LBB0_925
	s_and_saveexec_b64 s[60:61], s[56:57]
	s_xor_b64 s[60:61], exec, s[60:61]
	v_lshlrev_b32_e32 v2, 2, v0
	s_movk_i32 s0, 0x5b00
	v_lshl_add_u64 v[56:57], v[80:81], 0, v[2:3]
	s_mov_b64 s[68:69], 0xc0
	v_cmp_gt_u32_e32 vcc, s0, v138
	v_lshl_add_u64 v[56:57], v[56:57], 0, s[68:69]
	s_nop 0
	v_cndmask_b32_e32 v2, 1.0, v166, vcc
	s_andn2_saveexec_b64 s[60:61], s[60:61]
	v_and_b32_e32 v2, 0x7c, v176
	v_lshlrev_b32_e32 v2, 2, v2
	v_cmp_gt_i32_e32 vcc, s81, v176
	v_lshl_add_u64 v[56:57], v[78:79], 0, v[2:3]
	s_nop 0
	v_cndmask_b32_e32 v2, 1.0, v167, vcc
	s_or_b64 exec, exec, s[60:61]
	s_nop 0
	flat_load_dwordx4 v[56:59], v[56:57]
	s_waitcnt vmcnt(0) lgkmcnt(0)
	v_pk_mul_f32 v[62:63], v[52:53], v[56:57] op_sel:[1,1] op_sel_hi:[1,0]
	s_nop 0
	v_pk_fma_f32 v[64:65], v[52:53], v[56:57], v[62:63] neg_lo:[0,0,1] neg_hi:[0,0,1]
	v_pk_fma_f32 v[52:53], v[52:53], v[56:57], v[62:63] op_sel_hi:[0,1,1]
	v_mov_b32_e32 v56, v55
	v_pk_mul_f32 v[56:57], v[56:57], v[58:59] op_sel:[0,1] op_sel_hi:[0,0]
	v_pk_fma_f32 v[62:63], v[54:55], v[58:59], v[56:57] neg_lo:[0,0,1] neg_hi:[0,0,1]
	v_pk_fma_f32 v[54:55], v[54:55], v[58:59], v[56:57] op_sel_hi:[0,1,1]
	v_mov_b32_e32 v65, v53
	v_mov_b32_e32 v63, v55
	v_pk_mul_f32 v[52:53], v[2:3], v[64:65] op_sel_hi:[0,1]
	v_pk_mul_f32 v[54:55], v[2:3], v[62:63] op_sel_hi:[0,1]
.LBB0_925:
	s_or_b64 exec, exec, s[10:11]
	v_cvt_pk_bf16_f32 v2, v54, v55
	v_cvt_pk_bf16_f32 v54, v52, v53
	s_nop 1
	v_permlane16_swap_b32_e32 v60, v54
	v_permlane16_swap_b32_e32 v61, v2
	v_ashrrev_i32_e32 v133, 31, v132
	v_lshl_add_u64 v[52:53], v[132:133], 1, v[84:85]
	v_mov_b32_e32 v62, v54
	v_mov_b32_e32 v63, v2
	s_nop 0
	flat_store_dwordx4 v[52:53], v[60:63] offset:96
.LBB0_926:
	s_andn2_saveexec_b64 s[2:3], s[2:3]
	s_cbranch_execz .LBB0_928
	v_add_u32_e32 v2, 0xffffa400, v176
	v_lshlrev_b64 v[60:61], 2, v[2:3]
	v_lshl_add_u64 v[56:57], s[26:27], 0, v[60:61]
	s_nop 0
	flat_load_dwordx4 v[56:59], v[56:57]
	s_mov_b32 s0, 0x3d800000
	v_lshl_add_u64 v[60:61], v[70:71], 0, v[60:61]
	s_waitcnt vmcnt(0) lgkmcnt(0)
	v_add_f32_e32 v2, v52, v56
	v_min_f32_e32 v52, 0, v2
	v_mul_f32_e64 v2, |v2|, s82
	v_exp_f32_e32 v2, v2
	v_add_f32_e32 v56, v53, v57
	v_add_f32_e32 v57, v54, v58
	v_add_f32_e32 v59, v55, v59
	v_add_f32_e32 v2, 1.0, v2
	v_cmp_gt_f32_e32 vcc, s83, v2
	s_nop 1
	v_cndmask_b32_e64 v53, 0, 32, vcc
	v_ldexp_f32 v2, v2, v53
	v_log_f32_e32 v2, v2
	s_nop 0
	v_mul_f32_e32 v53, 0x3f317217, v2
	v_fma_f32 v53, v2, s86, -v53
	v_fmac_f32_e32 v53, 0x3377d1cf, v2
	v_fmac_f32_e32 v53, 0x3f317217, v2
	v_cmp_lt_f32_e64 s[10:11], |v2|, s87
	s_nop 1
	v_cndmask_b32_e64 v2, v2, v53, s[10:11]
	v_cndmask_b32_e32 v53, 0, v165, vcc
	v_sub_f32_e32 v54, v2, v53
	v_mul_f32_e64 v2, |v56|, s82
	v_exp_f32_e32 v2, v2
	v_min_f32_e32 v53, 0, v56
	v_min_f32_e32 v56, 0, v57
	v_add_f32_e32 v2, 1.0, v2
	v_cmp_gt_f32_e32 vcc, s83, v2
	s_nop 1
	v_cndmask_b32_e64 v55, 0, 32, vcc
	v_ldexp_f32 v2, v2, v55
	v_log_f32_e32 v2, v2
	s_nop 0
	v_mul_f32_e32 v55, 0x3f317217, v2
	v_fma_f32 v55, v2, s86, -v55
	v_fmac_f32_e32 v55, 0x3377d1cf, v2
	v_fmac_f32_e32 v55, 0x3f317217, v2
	v_cmp_lt_f32_e64 s[10:11], |v2|, s87
	s_nop 1
	v_cndmask_b32_e64 v2, v2, v55, s[10:11]
	v_cndmask_b32_e32 v55, 0, v165, vcc
	v_sub_f32_e32 v55, v2, v55
	v_mul_f32_e64 v2, |v57|, s82
	v_exp_f32_e32 v2, v2
	v_pk_add_f32 v[52:53], v[52:53], v[54:55] neg_lo:[0,1] neg_hi:[0,1]
	v_add_f32_e32 v2, 1.0, v2
	v_cmp_gt_f32_e32 vcc, s83, v2
	v_pk_mul_f32 v[52:53], v[52:53], s[0:1] op_sel_hi:[1,0]
	s_nop 0
	v_cndmask_b32_e64 v57, 0, 32, vcc
	v_ldexp_f32 v2, v2, v57
	v_log_f32_e32 v2, v2
	s_nop 0
	v_mul_f32_e32 v57, 0x3f317217, v2
	v_fma_f32 v57, v2, s86, -v57
	v_fmac_f32_e32 v57, 0x3377d1cf, v2
	v_fmac_f32_e32 v57, 0x3f317217, v2
	v_cmp_lt_f32_e64 s[10:11], |v2|, s87
	s_nop 1
	v_cndmask_b32_e64 v2, v2, v57, s[10:11]
	v_cndmask_b32_e32 v57, 0, v165, vcc
	v_sub_f32_e32 v58, v2, v57
	v_mul_f32_e64 v2, |v59|, s82
	v_exp_f32_e32 v2, v2
	v_min_f32_e32 v57, 0, v59
	v_add_f32_e32 v2, 1.0, v2
	v_cmp_gt_f32_e32 vcc, s83, v2
	s_nop 1
	v_cndmask_b32_e64 v59, 0, 32, vcc
	v_ldexp_f32 v2, v2, v59
	v_log_f32_e32 v2, v2
	s_nop 0
	v_mul_f32_e32 v59, 0x3f317217, v2
	v_fma_f32 v59, v2, s86, -v59
	v_fmac_f32_e32 v59, 0x3377d1cf, v2
	v_fmac_f32_e32 v59, 0x3f317217, v2
	v_cmp_lt_f32_e64 s[10:11], |v2|, s87
	s_nop 1
	v_cndmask_b32_e64 v2, v2, v59, s[10:11]
	v_cndmask_b32_e32 v59, 0, v165, vcc
	v_sub_f32_e32 v59, v2, v59
	v_pk_add_f32 v[54:55], v[56:57], v[58:59] neg_lo:[0,1] neg_hi:[0,1]
	s_nop 0
	v_pk_mul_f32 v[54:55], v[54:55], s[0:1] op_sel_hi:[1,0]
	flat_store_dwordx4 v[60:61], v[52:55]

; __device__ __forceinline__ void gemm_phase(const Ctx& cx, const GemmArgs& g_, char* shm) {
;     ...
;             } else if (g.epi == EPI_RES) {
;               const float4 hv = *(const float4*)(g.hin + (size_t)tok * DM + n0);
;               const float h0 = hv.x + a[0], h1 = hv.y + a[1], h2 = hv.z + a[2], h3 = hv.w + a[3];
;               *(float4*)(g.hout + (size_t)tok * DM + n0) = make_float4(h0, h1, h2, h3);
;               if (g.w != nullptr) {
;                 const float4 nw = *(const float4*)(g.w + n0);
;                 uint2 o; o.x = pack2(h0 * nw.x, h1 * nw.y); o.y = pack2(h2 * nw.z, h3 * nw.w);
;                 EMIT_BF16(DM, o);
;                 ssq += h0 * h0 + h1 * h1 + h2 * h2 + h3 * h3;
;               }
.LBB0_943:
	s_and_b64 vcc, exec, s[60:61]
	v_mov_b32_e32 v55, v64
	s_cbranch_vccz .LBB0_946
	v_lshlrev_b64 v[56:57], 2, v[122:123]
	v_lshl_add_u64 v[52:53], v[74:75], 0, v[56:57]
	s_nop 0
	flat_load_dwordx4 v[52:55], v[52:53]
	v_lshl_add_u64 v[56:57], v[72:73], 0, v[56:57]
	s_andn2_b64 vcc, exec, s[42:43]
	s_waitcnt vmcnt(0) lgkmcnt(0)
	v_pk_add_f32 v[52:53], v[48:49], v[52:53]
	v_pk_add_f32 v[54:55], v[50:51], v[54:55]
	flat_store_dwordx4 v[56:57], v[52:55]
	s_cbranch_vccnz .LBB0_1079
	v_lshl_add_u64 v[56:57], v[122:123], 2, s[30:31]
	global_load_dwordx4 v[56:59], v[56:57], off
	s_waitcnt vmcnt(0)
	v_pk_mul_f32 v[56:57], v[52:53], v[56:57]
	v_pk_mul_f32 v[52:53], v[52:53], v[52:53]
	v_pk_mul_f32 v[58:59], v[54:55], v[58:59]
	v_pk_mul_f32 v[54:55], v[54:55], v[54:55]
	v_add_f32_e32 v2, v52, v53
	v_add_f32_e32 v2, v2, v54
	v_add_f32_e32 v2, v2, v55
	v_cvt_pk_bf16_f32 v58, v58, v59
	v_cvt_pk_bf16_f32 v56, v56, v57
	v_add_f32_e32 v55, v64, v2

; __device__ __forceinline__ float b2f(u16 b) { return __uint_as_float(((uint32_t)b) << 16); }
; __device__ __forceinline__ float sigmoidf_(float x) { return 1.0f / (1.0f + __expf(-x)); }
; __device__ __forceinline__ void gemm_phase(const Ctx& cx, const GemmArgs& g_, char* shm) {
;     ...
;               const uint2 gv = *(const uint2*)(g.gate + (size_t)tok * NP + n0);
;               float v0 = sigmoidf_(b2f((u16)(gv.x & 0xffff))) * a[0], v1 = sigmoidf_(b2f((u16)(gv.x >> 16))) * a[1];
;               float v2 = sigmoidf_(b2f((u16)(gv.y & 0xffff))) * a[2], v3 = sigmoidf_(b2f((u16)(gv.y >> 16))) * a[3];
;               uint2* mp = (uint2*)(g.outb + (size_t)tok * DM + n0);
;               if (g.epi != EPI_BR0) {
;                 const uint2 pv = *mp;
;                 v0 += b2f((u16)(pv.x & 0xffff)); v1 += b2f((u16)(pv.x >> 16));
;                 v2 += b2f((u16)(pv.y & 0xffff)); v3 += b2f((u16)(pv.y >> 16));
;               }
.LBB0_948:
	v_lshlrev_b64 v[54:55], 1, v[122:123]
	v_lshl_add_u64 v[52:53], v[82:83], 0, v[54:55]
	s_nop 0
	flat_load_dwordx2 v[56:57], v[52:53]
	v_lshl_add_u64 v[54:55], v[68:69], 0, v[54:55]
	s_waitcnt vmcnt(0) lgkmcnt(0)
	v_lshlrev_b32_e32 v2, 16, v56
	v_mul_f32_e32 v2, 0xbfb8aa3b, v2
	v_exp_f32_e32 v52, v2
	v_and_b32_e32 v2, 0xffff0000, v56
	v_mul_f32_e32 v2, 0xbfb8aa3b, v2
	v_exp_f32_e32 v53, v2
	s_nop 0
	v_pk_add_f32 v[52:53], v[52:53], 1.0 op_sel_hi:[1,0]
	s_nop 0
	v_div_scale_f32 v2, s[2:3], v53, v53, 1.0
	v_rcp_f32_e32 v56, v2
	s_nop 0
	v_fma_f32 v58, -v2, v56, 1.0
	v_fmac_f32_e32 v56, v58, v56
	v_div_scale_f32 v58, vcc, 1.0, v53, 1.0
	v_mul_f32_e32 v59, v58, v56
	v_fma_f32 v60, -v2, v59, v58
	v_fmac_f32_e32 v59, v60, v56
	v_fma_f32 v2, -v2, v59, v58
	v_div_fmas_f32 v2, v2, v56, v59
	v_div_fixup_f32 v53, v2, v53, 1.0
	v_div_scale_f32 v2, s[2:3], v52, v52, 1.0
	v_rcp_f32_e32 v56, v2
	s_nop 0
	v_fma_f32 v58, -v2, v56, 1.0
	v_fmac_f32_e32 v56, v58, v56
	v_div_scale_f32 v58, vcc, 1.0, v52, 1.0
	v_mul_f32_e32 v59, v58, v56
	v_fma_f32 v60, -v2, v59, v58
	v_fmac_f32_e32 v59, v60, v56
	v_fma_f32 v2, -v2, v59, v58
	v_div_fmas_f32 v2, v2, v56, v59
	v_div_fixup_f32 v52, v2, v52, 1.0
	v_lshlrev_b32_e32 v2, 16, v57
	v_mul_f32_e32 v2, 0xbfb8aa3b, v2
	v_exp_f32_e32 v56, v2
	v_and_b32_e32 v2, 0xffff0000, v57
	v_mul_f32_e32 v2, 0xbfb8aa3b, v2
	v_exp_f32_e32 v57, v2
	v_pk_mul_f32 v[52:53], v[48:49], v[52:53]
	v_pk_add_f32 v[56:57], v[56:57], 1.0 op_sel_hi:[1,0]
	s_nop 0
	v_div_scale_f32 v2, s[2:3], v57, v57, 1.0
	v_rcp_f32_e32 v58, v2
	s_nop 0
	v_fma_f32 v59, -v2, v58, 1.0
	v_fmac_f32_e32 v58, v59, v58
	v_div_scale_f32 v59, vcc, 1.0, v57, 1.0
	v_mul_f32_e32 v60, v59, v58
	v_fma_f32 v61, -v2, v60, v59
	v_fmac_f32_e32 v60, v61, v58
	v_fma_f32 v2, -v2, v60, v59
	v_div_fmas_f32 v2, v2, v58, v60
	v_div_fixup_f32 v57, v2, v57, 1.0
	v_div_scale_f32 v2, s[2:3], v56, v56, 1.0
	v_rcp_f32_e32 v58, v2
	s_nop 0
	v_fma_f32 v59, -v2, v58, 1.0
	v_fmac_f32_e32 v58, v59, v58
	v_div_scale_f32 v59, vcc, 1.0, v56, 1.0
	v_mul_f32_e32 v60, v59, v58
	v_fma_f32 v61, -v2, v60, v59
	v_fmac_f32_e32 v60, v61, v58
	v_fma_f32 v2, -v2, v60, v59
	v_div_fmas_f32 v2, v2, v58, v60
	v_div_fixup_f32 v56, v2, v56, 1.0
	v_pk_mul_f32 v[56:57], v[50:51], v[56:57]
	s_and_b64 vcc, exec, s[4:5]
	s_cbranch_vccnz .LBB0_950
	flat_load_dwordx2 v[58:59], v[54:55]
	s_waitcnt vmcnt(0) lgkmcnt(0)
	v_lshlrev_b32_e32 v60, 16, v58
	v_and_b32_e32 v61, 0xffff0000, v58
	v_lshlrev_b32_e32 v58, 16, v59
	v_and_b32_e32 v59, 0xffff0000, v59
	v_pk_add_f32 v[52:53], v[52:53], v[60:61]
	v_pk_add_f32 v[56:57], v[56:57], v[58:59]

; __device__ __forceinline__ void gemm_phase(const Ctx& cx, const GemmArgs& g_, char* shm) {
;     ...
;                 const bool r128 = (n0 >= C_DSAQ && n0 < C_HGQ) || (n0 >= C_DSAK && n0 < C_DSAV);
;                 const bool r64 = (n0 >= C_IDXQ && n0 < C_GLAA);
;                 if (r128 || r64) {
;                   float4 cs;
;                   float sc;
;                   if (r128) {
;                     cs = *(const float4*)(g.w + ((size_t)tok * 64 + ((n0 & 127) >> 1)) * 2);
;                     sc = (n0 < C_HGQ) ? 0.08838834764831845f : 1.0f;
;                   } else {
;                     cs = *(const float4*)(g.hout + ((size_t)tok * 32 + ((n0 & 63) >> 1)) * 2);
;                     sc = (n0 < C_IDXK) ? 0.125f : 1.0f;
;                   }
;                   o0 = (a[0] * cs.x - a[1] * cs.y) * sc; o1 = (a[1] * cs.x + a[0] * cs.y) * sc;
;                   o2 = (a[2] * cs.z - a[3] * cs.w) * sc; o3 = (a[3] * cs.z + a[2] * cs.w) * sc;
;                 }
.LBB0_951:
	s_movk_i32 s0, 0x5c00
	v_cmp_gt_i32_e32 vcc, s0, v122
	s_and_saveexec_b64 s[2:3], vcc
	s_xor_b64 s[2:3], exec, s[2:3]
	s_cbranch_execz .LBB0_959
	v_add_u32_e32 v2, 0xffffa780, v138
	v_cmp_gt_u32_e32 vcc, s77, v2
	s_or_b64 s[60:61], s[54:55], vcc
	s_and_saveexec_b64 s[10:11], s[60:61]
	s_cbranch_execz .LBB0_958
	s_and_saveexec_b64 s[60:61], s[52:53]
	s_xor_b64 s[60:61], exec, s[60:61]
	s_movk_i32 s0, 0x5b00
	v_lshlrev_b32_e32 v2, 2, v0
	v_cmp_gt_u32_e32 vcc, s0, v120
	v_lshl_add_u64 v[52:53], v[80:81], 0, v[2:3]
	s_nop 0
	v_cndmask_b32_e32 v2, 1.0, v166, vcc
	s_andn2_saveexec_b64 s[60:61], s[60:61]
	v_and_b32_e32 v2, 0x4c, v122
	v_lshlrev_b32_e32 v2, 2, v2
	v_cmp_gt_i32_e32 vcc, s81, v122
	v_lshl_add_u64 v[52:53], v[78:79], 0, v[2:3]
	s_nop 0
	v_cndmask_b32_e32 v2, 1.0, v167, vcc
	s_or_b64 exec, exec, s[60:61]
	s_nop 0
	flat_load_dwordx4 v[52:55], v[52:53]
	s_waitcnt vmcnt(0) lgkmcnt(0)
	v_pk_mul_f32 v[56:57], v[48:49], v[52:53] op_sel:[1,1] op_sel_hi:[1,0]
	s_nop 0
	v_pk_fma_f32 v[58:59], v[48:49], v[52:53], v[56:57] neg_lo:[0,0,1] neg_hi:[0,0,1]
	v_pk_fma_f32 v[48:49], v[48:49], v[52:53], v[56:57] op_sel_hi:[0,1,1]
	v_mov_b32_e32 v52, v51
	v_pk_mul_f32 v[52:53], v[52:53], v[54:55] op_sel:[0,1] op_sel_hi:[0,0]
	v_pk_fma_f32 v[56:57], v[50:51], v[54:55], v[52:53] neg_lo:[0,0,1] neg_hi:[0,0,1]
	v_pk_fma_f32 v[50:51], v[50:51], v[54:55], v[52:53] op_sel_hi:[0,1,1]
	v_mov_b32_e32 v59, v49
	v_mov_b32_e32 v57, v51
	v_pk_mul_f32 v[48:49], v[2:3], v[58:59] op_sel_hi:[0,1]
	v_pk_mul_f32 v[50:51], v[2:3], v[56:57] op_sel_hi:[0,1]

; __device__ __forceinline__ void gemm_phase(const Ctx& cx, const GemmArgs& g_, char* shm) {
;     ...
;               if (n0 >= C_GLAX) {
;                 const int i = n0 - C_GLAX;
;                 const float4 b4 = *(const float4*)(g.hin + i);
;                 float xs[4] = {a[0] + b4.x, a[1] + b4.y, a[2] + b4.z, a[3] + b4.w};
; #pragma unroll
;                 for (int j = 0; j < 4; ++j)
;                   xs[j] = (fminf(xs[j], 0.f) - __logf(1.0f + __expf(-fabsf(xs[j])))) * (1.0f / 16.0f);
;                 *(float4*)(g.f32buf + (size_t)tok * 1024 + i) = make_float4(xs[0], xs[1], xs[2], xs[3]);
.LBB0_959:
	s_andn2_saveexec_b64 s[2:3], s[2:3]
	s_cbranch_execz .LBB0_961
	v_add_u32_e32 v2, 0xffffa400, v122
	v_lshlrev_b64 v[56:57], 2, v[2:3]
	v_lshl_add_u64 v[52:53], s[26:27], 0, v[56:57]
	s_nop 0
	flat_load_dwordx4 v[52:55], v[52:53]
	s_mov_b32 s0, 0x3d800000
	v_lshl_add_u64 v[56:57], v[70:71], 0, v[56:57]
	v_mov_b32_e32 v58, 0
	s_waitcnt vmcnt(0) lgkmcnt(0)
	v_add_f32_e32 v2, v48, v52
	v_min_f32_e32 v48, 0, v2
	v_mul_f32_e64 v2, |v2|, s82
	v_exp_f32_e32 v2, v2
	v_add_f32_e32 v52, v49, v53
	v_add_f32_e32 v53, v50, v54
	v_add_f32_e32 v55, v51, v55
	v_add_f32_e32 v2, 1.0, v2
	v_cmp_gt_f32_e32 vcc, s83, v2
	s_nop 1
	v_cndmask_b32_e64 v49, 0, 32, vcc
	v_ldexp_f32 v2, v2, v49
	v_log_f32_e32 v2, v2
	s_nop 0
	v_mul_f32_e32 v49, 0x3f317217, v2
	v_fma_f32 v49, v2, s86, -v49
	v_fmac_f32_e32 v49, 0x3377d1cf, v2
	v_fmac_f32_e32 v49, 0x3f317217, v2
	v_cmp_lt_f32_e64 s[10:11], |v2|, s87
	s_nop 1
	v_cndmask_b32_e64 v2, v2, v49, s[10:11]
	v_cndmask_b32_e32 v49, 0, v165, vcc
	v_sub_f32_e32 v50, v2, v49
	v_mul_f32_e64 v2, |v52|, s82
	v_exp_f32_e32 v2, v2
	v_min_f32_e32 v49, 0, v52
	v_min_f32_e32 v52, 0, v53
	v_add_f32_e32 v2, 1.0, v2
	v_cmp_gt_f32_e32 vcc, s83, v2
	s_nop 1
	v_cndmask_b32_e64 v51, 0, 32, vcc
	v_ldexp_f32 v2, v2, v51
	v_log_f32_e32 v2, v2
	s_nop 0
	v_mul_f32_e32 v51, 0x3f317217, v2
	v_fma_f32 v51, v2, s86, -v51
	v_fmac_f32_e32 v51, 0x3377d1cf, v2
	v_fmac_f32_e32 v51, 0x3f317217, v2
	v_cmp_lt_f32_e64 s[10:11], |v2|, s87
	s_nop 1
	v_cndmask_b32_e64 v2, v2, v51, s[10:11]
	v_cndmask_b32_e32 v51, 0, v165, vcc
	v_sub_f32_e32 v51, v2, v51
	v_mul_f32_e64 v2, |v53|, s82
	v_exp_f32_e32 v2, v2
	v_pk_add_f32 v[48:49], v[48:49], v[50:51] neg_lo:[0,1] neg_hi:[0,1]
	v_add_f32_e32 v2, 1.0, v2
	v_cmp_gt_f32_e32 vcc, s83, v2
	v_pk_mul_f32 v[48:49], v[48:49], s[0:1] op_sel_hi:[1,0]
	s_nop 0
	v_cndmask_b32_e64 v53, 0, 32, vcc
	v_ldexp_f32 v2, v2, v53
	v_log_f32_e32 v2, v2
	s_nop 0
	v_mul_f32_e32 v53, 0x3f317217, v2
	v_fma_f32 v53, v2, s86, -v53
	v_fmac_f32_e32 v53, 0x3377d1cf, v2
	v_fmac_f32_e32 v53, 0x3f317217, v2
	v_cmp_lt_f32_e64 s[10:11], |v2|, s87
	s_nop 1
	v_cndmask_b32_e64 v2, v2, v53, s[10:11]
	v_cndmask_b32_e32 v53, 0, v165, vcc
	v_sub_f32_e32 v54, v2, v53
	v_mul_f32_e64 v2, |v55|, s82
	v_exp_f32_e32 v2, v2
	v_min_f32_e32 v53, 0, v55
	v_add_f32_e32 v2, 1.0, v2
	v_cmp_gt_f32_e32 vcc, s83, v2
	s_nop 1
	v_cndmask_b32_e64 v55, 0, 32, vcc
	v_ldexp_f32 v2, v2, v55
	v_log_f32_e32 v2, v2
	s_nop 0
	v_mul_f32_e32 v55, 0x3f317217, v2
	v_fma_f32 v55, v2, s86, -v55
	v_fmac_f32_e32 v55, 0x3377d1cf, v2
	v_fmac_f32_e32 v55, 0x3f317217, v2
	v_cmp_lt_f32_e64 s[10:11], |v2|, s87
	s_nop 1
	v_cndmask_b32_e64 v2, v2, v55, s[10:11]
	v_cndmask_b32_e32 v55, 0, v165, vcc
	v_sub_f32_e32 v55, v2, v55
	v_pk_add_f32 v[50:51], v[52:53], v[54:55] neg_lo:[0,1] neg_hi:[0,1]
	s_nop 0
	v_pk_mul_f32 v[50:51], v[50:51], s[0:1] op_sel_hi:[1,0]
	flat_store_dwordx4 v[56:57], v[48:51]
	v_mov_b32_e32 v56, 0

; __device__ __forceinline__ void gemm_phase(const Ctx& cx, const GemmArgs& g_, char* shm) {
;     ...
;             } else if (g.epi == EPI_RELU2) {
;               float r0 = fmaxf(a[0], 0.f), r1 = fmaxf(a[1], 0.f), r2 = fmaxf(a[2], 0.f), r3 = fmaxf(a[3], 0.f);
;               uint2 o; o.x = pack2(r0 * r0, r1 * r1); o.y = pack2(r2 * r2, r3 * r3);
;               EMIT_BF16(g.ldo, o);
.LBB0_972:
	s_cmp_gt_i32 s38, 4
	s_cbranch_scc0 .LBB0_976
	s_cmp_eq_u32 s38, 5
	s_mov_b64 s[10:11], -1
	s_cbranch_scc0 .LBB0_975
	v_max_f32_e32 v2, v46, v46
	v_max_f32_e32 v48, 0, v2
	v_max_f32_e32 v2, v47, v47
	v_max_f32_e32 v49, 0, v2
	v_pk_mul_f32 v[48:49], v[48:49], v[48:49]
	v_max_f32_e32 v2, v44, v44
	v_cvt_pk_bf16_f32 v51, v48, v49
	v_max_f32_e32 v48, 0, v2
	v_max_f32_e32 v2, v45, v45
	v_max_f32_e32 v49, 0, v2
	v_pk_mul_f32 v[48:49], v[48:49], v[48:49]
	v_ashrrev_i32_e32 v117, 31, v116
	v_cvt_pk_bf16_f32 v50, v48, v49
	v_mov_b32_e32 v48, v56
	v_mov_b32_e32 v49, v58
	s_nop 0
	v_permlane16_swap_b32_e32 v48, v50
	v_permlane16_swap_b32_e32 v49, v51
	v_lshl_add_u64 v[52:53], v[116:117], 1, v[84:85]
	s_nop 0
	flat_store_dwordx4 v[52:53], v[48:51] offset:32
	s_mov_b64 s[10:11], 0

; __device__ __forceinline__ void gemm_phase(const Ctx& cx, const GemmArgs& g_, char* shm) {
;     ...
;             } else if (g.epi == EPI_RES) {
;               const float4 hv = *(const float4*)(g.hin + (size_t)tok * DM + n0);
;               const float h0 = hv.x + a[0], h1 = hv.y + a[1], h2 = hv.z + a[2], h3 = hv.w + a[3];
;               *(float4*)(g.hout + (size_t)tok * DM + n0) = make_float4(h0, h1, h2, h3);
;               if (g.w != nullptr) {
;                 const float4 nw = *(const float4*)(g.w + n0);
;                 uint2 o; o.x = pack2(h0 * nw.x, h1 * nw.y); o.y = pack2(h2 * nw.z, h3 * nw.w);
;                 EMIT_BF16(DM, o);
;                 ssq += h0 * h0 + h1 * h1 + h2 * h2 + h3 * h3;
;               }
.LBB0_976:
	s_and_b64 vcc, exec, s[60:61]
	v_mov_b32_e32 v54, v55
	s_cbranch_vccz .LBB0_979
	v_lshl_add_u64 v[52:53], v[120:121], 0, v[0:1]
	v_lshlrev_b64 v[60:61], 2, v[52:53]
	v_lshl_add_u64 v[48:49], v[74:75], 0, v[60:61]
	s_nop 0
	flat_load_dwordx4 v[48:51], v[48:49] offset:64
	v_lshl_add_u64 v[60:61], v[72:73], 0, v[60:61]
	s_andn2_b64 vcc, exec, s[42:43]
	v_mov_b32_e32 v54, v55
	s_waitcnt vmcnt(0) lgkmcnt(0)
	v_pk_add_f32 v[48:49], v[44:45], v[48:49]
	v_pk_add_f32 v[50:51], v[46:47], v[50:51]
	flat_store_dwordx4 v[60:61], v[48:51] offset:64
	s_cbranch_vccnz .LBB0_979
	v_lshl_add_u64 v[52:53], v[52:53], 2, s[30:31]
	global_load_dwordx4 v[60:63], v[52:53], off offset:64
	v_ashrrev_i32_e32 v117, 31, v116
	s_waitcnt vmcnt(0)
	v_pk_mul_f32 v[52:53], v[50:51], v[62:63]
	s_nop 0
	v_cvt_pk_bf16_f32 v63, v52, v53
	v_pk_mul_f32 v[52:53], v[48:49], v[60:61]
	v_pk_mul_f32 v[48:49], v[48:49], v[48:49]
	v_pk_mul_f32 v[50:51], v[50:51], v[50:51]
	v_add_f32_e32 v2, v48, v49
	v_cvt_pk_bf16_f32 v62, v52, v53
	v_mov_b32_e32 v60, v56
	v_mov_b32_e32 v61, v58
	v_add_f32_e32 v2, v2, v50
	v_permlane16_swap_b32_e32 v60, v62
	v_permlane16_swap_b32_e32 v61, v63
	v_lshl_add_u64 v[52:53], v[116:117], 1, v[68:69]
	v_add_f32_e32 v2, v2, v51
	flat_store_dwordx4 v[52:53], v[60:63] offset:32
	v_add_f32_e32 v54, v55, v2

; __device__ __forceinline__ float b2f(u16 b) { return __uint_as_float(((uint32_t)b) << 16); }
; __device__ __forceinline__ float sigmoidf_(float x) { return 1.0f / (1.0f + __expf(-x)); }
; __device__ __forceinline__ void gemm_phase(const Ctx& cx, const GemmArgs& g_, char* shm) {
;     ...
;               const uint2 gv = *(const uint2*)(g.gate + (size_t)tok * NP + n0);
;               float v0 = sigmoidf_(b2f((u16)(gv.x & 0xffff))) * a[0], v1 = sigmoidf_(b2f((u16)(gv.x >> 16))) * a[1];
;               float v2 = sigmoidf_(b2f((u16)(gv.y & 0xffff))) * a[2], v3 = sigmoidf_(b2f((u16)(gv.y >> 16))) * a[3];
;               uint2* mp = (uint2*)(g.outb + (size_t)tok * DM + n0);
;               if (g.epi != EPI_BR0) {
;                 const uint2 pv = *mp;
;                 v0 += b2f((u16)(pv.x & 0xffff)); v1 += b2f((u16)(pv.x >> 16));
;                 v2 += b2f((u16)(pv.y & 0xffff)); v3 += b2f((u16)(pv.y >> 16));
;               }
.LBB0_981:
	v_lshl_add_u64 v[48:49], v[120:121], 0, v[0:1]
	v_lshlrev_b64 v[50:51], 1, v[48:49]
	v_lshl_add_u64 v[48:49], v[82:83], 0, v[50:51]
	s_nop 0
	flat_load_dwordx2 v[52:53], v[48:49] offset:32
	v_lshl_add_u64 v[50:51], v[68:69], 0, v[50:51]
	s_waitcnt vmcnt(0) lgkmcnt(0)
	v_lshlrev_b32_e32 v2, 16, v52
	v_mul_f32_e32 v2, 0xbfb8aa3b, v2
	v_exp_f32_e32 v48, v2
	v_and_b32_e32 v2, 0xffff0000, v52
	v_mul_f32_e32 v2, 0xbfb8aa3b, v2
	v_exp_f32_e32 v49, v2
	s_nop 0
	v_pk_add_f32 v[48:49], v[48:49], 1.0 op_sel_hi:[1,0]
	s_nop 0
	v_div_scale_f32 v2, s[2:3], v49, v49, 1.0
	v_rcp_f32_e32 v52, v2
	s_nop 0
	v_fma_f32 v54, -v2, v52, 1.0
	v_fmac_f32_e32 v52, v54, v52
	v_div_scale_f32 v54, vcc, 1.0, v49, 1.0
	v_mul_f32_e32 v57, v54, v52
	v_fma_f32 v59, -v2, v57, v54
	v_fmac_f32_e32 v57, v59, v52
	v_fma_f32 v2, -v2, v57, v54
	v_div_fmas_f32 v2, v2, v52, v57
	v_div_fixup_f32 v49, v2, v49, 1.0
	v_div_scale_f32 v2, s[2:3], v48, v48, 1.0
	v_rcp_f32_e32 v52, v2
	s_nop 0
	v_fma_f32 v54, -v2, v52, 1.0
	v_fmac_f32_e32 v52, v54, v52
	v_div_scale_f32 v54, vcc, 1.0, v48, 1.0
	v_mul_f32_e32 v57, v54, v52
	v_fma_f32 v59, -v2, v57, v54
	v_fmac_f32_e32 v57, v59, v52
	v_fma_f32 v2, -v2, v57, v54
	v_div_fmas_f32 v2, v2, v52, v57
	v_div_fixup_f32 v48, v2, v48, 1.0
	v_lshlrev_b32_e32 v2, 16, v53
	v_mul_f32_e32 v2, 0xbfb8aa3b, v2
	v_exp_f32_e32 v52, v2
	v_and_b32_e32 v2, 0xffff0000, v53
	v_mul_f32_e32 v2, 0xbfb8aa3b, v2
	v_exp_f32_e32 v53, v2
	v_pk_mul_f32 v[48:49], v[44:45], v[48:49]
	v_pk_add_f32 v[52:53], v[52:53], 1.0 op_sel_hi:[1,0]
	s_nop 0
	v_div_scale_f32 v2, s[2:3], v53, v53, 1.0
	v_rcp_f32_e32 v54, v2
	s_nop 0
	v_fma_f32 v57, -v2, v54, 1.0
	v_fmac_f32_e32 v54, v57, v54
	v_div_scale_f32 v57, vcc, 1.0, v53, 1.0
	v_mul_f32_e32 v59, v57, v54
	v_fma_f32 v60, -v2, v59, v57
	v_fmac_f32_e32 v59, v60, v54
	v_fma_f32 v2, -v2, v59, v57
	v_div_fmas_f32 v2, v2, v54, v59
	v_div_fixup_f32 v53, v2, v53, 1.0
	v_div_scale_f32 v2, s[2:3], v52, v52, 1.0
	v_rcp_f32_e32 v54, v2
	s_nop 0
	v_fma_f32 v57, -v2, v54, 1.0
	v_fmac_f32_e32 v54, v57, v54
	v_div_scale_f32 v57, vcc, 1.0, v52, 1.0
	v_mul_f32_e32 v59, v57, v54
	v_fma_f32 v60, -v2, v59, v57
	v_fmac_f32_e32 v59, v60, v54
	v_fma_f32 v2, -v2, v59, v57
	v_div_fmas_f32 v2, v2, v54, v59
	v_div_fixup_f32 v52, v2, v52, 1.0
	v_pk_mul_f32 v[52:53], v[46:47], v[52:53]
	s_and_b64 vcc, exec, s[4:5]
	s_cbranch_vccnz .LBB0_983
	flat_load_dwordx2 v[60:61], v[50:51] offset:32
	s_waitcnt vmcnt(0) lgkmcnt(0)
	v_lshlrev_b32_e32 v62, 16, v60
	v_and_b32_e32 v63, 0xffff0000, v60
	v_lshlrev_b32_e32 v60, 16, v61
	v_and_b32_e32 v61, 0xffff0000, v61
	v_pk_add_f32 v[48:49], v[48:49], v[62:63]
	v_pk_add_f32 v[52:53], v[52:53], v[60:61]

; __device__ __forceinline__ void gemm_phase(const Ctx& cx, const GemmArgs& g_, char* shm) {
;     ...
;               if (n0 >= C_GLAX) {
;                 const int i = n0 - C_GLAX;
;                 const float4 b4 = *(const float4*)(g.hin + i);
;                 float xs[4] = {a[0] + b4.x, a[1] + b4.y, a[2] + b4.z, a[3] + b4.w};
; #pragma unroll
;                 for (int j = 0; j < 4; ++j)
;                   xs[j] = (fminf(xs[j], 0.f) - __logf(1.0f + __expf(-fabsf(xs[j])))) * (1.0f / 16.0f);
;                 *(float4*)(g.f32buf + (size_t)tok * 1024 + i) = make_float4(xs[0], xs[1], xs[2], xs[3]);
;               } else {
;                 float o0 = a[0], o1 = a[1], o2 = a[2], o3 = a[3];
;                 const bool r128 = (n0 >= C_DSAQ && n0 < C_HGQ) || (n0 >= C_DSAK && n0 < C_DSAV);
;                 const bool r64 = (n0 >= C_IDXQ && n0 < C_GLAA);
;                 if (r128 || r64) {
;                   float4 cs;
;                   float sc;
;                   if (r128) {
;                     cs = *(const float4*)(g.w + ((size_t)tok * 64 + ((n0 & 127) >> 1)) * 2);
;                     sc = (n0 < C_HGQ) ? 0.08838834764831845f : 1.0f;
;                   } else {
;                     cs = *(const float4*)(g.hout + ((size_t)tok * 32 + ((n0 & 63) >> 1)) * 2);
;                     sc = (n0 < C_IDXK) ? 0.125f : 1.0f;
;                   }
;                   o0 = (a[0] * cs.x - a[1] * cs.y) * sc; o1 = (a[1] * cs.x + a[0] * cs.y) * sc;
;                   o2 = (a[2] * cs.z - a[3] * cs.w) * sc; o3 = (a[3] * cs.z + a[2] * cs.w) * sc;
;                 }
;                 uint2 o; o.x = pack2(o0, o1); o.y = pack2(o2, o3);
;                 EMIT_BF16(g.ldo, o);
.LBB0_984:
	s_movk_i32 s0, 0x5c00
	v_cmp_gt_i32_e32 vcc, s0, v160
	s_and_saveexec_b64 s[2:3], vcc
	s_xor_b64 s[2:3], exec, s[2:3]
	s_cbranch_execz .LBB0_992
	v_add_u32_e32 v2, 0xffffa780, v138
	v_cmp_gt_u32_e32 vcc, s77, v2
	s_or_b64 s[60:61], s[54:55], vcc
	s_and_saveexec_b64 s[10:11], s[60:61]
	s_cbranch_execz .LBB0_991
	s_and_saveexec_b64 s[60:61], s[52:53]
	s_xor_b64 s[60:61], exec, s[60:61]
	v_lshlrev_b32_e32 v2, 2, v0
	s_movk_i32 s0, 0x5b00
	v_lshl_add_u64 v[48:49], v[80:81], 0, v[2:3]
	v_cmp_gt_u32_e32 vcc, s0, v120
	v_lshl_add_u64 v[48:49], v[48:49], 0, 64
	s_nop 0
	v_cndmask_b32_e32 v2, 1.0, v166, vcc
	s_andn2_saveexec_b64 s[60:61], s[60:61]
	v_and_b32_e32 v2, 0x5c, v160
	v_lshlrev_b32_e32 v2, 2, v2
	v_cmp_gt_i32_e32 vcc, s81, v160
	v_lshl_add_u64 v[48:49], v[78:79], 0, v[2:3]
	s_nop 0
	v_cndmask_b32_e32 v2, 1.0, v167, vcc
	s_or_b64 exec, exec, s[60:61]
	s_nop 0
	flat_load_dwordx4 v[48:51], v[48:49]
	s_waitcnt vmcnt(0) lgkmcnt(0)
	v_pk_mul_f32 v[52:53], v[44:45], v[48:49] op_sel:[1,1] op_sel_hi:[1,0]
	s_nop 0
	v_pk_fma_f32 v[60:61], v[44:45], v[48:49], v[52:53] neg_lo:[0,0,1] neg_hi:[0,0,1]
	v_pk_fma_f32 v[44:45], v[44:45], v[48:49], v[52:53] op_sel_hi:[0,1,1]
	v_mov_b32_e32 v48, v47
	v_pk_mul_f32 v[48:49], v[48:49], v[50:51] op_sel:[0,1] op_sel_hi:[0,0]
	v_pk_fma_f32 v[52:53], v[46:47], v[50:51], v[48:49] neg_lo:[0,0,1] neg_hi:[0,0,1]
	v_pk_fma_f32 v[46:47], v[46:47], v[50:51], v[48:49] op_sel_hi:[0,1,1]
	v_mov_b32_e32 v61, v45
	v_mov_b32_e32 v53, v47
	v_pk_mul_f32 v[44:45], v[2:3], v[60:61] op_sel_hi:[0,1]
	v_pk_mul_f32 v[46:47], v[2:3], v[52:53] op_sel_hi:[0,1]
.LBB0_991:
	s_or_b64 exec, exec, s[10:11]
	v_cvt_pk_bf16_f32 v47, v46, v47
	v_cvt_pk_bf16_f32 v46, v44, v45
	v_mov_b32_e32 v44, v56
	v_mov_b32_e32 v45, v58
	v_ashrrev_i32_e32 v117, 31, v116
	v_permlane16_swap_b32_e32 v44, v46
	v_permlane16_swap_b32_e32 v45, v47
	v_lshl_add_u64 v[48:49], v[116:117], 1, v[84:85]
	s_nop 0
	flat_store_dwordx4 v[48:49], v[44:47] offset:32
.LBB0_992:
	s_andn2_saveexec_b64 s[2:3], s[2:3]
	s_cbranch_execz .LBB0_994
	v_add_u32_e32 v2, 0xffffa400, v160
	v_lshlrev_b64 v[52:53], 2, v[2:3]
	v_lshl_add_u64 v[48:49], s[26:27], 0, v[52:53]
	s_nop 0
	flat_load_dwordx4 v[48:51], v[48:49]
	s_mov_b32 s0, 0x3d800000
	v_lshl_add_u64 v[52:53], v[70:71], 0, v[52:53]
	s_waitcnt vmcnt(0) lgkmcnt(0)
	v_add_f32_e32 v2, v44, v48
	v_min_f32_e32 v44, 0, v2
	v_mul_f32_e64 v2, |v2|, s82
	v_exp_f32_e32 v2, v2
	v_add_f32_e32 v48, v45, v49
	v_add_f32_e32 v49, v46, v50
	v_add_f32_e32 v51, v47, v51
	v_add_f32_e32 v2, 1.0, v2
	v_cmp_gt_f32_e32 vcc, s83, v2
	s_nop 1
	v_cndmask_b32_e64 v45, 0, 32, vcc
	v_ldexp_f32 v2, v2, v45
	v_log_f32_e32 v2, v2
	s_nop 0
	v_mul_f32_e32 v45, 0x3f317217, v2
	v_fma_f32 v45, v2, s86, -v45
	v_fmac_f32_e32 v45, 0x3377d1cf, v2
	v_fmac_f32_e32 v45, 0x3f317217, v2
	v_cmp_lt_f32_e64 s[10:11], |v2|, s87
	s_nop 1
	v_cndmask_b32_e64 v2, v2, v45, s[10:11]
	v_cndmask_b32_e32 v45, 0, v165, vcc
	v_sub_f32_e32 v46, v2, v45
	v_mul_f32_e64 v2, |v48|, s82
	v_exp_f32_e32 v2, v2
	v_min_f32_e32 v45, 0, v48
	v_min_f32_e32 v48, 0, v49
	v_add_f32_e32 v2, 1.0, v2
	v_cmp_gt_f32_e32 vcc, s83, v2
	s_nop 1
	v_cndmask_b32_e64 v47, 0, 32, vcc
	v_ldexp_f32 v2, v2, v47
	v_log_f32_e32 v2, v2
	s_nop 0
	v_mul_f32_e32 v47, 0x3f317217, v2
	v_fma_f32 v47, v2, s86, -v47
	v_fmac_f32_e32 v47, 0x3377d1cf, v2
	v_fmac_f32_e32 v47, 0x3f317217, v2
	v_cmp_lt_f32_e64 s[10:11], |v2|, s87
	s_nop 1
	v_cndmask_b32_e64 v2, v2, v47, s[10:11]
	v_cndmask_b32_e32 v47, 0, v165, vcc
	v_sub_f32_e32 v47, v2, v47
	v_mul_f32_e64 v2, |v49|, s82
	v_exp_f32_e32 v2, v2
	v_pk_add_f32 v[44:45], v[44:45], v[46:47] neg_lo:[0,1] neg_hi:[0,1]
	v_add_f32_e32 v2, 1.0, v2
	v_cmp_gt_f32_e32 vcc, s83, v2
	v_pk_mul_f32 v[44:45], v[44:45], s[0:1] op_sel_hi:[1,0]
	s_nop 0
	v_cndmask_b32_e64 v49, 0, 32, vcc
	v_ldexp_f32 v2, v2, v49
	v_log_f32_e32 v2, v2
	s_nop 0
	v_mul_f32_e32 v49, 0x3f317217, v2
	v_fma_f32 v49, v2, s86, -v49
	v_fmac_f32_e32 v49, 0x3377d1cf, v2
	v_fmac_f32_e32 v49, 0x3f317217, v2
	v_cmp_lt_f32_e64 s[10:11], |v2|, s87
	s_nop 1
	v_cndmask_b32_e64 v2, v2, v49, s[10:11]
	v_cndmask_b32_e32 v49, 0, v165, vcc
	v_sub_f32_e32 v50, v2, v49
	v_mul_f32_e64 v2, |v51|, s82
	v_exp_f32_e32 v2, v2
	v_min_f32_e32 v49, 0, v51
	v_add_f32_e32 v2, 1.0, v2
	v_cmp_gt_f32_e32 vcc, s83, v2
	s_nop 1
	v_cndmask_b32_e64 v51, 0, 32, vcc
	v_ldexp_f32 v2, v2, v51
	v_log_f32_e32 v2, v2
	s_nop 0
	v_mul_f32_e32 v51, 0x3f317217, v2
	v_fma_f32 v51, v2, s86, -v51
	v_fmac_f32_e32 v51, 0x3377d1cf, v2
	v_fmac_f32_e32 v51, 0x3f317217, v2
	v_cmp_lt_f32_e64 s[10:11], |v2|, s87
	s_nop 1
	v_cndmask_b32_e64 v2, v2, v51, s[10:11]
	v_cndmask_b32_e32 v51, 0, v165, vcc
	v_sub_f32_e32 v51, v2, v51
	v_pk_add_f32 v[46:47], v[48:49], v[50:51] neg_lo:[0,1] neg_hi:[0,1]
	s_nop 0
	v_pk_mul_f32 v[46:47], v[46:47], s[0:1] op_sel_hi:[1,0]
	flat_store_dwordx4 v[52:53], v[44:47]

; __device__ __forceinline__ void gemm_phase(const Ctx& cx, const GemmArgs& g_, char* shm) {
;     ...
;             } else if (g.epi == EPI_RES) {
;               const float4 hv = *(const float4*)(g.hin + (size_t)tok * DM + n0);
;               const float h0 = hv.x + a[0], h1 = hv.y + a[1], h2 = hv.z + a[2], h3 = hv.w + a[3];
;               *(float4*)(g.hout + (size_t)tok * DM + n0) = make_float4(h0, h1, h2, h3);
;               if (g.w != nullptr) {
;                 const float4 nw = *(const float4*)(g.w + n0);
;                 uint2 o; o.x = pack2(h0 * nw.x, h1 * nw.y); o.y = pack2(h2 * nw.z, h3 * nw.w);
;                 EMIT_BF16(DM, o);
;                 ssq += h0 * h0 + h1 * h1 + h2 * h2 + h3 * h3;
;               }
.LBB0_1009:
	s_and_b64 vcc, exec, s[60:61]
	v_mov_b32_e32 v52, v54
	s_cbranch_vccz .LBB0_1012
	v_lshl_add_u64 v[50:51], v[120:121], 0, v[0:1]
	v_lshlrev_b64 v[44:45], 2, v[50:51]
	v_lshl_add_u64 v[46:47], v[74:75], 0, v[44:45]
	s_nop 0
	flat_load_dwordx4 v[46:49], v[46:47] offset:128
	v_lshl_add_u64 v[44:45], v[72:73], 0, v[44:45]
	s_andn2_b64 vcc, exec, s[42:43]
	v_mov_b32_e32 v52, v54
	s_waitcnt vmcnt(0) lgkmcnt(0)
	v_pk_add_f32 v[46:47], v[40:41], v[46:47]
	v_pk_add_f32 v[48:49], v[42:43], v[48:49]
	flat_store_dwordx4 v[44:45], v[46:49] offset:128
	v_mov_b32_e32 v45, v58
	v_mov_b32_e32 v44, v56
	s_cbranch_vccnz .LBB0_1012
	v_lshl_add_u64 v[44:45], v[50:51], 2, s[30:31]
	global_load_dwordx4 v[50:53], v[44:45], off offset:128
	v_pk_mul_f32 v[44:45], v[46:47], v[46:47]
	v_pk_mul_f32 v[60:61], v[48:49], v[48:49]
	v_add_f32_e32 v2, v44, v45
	v_add_f32_e32 v2, v2, v60
	v_add_f32_e32 v2, v2, v61
	s_waitcnt vmcnt(0)
	v_pk_mul_f32 v[44:45], v[48:49], v[52:53]
	v_pk_mul_f32 v[46:47], v[46:47], v[50:51]
	v_cvt_pk_bf16_f32 v45, v44, v45
	v_cvt_pk_bf16_f32 v44, v46, v47
	v_add_f32_e32 v52, v54, v2

; __device__ __forceinline__ float b2f(u16 b) { return __uint_as_float(((uint32_t)b) << 16); }
; __device__ __forceinline__ float sigmoidf_(float x) { return 1.0f / (1.0f + __expf(-x)); }
; __device__ __forceinline__ void gemm_phase(const Ctx& cx, const GemmArgs& g_, char* shm) {
;     ...
;               const uint2 gv = *(const uint2*)(g.gate + (size_t)tok * NP + n0);
;               float v0 = sigmoidf_(b2f((u16)(gv.x & 0xffff))) * a[0], v1 = sigmoidf_(b2f((u16)(gv.x >> 16))) * a[1];
;               float v2 = sigmoidf_(b2f((u16)(gv.y & 0xffff))) * a[2], v3 = sigmoidf_(b2f((u16)(gv.y >> 16))) * a[3];
;               uint2* mp = (uint2*)(g.outb + (size_t)tok * DM + n0);
;               if (g.epi != EPI_BR0) {
;                 const uint2 pv = *mp;
;                 v0 += b2f((u16)(pv.x & 0xffff)); v1 += b2f((u16)(pv.x >> 16));
;                 v2 += b2f((u16)(pv.y & 0xffff)); v3 += b2f((u16)(pv.y >> 16));
;               }
.LBB0_1014:
	v_lshl_add_u64 v[44:45], v[120:121], 0, v[0:1]
	v_lshlrev_b64 v[46:47], 1, v[44:45]
	v_lshl_add_u64 v[44:45], v[82:83], 0, v[46:47]
	s_nop 0
	flat_load_dwordx2 v[48:49], v[44:45] offset:64
	v_lshl_add_u64 v[46:47], v[68:69], 0, v[46:47]
	s_waitcnt vmcnt(0) lgkmcnt(0)
	v_lshlrev_b32_e32 v2, 16, v48
	v_mul_f32_e32 v2, 0xbfb8aa3b, v2
	v_exp_f32_e32 v44, v2
	v_and_b32_e32 v2, 0xffff0000, v48
	v_mul_f32_e32 v2, 0xbfb8aa3b, v2
	v_exp_f32_e32 v45, v2
	s_nop 0
	v_pk_add_f32 v[44:45], v[44:45], 1.0 op_sel_hi:[1,0]
	s_nop 0
	v_div_scale_f32 v2, s[2:3], v45, v45, 1.0
	v_rcp_f32_e32 v48, v2
	s_nop 0
	v_fma_f32 v50, -v2, v48, 1.0
	v_fmac_f32_e32 v48, v50, v48
	v_div_scale_f32 v50, vcc, 1.0, v45, 1.0
	v_mul_f32_e32 v51, v50, v48
	v_fma_f32 v52, -v2, v51, v50
	v_fmac_f32_e32 v51, v52, v48
	v_fma_f32 v2, -v2, v51, v50
	v_div_fmas_f32 v2, v2, v48, v51
	v_div_fixup_f32 v45, v2, v45, 1.0
	v_div_scale_f32 v2, s[2:3], v44, v44, 1.0
	v_rcp_f32_e32 v48, v2
	s_nop 0
	v_fma_f32 v50, -v2, v48, 1.0
	v_fmac_f32_e32 v48, v50, v48
	v_div_scale_f32 v50, vcc, 1.0, v44, 1.0
	v_mul_f32_e32 v51, v50, v48
	v_fma_f32 v52, -v2, v51, v50
	v_fmac_f32_e32 v51, v52, v48
	v_fma_f32 v2, -v2, v51, v50
	v_div_fmas_f32 v2, v2, v48, v51
	v_div_fixup_f32 v44, v2, v44, 1.0
	v_lshlrev_b32_e32 v2, 16, v49
	v_mul_f32_e32 v2, 0xbfb8aa3b, v2
	v_exp_f32_e32 v48, v2
	v_and_b32_e32 v2, 0xffff0000, v49
	v_mul_f32_e32 v2, 0xbfb8aa3b, v2
	v_exp_f32_e32 v49, v2
	v_pk_mul_f32 v[44:45], v[40:41], v[44:45]
	v_pk_add_f32 v[48:49], v[48:49], 1.0 op_sel_hi:[1,0]
	s_nop 0
	v_div_scale_f32 v2, s[2:3], v49, v49, 1.0
	v_rcp_f32_e32 v50, v2
	s_nop 0
	v_fma_f32 v51, -v2, v50, 1.0
	v_fmac_f32_e32 v50, v51, v50
	v_div_scale_f32 v51, vcc, 1.0, v49, 1.0
	v_mul_f32_e32 v52, v51, v50
	v_fma_f32 v53, -v2, v52, v51
	v_fmac_f32_e32 v52, v53, v50
	v_fma_f32 v2, -v2, v52, v51
	v_div_fmas_f32 v2, v2, v50, v52
	v_div_fixup_f32 v49, v2, v49, 1.0
	v_div_scale_f32 v2, s[2:3], v48, v48, 1.0
	v_rcp_f32_e32 v50, v2
	s_nop 0
	v_fma_f32 v51, -v2, v50, 1.0
	v_fmac_f32_e32 v50, v51, v50
	v_div_scale_f32 v51, vcc, 1.0, v48, 1.0
	v_mul_f32_e32 v52, v51, v50
	v_fma_f32 v53, -v2, v52, v51
	v_fmac_f32_e32 v52, v53, v50
	v_fma_f32 v2, -v2, v52, v51
	v_div_fmas_f32 v2, v2, v50, v52
	v_div_fixup_f32 v48, v2, v48, 1.0
	v_pk_mul_f32 v[48:49], v[42:43], v[48:49]
	s_and_b64 vcc, exec, s[4:5]
	s_cbranch_vccnz .LBB0_1016
	flat_load_dwordx2 v[50:51], v[46:47] offset:64
	s_waitcnt vmcnt(0) lgkmcnt(0)
	v_lshlrev_b32_e32 v52, 16, v50
	v_and_b32_e32 v53, 0xffff0000, v50
	v_lshlrev_b32_e32 v50, 16, v51
	v_and_b32_e32 v51, 0xffff0000, v51
	v_pk_add_f32 v[44:45], v[44:45], v[52:53]
	v_pk_add_f32 v[48:49], v[48:49], v[50:51]

; __device__ __forceinline__ void gemm_phase(const Ctx& cx, const GemmArgs& g_, char* shm) {
;     ...
;                 const bool r128 = (n0 >= C_DSAQ && n0 < C_HGQ) || (n0 >= C_DSAK && n0 < C_DSAV);
;                 const bool r64 = (n0 >= C_IDXQ && n0 < C_GLAA);
;                 if (r128 || r64) {
;                   float4 cs;
;                   float sc;
;                   if (r128) {
;                     cs = *(const float4*)(g.w + ((size_t)tok * 64 + ((n0 & 127) >> 1)) * 2);
;                     sc = (n0 < C_HGQ) ? 0.08838834764831845f : 1.0f;
;                   } else {
;                     cs = *(const float4*)(g.hout + ((size_t)tok * 32 + ((n0 & 63) >> 1)) * 2);
;                     sc = (n0 < C_IDXK) ? 0.125f : 1.0f;
;                   }
;                   o0 = (a[0] * cs.x - a[1] * cs.y) * sc; o1 = (a[1] * cs.x + a[0] * cs.y) * sc;
;                   o2 = (a[2] * cs.z - a[3] * cs.w) * sc; o3 = (a[3] * cs.z + a[2] * cs.w) * sc;
;                 }
.LBB0_1017:
	s_movk_i32 s0, 0x5c00
	v_cmp_gt_i32_e32 vcc, s0, v131
	s_and_saveexec_b64 s[2:3], vcc
	s_xor_b64 s[2:3], exec, s[2:3]
	s_cbranch_execz .LBB0_1025
	v_add_u32_e32 v2, 0xffffa780, v138
	v_cmp_gt_u32_e32 vcc, s77, v2
	s_or_b64 s[60:61], s[54:55], vcc
	s_and_saveexec_b64 s[10:11], s[60:61]
	s_cbranch_execz .LBB0_1024
	s_and_saveexec_b64 s[60:61], s[52:53]
	s_xor_b64 s[60:61], exec, s[60:61]
	v_lshlrev_b32_e32 v2, 2, v0
	s_movk_i32 s0, 0x5b00
	v_lshl_add_u64 v[44:45], v[80:81], 0, v[2:3]
	v_cmp_gt_u32_e32 vcc, s0, v120
	v_lshl_add_u64 v[44:45], v[44:45], 0, s[70:71]
	s_nop 0
	v_cndmask_b32_e32 v2, 1.0, v166, vcc
	s_andn2_saveexec_b64 s[60:61], s[60:61]
	v_and_b32_e32 v2, 0x6c, v131
	v_lshlrev_b32_e32 v2, 2, v2
	v_cmp_gt_i32_e32 vcc, s81, v131
	v_lshl_add_u64 v[44:45], v[78:79], 0, v[2:3]
	s_nop 0
	v_cndmask_b32_e32 v2, 1.0, v167, vcc
	s_or_b64 exec, exec, s[60:61]
	s_nop 0
	flat_load_dwordx4 v[44:47], v[44:45]
	s_waitcnt vmcnt(0) lgkmcnt(0)
	v_pk_mul_f32 v[48:49], v[40:41], v[44:45] op_sel:[1,1] op_sel_hi:[1,0]
	s_nop 0
	v_pk_fma_f32 v[50:51], v[40:41], v[44:45], v[48:49] neg_lo:[0,0,1] neg_hi:[0,0,1]
	v_pk_fma_f32 v[40:41], v[40:41], v[44:45], v[48:49] op_sel_hi:[0,1,1]
	v_mov_b32_e32 v44, v43
	v_pk_mul_f32 v[44:45], v[44:45], v[46:47] op_sel:[0,1] op_sel_hi:[0,0]
	v_pk_fma_f32 v[48:49], v[42:43], v[46:47], v[44:45] neg_lo:[0,0,1] neg_hi:[0,0,1]
	v_pk_fma_f32 v[42:43], v[42:43], v[46:47], v[44:45] op_sel_hi:[0,1,1]
	v_mov_b32_e32 v51, v41
	v_mov_b32_e32 v49, v43
	v_pk_mul_f32 v[40:41], v[2:3], v[50:51] op_sel_hi:[0,1]
	v_pk_mul_f32 v[42:43], v[2:3], v[48:49] op_sel_hi:[0,1]

; __device__ __forceinline__ void gemm_phase(const Ctx& cx, const GemmArgs& g_, char* shm) {
;     ...
;               if (n0 >= C_GLAX) {
;                 const int i = n0 - C_GLAX;
;                 const float4 b4 = *(const float4*)(g.hin + i);
;                 float xs[4] = {a[0] + b4.x, a[1] + b4.y, a[2] + b4.z, a[3] + b4.w};
; #pragma unroll
;                 for (int j = 0; j < 4; ++j)
;                   xs[j] = (fminf(xs[j], 0.f) - __logf(1.0f + __expf(-fabsf(xs[j])))) * (1.0f / 16.0f);
;                 *(float4*)(g.f32buf + (size_t)tok * 1024 + i) = make_float4(xs[0], xs[1], xs[2], xs[3]);
.LBB0_1025:
	s_andn2_saveexec_b64 s[2:3], s[2:3]
	s_cbranch_execz .LBB0_1027
	v_add_u32_e32 v2, 0xffffa400, v131
	v_lshlrev_b64 v[48:49], 2, v[2:3]
	v_lshl_add_u64 v[44:45], s[26:27], 0, v[48:49]
	s_nop 0
	flat_load_dwordx4 v[44:47], v[44:45]
	s_mov_b32 s0, 0x3d800000
	v_lshl_add_u64 v[48:49], v[70:71], 0, v[48:49]
	s_waitcnt vmcnt(0) lgkmcnt(0)
	v_add_f32_e32 v2, v40, v44
	v_min_f32_e32 v40, 0, v2
	v_mul_f32_e64 v2, |v2|, s82
	v_exp_f32_e32 v2, v2
	v_add_f32_e32 v44, v41, v45
	v_add_f32_e32 v45, v42, v46
	v_add_f32_e32 v47, v43, v47
	v_add_f32_e32 v2, 1.0, v2
	v_cmp_gt_f32_e32 vcc, s83, v2
	s_nop 1
	v_cndmask_b32_e64 v41, 0, 32, vcc
	v_ldexp_f32 v2, v2, v41
	v_log_f32_e32 v2, v2
	s_nop 0
	v_mul_f32_e32 v41, 0x3f317217, v2
	v_fma_f32 v41, v2, s86, -v41
	v_fmac_f32_e32 v41, 0x3377d1cf, v2
	v_fmac_f32_e32 v41, 0x3f317217, v2
	v_cmp_lt_f32_e64 s[10:11], |v2|, s87
	s_nop 1
	v_cndmask_b32_e64 v2, v2, v41, s[10:11]
	v_cndmask_b32_e32 v41, 0, v165, vcc
	v_sub_f32_e32 v42, v2, v41
	v_mul_f32_e64 v2, |v44|, s82
	v_exp_f32_e32 v2, v2
	v_min_f32_e32 v41, 0, v44
	v_min_f32_e32 v44, 0, v45
	v_add_f32_e32 v2, 1.0, v2
	v_cmp_gt_f32_e32 vcc, s83, v2
	s_nop 1
	v_cndmask_b32_e64 v43, 0, 32, vcc
	v_ldexp_f32 v2, v2, v43
	v_log_f32_e32 v2, v2
	s_nop 0
	v_mul_f32_e32 v43, 0x3f317217, v2
	v_fma_f32 v43, v2, s86, -v43
	v_fmac_f32_e32 v43, 0x3377d1cf, v2
	v_fmac_f32_e32 v43, 0x3f317217, v2
	v_cmp_lt_f32_e64 s[10:11], |v2|, s87
	s_nop 1
	v_cndmask_b32_e64 v2, v2, v43, s[10:11]
	v_cndmask_b32_e32 v43, 0, v165, vcc
	v_sub_f32_e32 v43, v2, v43
	v_mul_f32_e64 v2, |v45|, s82
	v_exp_f32_e32 v2, v2
	v_pk_add_f32 v[40:41], v[40:41], v[42:43] neg_lo:[0,1] neg_hi:[0,1]
	v_add_f32_e32 v2, 1.0, v2
	v_cmp_gt_f32_e32 vcc, s83, v2
	v_pk_mul_f32 v[40:41], v[40:41], s[0:1] op_sel_hi:[1,0]
	s_nop 0
	v_cndmask_b32_e64 v45, 0, 32, vcc
	v_ldexp_f32 v2, v2, v45
	v_log_f32_e32 v2, v2
	s_nop 0
	v_mul_f32_e32 v45, 0x3f317217, v2
	v_fma_f32 v45, v2, s86, -v45
	v_fmac_f32_e32 v45, 0x3377d1cf, v2
	v_fmac_f32_e32 v45, 0x3f317217, v2
	v_cmp_lt_f32_e64 s[10:11], |v2|, s87
	s_nop 1
	v_cndmask_b32_e64 v2, v2, v45, s[10:11]
	v_cndmask_b32_e32 v45, 0, v165, vcc
	v_sub_f32_e32 v46, v2, v45
	v_mul_f32_e64 v2, |v47|, s82
	v_exp_f32_e32 v2, v2
	v_min_f32_e32 v45, 0, v47
	v_add_f32_e32 v2, 1.0, v2
	v_cmp_gt_f32_e32 vcc, s83, v2
	s_nop 1
	v_cndmask_b32_e64 v47, 0, 32, vcc
	v_ldexp_f32 v2, v2, v47
	v_log_f32_e32 v2, v2
	s_nop 0
	v_mul_f32_e32 v47, 0x3f317217, v2
	v_fma_f32 v47, v2, s86, -v47
	v_fmac_f32_e32 v47, 0x3377d1cf, v2
	v_fmac_f32_e32 v47, 0x3f317217, v2
	v_cmp_lt_f32_e64 s[10:11], |v2|, s87
	s_nop 1
	v_cndmask_b32_e64 v2, v2, v47, s[10:11]
	v_cndmask_b32_e32 v47, 0, v165, vcc
	v_sub_f32_e32 v47, v2, v47
	v_pk_add_f32 v[42:43], v[44:45], v[46:47] neg_lo:[0,1] neg_hi:[0,1]
	v_mov_b32_e32 v45, v58
	v_pk_mul_f32 v[42:43], v[42:43], s[0:1] op_sel_hi:[1,0]
	v_mov_b32_e32 v44, v56
	flat_store_dwordx4 v[48:49], v[40:43]

; __device__ __forceinline__ void gemm_phase(const Ctx& cx, const GemmArgs& g_, char* shm) {
;     ...
;             } else if (g.epi == EPI_RELU2) {
;               float r0 = fmaxf(a[0], 0.f), r1 = fmaxf(a[1], 0.f), r2 = fmaxf(a[2], 0.f), r3 = fmaxf(a[3], 0.f);
;               uint2 o; o.x = pack2(r0 * r0, r1 * r1); o.y = pack2(r2 * r2, r3 * r3);
;               EMIT_BF16(g.ldo, o);
.LBB0_1040:
	s_cmp_gt_i32 s38, 4
	s_cbranch_scc0 .LBB0_1044
	s_cmp_eq_u32 s38, 5
	s_mov_b64 s[10:11], -1
	s_cbranch_scc0 .LBB0_1043
	v_max_f32_e32 v2, v38, v38
	v_max_f32_e32 v40, 0, v2
	v_max_f32_e32 v2, v39, v39
	v_max_f32_e32 v41, 0, v2
	v_pk_mul_f32 v[40:41], v[40:41], v[40:41]
	v_max_f32_e32 v2, v36, v36
	v_cvt_pk_bf16_f32 v43, v40, v41
	v_max_f32_e32 v40, 0, v2
	v_max_f32_e32 v2, v37, v37
	v_max_f32_e32 v41, 0, v2
	v_pk_mul_f32 v[40:41], v[40:41], v[40:41]
	v_ashrrev_i32_e32 v117, 31, v116
	v_cvt_pk_bf16_f32 v42, v40, v41
	v_mov_b32_e32 v40, v44
	v_mov_b32_e32 v41, v45
	s_nop 0
	v_permlane16_swap_b32_e32 v40, v42
	v_permlane16_swap_b32_e32 v41, v43
	v_lshl_add_u64 v[46:47], v[116:117], 1, v[84:85]
	s_nop 0
	flat_store_dwordx4 v[46:47], v[40:43] offset:96
	s_mov_b64 s[10:11], 0

; __device__ __forceinline__ void gemm_phase(const Ctx& cx, const GemmArgs& g_, char* shm) {
;     ...
;             } else if (g.epi == EPI_RES) {
;               const float4 hv = *(const float4*)(g.hin + (size_t)tok * DM + n0);
;               const float h0 = hv.x + a[0], h1 = hv.y + a[1], h2 = hv.z + a[2], h3 = hv.w + a[3];
;               *(float4*)(g.hout + (size_t)tok * DM + n0) = make_float4(h0, h1, h2, h3);
;               if (g.w != nullptr) {
;                 const float4 nw = *(const float4*)(g.w + n0);
;                 uint2 o; o.x = pack2(h0 * nw.x, h1 * nw.y); o.y = pack2(h2 * nw.z, h3 * nw.w);
;                 EMIT_BF16(DM, o);
;                 ssq += h0 * h0 + h1 * h1 + h2 * h2 + h3 * h3;
;               }
.LBB0_1044:
	s_and_b64 vcc, exec, s[60:61]
	v_mov_b32_e32 v2, v52
	s_cbranch_vccz .LBB0_1047
	v_lshl_add_u64 v[46:47], v[120:121], 0, v[0:1]
	v_lshlrev_b64 v[48:49], 2, v[46:47]
	v_lshl_add_u64 v[40:41], v[74:75], 0, v[48:49]
	s_nop 0
	flat_load_dwordx4 v[40:43], v[40:41] offset:192
	v_lshl_add_u64 v[48:49], v[72:73], 0, v[48:49]
	s_andn2_b64 vcc, exec, s[42:43]
	v_mov_b32_e32 v2, v52
	s_waitcnt vmcnt(0) lgkmcnt(0)
	v_pk_add_f32 v[40:41], v[36:37], v[40:41]
	v_pk_add_f32 v[42:43], v[38:39], v[42:43]
	flat_store_dwordx4 v[48:49], v[40:43] offset:192
	s_cbranch_vccnz .LBB0_1047
	v_lshl_add_u64 v[46:47], v[46:47], 2, s[30:31]
	global_load_dwordx4 v[46:49], v[46:47], off offset:192
	v_ashrrev_i32_e32 v117, 31, v116
	v_lshl_add_u64 v[50:51], v[116:117], 1, v[68:69]
	s_waitcnt vmcnt(0)
	v_pk_mul_f32 v[46:47], v[40:41], v[46:47]
	v_pk_mul_f32 v[40:41], v[40:41], v[40:41]
	v_pk_mul_f32 v[48:49], v[42:43], v[48:49]
	v_pk_mul_f32 v[42:43], v[42:43], v[42:43]
	v_add_f32_e32 v2, v40, v41
	v_cvt_pk_bf16_f32 v49, v48, v49
	v_cvt_pk_bf16_f32 v48, v46, v47
	v_mov_b32_e32 v46, v44
	v_mov_b32_e32 v47, v45
	v_add_f32_e32 v2, v2, v42
	v_permlane16_swap_b32_e32 v46, v48
	v_permlane16_swap_b32_e32 v47, v49
	v_add_f32_e32 v2, v2, v43
	flat_store_dwordx4 v[50:51], v[46:49] offset:96
	v_add_f32_e32 v2, v52, v2

; __device__ __forceinline__ float b2f(u16 b) { return __uint_as_float(((uint32_t)b) << 16); }
; __device__ __forceinline__ float sigmoidf_(float x) { return 1.0f / (1.0f + __expf(-x)); }
; __device__ __forceinline__ void gemm_phase(const Ctx& cx, const GemmArgs& g_, char* shm) {
;     ...
;               const uint2 gv = *(const uint2*)(g.gate + (size_t)tok * NP + n0);
;               float v0 = sigmoidf_(b2f((u16)(gv.x & 0xffff))) * a[0], v1 = sigmoidf_(b2f((u16)(gv.x >> 16))) * a[1];
;               float v2 = sigmoidf_(b2f((u16)(gv.y & 0xffff))) * a[2], v3 = sigmoidf_(b2f((u16)(gv.y >> 16))) * a[3];
;               uint2* mp = (uint2*)(g.outb + (size_t)tok * DM + n0);
;               if (g.epi != EPI_BR0) {
;                 const uint2 pv = *mp;
;                 v0 += b2f((u16)(pv.x & 0xffff)); v1 += b2f((u16)(pv.x >> 16));
;                 v2 += b2f((u16)(pv.y & 0xffff)); v3 += b2f((u16)(pv.y >> 16));
;               }
.LBB0_1049:
	v_lshl_add_u64 v[40:41], v[120:121], 0, v[0:1]
	v_lshlrev_b64 v[42:43], 1, v[40:41]
	v_lshl_add_u64 v[40:41], v[82:83], 0, v[42:43]
	s_nop 0
	flat_load_dwordx2 v[46:47], v[40:41] offset:96
	v_lshl_add_u64 v[42:43], v[68:69], 0, v[42:43]
	s_waitcnt vmcnt(0) lgkmcnt(0)
	v_lshlrev_b32_e32 v2, 16, v46
	v_mul_f32_e32 v2, 0xbfb8aa3b, v2
	v_exp_f32_e32 v40, v2
	v_and_b32_e32 v2, 0xffff0000, v46
	v_mul_f32_e32 v2, 0xbfb8aa3b, v2
	v_exp_f32_e32 v41, v2
	s_nop 0
	v_pk_add_f32 v[40:41], v[40:41], 1.0 op_sel_hi:[1,0]
	s_nop 0
	v_div_scale_f32 v2, s[2:3], v41, v41, 1.0
	v_rcp_f32_e32 v46, v2
	s_nop 0
	v_fma_f32 v48, -v2, v46, 1.0
	v_fmac_f32_e32 v46, v48, v46
	v_div_scale_f32 v48, vcc, 1.0, v41, 1.0
	v_mul_f32_e32 v49, v48, v46
	v_fma_f32 v50, -v2, v49, v48
	v_fmac_f32_e32 v49, v50, v46
	v_fma_f32 v2, -v2, v49, v48
	v_div_fmas_f32 v2, v2, v46, v49
	v_div_fixup_f32 v41, v2, v41, 1.0
	v_div_scale_f32 v2, s[2:3], v40, v40, 1.0
	v_rcp_f32_e32 v46, v2
	s_nop 0
	v_fma_f32 v48, -v2, v46, 1.0
	v_fmac_f32_e32 v46, v48, v46
	v_div_scale_f32 v48, vcc, 1.0, v40, 1.0
	v_mul_f32_e32 v49, v48, v46
	v_fma_f32 v50, -v2, v49, v48
	v_fmac_f32_e32 v49, v50, v46
	v_fma_f32 v2, -v2, v49, v48
	v_div_fmas_f32 v2, v2, v46, v49
	v_div_fixup_f32 v40, v2, v40, 1.0
	v_lshlrev_b32_e32 v2, 16, v47
	v_mul_f32_e32 v2, 0xbfb8aa3b, v2
	v_exp_f32_e32 v46, v2
	v_and_b32_e32 v2, 0xffff0000, v47
	v_mul_f32_e32 v2, 0xbfb8aa3b, v2
	v_exp_f32_e32 v47, v2
	v_pk_mul_f32 v[40:41], v[36:37], v[40:41]
	v_pk_add_f32 v[46:47], v[46:47], 1.0 op_sel_hi:[1,0]
	s_nop 0
	v_div_scale_f32 v2, s[2:3], v47, v47, 1.0
	v_rcp_f32_e32 v48, v2
	s_nop 0
	v_fma_f32 v49, -v2, v48, 1.0
	v_fmac_f32_e32 v48, v49, v48
	v_div_scale_f32 v49, vcc, 1.0, v47, 1.0
	v_mul_f32_e32 v50, v49, v48
	v_fma_f32 v51, -v2, v50, v49
	v_fmac_f32_e32 v50, v51, v48
	v_fma_f32 v2, -v2, v50, v49
	v_div_fmas_f32 v2, v2, v48, v50
	v_div_fixup_f32 v47, v2, v47, 1.0
	v_div_scale_f32 v2, s[2:3], v46, v46, 1.0
	v_rcp_f32_e32 v48, v2
	s_nop 0
	v_fma_f32 v49, -v2, v48, 1.0
	v_fmac_f32_e32 v48, v49, v48
	v_div_scale_f32 v49, vcc, 1.0, v46, 1.0
	v_mul_f32_e32 v50, v49, v48
	v_fma_f32 v51, -v2, v50, v49
	v_fmac_f32_e32 v50, v51, v48
	v_fma_f32 v2, -v2, v50, v49
	v_div_fmas_f32 v2, v2, v48, v50
	v_div_fixup_f32 v46, v2, v46, 1.0
	v_pk_mul_f32 v[46:47], v[38:39], v[46:47]
	s_and_b64 vcc, exec, s[4:5]
	s_cbranch_vccnz .LBB0_1051
	flat_load_dwordx2 v[48:49], v[42:43] offset:96
	s_waitcnt vmcnt(0) lgkmcnt(0)
	v_lshlrev_b32_e32 v50, 16, v48
	v_and_b32_e32 v51, 0xffff0000, v48
	v_lshlrev_b32_e32 v48, 16, v49
	v_and_b32_e32 v49, 0xffff0000, v49
	v_pk_add_f32 v[40:41], v[40:41], v[50:51]
	v_pk_add_f32 v[46:47], v[46:47], v[48:49]

; __device__ __forceinline__ void gemm_phase(const Ctx& cx, const GemmArgs& g_, char* shm) {
;     ...
;               if (n0 >= C_GLAX) {
;                 const int i = n0 - C_GLAX;
;                 const float4 b4 = *(const float4*)(g.hin + i);
;                 float xs[4] = {a[0] + b4.x, a[1] + b4.y, a[2] + b4.z, a[3] + b4.w};
; #pragma unroll
;                 for (int j = 0; j < 4; ++j)
;                   xs[j] = (fminf(xs[j], 0.f) - __logf(1.0f + __expf(-fabsf(xs[j])))) * (1.0f / 16.0f);
;                 *(float4*)(g.f32buf + (size_t)tok * 1024 + i) = make_float4(xs[0], xs[1], xs[2], xs[3]);
;               } else {
;                 float o0 = a[0], o1 = a[1], o2 = a[2], o3 = a[3];
;                 const bool r128 = (n0 >= C_DSAQ && n0 < C_HGQ) || (n0 >= C_DSAK && n0 < C_DSAV);
;                 const bool r64 = (n0 >= C_IDXQ && n0 < C_GLAA);
;                 if (r128 || r64) {
;                   float4 cs;
;                   float sc;
;                   if (r128) {
;                     cs = *(const float4*)(g.w + ((size_t)tok * 64 + ((n0 & 127) >> 1)) * 2);
;                     sc = (n0 < C_HGQ) ? 0.08838834764831845f : 1.0f;
;                   } else {
;                     cs = *(const float4*)(g.hout + ((size_t)tok * 32 + ((n0 & 63) >> 1)) * 2);
;                     sc = (n0 < C_IDXK) ? 0.125f : 1.0f;
;                   }
;                   o0 = (a[0] * cs.x - a[1] * cs.y) * sc; o1 = (a[1] * cs.x + a[0] * cs.y) * sc;
;                   o2 = (a[2] * cs.z - a[3] * cs.w) * sc; o3 = (a[3] * cs.z + a[2] * cs.w) * sc;
;                 }
;                 uint2 o; o.x = pack2(o0, o1); o.y = pack2(o2, o3);
;                 EMIT_BF16(g.ldo, o);
.LBB0_1052:
	s_movk_i32 s0, 0x5c00
	v_cmp_gt_i32_e32 vcc, s0, v130
	s_and_saveexec_b64 s[2:3], vcc
	s_xor_b64 s[2:3], exec, s[2:3]
	s_cbranch_execz .LBB0_1060
	v_add_u32_e32 v2, 0xffffa780, v138
	v_cmp_gt_u32_e32 vcc, s77, v2
	s_or_b64 s[60:61], s[54:55], vcc
	s_and_saveexec_b64 s[10:11], s[60:61]
	s_cbranch_execz .LBB0_1059
	s_and_saveexec_b64 s[60:61], s[52:53]
	s_xor_b64 s[60:61], exec, s[60:61]
	v_lshlrev_b32_e32 v2, 2, v0
	s_movk_i32 s0, 0x5b00
	v_lshl_add_u64 v[40:41], v[80:81], 0, v[2:3]
	s_mov_b64 s[68:69], 0xc0
	v_cmp_gt_u32_e32 vcc, s0, v120
	v_lshl_add_u64 v[40:41], v[40:41], 0, s[68:69]
	s_nop 0
	v_cndmask_b32_e32 v2, 1.0, v166, vcc
	s_andn2_saveexec_b64 s[60:61], s[60:61]
	v_and_b32_e32 v2, 0x7c, v130
	v_lshlrev_b32_e32 v2, 2, v2
	v_cmp_gt_i32_e32 vcc, s81, v130
	v_lshl_add_u64 v[40:41], v[78:79], 0, v[2:3]
	s_nop 0
	v_cndmask_b32_e32 v2, 1.0, v167, vcc
	s_or_b64 exec, exec, s[60:61]
	s_nop 0
	flat_load_dwordx4 v[40:43], v[40:41]
	s_waitcnt vmcnt(0) lgkmcnt(0)
	v_pk_mul_f32 v[46:47], v[36:37], v[40:41] op_sel:[1,1] op_sel_hi:[1,0]
	s_nop 0
	v_pk_fma_f32 v[48:49], v[36:37], v[40:41], v[46:47] neg_lo:[0,0,1] neg_hi:[0,0,1]
	v_pk_fma_f32 v[36:37], v[36:37], v[40:41], v[46:47] op_sel_hi:[0,1,1]
	v_mov_b32_e32 v40, v39
	v_pk_mul_f32 v[40:41], v[40:41], v[42:43] op_sel:[0,1] op_sel_hi:[0,0]
	v_pk_fma_f32 v[46:47], v[38:39], v[42:43], v[40:41] neg_lo:[0,0,1] neg_hi:[0,0,1]
	v_pk_fma_f32 v[38:39], v[38:39], v[42:43], v[40:41] op_sel_hi:[0,1,1]
	v_mov_b32_e32 v49, v37
	v_mov_b32_e32 v47, v39
	v_pk_mul_f32 v[36:37], v[2:3], v[48:49] op_sel_hi:[0,1]
	v_pk_mul_f32 v[38:39], v[2:3], v[46:47] op_sel_hi:[0,1]
.LBB0_1059:
	s_or_b64 exec, exec, s[10:11]
	v_cvt_pk_bf16_f32 v2, v38, v39
	v_cvt_pk_bf16_f32 v38, v36, v37
	s_nop 1
	v_permlane16_swap_b32_e32 v44, v38
	v_permlane16_swap_b32_e32 v45, v2
	v_ashrrev_i32_e32 v117, 31, v116
	v_lshl_add_u64 v[36:37], v[116:117], 1, v[84:85]
	v_mov_b32_e32 v46, v38
	v_mov_b32_e32 v47, v2
	s_nop 0
	flat_store_dwordx4 v[36:37], v[44:47] offset:96
.LBB0_1060:
	s_andn2_saveexec_b64 s[2:3], s[2:3]
	s_cbranch_execz .LBB0_1062
	v_add_u32_e32 v2, 0xffffa400, v130
	v_lshlrev_b64 v[44:45], 2, v[2:3]
	v_lshl_add_u64 v[40:41], s[26:27], 0, v[44:45]
	s_nop 0
	flat_load_dwordx4 v[40:43], v[40:41]
	s_mov_b32 s0, 0x3d800000
	v_lshl_add_u64 v[44:45], v[70:71], 0, v[44:45]
	s_waitcnt vmcnt(0) lgkmcnt(0)
	v_add_f32_e32 v2, v36, v40
	v_min_f32_e32 v36, 0, v2
	v_mul_f32_e64 v2, |v2|, s82
	v_exp_f32_e32 v2, v2
	v_add_f32_e32 v40, v37, v41
	v_add_f32_e32 v41, v38, v42
	v_add_f32_e32 v43, v39, v43
	v_add_f32_e32 v2, 1.0, v2
	v_cmp_gt_f32_e32 vcc, s83, v2
	s_nop 1
	v_cndmask_b32_e64 v37, 0, 32, vcc
	v_ldexp_f32 v2, v2, v37
	v_log_f32_e32 v2, v2
	s_nop 0
	v_mul_f32_e32 v37, 0x3f317217, v2
	v_fma_f32 v37, v2, s86, -v37
	v_fmac_f32_e32 v37, 0x3377d1cf, v2
	v_fmac_f32_e32 v37, 0x3f317217, v2
	v_cmp_lt_f32_e64 s[10:11], |v2|, s87
	s_nop 1
	v_cndmask_b32_e64 v2, v2, v37, s[10:11]
	v_cndmask_b32_e32 v37, 0, v165, vcc
	v_sub_f32_e32 v38, v2, v37
	v_mul_f32_e64 v2, |v40|, s82
	v_exp_f32_e32 v2, v2
	v_min_f32_e32 v37, 0, v40
	v_min_f32_e32 v40, 0, v41
	v_add_f32_e32 v2, 1.0, v2
	v_cmp_gt_f32_e32 vcc, s83, v2
	s_nop 1
	v_cndmask_b32_e64 v39, 0, 32, vcc
	v_ldexp_f32 v2, v2, v39
	v_log_f32_e32 v2, v2
	s_nop 0
	v_mul_f32_e32 v39, 0x3f317217, v2
	v_fma_f32 v39, v2, s86, -v39
	v_fmac_f32_e32 v39, 0x3377d1cf, v2
	v_fmac_f32_e32 v39, 0x3f317217, v2
	v_cmp_lt_f32_e64 s[10:11], |v2|, s87
	s_nop 1
	v_cndmask_b32_e64 v2, v2, v39, s[10:11]
	v_cndmask_b32_e32 v39, 0, v165, vcc
	v_sub_f32_e32 v39, v2, v39
	v_mul_f32_e64 v2, |v41|, s82
	v_exp_f32_e32 v2, v2
	v_pk_add_f32 v[36:37], v[36:37], v[38:39] neg_lo:[0,1] neg_hi:[0,1]
	v_add_f32_e32 v2, 1.0, v2
	v_cmp_gt_f32_e32 vcc, s83, v2
	v_pk_mul_f32 v[36:37], v[36:37], s[0:1] op_sel_hi:[1,0]
	s_nop 0
	v_cndmask_b32_e64 v41, 0, 32, vcc
	v_ldexp_f32 v2, v2, v41
	v_log_f32_e32 v2, v2
	s_nop 0
	v_mul_f32_e32 v41, 0x3f317217, v2
	v_fma_f32 v41, v2, s86, -v41
	v_fmac_f32_e32 v41, 0x3377d1cf, v2
	v_fmac_f32_e32 v41, 0x3f317217, v2
	v_cmp_lt_f32_e64 s[10:11], |v2|, s87
	s_nop 1
	v_cndmask_b32_e64 v2, v2, v41, s[10:11]
	v_cndmask_b32_e32 v41, 0, v165, vcc
	v_sub_f32_e32 v42, v2, v41
	v_mul_f32_e64 v2, |v43|, s82
	v_exp_f32_e32 v2, v2
	v_min_f32_e32 v41, 0, v43
	v_add_f32_e32 v2, 1.0, v2
	v_cmp_gt_f32_e32 vcc, s83, v2
	s_nop 1
	v_cndmask_b32_e64 v43, 0, 32, vcc
	v_ldexp_f32 v2, v2, v43
	v_log_f32_e32 v2, v2
	s_nop 0
	v_mul_f32_e32 v43, 0x3f317217, v2
	v_fma_f32 v43, v2, s86, -v43
	v_fmac_f32_e32 v43, 0x3377d1cf, v2
	v_fmac_f32_e32 v43, 0x3f317217, v2
	v_cmp_lt_f32_e64 s[10:11], |v2|, s87
	s_nop 1
	v_cndmask_b32_e64 v2, v2, v43, s[10:11]
	v_cndmask_b32_e32 v43, 0, v165, vcc
	v_sub_f32_e32 v43, v2, v43
	v_pk_add_f32 v[38:39], v[40:41], v[42:43] neg_lo:[0,1] neg_hi:[0,1]
	s_nop 0
	v_pk_mul_f32 v[38:39], v[38:39], s[0:1] op_sel_hi:[1,0]
	flat_store_dwordx4 v[44:45], v[36:39]

; __device__ __forceinline__ void gemm_phase(const Ctx& cx, const GemmArgs& g_, char* shm) {
;     ...
;         if (g.epi == EPI_RES && g.w != nullptr) {
;           float v2 = ssq;
;           v2 += shx(lane, v2, 16);
;           v2 += shx(lane, v2, 32);
;           if (fq == 0) __hip_atomic_fetch_add(g.f32buf + tok, v2, __ATOMIC_RELAXED, __HIP_MEMORY_SCOPE_AGENT);
;         }
.LBB0_1063:
	ds_bpermute_b32 v36, v171, v2
	s_waitcnt lgkmcnt(0)
	v_add_f32_e32 v2, v2, v36
	ds_bpermute_b32 v36, v172, v2
	s_and_saveexec_b64 s[2:3], s[12:13]
	s_cbranch_execz .LBB0_1065
	s_waitcnt lgkmcnt(0)
	v_add_f32_e32 v2, v2, v36
	v_lshl_add_u64 v[36:37], v[136:137], 2, s[24:25]
	s_nop 0
	flat_atomic_add_f32 v[36:37], v2 offset:512

; __device__ __forceinline__ void gemm_phase(const Ctx& cx, const GemmArgs& g_, char* shm) {
;     ...
;             } else if (g.epi == EPI_RES) {
;               const float4 hv = *(const float4*)(g.hin + (size_t)tok * DM + n0);
;               const float h0 = hv.x + a[0], h1 = hv.y + a[1], h2 = hv.z + a[2], h3 = hv.w + a[3];
;               *(float4*)(g.hout + (size_t)tok * DM + n0) = make_float4(h0, h1, h2, h3);
;               if (g.w != nullptr) {
;                 const float4 nw = *(const float4*)(g.w + n0);
;                 uint2 o; o.x = pack2(h0 * nw.x, h1 * nw.y); o.y = pack2(h2 * nw.z, h3 * nw.w);
;                 EMIT_BF16(DM, o);
;                 ssq += h0 * h0 + h1 * h1 + h2 * h2 + h3 * h3;
;               }
.LBB0_1076:
	v_mov_b32_e32 v57, 0
	s_and_b64 vcc, exec, s[10:11]
	s_cbranch_vccz .LBB0_1081
	v_lshlrev_b64 v[44:45], 2, v[140:141]
	v_lshl_add_u64 v[36:37], v[42:43], 0, v[44:45]
	s_nop 0
	flat_load_dwordx4 v[36:39], v[36:37]
	v_lshl_add_u64 v[44:45], v[40:41], 0, v[44:45]
	s_andn2_b64 vcc, exec, s[42:43]
	s_waitcnt vmcnt(0) lgkmcnt(0)
	v_pk_add_f32 v[36:37], v[32:33], v[36:37]
	v_pk_add_f32 v[38:39], v[34:35], v[38:39]
	flat_store_dwordx4 v[44:45], v[36:39]
	s_cbranch_vccnz .LBB0_1080
	v_lshl_add_u64 v[44:45], v[140:141], 2, s[30:31]
	global_load_dwordx4 v[48:51], v[44:45], off
	s_waitcnt vmcnt(0)
	v_pk_mul_f32 v[44:45], v[38:39], v[50:51]
	s_nop 0
	v_cvt_pk_bf16_f32 v47, v44, v45
	v_pk_mul_f32 v[44:45], v[36:37], v[48:49]
	v_pk_mul_f32 v[36:37], v[36:37], v[36:37]
	v_pk_mul_f32 v[38:39], v[38:39], v[38:39]
	v_add_f32_e32 v2, v36, v37
	v_add_f32_e32 v2, v2, v38
	v_cvt_pk_bf16_f32 v56, v44, v45
	v_add_f32_e32 v57, v2, v39
	s_branch .LBB0_1081

; __device__ __forceinline__ float b2f(u16 b) { return __uint_as_float(((uint32_t)b) << 16); }
; __device__ __forceinline__ float sigmoidf_(float x) { return 1.0f / (1.0f + __expf(-x)); }
; __device__ __forceinline__ void gemm_phase(const Ctx& cx, const GemmArgs& g_, char* shm) {
;     ...
;               const uint2 gv = *(const uint2*)(g.gate + (size_t)tok * NP + n0);
;               float v0 = sigmoidf_(b2f((u16)(gv.x & 0xffff))) * a[0], v1 = sigmoidf_(b2f((u16)(gv.x >> 16))) * a[1];
;               float v2 = sigmoidf_(b2f((u16)(gv.y & 0xffff))) * a[2], v3 = sigmoidf_(b2f((u16)(gv.y >> 16))) * a[3];
;               uint2* mp = (uint2*)(g.outb + (size_t)tok * DM + n0);
;               if (g.epi != EPI_BR0) {
;                 const uint2 pv = *mp;
;                 v0 += b2f((u16)(pv.x & 0xffff)); v1 += b2f((u16)(pv.x >> 16));
;                 v2 += b2f((u16)(pv.y & 0xffff)); v3 += b2f((u16)(pv.y >> 16));
;               }
.LBB0_1084:
	v_lshlrev_b64 v[38:39], 12, v[52:53]
	v_mov_b64_e32 v[44:45], s[22:23]
	v_lshl_add_u64 v[36:37], s[20:21], 0, v[38:39]
	s_andn2_b64 vcc, exec, s[8:9]
	v_mad_i64_i32 v[50:51], s[8:9], v52, s76, v[44:45]
	s_cbranch_vccnz .LBB0_1088
	v_lshlrev_b64 v[48:49], 1, v[140:141]
	v_lshl_add_u64 v[44:45], v[50:51], 0, v[48:49]
	s_nop 0
	flat_load_dwordx2 v[54:55], v[44:45]
	v_lshl_add_u64 v[48:49], v[36:37], 0, v[48:49]
	s_waitcnt vmcnt(0) lgkmcnt(0)
	v_lshlrev_b32_e32 v2, 16, v54
	v_mul_f32_e32 v2, 0xbfb8aa3b, v2
	v_exp_f32_e32 v44, v2
	v_and_b32_e32 v2, 0xffff0000, v54
	v_mul_f32_e32 v2, 0xbfb8aa3b, v2
	v_exp_f32_e32 v45, v2
	s_nop 0
	v_pk_add_f32 v[44:45], v[44:45], 1.0 op_sel_hi:[1,0]
	s_nop 0
	v_div_scale_f32 v2, s[2:3], v45, v45, 1.0
	v_rcp_f32_e32 v47, v2
	s_nop 0
	v_fma_f32 v54, -v2, v47, 1.0
	v_fmac_f32_e32 v47, v54, v47
	v_div_scale_f32 v54, vcc, 1.0, v45, 1.0
	v_mul_f32_e32 v56, v54, v47
	v_fma_f32 v57, -v2, v56, v54
	v_fmac_f32_e32 v56, v57, v47
	v_fma_f32 v2, -v2, v56, v54
	v_div_fmas_f32 v2, v2, v47, v56
	v_div_fixup_f32 v45, v2, v45, 1.0
	v_div_scale_f32 v2, s[2:3], v44, v44, 1.0
	v_rcp_f32_e32 v47, v2
	s_nop 0
	v_fma_f32 v54, -v2, v47, 1.0
	v_fmac_f32_e32 v47, v54, v47
	v_div_scale_f32 v54, vcc, 1.0, v44, 1.0
	v_mul_f32_e32 v56, v54, v47
	v_fma_f32 v57, -v2, v56, v54
	v_fmac_f32_e32 v56, v57, v47
	v_fma_f32 v2, -v2, v56, v54
	v_div_fmas_f32 v2, v2, v47, v56
	v_div_fixup_f32 v44, v2, v44, 1.0
	v_lshlrev_b32_e32 v2, 16, v55
	v_mul_f32_e32 v2, 0xbfb8aa3b, v2
	v_exp_f32_e32 v54, v2
	v_and_b32_e32 v2, 0xffff0000, v55
	v_mul_f32_e32 v2, 0xbfb8aa3b, v2
	v_exp_f32_e32 v55, v2
	v_pk_mul_f32 v[44:45], v[32:33], v[44:45]
	v_pk_add_f32 v[54:55], v[54:55], 1.0 op_sel_hi:[1,0]
	s_nop 0
	v_div_scale_f32 v2, s[2:3], v55, v55, 1.0
	v_rcp_f32_e32 v47, v2
	s_nop 0
	v_fma_f32 v56, -v2, v47, 1.0
	v_fmac_f32_e32 v47, v56, v47
	v_div_scale_f32 v56, vcc, 1.0, v55, 1.0
	v_mul_f32_e32 v57, v56, v47
	v_fma_f32 v58, -v2, v57, v56
	v_fmac_f32_e32 v57, v58, v47
	v_fma_f32 v2, -v2, v57, v56
	v_div_fmas_f32 v2, v2, v47, v57
	v_div_fixup_f32 v55, v2, v55, 1.0
	v_div_scale_f32 v2, s[2:3], v54, v54, 1.0
	v_rcp_f32_e32 v47, v2
	s_nop 0
	v_fma_f32 v56, -v2, v47, 1.0
	v_fmac_f32_e32 v47, v56, v47
	v_div_scale_f32 v56, vcc, 1.0, v54, 1.0
	v_mul_f32_e32 v57, v56, v47
	v_fma_f32 v58, -v2, v57, v56
	v_fmac_f32_e32 v57, v58, v47
	v_fma_f32 v2, -v2, v57, v56
	v_div_fmas_f32 v2, v2, v47, v57
	v_div_fixup_f32 v54, v2, v54, 1.0
	v_pk_mul_f32 v[54:55], v[34:35], v[54:55]
	s_and_b64 vcc, exec, s[4:5]
	s_cbranch_vccnz .LBB0_1087
	flat_load_dwordx2 v[56:57], v[48:49]
	s_waitcnt vmcnt(0) lgkmcnt(0)
	v_lshlrev_b32_e32 v58, 16, v56
	v_and_b32_e32 v59, 0xffff0000, v56
	v_lshlrev_b32_e32 v56, 16, v57
	v_and_b32_e32 v57, 0xffff0000, v57
	v_pk_add_f32 v[44:45], v[44:45], v[58:59]
	v_pk_add_f32 v[54:55], v[54:55], v[56:57]

; __device__ __forceinline__ void gemm_phase(const Ctx& cx, const GemmArgs& g_, char* shm) {
;     ...
;                 const bool r128 = (n0 >= C_DSAQ && n0 < C_HGQ) || (n0 >= C_DSAK && n0 < C_DSAV);
;                 const bool r64 = (n0 >= C_IDXQ && n0 < C_GLAA);
;                 if (r128 || r64) {
;                   float4 cs;
;                   float sc;
;                   if (r128) {
;                     cs = *(const float4*)(g.w + ((size_t)tok * 64 + ((n0 & 127) >> 1)) * 2);
;                     sc = (n0 < C_HGQ) ? 0.08838834764831845f : 1.0f;
;                   } else {
;                     cs = *(const float4*)(g.hout + ((size_t)tok * 32 + ((n0 & 63) >> 1)) * 2);
;                     sc = (n0 < C_IDXK) ? 0.125f : 1.0f;
;                   }
;                   o0 = (a[0] * cs.x - a[1] * cs.y) * sc; o1 = (a[1] * cs.x + a[0] * cs.y) * sc;
;                   o2 = (a[2] * cs.z - a[3] * cs.w) * sc; o3 = (a[3] * cs.z + a[2] * cs.w) * sc;
;                 }
.LBB0_1088:
	s_movk_i32 s0, 0xe100
	v_lshlrev_b64 v[44:45], 9, v[52:53]
	v_mad_i64_i32 v[48:49], s[8:9], v52, s0, v[40:41]
	v_lshl_add_u64 v[44:45], s[30:31], 0, v[44:45]
	v_lshl_add_u64 v[38:39], s[24:25], 0, v[38:39]
	s_and_b64 vcc, exec, s[2:3]
	s_cbranch_vccz .LBB0_1100
	s_movk_i32 s0, 0x5c00
	v_cmp_gt_i32_e32 vcc, s0, v140
	s_and_saveexec_b64 s[2:3], vcc
	s_xor_b64 s[2:3], exec, s[2:3]
	s_cbranch_execz .LBB0_1097
	v_add_u32_e32 v2, 0xffffa700, v138
	v_cmp_gt_u32_e32 vcc, s77, v2
	s_or_b64 s[10:11], s[58:59], vcc
	s_and_saveexec_b64 s[8:9], s[10:11]
	s_cbranch_execz .LBB0_1096
	s_and_saveexec_b64 s[10:11], s[56:57]
	s_xor_b64 s[10:11], exec, s[10:11]
	s_movk_i32 s0, 0x5b00
	v_lshlrev_b32_e32 v2, 2, v0
	v_cmp_gt_u32_e32 vcc, s0, v138
	v_lshl_add_u64 v[54:55], v[48:49], 0, v[2:3]
	s_nop 0
	v_cndmask_b32_e32 v2, 1.0, v166, vcc
	s_andn2_saveexec_b64 s[10:11], s[10:11]
	v_and_b32_e32 v2, 0x4c, v140
	v_cmp_gt_i32_e32 vcc, s81, v140
	v_lshlrev_b32_e32 v2, 2, v2
	v_lshl_add_u64 v[54:55], v[44:45], 0, v[2:3]
	v_cndmask_b32_e32 v2, 1.0, v167, vcc
	s_or_b64 exec, exec, s[10:11]
	s_nop 0
	flat_load_dwordx4 v[54:57], v[54:55]
	s_waitcnt vmcnt(0) lgkmcnt(0)
	v_pk_mul_f32 v[58:59], v[32:33], v[54:55] op_sel:[1,1] op_sel_hi:[1,0]
	s_nop 0
	v_pk_fma_f32 v[60:61], v[32:33], v[54:55], v[58:59] neg_lo:[0,0,1] neg_hi:[0,0,1]
	v_pk_fma_f32 v[32:33], v[32:33], v[54:55], v[58:59] op_sel_hi:[0,1,1]
	v_mov_b32_e32 v54, v35
	v_pk_mul_f32 v[54:55], v[54:55], v[56:57] op_sel:[0,1] op_sel_hi:[0,0]
	v_pk_fma_f32 v[58:59], v[34:35], v[56:57], v[54:55] neg_lo:[0,0,1] neg_hi:[0,0,1]
	v_pk_fma_f32 v[34:35], v[34:35], v[56:57], v[54:55] op_sel_hi:[0,1,1]
	v_mov_b32_e32 v61, v33
	v_mov_b32_e32 v59, v35
	v_pk_mul_f32 v[32:33], v[2:3], v[60:61] op_sel_hi:[0,1]
	v_pk_mul_f32 v[34:35], v[2:3], v[58:59] op_sel_hi:[0,1]

; __device__ __forceinline__ void gemm_phase(const Ctx& cx, const GemmArgs& g_, char* shm) {
;     ...
;               if (n0 >= C_GLAX) {
;                 const int i = n0 - C_GLAX;
;                 const float4 b4 = *(const float4*)(g.hin + i);
;                 float xs[4] = {a[0] + b4.x, a[1] + b4.y, a[2] + b4.z, a[3] + b4.w};
; #pragma unroll
;                 for (int j = 0; j < 4; ++j)
;                   xs[j] = (fminf(xs[j], 0.f) - __logf(1.0f + __expf(-fabsf(xs[j])))) * (1.0f / 16.0f);
;                 *(float4*)(g.f32buf + (size_t)tok * 1024 + i) = make_float4(xs[0], xs[1], xs[2], xs[3]);
.LBB0_1097:
	s_andn2_saveexec_b64 s[2:3], s[2:3]
	s_cbranch_execz .LBB0_1099
	v_add_u32_e32 v2, 0xffffa400, v140
	v_lshlrev_b64 v[58:59], 2, v[2:3]
	v_lshl_add_u64 v[54:55], s[26:27], 0, v[58:59]
	s_nop 0
	flat_load_dwordx4 v[54:57], v[54:55]
	s_mov_b32 s0, 0x3d800000
	v_mov_b32_e32 v47, 0
	v_lshl_add_u64 v[58:59], v[38:39], 0, v[58:59]
	s_waitcnt vmcnt(0) lgkmcnt(0)
	v_add_f32_e32 v2, v32, v54
	v_min_f32_e32 v32, 0, v2
	v_mul_f32_e64 v2, |v2|, s82
	v_exp_f32_e32 v2, v2
	v_add_f32_e32 v53, v33, v55
	v_add_f32_e32 v55, v34, v56
	v_add_f32_e32 v57, v35, v57
	v_add_f32_e32 v2, 1.0, v2
	v_cmp_gt_f32_e32 vcc, s83, v2
	v_min_f32_e32 v54, 0, v55
	s_nop 0
	v_cndmask_b32_e64 v33, 0, 32, vcc
	v_ldexp_f32 v2, v2, v33
	v_log_f32_e32 v2, v2
	s_nop 0
	v_mul_f32_e32 v33, 0x3f317217, v2
	v_fma_f32 v33, v2, s86, -v33
	v_fmac_f32_e32 v33, 0x3377d1cf, v2
	v_fmac_f32_e32 v33, 0x3f317217, v2
	v_cmp_lt_f32_e64 s[8:9], |v2|, s87
	s_nop 1
	v_cndmask_b32_e64 v2, v2, v33, s[8:9]
	v_cndmask_b32_e32 v33, 0, v165, vcc
	v_sub_f32_e32 v34, v2, v33
	v_mul_f32_e64 v2, |v53|, s82
	v_exp_f32_e32 v2, v2
	v_min_f32_e32 v33, 0, v53
	v_add_f32_e32 v2, 1.0, v2
	v_cmp_gt_f32_e32 vcc, s83, v2
	s_nop 1
	v_cndmask_b32_e64 v35, 0, 32, vcc
	v_ldexp_f32 v2, v2, v35
	v_log_f32_e32 v2, v2
	s_nop 0
	v_mul_f32_e32 v35, 0x3f317217, v2
	v_fma_f32 v35, v2, s86, -v35
	v_fmac_f32_e32 v35, 0x3377d1cf, v2
	v_fmac_f32_e32 v35, 0x3f317217, v2
	v_cmp_lt_f32_e64 s[8:9], |v2|, s87
	s_nop 1
	v_cndmask_b32_e64 v2, v2, v35, s[8:9]
	v_cndmask_b32_e32 v35, 0, v165, vcc
	v_sub_f32_e32 v35, v2, v35
	v_mul_f32_e64 v2, |v55|, s82
	v_exp_f32_e32 v2, v2
	v_min_f32_e32 v55, 0, v57
	v_pk_add_f32 v[32:33], v[32:33], v[34:35] neg_lo:[0,1] neg_hi:[0,1]
	v_add_f32_e32 v2, 1.0, v2
	v_cmp_gt_f32_e32 vcc, s83, v2
	v_pk_mul_f32 v[32:33], v[32:33], s[0:1] op_sel_hi:[1,0]
	s_nop 0
	v_cndmask_b32_e64 v53, 0, 32, vcc
	v_ldexp_f32 v2, v2, v53
	v_log_f32_e32 v2, v2
	s_nop 0
	v_mul_f32_e32 v53, 0x3f317217, v2
	v_fma_f32 v53, v2, s86, -v53
	v_fmac_f32_e32 v53, 0x3377d1cf, v2
	v_fmac_f32_e32 v53, 0x3f317217, v2
	v_cmp_lt_f32_e64 s[8:9], |v2|, s87
	s_nop 1
	v_cndmask_b32_e64 v2, v2, v53, s[8:9]
	v_cndmask_b32_e32 v53, 0, v165, vcc
	v_sub_f32_e32 v56, v2, v53
	v_mul_f32_e64 v2, |v57|, s82
	v_exp_f32_e32 v2, v2
	s_nop 0
	v_add_f32_e32 v2, 1.0, v2
	v_cmp_gt_f32_e32 vcc, s83, v2
	s_nop 1
	v_cndmask_b32_e64 v53, 0, 32, vcc
	v_ldexp_f32 v2, v2, v53
	v_log_f32_e32 v2, v2
	s_nop 0
	v_mul_f32_e32 v53, 0x3f317217, v2
	v_fma_f32 v53, v2, s86, -v53
	v_fmac_f32_e32 v53, 0x3377d1cf, v2
	v_fmac_f32_e32 v53, 0x3f317217, v2
	v_cmp_lt_f32_e64 s[8:9], |v2|, s87
	s_nop 1
	v_cndmask_b32_e64 v2, v2, v53, s[8:9]
	v_cndmask_b32_e32 v53, 0, v165, vcc
	v_sub_f32_e32 v57, v2, v53
	v_pk_add_f32 v[34:35], v[54:55], v[56:57] neg_lo:[0,1] neg_hi:[0,1]
	v_mov_b32_e32 v56, 0
	v_pk_mul_f32 v[34:35], v[34:35], s[0:1] op_sel_hi:[1,0]
	flat_store_dwordx4 v[58:59], v[32:35]

; __device__ __forceinline__ void gemm_phase(const Ctx& cx, const GemmArgs& g_, char* shm) {
;     ...
;             } else if (g.epi == EPI_RELU2) {
;               float r0 = fmaxf(a[0], 0.f), r1 = fmaxf(a[1], 0.f), r2 = fmaxf(a[2], 0.f), r3 = fmaxf(a[3], 0.f);
;               uint2 o; o.x = pack2(r0 * r0, r1 * r1); o.y = pack2(r2 * r2, r3 * r3);
;               EMIT_BF16(g.ldo, o);
.LBB0_1112:
	s_cmp_gt_i32 s38, 4
	s_cbranch_scc0 .LBB0_1116
	s_cmp_eq_u32 s38, 5
	s_mov_b64 s[8:9], -1
	s_cbranch_scc0 .LBB0_1115
	v_max_f32_e32 v2, v30, v30
	v_max_f32_e32 v32, 0, v2
	v_max_f32_e32 v2, v31, v31
	v_max_f32_e32 v33, 0, v2
	v_pk_mul_f32 v[32:33], v[32:33], v[32:33]
	v_max_f32_e32 v2, v28, v28
	v_cvt_pk_bf16_f32 v35, v32, v33
	v_max_f32_e32 v32, 0, v2
	v_max_f32_e32 v2, v29, v29
	v_max_f32_e32 v33, 0, v2
	v_pk_mul_f32 v[32:33], v[32:33], v[32:33]
	v_ashrrev_i32_e32 v133, 31, v132
	v_cvt_pk_bf16_f32 v34, v32, v33
	v_mov_b32_e32 v32, v56
	v_mov_b32_e32 v33, v47
	s_nop 0
	v_permlane16_swap_b32_e32 v32, v34
	v_permlane16_swap_b32_e32 v33, v35
	v_lshl_add_u64 v[54:55], v[132:133], 1, v[52:53]
	s_nop 0
	flat_store_dwordx4 v[54:55], v[32:35] offset:32
	s_mov_b64 s[8:9], 0

; __device__ __forceinline__ void gemm_phase(const Ctx& cx, const GemmArgs& g_, char* shm) {
;     ...
;             } else if (g.epi == EPI_RES) {
;               const float4 hv = *(const float4*)(g.hin + (size_t)tok * DM + n0);
;               const float h0 = hv.x + a[0], h1 = hv.y + a[1], h2 = hv.z + a[2], h3 = hv.w + a[3];
;               *(float4*)(g.hout + (size_t)tok * DM + n0) = make_float4(h0, h1, h2, h3);
;               if (g.w != nullptr) {
;                 const float4 nw = *(const float4*)(g.w + n0);
;                 uint2 o; o.x = pack2(h0 * nw.x, h1 * nw.y); o.y = pack2(h2 * nw.z, h3 * nw.w);
;                 EMIT_BF16(DM, o);
;                 ssq += h0 * h0 + h1 * h1 + h2 * h2 + h3 * h3;
;               }
.LBB0_1116:
	s_and_b64 vcc, exec, s[10:11]
	v_mov_b32_e32 v58, v57
	s_cbranch_vccz .LBB0_1119
	v_lshl_add_u64 v[54:55], v[138:139], 0, v[0:1]
	v_lshlrev_b64 v[58:59], 2, v[54:55]
	v_lshl_add_u64 v[32:33], v[42:43], 0, v[58:59]
	s_nop 0
	flat_load_dwordx4 v[32:35], v[32:33] offset:64
	v_lshl_add_u64 v[58:59], v[40:41], 0, v[58:59]
	s_andn2_b64 vcc, exec, s[42:43]
	s_waitcnt vmcnt(0) lgkmcnt(0)
	v_pk_add_f32 v[32:33], v[28:29], v[32:33]
	v_pk_add_f32 v[34:35], v[30:31], v[34:35]
	flat_store_dwordx4 v[58:59], v[32:35] offset:64
	v_mov_b32_e32 v58, v57
	s_cbranch_vccnz .LBB0_1119
	v_lshl_add_u64 v[54:55], v[54:55], 2, s[30:31]
	global_load_dwordx4 v[58:61], v[54:55], off offset:64
	v_ashrrev_i32_e32 v133, 31, v132
	s_waitcnt vmcnt(0)
	v_pk_mul_f32 v[54:55], v[34:35], v[60:61]
	s_nop 0
	v_cvt_pk_bf16_f32 v61, v54, v55
	v_pk_mul_f32 v[54:55], v[32:33], v[58:59]
	v_pk_mul_f32 v[32:33], v[32:33], v[32:33]
	v_pk_mul_f32 v[34:35], v[34:35], v[34:35]
	v_add_f32_e32 v2, v32, v33
	v_cvt_pk_bf16_f32 v60, v54, v55
	v_mov_b32_e32 v58, v56
	v_mov_b32_e32 v59, v47
	v_add_f32_e32 v2, v2, v34
	v_permlane16_swap_b32_e32 v58, v60
	v_permlane16_swap_b32_e32 v59, v61
	v_lshl_add_u64 v[54:55], v[132:133], 1, v[36:37]
	v_add_f32_e32 v2, v2, v35
	flat_store_dwordx4 v[54:55], v[58:61] offset:32
	s_nop 1
	v_add_f32_e32 v58, v57, v2

; __device__ __forceinline__ float b2f(u16 b) { return __uint_as_float(((uint32_t)b) << 16); }
; __device__ __forceinline__ float sigmoidf_(float x) { return 1.0f / (1.0f + __expf(-x)); }
; __device__ __forceinline__ void gemm_phase(const Ctx& cx, const GemmArgs& g_, char* shm) {
;     ...
;               const uint2 gv = *(const uint2*)(g.gate + (size_t)tok * NP + n0);
;               float v0 = sigmoidf_(b2f((u16)(gv.x & 0xffff))) * a[0], v1 = sigmoidf_(b2f((u16)(gv.x >> 16))) * a[1];
;               float v2 = sigmoidf_(b2f((u16)(gv.y & 0xffff))) * a[2], v3 = sigmoidf_(b2f((u16)(gv.y >> 16))) * a[3];
;               uint2* mp = (uint2*)(g.outb + (size_t)tok * DM + n0);
;               if (g.epi != EPI_BR0) {
;                 const uint2 pv = *mp;
;                 v0 += b2f((u16)(pv.x & 0xffff)); v1 += b2f((u16)(pv.x >> 16));
;                 v2 += b2f((u16)(pv.y & 0xffff)); v3 += b2f((u16)(pv.y >> 16));
;               }
.LBB0_1121:
	v_lshl_add_u64 v[32:33], v[138:139], 0, v[0:1]
	v_lshlrev_b64 v[34:35], 1, v[32:33]
	v_lshl_add_u64 v[32:33], v[50:51], 0, v[34:35]
	s_nop 0
	flat_load_dwordx2 v[54:55], v[32:33] offset:32
	v_lshl_add_u64 v[34:35], v[36:37], 0, v[34:35]
	s_waitcnt vmcnt(0) lgkmcnt(0)
	v_lshlrev_b32_e32 v2, 16, v54
	v_mul_f32_e32 v2, 0xbfb8aa3b, v2
	v_exp_f32_e32 v32, v2
	v_and_b32_e32 v2, 0xffff0000, v54
	v_mul_f32_e32 v2, 0xbfb8aa3b, v2
	v_exp_f32_e32 v33, v2
	s_nop 0
	v_pk_add_f32 v[32:33], v[32:33], 1.0 op_sel_hi:[1,0]
	s_nop 0
	v_div_scale_f32 v2, s[2:3], v33, v33, 1.0
	v_rcp_f32_e32 v54, v2
	s_nop 0
	v_fma_f32 v58, -v2, v54, 1.0
	v_fmac_f32_e32 v54, v58, v54
	v_div_scale_f32 v58, vcc, 1.0, v33, 1.0
	v_mul_f32_e32 v59, v58, v54
	v_fma_f32 v60, -v2, v59, v58
	v_fmac_f32_e32 v59, v60, v54
	v_fma_f32 v2, -v2, v59, v58
	v_div_fmas_f32 v2, v2, v54, v59
	v_div_fixup_f32 v33, v2, v33, 1.0
	v_div_scale_f32 v2, s[2:3], v32, v32, 1.0
	v_rcp_f32_e32 v54, v2
	s_nop 0
	v_fma_f32 v58, -v2, v54, 1.0
	v_fmac_f32_e32 v54, v58, v54
	v_div_scale_f32 v58, vcc, 1.0, v32, 1.0
	v_mul_f32_e32 v59, v58, v54
	v_fma_f32 v60, -v2, v59, v58
	v_fmac_f32_e32 v59, v60, v54
	v_fma_f32 v2, -v2, v59, v58
	v_div_fmas_f32 v2, v2, v54, v59
	v_div_fixup_f32 v32, v2, v32, 1.0
	v_lshlrev_b32_e32 v2, 16, v55
	v_mul_f32_e32 v2, 0xbfb8aa3b, v2
	v_exp_f32_e32 v54, v2
	v_and_b32_e32 v2, 0xffff0000, v55
	v_mul_f32_e32 v2, 0xbfb8aa3b, v2
	v_exp_f32_e32 v55, v2
	v_pk_mul_f32 v[32:33], v[28:29], v[32:33]
	v_pk_add_f32 v[54:55], v[54:55], 1.0 op_sel_hi:[1,0]
	s_nop 0
	v_div_scale_f32 v2, s[2:3], v55, v55, 1.0
	v_rcp_f32_e32 v58, v2
	s_nop 0
	v_fma_f32 v59, -v2, v58, 1.0
	v_fmac_f32_e32 v58, v59, v58
	v_div_scale_f32 v59, vcc, 1.0, v55, 1.0
	v_mul_f32_e32 v60, v59, v58
	v_fma_f32 v61, -v2, v60, v59
	v_fmac_f32_e32 v60, v61, v58
	v_fma_f32 v2, -v2, v60, v59
	v_div_fmas_f32 v2, v2, v58, v60
	v_div_fixup_f32 v55, v2, v55, 1.0
	v_div_scale_f32 v2, s[2:3], v54, v54, 1.0
	v_rcp_f32_e32 v58, v2
	s_nop 0
	v_fma_f32 v59, -v2, v58, 1.0
	v_fmac_f32_e32 v58, v59, v58
	v_div_scale_f32 v59, vcc, 1.0, v54, 1.0
	v_mul_f32_e32 v60, v59, v58
	v_fma_f32 v61, -v2, v60, v59
	v_fmac_f32_e32 v60, v61, v58
	v_fma_f32 v2, -v2, v60, v59
	v_div_fmas_f32 v2, v2, v58, v60
	v_div_fixup_f32 v54, v2, v54, 1.0
	v_pk_mul_f32 v[54:55], v[30:31], v[54:55]
	s_and_b64 vcc, exec, s[4:5]
	s_cbranch_vccnz .LBB0_1123
	flat_load_dwordx2 v[58:59], v[34:35] offset:32
	s_waitcnt vmcnt(0) lgkmcnt(0)
	v_lshlrev_b32_e32 v60, 16, v58
	v_and_b32_e32 v61, 0xffff0000, v58
	v_lshlrev_b32_e32 v58, 16, v59
	v_and_b32_e32 v59, 0xffff0000, v59
	v_pk_add_f32 v[32:33], v[32:33], v[60:61]
	v_pk_add_f32 v[54:55], v[54:55], v[58:59]

; __device__ __forceinline__ void gemm_phase(const Ctx& cx, const GemmArgs& g_, char* shm) {
;     ...
;               if (n0 >= C_GLAX) {
;                 const int i = n0 - C_GLAX;
;                 const float4 b4 = *(const float4*)(g.hin + i);
;                 float xs[4] = {a[0] + b4.x, a[1] + b4.y, a[2] + b4.z, a[3] + b4.w};
; #pragma unroll
;                 for (int j = 0; j < 4; ++j)
;                   xs[j] = (fminf(xs[j], 0.f) - __logf(1.0f + __expf(-fabsf(xs[j])))) * (1.0f / 16.0f);
;                 *(float4*)(g.f32buf + (size_t)tok * 1024 + i) = make_float4(xs[0], xs[1], xs[2], xs[3]);
;               } else {
;                 float o0 = a[0], o1 = a[1], o2 = a[2], o3 = a[3];
;                 const bool r128 = (n0 >= C_DSAQ && n0 < C_HGQ) || (n0 >= C_DSAK && n0 < C_DSAV);
;                 const bool r64 = (n0 >= C_IDXQ && n0 < C_GLAA);
;                 if (r128 || r64) {
;                   float4 cs;
;                   float sc;
;                   if (r128) {
;                     cs = *(const float4*)(g.w + ((size_t)tok * 64 + ((n0 & 127) >> 1)) * 2);
;                     sc = (n0 < C_HGQ) ? 0.08838834764831845f : 1.0f;
;                   } else {
;                     cs = *(const float4*)(g.hout + ((size_t)tok * 32 + ((n0 & 63) >> 1)) * 2);
;                     sc = (n0 < C_IDXK) ? 0.125f : 1.0f;
;                   }
;                   o0 = (a[0] * cs.x - a[1] * cs.y) * sc; o1 = (a[1] * cs.x + a[0] * cs.y) * sc;
;                   o2 = (a[2] * cs.z - a[3] * cs.w) * sc; o3 = (a[3] * cs.z + a[2] * cs.w) * sc;
;                 }
;                 uint2 o; o.x = pack2(o0, o1); o.y = pack2(o2, o3);
;                 EMIT_BF16(g.ldo, o);
.LBB0_1124:
	s_movk_i32 s0, 0x5c00
	v_cmp_gt_i32_e32 vcc, s0, v177
	s_and_saveexec_b64 s[2:3], vcc
	s_xor_b64 s[2:3], exec, s[2:3]
	s_cbranch_execz .LBB0_1132
	v_add_u32_e32 v2, 0xffffa700, v138
	v_cmp_gt_u32_e32 vcc, s77, v2
	s_or_b64 s[10:11], s[58:59], vcc
	s_and_saveexec_b64 s[8:9], s[10:11]
	s_cbranch_execz .LBB0_1131
	s_and_saveexec_b64 s[10:11], s[56:57]
	s_xor_b64 s[10:11], exec, s[10:11]
	v_lshlrev_b32_e32 v2, 2, v0
	s_movk_i32 s0, 0x5b00
	v_lshl_add_u64 v[32:33], v[48:49], 0, v[2:3]
	v_cmp_gt_u32_e32 vcc, s0, v138
	v_lshl_add_u64 v[32:33], v[32:33], 0, 64
	s_nop 0
	v_cndmask_b32_e32 v2, 1.0, v166, vcc
	s_andn2_saveexec_b64 s[10:11], s[10:11]
	v_and_b32_e32 v2, 0x5c, v177
	v_cmp_gt_i32_e32 vcc, s81, v177
	v_lshlrev_b32_e32 v2, 2, v2
	v_lshl_add_u64 v[32:33], v[44:45], 0, v[2:3]
	v_cndmask_b32_e32 v2, 1.0, v167, vcc
	s_or_b64 exec, exec, s[10:11]
	s_nop 0
	flat_load_dwordx4 v[32:35], v[32:33]
	s_waitcnt vmcnt(0) lgkmcnt(0)
	v_pk_mul_f32 v[54:55], v[28:29], v[32:33] op_sel:[1,1] op_sel_hi:[1,0]
	s_nop 0
	v_pk_fma_f32 v[58:59], v[28:29], v[32:33], v[54:55] neg_lo:[0,0,1] neg_hi:[0,0,1]
	v_pk_fma_f32 v[28:29], v[28:29], v[32:33], v[54:55] op_sel_hi:[0,1,1]
	v_mov_b32_e32 v32, v31
	v_pk_mul_f32 v[32:33], v[32:33], v[34:35] op_sel:[0,1] op_sel_hi:[0,0]
	v_pk_fma_f32 v[54:55], v[30:31], v[34:35], v[32:33] neg_lo:[0,0,1] neg_hi:[0,0,1]
	v_pk_fma_f32 v[30:31], v[30:31], v[34:35], v[32:33] op_sel_hi:[0,1,1]
	v_mov_b32_e32 v59, v29
	v_mov_b32_e32 v55, v31
	v_pk_mul_f32 v[28:29], v[2:3], v[58:59] op_sel_hi:[0,1]
	v_pk_mul_f32 v[30:31], v[2:3], v[54:55] op_sel_hi:[0,1]
.LBB0_1131:
	s_or_b64 exec, exec, s[8:9]
	v_cvt_pk_bf16_f32 v31, v30, v31
	v_cvt_pk_bf16_f32 v30, v28, v29
	v_mov_b32_e32 v28, v56
	v_mov_b32_e32 v29, v47
	v_ashrrev_i32_e32 v133, 31, v132
	v_permlane16_swap_b32_e32 v28, v30
	v_permlane16_swap_b32_e32 v29, v31
	v_lshl_add_u64 v[32:33], v[132:133], 1, v[52:53]
	s_nop 0
	flat_store_dwordx4 v[32:33], v[28:31] offset:32
.LBB0_1132:
	s_andn2_saveexec_b64 s[2:3], s[2:3]
	s_cbranch_execz .LBB0_1134
	v_add_u32_e32 v2, 0xffffa400, v177
	v_lshlrev_b64 v[54:55], 2, v[2:3]
	v_lshl_add_u64 v[32:33], s[26:27], 0, v[54:55]
	s_nop 0
	flat_load_dwordx4 v[32:35], v[32:33]
	s_mov_b32 s0, 0x3d800000
	v_lshl_add_u64 v[54:55], v[38:39], 0, v[54:55]
	s_waitcnt vmcnt(0) lgkmcnt(0)
	v_add_f32_e32 v2, v28, v32
	v_min_f32_e32 v28, 0, v2
	v_mul_f32_e64 v2, |v2|, s82
	v_exp_f32_e32 v2, v2
	v_add_f32_e32 v32, v29, v33
	v_add_f32_e32 v33, v30, v34
	v_add_f32_e32 v35, v31, v35
	v_add_f32_e32 v2, 1.0, v2
	v_cmp_gt_f32_e32 vcc, s83, v2
	s_nop 1
	v_cndmask_b32_e64 v29, 0, 32, vcc
	v_ldexp_f32 v2, v2, v29
	v_log_f32_e32 v2, v2
	s_nop 0
	v_mul_f32_e32 v29, 0x3f317217, v2
	v_fma_f32 v29, v2, s86, -v29
	v_fmac_f32_e32 v29, 0x3377d1cf, v2
	v_fmac_f32_e32 v29, 0x3f317217, v2
	v_cmp_lt_f32_e64 s[8:9], |v2|, s87
	s_nop 1
	v_cndmask_b32_e64 v2, v2, v29, s[8:9]
	v_cndmask_b32_e32 v29, 0, v165, vcc
	v_sub_f32_e32 v30, v2, v29
	v_mul_f32_e64 v2, |v32|, s82
	v_exp_f32_e32 v2, v2
	v_min_f32_e32 v29, 0, v32
	v_min_f32_e32 v32, 0, v33
	v_add_f32_e32 v2, 1.0, v2
	v_cmp_gt_f32_e32 vcc, s83, v2
	s_nop 1
	v_cndmask_b32_e64 v31, 0, 32, vcc
	v_ldexp_f32 v2, v2, v31
	v_log_f32_e32 v2, v2
	s_nop 0
	v_mul_f32_e32 v31, 0x3f317217, v2
	v_fma_f32 v31, v2, s86, -v31
	v_fmac_f32_e32 v31, 0x3377d1cf, v2
	v_fmac_f32_e32 v31, 0x3f317217, v2
	v_cmp_lt_f32_e64 s[8:9], |v2|, s87
	s_nop 1
	v_cndmask_b32_e64 v2, v2, v31, s[8:9]
	v_cndmask_b32_e32 v31, 0, v165, vcc
	v_sub_f32_e32 v31, v2, v31
	v_mul_f32_e64 v2, |v33|, s82
	v_exp_f32_e32 v2, v2
	v_pk_add_f32 v[28:29], v[28:29], v[30:31] neg_lo:[0,1] neg_hi:[0,1]
	v_add_f32_e32 v2, 1.0, v2
	v_cmp_gt_f32_e32 vcc, s83, v2
	v_pk_mul_f32 v[28:29], v[28:29], s[0:1] op_sel_hi:[1,0]
	s_nop 0
	v_cndmask_b32_e64 v33, 0, 32, vcc
	v_ldexp_f32 v2, v2, v33
	v_log_f32_e32 v2, v2
	s_nop 0
	v_mul_f32_e32 v33, 0x3f317217, v2
	v_fma_f32 v33, v2, s86, -v33
	v_fmac_f32_e32 v33, 0x3377d1cf, v2
	v_fmac_f32_e32 v33, 0x3f317217, v2
	v_cmp_lt_f32_e64 s[8:9], |v2|, s87
	s_nop 1
	v_cndmask_b32_e64 v2, v2, v33, s[8:9]
	v_cndmask_b32_e32 v33, 0, v165, vcc
	v_sub_f32_e32 v34, v2, v33
	v_mul_f32_e64 v2, |v35|, s82
	v_exp_f32_e32 v2, v2
	v_min_f32_e32 v33, 0, v35
	v_add_f32_e32 v2, 1.0, v2
	v_cmp_gt_f32_e32 vcc, s83, v2
	s_nop 1
	v_cndmask_b32_e64 v35, 0, 32, vcc
	v_ldexp_f32 v2, v2, v35
	v_log_f32_e32 v2, v2
	s_nop 0
	v_mul_f32_e32 v35, 0x3f317217, v2
	v_fma_f32 v35, v2, s86, -v35
	v_fmac_f32_e32 v35, 0x3377d1cf, v2
	v_fmac_f32_e32 v35, 0x3f317217, v2
	v_cmp_lt_f32_e64 s[8:9], |v2|, s87
	s_nop 1
	v_cndmask_b32_e64 v2, v2, v35, s[8:9]
	v_cndmask_b32_e32 v35, 0, v165, vcc
	v_sub_f32_e32 v35, v2, v35
	v_pk_add_f32 v[30:31], v[32:33], v[34:35] neg_lo:[0,1] neg_hi:[0,1]
	s_nop 0
	v_pk_mul_f32 v[30:31], v[30:31], s[0:1] op_sel_hi:[1,0]
	flat_store_dwordx4 v[54:55], v[28:31]

; __device__ __forceinline__ void gemm_phase(const Ctx& cx, const GemmArgs& g_, char* shm) {
;     ...
;             } else if (g.epi == EPI_RES) {
;               const float4 hv = *(const float4*)(g.hin + (size_t)tok * DM + n0);
;               const float h0 = hv.x + a[0], h1 = hv.y + a[1], h2 = hv.z + a[2], h3 = hv.w + a[3];
;               *(float4*)(g.hout + (size_t)tok * DM + n0) = make_float4(h0, h1, h2, h3);
;               if (g.w != nullptr) {
;                 const float4 nw = *(const float4*)(g.w + n0);
;                 uint2 o; o.x = pack2(h0 * nw.x, h1 * nw.y); o.y = pack2(h2 * nw.z, h3 * nw.w);
;                 EMIT_BF16(DM, o);
;                 ssq += h0 * h0 + h1 * h1 + h2 * h2 + h3 * h3;
;               }
.LBB0_1149:
	s_and_b64 vcc, exec, s[10:11]
	v_mov_b32_e32 v54, v58
	s_cbranch_vccz .LBB0_1152
	v_lshl_add_u64 v[34:35], v[138:139], 0, v[0:1]
	v_lshlrev_b64 v[28:29], 2, v[34:35]
	v_lshl_add_u64 v[30:31], v[42:43], 0, v[28:29]
	s_nop 0
	flat_load_dwordx4 v[30:33], v[30:31] offset:128
	v_lshl_add_u64 v[28:29], v[40:41], 0, v[28:29]
	s_andn2_b64 vcc, exec, s[42:43]
	v_mov_b32_e32 v54, v58
	s_waitcnt vmcnt(0) lgkmcnt(0)
	v_pk_add_f32 v[30:31], v[24:25], v[30:31]
	v_pk_add_f32 v[32:33], v[26:27], v[32:33]
	flat_store_dwordx4 v[28:29], v[30:33] offset:128
	v_mov_b32_e32 v29, v47
	v_mov_b32_e32 v28, v56
	s_cbranch_vccnz .LBB0_1152
	v_lshl_add_u64 v[28:29], v[34:35], 2, s[30:31]
	global_load_dwordx4 v[60:63], v[28:29], off offset:128
	v_pk_mul_f32 v[28:29], v[30:31], v[30:31]
	v_pk_mul_f32 v[34:35], v[32:33], v[32:33]
	v_add_f32_e32 v2, v28, v29
	v_add_f32_e32 v2, v2, v34
	v_add_f32_e32 v2, v2, v35
	v_add_f32_e32 v54, v58, v2
	s_waitcnt vmcnt(0)
	v_pk_mul_f32 v[28:29], v[32:33], v[62:63]
	v_pk_mul_f32 v[30:31], v[30:31], v[60:61]
	v_cvt_pk_bf16_f32 v29, v28, v29
	v_cvt_pk_bf16_f32 v28, v30, v31

; __device__ __forceinline__ float b2f(u16 b) { return __uint_as_float(((uint32_t)b) << 16); }
; __device__ __forceinline__ float sigmoidf_(float x) { return 1.0f / (1.0f + __expf(-x)); }
; __device__ __forceinline__ void gemm_phase(const Ctx& cx, const GemmArgs& g_, char* shm) {
;     ...
;               const uint2 gv = *(const uint2*)(g.gate + (size_t)tok * NP + n0);
;               float v0 = sigmoidf_(b2f((u16)(gv.x & 0xffff))) * a[0], v1 = sigmoidf_(b2f((u16)(gv.x >> 16))) * a[1];
;               float v2 = sigmoidf_(b2f((u16)(gv.y & 0xffff))) * a[2], v3 = sigmoidf_(b2f((u16)(gv.y >> 16))) * a[3];
;               uint2* mp = (uint2*)(g.outb + (size_t)tok * DM + n0);
;               if (g.epi != EPI_BR0) {
;                 const uint2 pv = *mp;
;                 v0 += b2f((u16)(pv.x & 0xffff)); v1 += b2f((u16)(pv.x >> 16));
;                 v2 += b2f((u16)(pv.y & 0xffff)); v3 += b2f((u16)(pv.y >> 16));
;               }
.LBB0_1154:
	v_lshl_add_u64 v[28:29], v[138:139], 0, v[0:1]
	v_lshlrev_b64 v[30:31], 1, v[28:29]
	v_lshl_add_u64 v[28:29], v[50:51], 0, v[30:31]
	s_nop 0
	flat_load_dwordx2 v[32:33], v[28:29] offset:64
	v_lshl_add_u64 v[30:31], v[36:37], 0, v[30:31]
	s_waitcnt vmcnt(0) lgkmcnt(0)
	v_lshlrev_b32_e32 v2, 16, v32
	v_mul_f32_e32 v2, 0xbfb8aa3b, v2
	v_exp_f32_e32 v28, v2
	v_and_b32_e32 v2, 0xffff0000, v32
	v_mul_f32_e32 v2, 0xbfb8aa3b, v2
	v_exp_f32_e32 v29, v2
	s_nop 0
	v_pk_add_f32 v[28:29], v[28:29], 1.0 op_sel_hi:[1,0]
	s_nop 0
	v_div_scale_f32 v2, s[2:3], v29, v29, 1.0
	v_rcp_f32_e32 v32, v2
	s_nop 0
	v_fma_f32 v34, -v2, v32, 1.0
	v_fmac_f32_e32 v32, v34, v32
	v_div_scale_f32 v34, vcc, 1.0, v29, 1.0
	v_mul_f32_e32 v35, v34, v32
	v_fma_f32 v54, -v2, v35, v34
	v_fmac_f32_e32 v35, v54, v32
	v_fma_f32 v2, -v2, v35, v34
	v_div_fmas_f32 v2, v2, v32, v35
	v_div_fixup_f32 v29, v2, v29, 1.0
	v_div_scale_f32 v2, s[2:3], v28, v28, 1.0
	v_rcp_f32_e32 v32, v2
	s_nop 0
	v_fma_f32 v34, -v2, v32, 1.0
	v_fmac_f32_e32 v32, v34, v32
	v_div_scale_f32 v34, vcc, 1.0, v28, 1.0
	v_mul_f32_e32 v35, v34, v32
	v_fma_f32 v54, -v2, v35, v34
	v_fmac_f32_e32 v35, v54, v32
	v_fma_f32 v2, -v2, v35, v34
	v_div_fmas_f32 v2, v2, v32, v35
	v_div_fixup_f32 v28, v2, v28, 1.0
	v_lshlrev_b32_e32 v2, 16, v33
	v_mul_f32_e32 v2, 0xbfb8aa3b, v2
	v_exp_f32_e32 v32, v2
	v_and_b32_e32 v2, 0xffff0000, v33
	v_mul_f32_e32 v2, 0xbfb8aa3b, v2
	v_exp_f32_e32 v33, v2
	v_pk_mul_f32 v[28:29], v[24:25], v[28:29]
	v_pk_add_f32 v[32:33], v[32:33], 1.0 op_sel_hi:[1,0]
	s_nop 0
	v_div_scale_f32 v2, s[2:3], v33, v33, 1.0
	v_rcp_f32_e32 v34, v2
	s_nop 0
	v_fma_f32 v35, -v2, v34, 1.0
	v_fmac_f32_e32 v34, v35, v34
	v_div_scale_f32 v35, vcc, 1.0, v33, 1.0
	v_mul_f32_e32 v54, v35, v34
	v_fma_f32 v55, -v2, v54, v35
	v_fmac_f32_e32 v54, v55, v34
	v_fma_f32 v2, -v2, v54, v35
	v_div_fmas_f32 v2, v2, v34, v54
	v_div_fixup_f32 v33, v2, v33, 1.0
	v_div_scale_f32 v2, s[2:3], v32, v32, 1.0
	v_rcp_f32_e32 v34, v2
	s_nop 0
	v_fma_f32 v35, -v2, v34, 1.0
	v_fmac_f32_e32 v34, v35, v34
	v_div_scale_f32 v35, vcc, 1.0, v32, 1.0
	v_mul_f32_e32 v54, v35, v34
	v_fma_f32 v55, -v2, v54, v35
	v_fmac_f32_e32 v54, v55, v34
	v_fma_f32 v2, -v2, v54, v35
	v_div_fmas_f32 v2, v2, v34, v54
	v_div_fixup_f32 v32, v2, v32, 1.0
	v_pk_mul_f32 v[32:33], v[26:27], v[32:33]
	s_and_b64 vcc, exec, s[4:5]
	s_cbranch_vccnz .LBB0_1156
	flat_load_dwordx2 v[34:35], v[30:31] offset:64
	s_waitcnt vmcnt(0) lgkmcnt(0)
	v_lshlrev_b32_e32 v54, 16, v34
	v_and_b32_e32 v55, 0xffff0000, v34
	v_lshlrev_b32_e32 v34, 16, v35
	v_and_b32_e32 v35, 0xffff0000, v35
	v_pk_add_f32 v[28:29], v[28:29], v[54:55]
	v_pk_add_f32 v[32:33], v[32:33], v[34:35]

; __device__ __forceinline__ void gemm_phase(const Ctx& cx, const GemmArgs& g_, char* shm) {
;     ...
;                 const bool r128 = (n0 >= C_DSAQ && n0 < C_HGQ) || (n0 >= C_DSAK && n0 < C_DSAV);
;                 const bool r64 = (n0 >= C_IDXQ && n0 < C_GLAA);
;                 if (r128 || r64) {
;                   float4 cs;
;                   float sc;
;                   if (r128) {
;                     cs = *(const float4*)(g.w + ((size_t)tok * 64 + ((n0 & 127) >> 1)) * 2);
;                     sc = (n0 < C_HGQ) ? 0.08838834764831845f : 1.0f;
;                   } else {
;                     cs = *(const float4*)(g.hout + ((size_t)tok * 32 + ((n0 & 63) >> 1)) * 2);
;                     sc = (n0 < C_IDXK) ? 0.125f : 1.0f;
;                   }
;                   o0 = (a[0] * cs.x - a[1] * cs.y) * sc; o1 = (a[1] * cs.x + a[0] * cs.y) * sc;
;                   o2 = (a[2] * cs.z - a[3] * cs.w) * sc; o3 = (a[3] * cs.z + a[2] * cs.w) * sc;
;                 }
.LBB0_1157:
	s_movk_i32 s0, 0x5c00
	v_cmp_gt_i32_e32 vcc, s0, v161
	s_and_saveexec_b64 s[2:3], vcc
	s_xor_b64 s[2:3], exec, s[2:3]
	s_cbranch_execz .LBB0_1165
	v_add_u32_e32 v2, 0xffffa700, v138
	v_cmp_gt_u32_e32 vcc, s77, v2
	s_or_b64 s[10:11], s[58:59], vcc
	s_and_saveexec_b64 s[8:9], s[10:11]
	s_cbranch_execz .LBB0_1164
	s_and_saveexec_b64 s[10:11], s[56:57]
	s_xor_b64 s[10:11], exec, s[10:11]
	v_lshlrev_b32_e32 v2, 2, v0
	s_movk_i32 s0, 0x5b00
	v_lshl_add_u64 v[28:29], v[48:49], 0, v[2:3]
	v_cmp_gt_u32_e32 vcc, s0, v138
	v_lshl_add_u64 v[28:29], v[28:29], 0, s[70:71]
	s_nop 0
	v_cndmask_b32_e32 v2, 1.0, v166, vcc
	s_andn2_saveexec_b64 s[10:11], s[10:11]
	v_and_b32_e32 v2, 0x6c, v161
	v_cmp_gt_i32_e32 vcc, s81, v161
	v_lshlrev_b32_e32 v2, 2, v2
	v_lshl_add_u64 v[28:29], v[44:45], 0, v[2:3]
	v_cndmask_b32_e32 v2, 1.0, v167, vcc
	s_or_b64 exec, exec, s[10:11]
	s_nop 0
	flat_load_dwordx4 v[28:31], v[28:29]
	s_waitcnt vmcnt(0) lgkmcnt(0)
	v_pk_mul_f32 v[32:33], v[24:25], v[28:29] op_sel:[1,1] op_sel_hi:[1,0]
	s_nop 0
	v_pk_fma_f32 v[34:35], v[24:25], v[28:29], v[32:33] neg_lo:[0,0,1] neg_hi:[0,0,1]
	v_pk_fma_f32 v[24:25], v[24:25], v[28:29], v[32:33] op_sel_hi:[0,1,1]
	v_mov_b32_e32 v28, v27
	v_pk_mul_f32 v[28:29], v[28:29], v[30:31] op_sel:[0,1] op_sel_hi:[0,0]
	v_pk_fma_f32 v[32:33], v[26:27], v[30:31], v[28:29] neg_lo:[0,0,1] neg_hi:[0,0,1]
	v_pk_fma_f32 v[26:27], v[26:27], v[30:31], v[28:29] op_sel_hi:[0,1,1]
	v_mov_b32_e32 v35, v25
	v_mov_b32_e32 v33, v27
	v_pk_mul_f32 v[24:25], v[2:3], v[34:35] op_sel_hi:[0,1]
	v_pk_mul_f32 v[26:27], v[2:3], v[32:33] op_sel_hi:[0,1]

; __device__ __forceinline__ void gemm_phase(const Ctx& cx, const GemmArgs& g_, char* shm) {
;     ...
;               if (n0 >= C_GLAX) {
;                 const int i = n0 - C_GLAX;
;                 const float4 b4 = *(const float4*)(g.hin + i);
;                 float xs[4] = {a[0] + b4.x, a[1] + b4.y, a[2] + b4.z, a[3] + b4.w};
; #pragma unroll
;                 for (int j = 0; j < 4; ++j)
;                   xs[j] = (fminf(xs[j], 0.f) - __logf(1.0f + __expf(-fabsf(xs[j])))) * (1.0f / 16.0f);
;                 *(float4*)(g.f32buf + (size_t)tok * 1024 + i) = make_float4(xs[0], xs[1], xs[2], xs[3]);
.LBB0_1165:
	s_andn2_saveexec_b64 s[2:3], s[2:3]
	s_cbranch_execz .LBB0_1167
	v_add_u32_e32 v2, 0xffffa400, v161
	v_lshlrev_b64 v[32:33], 2, v[2:3]
	v_lshl_add_u64 v[28:29], s[26:27], 0, v[32:33]
	s_nop 0
	flat_load_dwordx4 v[28:31], v[28:29]
	s_mov_b32 s0, 0x3d800000
	v_lshl_add_u64 v[32:33], v[38:39], 0, v[32:33]
	s_waitcnt vmcnt(0) lgkmcnt(0)
	v_add_f32_e32 v2, v24, v28
	v_min_f32_e32 v24, 0, v2
	v_mul_f32_e64 v2, |v2|, s82
	v_exp_f32_e32 v2, v2
	v_add_f32_e32 v28, v25, v29
	v_add_f32_e32 v29, v26, v30
	v_add_f32_e32 v31, v27, v31
	v_add_f32_e32 v2, 1.0, v2
	v_cmp_gt_f32_e32 vcc, s83, v2
	s_nop 1
	v_cndmask_b32_e64 v25, 0, 32, vcc
	v_ldexp_f32 v2, v2, v25
	v_log_f32_e32 v2, v2
	s_nop 0
	v_mul_f32_e32 v25, 0x3f317217, v2
	v_fma_f32 v25, v2, s86, -v25
	v_fmac_f32_e32 v25, 0x3377d1cf, v2
	v_fmac_f32_e32 v25, 0x3f317217, v2
	v_cmp_lt_f32_e64 s[8:9], |v2|, s87
	s_nop 1
	v_cndmask_b32_e64 v2, v2, v25, s[8:9]
	v_cndmask_b32_e32 v25, 0, v165, vcc
	v_sub_f32_e32 v26, v2, v25
	v_mul_f32_e64 v2, |v28|, s82
	v_exp_f32_e32 v2, v2
	v_min_f32_e32 v25, 0, v28
	v_min_f32_e32 v28, 0, v29
	v_add_f32_e32 v2, 1.0, v2
	v_cmp_gt_f32_e32 vcc, s83, v2
	s_nop 1
	v_cndmask_b32_e64 v27, 0, 32, vcc
	v_ldexp_f32 v2, v2, v27
	v_log_f32_e32 v2, v2
	s_nop 0
	v_mul_f32_e32 v27, 0x3f317217, v2
	v_fma_f32 v27, v2, s86, -v27
	v_fmac_f32_e32 v27, 0x3377d1cf, v2
	v_fmac_f32_e32 v27, 0x3f317217, v2
	v_cmp_lt_f32_e64 s[8:9], |v2|, s87
	s_nop 1
	v_cndmask_b32_e64 v2, v2, v27, s[8:9]
	v_cndmask_b32_e32 v27, 0, v165, vcc
	v_sub_f32_e32 v27, v2, v27
	v_mul_f32_e64 v2, |v29|, s82
	v_exp_f32_e32 v2, v2
	v_pk_add_f32 v[24:25], v[24:25], v[26:27] neg_lo:[0,1] neg_hi:[0,1]
	v_add_f32_e32 v2, 1.0, v2
	v_cmp_gt_f32_e32 vcc, s83, v2
	v_pk_mul_f32 v[24:25], v[24:25], s[0:1] op_sel_hi:[1,0]
	s_nop 0
	v_cndmask_b32_e64 v29, 0, 32, vcc
	v_ldexp_f32 v2, v2, v29
	v_log_f32_e32 v2, v2
	s_nop 0
	v_mul_f32_e32 v29, 0x3f317217, v2
	v_fma_f32 v29, v2, s86, -v29
	v_fmac_f32_e32 v29, 0x3377d1cf, v2
	v_fmac_f32_e32 v29, 0x3f317217, v2
	v_cmp_lt_f32_e64 s[8:9], |v2|, s87
	s_nop 1
	v_cndmask_b32_e64 v2, v2, v29, s[8:9]
	v_cndmask_b32_e32 v29, 0, v165, vcc
	v_sub_f32_e32 v30, v2, v29
	v_mul_f32_e64 v2, |v31|, s82
	v_exp_f32_e32 v2, v2
	v_min_f32_e32 v29, 0, v31
	v_add_f32_e32 v2, 1.0, v2
	v_cmp_gt_f32_e32 vcc, s83, v2
	s_nop 1
	v_cndmask_b32_e64 v31, 0, 32, vcc
	v_ldexp_f32 v2, v2, v31
	v_log_f32_e32 v2, v2
	s_nop 0
	v_mul_f32_e32 v31, 0x3f317217, v2
	v_fma_f32 v31, v2, s86, -v31
	v_fmac_f32_e32 v31, 0x3377d1cf, v2
	v_fmac_f32_e32 v31, 0x3f317217, v2
	v_cmp_lt_f32_e64 s[8:9], |v2|, s87
	s_nop 1
	v_cndmask_b32_e64 v2, v2, v31, s[8:9]
	v_cndmask_b32_e32 v31, 0, v165, vcc
	v_sub_f32_e32 v31, v2, v31
	v_pk_add_f32 v[26:27], v[28:29], v[30:31] neg_lo:[0,1] neg_hi:[0,1]
	v_mov_b32_e32 v29, v47
	v_pk_mul_f32 v[26:27], v[26:27], s[0:1] op_sel_hi:[1,0]
	v_mov_b32_e32 v28, v56
	flat_store_dwordx4 v[32:33], v[24:27]

; __device__ __forceinline__ void gemm_phase(const Ctx& cx, const GemmArgs& g_, char* shm) {
;     ...
;             } else if (g.epi == EPI_RELU2) {
;               float r0 = fmaxf(a[0], 0.f), r1 = fmaxf(a[1], 0.f), r2 = fmaxf(a[2], 0.f), r3 = fmaxf(a[3], 0.f);
;               uint2 o; o.x = pack2(r0 * r0, r1 * r1); o.y = pack2(r2 * r2, r3 * r3);
;               EMIT_BF16(g.ldo, o);
.LBB0_1178:
	s_cmp_gt_i32 s38, 4
	s_cbranch_scc0 .LBB0_1182
	s_cmp_eq_u32 s38, 5
	s_mov_b64 s[8:9], -1
	s_cbranch_scc0 .LBB0_1181
	v_max_f32_e32 v2, v22, v22
	v_max_f32_e32 v24, 0, v2
	v_max_f32_e32 v2, v23, v23
	v_max_f32_e32 v25, 0, v2
	v_pk_mul_f32 v[24:25], v[24:25], v[24:25]
	v_max_f32_e32 v2, v20, v20
	v_cvt_pk_bf16_f32 v27, v24, v25
	v_max_f32_e32 v24, 0, v2
	v_max_f32_e32 v2, v21, v21
	v_max_f32_e32 v25, 0, v2
	v_pk_mul_f32 v[24:25], v[24:25], v[24:25]
	v_ashrrev_i32_e32 v133, 31, v132
	v_cvt_pk_bf16_f32 v26, v24, v25
	v_mov_b32_e32 v24, v28
	v_mov_b32_e32 v25, v29
	s_nop 0
	v_permlane16_swap_b32_e32 v24, v26
	v_permlane16_swap_b32_e32 v25, v27
	v_lshl_add_u64 v[30:31], v[132:133], 1, v[52:53]
	s_nop 0
	flat_store_dwordx4 v[30:31], v[24:27] offset:96
	s_mov_b64 s[8:9], 0

; __device__ __forceinline__ void gemm_phase(const Ctx& cx, const GemmArgs& g_, char* shm) {
;     ...
;             } else if (g.epi == EPI_RES) {
;               const float4 hv = *(const float4*)(g.hin + (size_t)tok * DM + n0);
;               const float h0 = hv.x + a[0], h1 = hv.y + a[1], h2 = hv.z + a[2], h3 = hv.w + a[3];
;               *(float4*)(g.hout + (size_t)tok * DM + n0) = make_float4(h0, h1, h2, h3);
;               if (g.w != nullptr) {
;                 const float4 nw = *(const float4*)(g.w + n0);
;                 uint2 o; o.x = pack2(h0 * nw.x, h1 * nw.y); o.y = pack2(h2 * nw.z, h3 * nw.w);
;                 EMIT_BF16(DM, o);
;                 ssq += h0 * h0 + h1 * h1 + h2 * h2 + h3 * h3;
;               }
.LBB0_1182:
	s_and_b64 vcc, exec, s[10:11]
	v_mov_b32_e32 v32, v54
	s_cbranch_vccz .LBB0_1185
	v_lshl_add_u64 v[30:31], v[138:139], 0, v[0:1]
	v_lshlrev_b64 v[32:33], 2, v[30:31]
	v_lshl_add_u64 v[24:25], v[42:43], 0, v[32:33]
	s_nop 0
	flat_load_dwordx4 v[24:27], v[24:25] offset:192
	v_lshl_add_u64 v[32:33], v[40:41], 0, v[32:33]
	s_andn2_b64 vcc, exec, s[42:43]
	s_waitcnt vmcnt(0) lgkmcnt(0)
	v_pk_add_f32 v[24:25], v[20:21], v[24:25]
	v_pk_add_f32 v[26:27], v[22:23], v[26:27]
	flat_store_dwordx4 v[32:33], v[24:27] offset:192
	v_mov_b32_e32 v32, v54
	s_cbranch_vccnz .LBB0_1185
	v_lshl_add_u64 v[30:31], v[30:31], 2, s[30:31]
	global_load_dwordx4 v[30:33], v[30:31], off offset:192
	v_ashrrev_i32_e32 v133, 31, v132
	v_lshl_add_u64 v[34:35], v[132:133], 1, v[36:37]
	s_waitcnt vmcnt(0)
	v_pk_mul_f32 v[30:31], v[24:25], v[30:31]
	v_pk_mul_f32 v[24:25], v[24:25], v[24:25]
	v_pk_mul_f32 v[32:33], v[26:27], v[32:33]
	v_pk_mul_f32 v[26:27], v[26:27], v[26:27]
	v_add_f32_e32 v2, v24, v25
	v_cvt_pk_bf16_f32 v33, v32, v33
	v_cvt_pk_bf16_f32 v32, v30, v31
	v_mov_b32_e32 v30, v28
	v_mov_b32_e32 v31, v29
	v_add_f32_e32 v2, v2, v26
	v_permlane16_swap_b32_e32 v30, v32
	v_permlane16_swap_b32_e32 v31, v33
	v_add_f32_e32 v2, v2, v27
	flat_store_dwordx4 v[34:35], v[30:33] offset:96
	s_nop 1
	v_add_f32_e32 v32, v54, v2

; __device__ __forceinline__ float b2f(u16 b) { return __uint_as_float(((uint32_t)b) << 16); }
; __device__ __forceinline__ float sigmoidf_(float x) { return 1.0f / (1.0f + __expf(-x)); }
; __device__ __forceinline__ void gemm_phase(const Ctx& cx, const GemmArgs& g_, char* shm) {
;     ...
;               const uint2 gv = *(const uint2*)(g.gate + (size_t)tok * NP + n0);
;               float v0 = sigmoidf_(b2f((u16)(gv.x & 0xffff))) * a[0], v1 = sigmoidf_(b2f((u16)(gv.x >> 16))) * a[1];
;               float v2 = sigmoidf_(b2f((u16)(gv.y & 0xffff))) * a[2], v3 = sigmoidf_(b2f((u16)(gv.y >> 16))) * a[3];
;               uint2* mp = (uint2*)(g.outb + (size_t)tok * DM + n0);
;               if (g.epi != EPI_BR0) {
;                 const uint2 pv = *mp;
;                 v0 += b2f((u16)(pv.x & 0xffff)); v1 += b2f((u16)(pv.x >> 16));
;                 v2 += b2f((u16)(pv.y & 0xffff)); v3 += b2f((u16)(pv.y >> 16));
;               }
.LBB0_1187:
	v_lshl_add_u64 v[24:25], v[138:139], 0, v[0:1]
	v_lshlrev_b64 v[26:27], 1, v[24:25]
	v_lshl_add_u64 v[24:25], v[50:51], 0, v[26:27]
	s_nop 0
	flat_load_dwordx2 v[30:31], v[24:25] offset:96
	v_lshl_add_u64 v[26:27], v[36:37], 0, v[26:27]
	s_waitcnt vmcnt(0) lgkmcnt(0)
	v_lshlrev_b32_e32 v2, 16, v30
	v_mul_f32_e32 v2, 0xbfb8aa3b, v2
	v_exp_f32_e32 v24, v2
	v_and_b32_e32 v2, 0xffff0000, v30
	v_mul_f32_e32 v2, 0xbfb8aa3b, v2
	v_exp_f32_e32 v25, v2
	s_nop 0
	v_pk_add_f32 v[24:25], v[24:25], 1.0 op_sel_hi:[1,0]
	s_nop 0
	v_div_scale_f32 v2, s[2:3], v25, v25, 1.0
	v_rcp_f32_e32 v30, v2
	s_nop 0
	v_fma_f32 v32, -v2, v30, 1.0
	v_fmac_f32_e32 v30, v32, v30
	v_div_scale_f32 v32, vcc, 1.0, v25, 1.0
	v_mul_f32_e32 v33, v32, v30
	v_fma_f32 v34, -v2, v33, v32
	v_fmac_f32_e32 v33, v34, v30
	v_fma_f32 v2, -v2, v33, v32
	v_div_fmas_f32 v2, v2, v30, v33
	v_div_fixup_f32 v25, v2, v25, 1.0
	v_div_scale_f32 v2, s[2:3], v24, v24, 1.0
	v_rcp_f32_e32 v30, v2
	s_nop 0
	v_fma_f32 v32, -v2, v30, 1.0
	v_fmac_f32_e32 v30, v32, v30
	v_div_scale_f32 v32, vcc, 1.0, v24, 1.0
	v_mul_f32_e32 v33, v32, v30
	v_fma_f32 v34, -v2, v33, v32
	v_fmac_f32_e32 v33, v34, v30
	v_fma_f32 v2, -v2, v33, v32
	v_div_fmas_f32 v2, v2, v30, v33
	v_div_fixup_f32 v24, v2, v24, 1.0
	v_lshlrev_b32_e32 v2, 16, v31
	v_mul_f32_e32 v2, 0xbfb8aa3b, v2
	v_exp_f32_e32 v30, v2
	v_and_b32_e32 v2, 0xffff0000, v31
	v_mul_f32_e32 v2, 0xbfb8aa3b, v2
	v_exp_f32_e32 v31, v2
	v_pk_mul_f32 v[24:25], v[20:21], v[24:25]
	v_pk_add_f32 v[30:31], v[30:31], 1.0 op_sel_hi:[1,0]
	s_nop 0
	v_div_scale_f32 v2, s[2:3], v31, v31, 1.0
	v_rcp_f32_e32 v32, v2
	s_nop 0
	v_fma_f32 v33, -v2, v32, 1.0
	v_fmac_f32_e32 v32, v33, v32
	v_div_scale_f32 v33, vcc, 1.0, v31, 1.0
	v_mul_f32_e32 v34, v33, v32
	v_fma_f32 v35, -v2, v34, v33
	v_fmac_f32_e32 v34, v35, v32
	v_fma_f32 v2, -v2, v34, v33
	v_div_fmas_f32 v2, v2, v32, v34
	v_div_fixup_f32 v31, v2, v31, 1.0
	v_div_scale_f32 v2, s[2:3], v30, v30, 1.0
	v_rcp_f32_e32 v32, v2
	s_nop 0
	v_fma_f32 v33, -v2, v32, 1.0
	v_fmac_f32_e32 v32, v33, v32
	v_div_scale_f32 v33, vcc, 1.0, v30, 1.0
	v_mul_f32_e32 v34, v33, v32
	v_fma_f32 v35, -v2, v34, v33
	v_fmac_f32_e32 v34, v35, v32
	v_fma_f32 v2, -v2, v34, v33
	v_div_fmas_f32 v2, v2, v32, v34
	v_div_fixup_f32 v30, v2, v30, 1.0
	v_pk_mul_f32 v[30:31], v[22:23], v[30:31]
	s_and_b64 vcc, exec, s[4:5]
	s_cbranch_vccnz .LBB0_1189
	flat_load_dwordx2 v[32:33], v[26:27] offset:96
	s_waitcnt vmcnt(0) lgkmcnt(0)
	v_lshlrev_b32_e32 v34, 16, v32
	v_and_b32_e32 v35, 0xffff0000, v32
	v_lshlrev_b32_e32 v32, 16, v33
	v_and_b32_e32 v33, 0xffff0000, v33
	v_pk_add_f32 v[24:25], v[24:25], v[34:35]
	v_pk_add_f32 v[30:31], v[30:31], v[32:33]

; __device__ __forceinline__ void gemm_phase(const Ctx& cx, const GemmArgs& g_, char* shm) {
;     ...
;               if (n0 >= C_GLAX) {
;                 const int i = n0 - C_GLAX;
;                 const float4 b4 = *(const float4*)(g.hin + i);
;                 float xs[4] = {a[0] + b4.x, a[1] + b4.y, a[2] + b4.z, a[3] + b4.w};
; #pragma unroll
;                 for (int j = 0; j < 4; ++j)
;                   xs[j] = (fminf(xs[j], 0.f) - __logf(1.0f + __expf(-fabsf(xs[j])))) * (1.0f / 16.0f);
;                 *(float4*)(g.f32buf + (size_t)tok * 1024 + i) = make_float4(xs[0], xs[1], xs[2], xs[3]);
;               } else {
;                 float o0 = a[0], o1 = a[1], o2 = a[2], o3 = a[3];
;                 const bool r128 = (n0 >= C_DSAQ && n0 < C_HGQ) || (n0 >= C_DSAK && n0 < C_DSAV);
;                 const bool r64 = (n0 >= C_IDXQ && n0 < C_GLAA);
;                 if (r128 || r64) {
;                   float4 cs;
;                   float sc;
;                   if (r128) {
;                     cs = *(const float4*)(g.w + ((size_t)tok * 64 + ((n0 & 127) >> 1)) * 2);
;                     sc = (n0 < C_HGQ) ? 0.08838834764831845f : 1.0f;
;                   } else {
;                     cs = *(const float4*)(g.hout + ((size_t)tok * 32 + ((n0 & 63) >> 1)) * 2);
;                     sc = (n0 < C_IDXK) ? 0.125f : 1.0f;
;                   }
;                   o0 = (a[0] * cs.x - a[1] * cs.y) * sc; o1 = (a[1] * cs.x + a[0] * cs.y) * sc;
;                   o2 = (a[2] * cs.z - a[3] * cs.w) * sc; o3 = (a[3] * cs.z + a[2] * cs.w) * sc;
;                 }
;                 uint2 o; o.x = pack2(o0, o1); o.y = pack2(o2, o3);
;                 EMIT_BF16(g.ldo, o);
.LBB0_1190:
	s_movk_i32 s0, 0x5c00
	v_cmp_gt_i32_e32 vcc, s0, v176
	s_and_saveexec_b64 s[2:3], vcc
	s_xor_b64 s[2:3], exec, s[2:3]
	s_cbranch_execz .LBB0_1198
	v_add_u32_e32 v2, 0xffffa700, v138
	v_cmp_gt_u32_e32 vcc, s77, v2
	s_or_b64 s[10:11], s[58:59], vcc
	s_and_saveexec_b64 s[8:9], s[10:11]
	s_cbranch_execz .LBB0_1197
	s_and_saveexec_b64 s[10:11], s[56:57]
	s_xor_b64 s[10:11], exec, s[10:11]
	v_lshlrev_b32_e32 v2, 2, v0
	s_movk_i32 s0, 0x5b00
	v_lshl_add_u64 v[24:25], v[48:49], 0, v[2:3]
	s_mov_b64 s[56:57], 0xc0
	v_cmp_gt_u32_e32 vcc, s0, v138
	v_lshl_add_u64 v[24:25], v[24:25], 0, s[56:57]
	s_nop 0
	v_cndmask_b32_e32 v2, 1.0, v166, vcc
	s_andn2_saveexec_b64 s[10:11], s[10:11]
	v_and_b32_e32 v2, 0x7c, v176
	v_cmp_gt_i32_e32 vcc, s81, v176
	v_lshlrev_b32_e32 v2, 2, v2
	v_lshl_add_u64 v[24:25], v[44:45], 0, v[2:3]
	v_cndmask_b32_e32 v2, 1.0, v167, vcc
	s_or_b64 exec, exec, s[10:11]
	s_nop 0
	flat_load_dwordx4 v[24:27], v[24:25]
	s_waitcnt vmcnt(0) lgkmcnt(0)
	v_pk_mul_f32 v[30:31], v[20:21], v[24:25] op_sel:[1,1] op_sel_hi:[1,0]
	s_nop 0
	v_pk_fma_f32 v[32:33], v[20:21], v[24:25], v[30:31] neg_lo:[0,0,1] neg_hi:[0,0,1]
	v_pk_fma_f32 v[20:21], v[20:21], v[24:25], v[30:31] op_sel_hi:[0,1,1]
	v_mov_b32_e32 v24, v23
	v_pk_mul_f32 v[24:25], v[24:25], v[26:27] op_sel:[0,1] op_sel_hi:[0,0]
	v_pk_fma_f32 v[30:31], v[22:23], v[26:27], v[24:25] neg_lo:[0,0,1] neg_hi:[0,0,1]
	v_pk_fma_f32 v[22:23], v[22:23], v[26:27], v[24:25] op_sel_hi:[0,1,1]
	v_mov_b32_e32 v33, v21
	v_mov_b32_e32 v31, v23
	v_pk_mul_f32 v[20:21], v[2:3], v[32:33] op_sel_hi:[0,1]
	v_pk_mul_f32 v[22:23], v[2:3], v[30:31] op_sel_hi:[0,1]
.LBB0_1197:
	s_or_b64 exec, exec, s[8:9]
	v_cvt_pk_bf16_f32 v2, v22, v23
	v_cvt_pk_bf16_f32 v22, v20, v21
	s_nop 1
	v_permlane16_swap_b32_e32 v28, v22
	v_permlane16_swap_b32_e32 v29, v2
	v_ashrrev_i32_e32 v133, 31, v132
	v_lshl_add_u64 v[20:21], v[132:133], 1, v[52:53]
	v_mov_b32_e32 v30, v22
	v_mov_b32_e32 v31, v2
	s_nop 0
	flat_store_dwordx4 v[20:21], v[28:31] offset:96
.LBB0_1198:
	s_andn2_saveexec_b64 s[2:3], s[2:3]
	s_cbranch_execz .LBB0_1200
	v_add_u32_e32 v2, 0xffffa400, v176
	v_lshlrev_b64 v[28:29], 2, v[2:3]
	v_lshl_add_u64 v[24:25], s[26:27], 0, v[28:29]
	s_nop 0
	flat_load_dwordx4 v[24:27], v[24:25]
	s_mov_b32 s0, 0x3d800000
	v_lshl_add_u64 v[28:29], v[38:39], 0, v[28:29]
	s_waitcnt vmcnt(0) lgkmcnt(0)
	v_add_f32_e32 v2, v20, v24
	v_min_f32_e32 v20, 0, v2
	v_mul_f32_e64 v2, |v2|, s82
	v_exp_f32_e32 v2, v2
	v_add_f32_e32 v24, v21, v25
	v_add_f32_e32 v25, v22, v26
	v_add_f32_e32 v27, v23, v27
	v_add_f32_e32 v2, 1.0, v2
	v_cmp_gt_f32_e32 vcc, s83, v2
	s_nop 1
	v_cndmask_b32_e64 v21, 0, 32, vcc
	v_ldexp_f32 v2, v2, v21
	v_log_f32_e32 v2, v2
	s_nop 0
	v_mul_f32_e32 v21, 0x3f317217, v2
	v_fma_f32 v21, v2, s86, -v21
	v_fmac_f32_e32 v21, 0x3377d1cf, v2
	v_fmac_f32_e32 v21, 0x3f317217, v2
	v_cmp_lt_f32_e64 s[8:9], |v2|, s87
	s_nop 1
	v_cndmask_b32_e64 v2, v2, v21, s[8:9]
	v_cndmask_b32_e32 v21, 0, v165, vcc
	v_sub_f32_e32 v22, v2, v21
	v_mul_f32_e64 v2, |v24|, s82
	v_exp_f32_e32 v2, v2
	v_min_f32_e32 v21, 0, v24
	v_min_f32_e32 v24, 0, v25
	v_add_f32_e32 v2, 1.0, v2
	v_cmp_gt_f32_e32 vcc, s83, v2
	s_nop 1
	v_cndmask_b32_e64 v23, 0, 32, vcc
	v_ldexp_f32 v2, v2, v23
	v_log_f32_e32 v2, v2
	s_nop 0
	v_mul_f32_e32 v23, 0x3f317217, v2
	v_fma_f32 v23, v2, s86, -v23
	v_fmac_f32_e32 v23, 0x3377d1cf, v2
	v_fmac_f32_e32 v23, 0x3f317217, v2
	v_cmp_lt_f32_e64 s[8:9], |v2|, s87
	s_nop 1
	v_cndmask_b32_e64 v2, v2, v23, s[8:9]
	v_cndmask_b32_e32 v23, 0, v165, vcc
	v_sub_f32_e32 v23, v2, v23
	v_mul_f32_e64 v2, |v25|, s82
	v_exp_f32_e32 v2, v2
	v_pk_add_f32 v[20:21], v[20:21], v[22:23] neg_lo:[0,1] neg_hi:[0,1]
	v_add_f32_e32 v2, 1.0, v2
	v_cmp_gt_f32_e32 vcc, s83, v2
	v_pk_mul_f32 v[20:21], v[20:21], s[0:1] op_sel_hi:[1,0]
	s_nop 0
	v_cndmask_b32_e64 v25, 0, 32, vcc
	v_ldexp_f32 v2, v2, v25
	v_log_f32_e32 v2, v2
	s_nop 0
	v_mul_f32_e32 v25, 0x3f317217, v2
	v_fma_f32 v25, v2, s86, -v25
	v_fmac_f32_e32 v25, 0x3377d1cf, v2
	v_fmac_f32_e32 v25, 0x3f317217, v2
	v_cmp_lt_f32_e64 s[8:9], |v2|, s87
	s_nop 1
	v_cndmask_b32_e64 v2, v2, v25, s[8:9]
	v_cndmask_b32_e32 v25, 0, v165, vcc
	v_sub_f32_e32 v26, v2, v25
	v_mul_f32_e64 v2, |v27|, s82
	v_exp_f32_e32 v2, v2
	v_min_f32_e32 v25, 0, v27
	v_add_f32_e32 v2, 1.0, v2
	v_cmp_gt_f32_e32 vcc, s83, v2
	s_nop 1
	v_cndmask_b32_e64 v27, 0, 32, vcc
	v_ldexp_f32 v2, v2, v27
	v_log_f32_e32 v2, v2
	s_nop 0
	v_mul_f32_e32 v27, 0x3f317217, v2
	v_fma_f32 v27, v2, s86, -v27
	v_fmac_f32_e32 v27, 0x3377d1cf, v2
	v_fmac_f32_e32 v27, 0x3f317217, v2
	v_cmp_lt_f32_e64 s[8:9], |v2|, s87
	s_nop 1
	v_cndmask_b32_e64 v2, v2, v27, s[8:9]
	v_cndmask_b32_e32 v27, 0, v165, vcc
	v_sub_f32_e32 v27, v2, v27
	v_pk_add_f32 v[22:23], v[24:25], v[26:27] neg_lo:[0,1] neg_hi:[0,1]
	s_nop 0
	v_pk_mul_f32 v[22:23], v[22:23], s[0:1] op_sel_hi:[1,0]
	flat_store_dwordx4 v[28:29], v[20:23]

; __device__ __forceinline__ void gemm_phase(const Ctx& cx, const GemmArgs& g_, char* shm) {
;     ...
;             } else if (g.epi == EPI_RES) {
;               const float4 hv = *(const float4*)(g.hin + (size_t)tok * DM + n0);
;               const float h0 = hv.x + a[0], h1 = hv.y + a[1], h2 = hv.z + a[2], h3 = hv.w + a[3];
;               *(float4*)(g.hout + (size_t)tok * DM + n0) = make_float4(h0, h1, h2, h3);
;               if (g.w != nullptr) {
;                 const float4 nw = *(const float4*)(g.w + n0);
;                 uint2 o; o.x = pack2(h0 * nw.x, h1 * nw.y); o.y = pack2(h2 * nw.z, h3 * nw.w);
;                 EMIT_BF16(DM, o);
;                 ssq += h0 * h0 + h1 * h1 + h2 * h2 + h3 * h3;
;               }
.LBB0_1215:
	s_and_b64 vcc, exec, s[10:11]
	v_mov_b32_e32 v23, v32
	s_cbranch_vccz .LBB0_1218
	v_lshlrev_b64 v[24:25], 2, v[122:123]
	v_lshl_add_u64 v[20:21], v[42:43], 0, v[24:25]
	s_nop 0
	flat_load_dwordx4 v[20:23], v[20:21]
	v_lshl_add_u64 v[24:25], v[40:41], 0, v[24:25]
	s_andn2_b64 vcc, exec, s[42:43]
	s_waitcnt vmcnt(0) lgkmcnt(0)
	v_pk_add_f32 v[20:21], v[16:17], v[20:21]
	v_pk_add_f32 v[22:23], v[18:19], v[22:23]
	flat_store_dwordx4 v[24:25], v[20:23]
	s_cbranch_vccnz .LBB0_1334
	v_lshl_add_u64 v[24:25], v[122:123], 2, s[30:31]
	global_load_dwordx4 v[24:27], v[24:25], off
	s_waitcnt vmcnt(0)
	v_pk_mul_f32 v[24:25], v[20:21], v[24:25]
	v_pk_mul_f32 v[20:21], v[20:21], v[20:21]
	v_pk_mul_f32 v[26:27], v[22:23], v[26:27]
	v_pk_mul_f32 v[22:23], v[22:23], v[22:23]
	v_add_f32_e32 v2, v20, v21
	v_add_f32_e32 v2, v2, v22
	v_add_f32_e32 v2, v2, v23
	v_cvt_pk_bf16_f32 v26, v26, v27
	v_cvt_pk_bf16_f32 v24, v24, v25
	v_add_f32_e32 v23, v32, v2

; __device__ __forceinline__ float b2f(u16 b) { return __uint_as_float(((uint32_t)b) << 16); }
; __device__ __forceinline__ float sigmoidf_(float x) { return 1.0f / (1.0f + __expf(-x)); }
; __device__ __forceinline__ void gemm_phase(const Ctx& cx, const GemmArgs& g_, char* shm) {
;     ...
;               const uint2 gv = *(const uint2*)(g.gate + (size_t)tok * NP + n0);
;               float v0 = sigmoidf_(b2f((u16)(gv.x & 0xffff))) * a[0], v1 = sigmoidf_(b2f((u16)(gv.x >> 16))) * a[1];
;               float v2 = sigmoidf_(b2f((u16)(gv.y & 0xffff))) * a[2], v3 = sigmoidf_(b2f((u16)(gv.y >> 16))) * a[3];
;               uint2* mp = (uint2*)(g.outb + (size_t)tok * DM + n0);
;               if (g.epi != EPI_BR0) {
;                 const uint2 pv = *mp;
;                 v0 += b2f((u16)(pv.x & 0xffff)); v1 += b2f((u16)(pv.x >> 16));
;                 v2 += b2f((u16)(pv.y & 0xffff)); v3 += b2f((u16)(pv.y >> 16));
;               }
.LBB0_1220:
	v_lshlrev_b64 v[22:23], 1, v[122:123]
	v_lshl_add_u64 v[20:21], v[50:51], 0, v[22:23]
	s_nop 0
	flat_load_dwordx2 v[24:25], v[20:21]
	v_lshl_add_u64 v[22:23], v[36:37], 0, v[22:23]
	s_waitcnt vmcnt(0) lgkmcnt(0)
	v_lshlrev_b32_e32 v2, 16, v24
	v_mul_f32_e32 v2, 0xbfb8aa3b, v2
	v_exp_f32_e32 v20, v2
	v_and_b32_e32 v2, 0xffff0000, v24
	v_mul_f32_e32 v2, 0xbfb8aa3b, v2
	v_exp_f32_e32 v21, v2
	s_nop 0
	v_pk_add_f32 v[20:21], v[20:21], 1.0 op_sel_hi:[1,0]
	s_nop 0
	v_div_scale_f32 v2, s[2:3], v21, v21, 1.0
	v_rcp_f32_e32 v24, v2
	s_nop 0
	v_fma_f32 v26, -v2, v24, 1.0
	v_fmac_f32_e32 v24, v26, v24
	v_div_scale_f32 v26, vcc, 1.0, v21, 1.0
	v_mul_f32_e32 v27, v26, v24
	v_fma_f32 v28, -v2, v27, v26
	v_fmac_f32_e32 v27, v28, v24
	v_fma_f32 v2, -v2, v27, v26
	v_div_fmas_f32 v2, v2, v24, v27
	v_div_fixup_f32 v21, v2, v21, 1.0
	v_div_scale_f32 v2, s[2:3], v20, v20, 1.0
	v_rcp_f32_e32 v24, v2
	s_nop 0
	v_fma_f32 v26, -v2, v24, 1.0
	v_fmac_f32_e32 v24, v26, v24
	v_div_scale_f32 v26, vcc, 1.0, v20, 1.0
	v_mul_f32_e32 v27, v26, v24
	v_fma_f32 v28, -v2, v27, v26
	v_fmac_f32_e32 v27, v28, v24
	v_fma_f32 v2, -v2, v27, v26
	v_div_fmas_f32 v2, v2, v24, v27
	v_div_fixup_f32 v20, v2, v20, 1.0
	v_lshlrev_b32_e32 v2, 16, v25
	v_mul_f32_e32 v2, 0xbfb8aa3b, v2
	v_exp_f32_e32 v24, v2
	v_and_b32_e32 v2, 0xffff0000, v25
	v_mul_f32_e32 v2, 0xbfb8aa3b, v2
	v_exp_f32_e32 v25, v2
	v_pk_mul_f32 v[20:21], v[16:17], v[20:21]
	v_pk_add_f32 v[24:25], v[24:25], 1.0 op_sel_hi:[1,0]
	s_nop 0
	v_div_scale_f32 v2, s[2:3], v25, v25, 1.0
	v_rcp_f32_e32 v26, v2
	s_nop 0
	v_fma_f32 v27, -v2, v26, 1.0
	v_fmac_f32_e32 v26, v27, v26
	v_div_scale_f32 v27, vcc, 1.0, v25, 1.0
	v_mul_f32_e32 v28, v27, v26
	v_fma_f32 v29, -v2, v28, v27
	v_fmac_f32_e32 v28, v29, v26
	v_fma_f32 v2, -v2, v28, v27
	v_div_fmas_f32 v2, v2, v26, v28
	v_div_fixup_f32 v25, v2, v25, 1.0
	v_div_scale_f32 v2, s[2:3], v24, v24, 1.0
	v_rcp_f32_e32 v26, v2
	s_nop 0
	v_fma_f32 v27, -v2, v26, 1.0
	v_fmac_f32_e32 v26, v27, v26
	v_div_scale_f32 v27, vcc, 1.0, v24, 1.0
	v_mul_f32_e32 v28, v27, v26
	v_fma_f32 v29, -v2, v28, v27
	v_fmac_f32_e32 v28, v29, v26
	v_fma_f32 v2, -v2, v28, v27
	v_div_fmas_f32 v2, v2, v26, v28
	v_div_fixup_f32 v24, v2, v24, 1.0
	v_pk_mul_f32 v[24:25], v[18:19], v[24:25]
	s_and_b64 vcc, exec, s[4:5]
	s_cbranch_vccnz .LBB0_1222
	flat_load_dwordx2 v[26:27], v[22:23]
	s_waitcnt vmcnt(0) lgkmcnt(0)
	v_lshlrev_b32_e32 v28, 16, v26
	v_and_b32_e32 v29, 0xffff0000, v26
	v_lshlrev_b32_e32 v26, 16, v27
	v_and_b32_e32 v27, 0xffff0000, v27
	v_pk_add_f32 v[20:21], v[20:21], v[28:29]
	v_pk_add_f32 v[24:25], v[24:25], v[26:27]

; __device__ __forceinline__ void gemm_phase(const Ctx& cx, const GemmArgs& g_, char* shm) {
;     ...
;                 const bool r128 = (n0 >= C_DSAQ && n0 < C_HGQ) || (n0 >= C_DSAK && n0 < C_DSAV);
;                 const bool r64 = (n0 >= C_IDXQ && n0 < C_GLAA);
;                 if (r128 || r64) {
;                   float4 cs;
;                   float sc;
;                   if (r128) {
;                     cs = *(const float4*)(g.w + ((size_t)tok * 64 + ((n0 & 127) >> 1)) * 2);
;                     sc = (n0 < C_HGQ) ? 0.08838834764831845f : 1.0f;
;                   } else {
;                     cs = *(const float4*)(g.hout + ((size_t)tok * 32 + ((n0 & 63) >> 1)) * 2);
;                     sc = (n0 < C_IDXK) ? 0.125f : 1.0f;
;                   }
;                   o0 = (a[0] * cs.x - a[1] * cs.y) * sc; o1 = (a[1] * cs.x + a[0] * cs.y) * sc;
;                   o2 = (a[2] * cs.z - a[3] * cs.w) * sc; o3 = (a[3] * cs.z + a[2] * cs.w) * sc;
;                 }
.LBB0_1223:
	s_movk_i32 s0, 0x5c00
	v_cmp_gt_i32_e32 vcc, s0, v122
	s_and_saveexec_b64 s[2:3], vcc
	s_xor_b64 s[2:3], exec, s[2:3]
	s_cbranch_execz .LBB0_1231
	v_add_u32_e32 v2, 0xffffa780, v138
	v_cmp_gt_u32_e32 vcc, s77, v2
	s_or_b64 s[10:11], s[54:55], vcc
	s_and_saveexec_b64 s[8:9], s[10:11]
	s_cbranch_execz .LBB0_1230
	s_and_saveexec_b64 s[10:11], s[52:53]
	s_xor_b64 s[10:11], exec, s[10:11]
	s_movk_i32 s0, 0x5b00
	v_lshlrev_b32_e32 v2, 2, v0
	v_cmp_gt_u32_e32 vcc, s0, v120
	v_lshl_add_u64 v[20:21], v[48:49], 0, v[2:3]
	s_nop 0
	v_cndmask_b32_e32 v2, 1.0, v166, vcc
	s_andn2_saveexec_b64 s[10:11], s[10:11]
	v_and_b32_e32 v2, 0x4c, v122
	v_cmp_gt_i32_e32 vcc, s81, v122
	v_lshlrev_b32_e32 v2, 2, v2
	v_lshl_add_u64 v[20:21], v[44:45], 0, v[2:3]
	v_cndmask_b32_e32 v2, 1.0, v167, vcc
	s_or_b64 exec, exec, s[10:11]
	s_nop 0
	flat_load_dwordx4 v[20:23], v[20:21]
	s_waitcnt vmcnt(0) lgkmcnt(0)
	v_pk_mul_f32 v[24:25], v[16:17], v[20:21] op_sel:[1,1] op_sel_hi:[1,0]
	s_nop 0
	v_pk_fma_f32 v[26:27], v[16:17], v[20:21], v[24:25] neg_lo:[0,0,1] neg_hi:[0,0,1]
	v_pk_fma_f32 v[16:17], v[16:17], v[20:21], v[24:25] op_sel_hi:[0,1,1]
	v_mov_b32_e32 v20, v19
	v_pk_mul_f32 v[20:21], v[20:21], v[22:23] op_sel:[0,1] op_sel_hi:[0,0]
	v_pk_fma_f32 v[24:25], v[18:19], v[22:23], v[20:21] neg_lo:[0,0,1] neg_hi:[0,0,1]
	v_pk_fma_f32 v[18:19], v[18:19], v[22:23], v[20:21] op_sel_hi:[0,1,1]
	v_mov_b32_e32 v27, v17
	v_mov_b32_e32 v25, v19
	v_pk_mul_f32 v[16:17], v[2:3], v[26:27] op_sel_hi:[0,1]
	v_pk_mul_f32 v[18:19], v[2:3], v[24:25] op_sel_hi:[0,1]

; __device__ __forceinline__ void gemm_phase(const Ctx& cx, const GemmArgs& g_, char* shm) {
;     ...
;               if (n0 >= C_GLAX) {
;                 const int i = n0 - C_GLAX;
;                 const float4 b4 = *(const float4*)(g.hin + i);
;                 float xs[4] = {a[0] + b4.x, a[1] + b4.y, a[2] + b4.z, a[3] + b4.w};
; #pragma unroll
;                 for (int j = 0; j < 4; ++j)
;                   xs[j] = (fminf(xs[j], 0.f) - __logf(1.0f + __expf(-fabsf(xs[j])))) * (1.0f / 16.0f);
;                 *(float4*)(g.f32buf + (size_t)tok * 1024 + i) = make_float4(xs[0], xs[1], xs[2], xs[3]);
.LBB0_1231:
	s_andn2_saveexec_b64 s[2:3], s[2:3]
	s_cbranch_execz .LBB0_1233
	v_add_u32_e32 v2, 0xffffa400, v122
	v_lshlrev_b64 v[24:25], 2, v[2:3]
	v_lshl_add_u64 v[20:21], s[26:27], 0, v[24:25]
	s_nop 0
	flat_load_dwordx4 v[20:23], v[20:21]
	s_mov_b32 s0, 0x3d800000
	v_lshl_add_u64 v[24:25], v[38:39], 0, v[24:25]
	v_mov_b32_e32 v26, 0
	s_waitcnt vmcnt(0) lgkmcnt(0)
	v_add_f32_e32 v2, v16, v20
	v_min_f32_e32 v16, 0, v2
	v_mul_f32_e64 v2, |v2|, s82
	v_exp_f32_e32 v2, v2
	v_add_f32_e32 v20, v17, v21
	v_add_f32_e32 v21, v18, v22
	v_add_f32_e32 v23, v19, v23
	v_add_f32_e32 v2, 1.0, v2
	v_cmp_gt_f32_e32 vcc, s83, v2
	s_nop 1
	v_cndmask_b32_e64 v17, 0, 32, vcc
	v_ldexp_f32 v2, v2, v17
	v_log_f32_e32 v2, v2
	s_nop 0
	v_mul_f32_e32 v17, 0x3f317217, v2
	v_fma_f32 v17, v2, s86, -v17
	v_fmac_f32_e32 v17, 0x3377d1cf, v2
	v_fmac_f32_e32 v17, 0x3f317217, v2
	v_cmp_lt_f32_e64 s[8:9], |v2|, s87
	s_nop 1
	v_cndmask_b32_e64 v2, v2, v17, s[8:9]
	v_cndmask_b32_e32 v17, 0, v165, vcc
	v_sub_f32_e32 v18, v2, v17
	v_mul_f32_e64 v2, |v20|, s82
	v_exp_f32_e32 v2, v2
	v_min_f32_e32 v17, 0, v20
	v_min_f32_e32 v20, 0, v21
	v_add_f32_e32 v2, 1.0, v2
	v_cmp_gt_f32_e32 vcc, s83, v2
	s_nop 1
	v_cndmask_b32_e64 v19, 0, 32, vcc
	v_ldexp_f32 v2, v2, v19
	v_log_f32_e32 v2, v2
	s_nop 0
	v_mul_f32_e32 v19, 0x3f317217, v2
	v_fma_f32 v19, v2, s86, -v19
	v_fmac_f32_e32 v19, 0x3377d1cf, v2
	v_fmac_f32_e32 v19, 0x3f317217, v2
	v_cmp_lt_f32_e64 s[8:9], |v2|, s87
	s_nop 1
	v_cndmask_b32_e64 v2, v2, v19, s[8:9]
	v_cndmask_b32_e32 v19, 0, v165, vcc
	v_sub_f32_e32 v19, v2, v19
	v_mul_f32_e64 v2, |v21|, s82
	v_exp_f32_e32 v2, v2
	v_pk_add_f32 v[16:17], v[16:17], v[18:19] neg_lo:[0,1] neg_hi:[0,1]
	v_add_f32_e32 v2, 1.0, v2
	v_cmp_gt_f32_e32 vcc, s83, v2
	v_pk_mul_f32 v[16:17], v[16:17], s[0:1] op_sel_hi:[1,0]
	s_nop 0
	v_cndmask_b32_e64 v21, 0, 32, vcc
	v_ldexp_f32 v2, v2, v21
	v_log_f32_e32 v2, v2
	s_nop 0
	v_mul_f32_e32 v21, 0x3f317217, v2
	v_fma_f32 v21, v2, s86, -v21
	v_fmac_f32_e32 v21, 0x3377d1cf, v2
	v_fmac_f32_e32 v21, 0x3f317217, v2
	v_cmp_lt_f32_e64 s[8:9], |v2|, s87
	s_nop 1
	v_cndmask_b32_e64 v2, v2, v21, s[8:9]
	v_cndmask_b32_e32 v21, 0, v165, vcc
	v_sub_f32_e32 v22, v2, v21
	v_mul_f32_e64 v2, |v23|, s82
	v_exp_f32_e32 v2, v2
	v_min_f32_e32 v21, 0, v23
	v_add_f32_e32 v2, 1.0, v2
	v_cmp_gt_f32_e32 vcc, s83, v2
	s_nop 1
	v_cndmask_b32_e64 v23, 0, 32, vcc
	v_ldexp_f32 v2, v2, v23
	v_log_f32_e32 v2, v2
	s_nop 0
	v_mul_f32_e32 v23, 0x3f317217, v2
	v_fma_f32 v23, v2, s86, -v23
	v_fmac_f32_e32 v23, 0x3377d1cf, v2
	v_fmac_f32_e32 v23, 0x3f317217, v2
	v_cmp_lt_f32_e64 s[8:9], |v2|, s87
	s_nop 1
	v_cndmask_b32_e64 v2, v2, v23, s[8:9]
	v_cndmask_b32_e32 v23, 0, v165, vcc
	v_sub_f32_e32 v23, v2, v23
	v_pk_add_f32 v[18:19], v[20:21], v[22:23] neg_lo:[0,1] neg_hi:[0,1]
	s_nop 0
	v_pk_mul_f32 v[18:19], v[18:19], s[0:1] op_sel_hi:[1,0]
	flat_store_dwordx4 v[24:25], v[16:19]
	v_mov_b32_e32 v24, 0

; __device__ __forceinline__ void gemm_phase(const Ctx& cx, const GemmArgs& g_, char* shm) {
;     ...
;             } else if (g.epi == EPI_RELU2) {
;               float r0 = fmaxf(a[0], 0.f), r1 = fmaxf(a[1], 0.f), r2 = fmaxf(a[2], 0.f), r3 = fmaxf(a[3], 0.f);
;               uint2 o; o.x = pack2(r0 * r0, r1 * r1); o.y = pack2(r2 * r2, r3 * r3);
;               EMIT_BF16(g.ldo, o);
.LBB0_1244:
	s_cmp_gt_i32 s38, 4
	s_cbranch_scc0 .LBB0_1248
	s_cmp_eq_u32 s38, 5
	s_mov_b64 s[8:9], -1
	s_cbranch_scc0 .LBB0_1247
	v_max_f32_e32 v2, v14, v14
	v_max_f32_e32 v16, 0, v2
	v_max_f32_e32 v2, v15, v15
	v_max_f32_e32 v17, 0, v2
	v_pk_mul_f32 v[16:17], v[16:17], v[16:17]
	v_max_f32_e32 v2, v12, v12
	v_cvt_pk_bf16_f32 v19, v16, v17
	v_max_f32_e32 v16, 0, v2
	v_max_f32_e32 v2, v13, v13
	v_max_f32_e32 v17, 0, v2
	v_pk_mul_f32 v[16:17], v[16:17], v[16:17]
	v_ashrrev_i32_e32 v117, 31, v116
	v_cvt_pk_bf16_f32 v18, v16, v17
	v_mov_b32_e32 v16, v24
	v_mov_b32_e32 v17, v26
	s_nop 0
	v_permlane16_swap_b32_e32 v16, v18
	v_permlane16_swap_b32_e32 v17, v19
	v_lshl_add_u64 v[20:21], v[116:117], 1, v[52:53]
	s_nop 0
	flat_store_dwordx4 v[20:21], v[16:19] offset:32
	s_mov_b64 s[8:9], 0

; __device__ __forceinline__ void gemm_phase(const Ctx& cx, const GemmArgs& g_, char* shm) {
;     ...
;             } else if (g.epi == EPI_RES) {
;               const float4 hv = *(const float4*)(g.hin + (size_t)tok * DM + n0);
;               const float h0 = hv.x + a[0], h1 = hv.y + a[1], h2 = hv.z + a[2], h3 = hv.w + a[3];
;               *(float4*)(g.hout + (size_t)tok * DM + n0) = make_float4(h0, h1, h2, h3);
;               if (g.w != nullptr) {
;                 const float4 nw = *(const float4*)(g.w + n0);
;                 uint2 o; o.x = pack2(h0 * nw.x, h1 * nw.y); o.y = pack2(h2 * nw.z, h3 * nw.w);
;                 EMIT_BF16(DM, o);
;                 ssq += h0 * h0 + h1 * h1 + h2 * h2 + h3 * h3;
;               }
.LBB0_1248:
	s_and_b64 vcc, exec, s[10:11]
	v_mov_b32_e32 v22, v23
	s_cbranch_vccz .LBB0_1251
	v_lshl_add_u64 v[20:21], v[120:121], 0, v[0:1]
	v_lshlrev_b64 v[28:29], 2, v[20:21]
	v_lshl_add_u64 v[16:17], v[42:43], 0, v[28:29]
	s_nop 0
	flat_load_dwordx4 v[16:19], v[16:17] offset:64
	v_lshl_add_u64 v[28:29], v[40:41], 0, v[28:29]
	s_andn2_b64 vcc, exec, s[42:43]
	v_mov_b32_e32 v22, v23
	s_waitcnt vmcnt(0) lgkmcnt(0)
	v_pk_add_f32 v[16:17], v[12:13], v[16:17]
	v_pk_add_f32 v[18:19], v[14:15], v[18:19]
	flat_store_dwordx4 v[28:29], v[16:19] offset:64
	s_cbranch_vccnz .LBB0_1251
	v_lshl_add_u64 v[20:21], v[20:21], 2, s[30:31]
	global_load_dwordx4 v[28:31], v[20:21], off offset:64
	v_ashrrev_i32_e32 v117, 31, v116
	s_waitcnt vmcnt(0)
	v_pk_mul_f32 v[20:21], v[18:19], v[30:31]
	s_nop 0
	v_cvt_pk_bf16_f32 v31, v20, v21
	v_pk_mul_f32 v[20:21], v[16:17], v[28:29]
	v_pk_mul_f32 v[16:17], v[16:17], v[16:17]
	v_pk_mul_f32 v[18:19], v[18:19], v[18:19]
	v_add_f32_e32 v2, v16, v17
	v_cvt_pk_bf16_f32 v30, v20, v21
	v_mov_b32_e32 v28, v24
	v_mov_b32_e32 v29, v26
	v_add_f32_e32 v2, v2, v18
	v_permlane16_swap_b32_e32 v28, v30
	v_permlane16_swap_b32_e32 v29, v31
	v_lshl_add_u64 v[20:21], v[116:117], 1, v[36:37]
	v_add_f32_e32 v2, v2, v19
	flat_store_dwordx4 v[20:21], v[28:31] offset:32
	v_add_f32_e32 v22, v23, v2

; __device__ __forceinline__ float b2f(u16 b) { return __uint_as_float(((uint32_t)b) << 16); }
; __device__ __forceinline__ float sigmoidf_(float x) { return 1.0f / (1.0f + __expf(-x)); }
; __device__ __forceinline__ void gemm_phase(const Ctx& cx, const GemmArgs& g_, char* shm) {
;     ...
;               const uint2 gv = *(const uint2*)(g.gate + (size_t)tok * NP + n0);
;               float v0 = sigmoidf_(b2f((u16)(gv.x & 0xffff))) * a[0], v1 = sigmoidf_(b2f((u16)(gv.x >> 16))) * a[1];
;               float v2 = sigmoidf_(b2f((u16)(gv.y & 0xffff))) * a[2], v3 = sigmoidf_(b2f((u16)(gv.y >> 16))) * a[3];
;               uint2* mp = (uint2*)(g.outb + (size_t)tok * DM + n0);
;               if (g.epi != EPI_BR0) {
;                 const uint2 pv = *mp;
;                 v0 += b2f((u16)(pv.x & 0xffff)); v1 += b2f((u16)(pv.x >> 16));
;                 v2 += b2f((u16)(pv.y & 0xffff)); v3 += b2f((u16)(pv.y >> 16));
;               }
.LBB0_1253:
	v_lshl_add_u64 v[16:17], v[120:121], 0, v[0:1]
	v_lshlrev_b64 v[18:19], 1, v[16:17]
	v_lshl_add_u64 v[16:17], v[50:51], 0, v[18:19]
	s_nop 0
	flat_load_dwordx2 v[20:21], v[16:17] offset:32
	v_lshl_add_u64 v[18:19], v[36:37], 0, v[18:19]
	s_waitcnt vmcnt(0) lgkmcnt(0)
	v_lshlrev_b32_e32 v2, 16, v20
	v_mul_f32_e32 v2, 0xbfb8aa3b, v2
	v_exp_f32_e32 v16, v2
	v_and_b32_e32 v2, 0xffff0000, v20
	v_mul_f32_e32 v2, 0xbfb8aa3b, v2
	v_exp_f32_e32 v17, v2
	s_nop 0
	v_pk_add_f32 v[16:17], v[16:17], 1.0 op_sel_hi:[1,0]
	s_nop 0
	v_div_scale_f32 v2, s[2:3], v17, v17, 1.0
	v_rcp_f32_e32 v20, v2
	s_nop 0
	v_fma_f32 v22, -v2, v20, 1.0
	v_fmac_f32_e32 v20, v22, v20
	v_div_scale_f32 v22, vcc, 1.0, v17, 1.0
	v_mul_f32_e32 v25, v22, v20
	v_fma_f32 v27, -v2, v25, v22
	v_fmac_f32_e32 v25, v27, v20
	v_fma_f32 v2, -v2, v25, v22
	v_div_fmas_f32 v2, v2, v20, v25
	v_div_fixup_f32 v17, v2, v17, 1.0
	v_div_scale_f32 v2, s[2:3], v16, v16, 1.0
	v_rcp_f32_e32 v20, v2
	s_nop 0
	v_fma_f32 v22, -v2, v20, 1.0
	v_fmac_f32_e32 v20, v22, v20
	v_div_scale_f32 v22, vcc, 1.0, v16, 1.0
	v_mul_f32_e32 v25, v22, v20
	v_fma_f32 v27, -v2, v25, v22
	v_fmac_f32_e32 v25, v27, v20
	v_fma_f32 v2, -v2, v25, v22
	v_div_fmas_f32 v2, v2, v20, v25
	v_div_fixup_f32 v16, v2, v16, 1.0
	v_lshlrev_b32_e32 v2, 16, v21
	v_mul_f32_e32 v2, 0xbfb8aa3b, v2
	v_exp_f32_e32 v20, v2
	v_and_b32_e32 v2, 0xffff0000, v21
	v_mul_f32_e32 v2, 0xbfb8aa3b, v2
	v_exp_f32_e32 v21, v2
	v_pk_mul_f32 v[16:17], v[12:13], v[16:17]
	v_pk_add_f32 v[20:21], v[20:21], 1.0 op_sel_hi:[1,0]
	s_nop 0
	v_div_scale_f32 v2, s[2:3], v21, v21, 1.0
	v_rcp_f32_e32 v22, v2
	s_nop 0
	v_fma_f32 v25, -v2, v22, 1.0
	v_fmac_f32_e32 v22, v25, v22
	v_div_scale_f32 v25, vcc, 1.0, v21, 1.0
	v_mul_f32_e32 v27, v25, v22
	v_fma_f32 v28, -v2, v27, v25
	v_fmac_f32_e32 v27, v28, v22
	v_fma_f32 v2, -v2, v27, v25
	v_div_fmas_f32 v2, v2, v22, v27
	v_div_fixup_f32 v21, v2, v21, 1.0
	v_div_scale_f32 v2, s[2:3], v20, v20, 1.0
	v_rcp_f32_e32 v22, v2
	s_nop 0
	v_fma_f32 v25, -v2, v22, 1.0
	v_fmac_f32_e32 v22, v25, v22
	v_div_scale_f32 v25, vcc, 1.0, v20, 1.0
	v_mul_f32_e32 v27, v25, v22
	v_fma_f32 v28, -v2, v27, v25
	v_fmac_f32_e32 v27, v28, v22
	v_fma_f32 v2, -v2, v27, v25
	v_div_fmas_f32 v2, v2, v22, v27
	v_div_fixup_f32 v20, v2, v20, 1.0
	v_pk_mul_f32 v[20:21], v[14:15], v[20:21]
	s_and_b64 vcc, exec, s[4:5]
	s_cbranch_vccnz .LBB0_1255
	flat_load_dwordx2 v[28:29], v[18:19] offset:32
	s_waitcnt vmcnt(0) lgkmcnt(0)
	v_lshlrev_b32_e32 v30, 16, v28
	v_and_b32_e32 v31, 0xffff0000, v28
	v_lshlrev_b32_e32 v28, 16, v29
	v_and_b32_e32 v29, 0xffff0000, v29
	v_pk_add_f32 v[16:17], v[16:17], v[30:31]
	v_pk_add_f32 v[20:21], v[20:21], v[28:29]

; __device__ __forceinline__ void gemm_phase(const Ctx& cx, const GemmArgs& g_, char* shm) {
;     ...
;               if (n0 >= C_GLAX) {
;                 const int i = n0 - C_GLAX;
;                 const float4 b4 = *(const float4*)(g.hin + i);
;                 float xs[4] = {a[0] + b4.x, a[1] + b4.y, a[2] + b4.z, a[3] + b4.w};
; #pragma unroll
;                 for (int j = 0; j < 4; ++j)
;                   xs[j] = (fminf(xs[j], 0.f) - __logf(1.0f + __expf(-fabsf(xs[j])))) * (1.0f / 16.0f);
;                 *(float4*)(g.f32buf + (size_t)tok * 1024 + i) = make_float4(xs[0], xs[1], xs[2], xs[3]);
;               } else {
;                 float o0 = a[0], o1 = a[1], o2 = a[2], o3 = a[3];
;                 const bool r128 = (n0 >= C_DSAQ && n0 < C_HGQ) || (n0 >= C_DSAK && n0 < C_DSAV);
;                 const bool r64 = (n0 >= C_IDXQ && n0 < C_GLAA);
;                 if (r128 || r64) {
;                   float4 cs;
;                   float sc;
;                   if (r128) {
;                     cs = *(const float4*)(g.w + ((size_t)tok * 64 + ((n0 & 127) >> 1)) * 2);
;                     sc = (n0 < C_HGQ) ? 0.08838834764831845f : 1.0f;
;                   } else {
;                     cs = *(const float4*)(g.hout + ((size_t)tok * 32 + ((n0 & 63) >> 1)) * 2);
;                     sc = (n0 < C_IDXK) ? 0.125f : 1.0f;
;                   }
;                   o0 = (a[0] * cs.x - a[1] * cs.y) * sc; o1 = (a[1] * cs.x + a[0] * cs.y) * sc;
;                   o2 = (a[2] * cs.z - a[3] * cs.w) * sc; o3 = (a[3] * cs.z + a[2] * cs.w) * sc;
;                 }
;                 uint2 o; o.x = pack2(o0, o1); o.y = pack2(o2, o3);
;                 EMIT_BF16(g.ldo, o);
.LBB0_1256:
	s_movk_i32 s0, 0x5c00
	v_cmp_gt_i32_e32 vcc, s0, v160
	s_and_saveexec_b64 s[2:3], vcc
	s_xor_b64 s[2:3], exec, s[2:3]
	s_cbranch_execz .LBB0_1264
	v_add_u32_e32 v2, 0xffffa780, v138
	v_cmp_gt_u32_e32 vcc, s77, v2
	s_or_b64 s[10:11], s[54:55], vcc
	s_and_saveexec_b64 s[8:9], s[10:11]
	s_cbranch_execz .LBB0_1263
	s_and_saveexec_b64 s[10:11], s[52:53]
	s_xor_b64 s[10:11], exec, s[10:11]
	v_lshlrev_b32_e32 v2, 2, v0
	s_movk_i32 s0, 0x5b00
	v_lshl_add_u64 v[16:17], v[48:49], 0, v[2:3]
	v_cmp_gt_u32_e32 vcc, s0, v120
	v_lshl_add_u64 v[16:17], v[16:17], 0, 64
	s_nop 0
	v_cndmask_b32_e32 v2, 1.0, v166, vcc
	s_andn2_saveexec_b64 s[10:11], s[10:11]
	v_and_b32_e32 v2, 0x5c, v160
	v_cmp_gt_i32_e32 vcc, s81, v160
	v_lshlrev_b32_e32 v2, 2, v2
	v_lshl_add_u64 v[16:17], v[44:45], 0, v[2:3]
	v_cndmask_b32_e32 v2, 1.0, v167, vcc
	s_or_b64 exec, exec, s[10:11]
	s_nop 0
	flat_load_dwordx4 v[16:19], v[16:17]
	s_waitcnt vmcnt(0) lgkmcnt(0)
	v_pk_mul_f32 v[20:21], v[12:13], v[16:17] op_sel:[1,1] op_sel_hi:[1,0]
	s_nop 0
	v_pk_fma_f32 v[28:29], v[12:13], v[16:17], v[20:21] neg_lo:[0,0,1] neg_hi:[0,0,1]
	v_pk_fma_f32 v[12:13], v[12:13], v[16:17], v[20:21] op_sel_hi:[0,1,1]
	v_mov_b32_e32 v16, v15
	v_pk_mul_f32 v[16:17], v[16:17], v[18:19] op_sel:[0,1] op_sel_hi:[0,0]
	v_pk_fma_f32 v[20:21], v[14:15], v[18:19], v[16:17] neg_lo:[0,0,1] neg_hi:[0,0,1]
	v_pk_fma_f32 v[14:15], v[14:15], v[18:19], v[16:17] op_sel_hi:[0,1,1]
	v_mov_b32_e32 v29, v13
	v_mov_b32_e32 v21, v15
	v_pk_mul_f32 v[12:13], v[2:3], v[28:29] op_sel_hi:[0,1]
	v_pk_mul_f32 v[14:15], v[2:3], v[20:21] op_sel_hi:[0,1]
.LBB0_1263:
	s_or_b64 exec, exec, s[8:9]
	v_cvt_pk_bf16_f32 v15, v14, v15
	v_cvt_pk_bf16_f32 v14, v12, v13
	v_mov_b32_e32 v12, v24
	v_mov_b32_e32 v13, v26
	v_ashrrev_i32_e32 v117, 31, v116
	v_permlane16_swap_b32_e32 v12, v14
	v_permlane16_swap_b32_e32 v13, v15
	v_lshl_add_u64 v[16:17], v[116:117], 1, v[52:53]
	s_nop 0
	flat_store_dwordx4 v[16:17], v[12:15] offset:32
.LBB0_1264:
	s_andn2_saveexec_b64 s[2:3], s[2:3]
	s_cbranch_execz .LBB0_1266
	v_add_u32_e32 v2, 0xffffa400, v160
	v_lshlrev_b64 v[20:21], 2, v[2:3]
	v_lshl_add_u64 v[16:17], s[26:27], 0, v[20:21]
	s_nop 0
	flat_load_dwordx4 v[16:19], v[16:17]
	s_mov_b32 s0, 0x3d800000
	v_lshl_add_u64 v[20:21], v[38:39], 0, v[20:21]
	s_waitcnt vmcnt(0) lgkmcnt(0)
	v_add_f32_e32 v2, v12, v16
	v_min_f32_e32 v12, 0, v2
	v_mul_f32_e64 v2, |v2|, s82
	v_exp_f32_e32 v2, v2
	v_add_f32_e32 v16, v13, v17
	v_add_f32_e32 v17, v14, v18
	v_add_f32_e32 v19, v15, v19
	v_add_f32_e32 v2, 1.0, v2
	v_cmp_gt_f32_e32 vcc, s83, v2
	s_nop 1
	v_cndmask_b32_e64 v13, 0, 32, vcc
	v_ldexp_f32 v2, v2, v13
	v_log_f32_e32 v2, v2
	s_nop 0
	v_mul_f32_e32 v13, 0x3f317217, v2
	v_fma_f32 v13, v2, s86, -v13
	v_fmac_f32_e32 v13, 0x3377d1cf, v2
	v_fmac_f32_e32 v13, 0x3f317217, v2
	v_cmp_lt_f32_e64 s[8:9], |v2|, s87
	s_nop 1
	v_cndmask_b32_e64 v2, v2, v13, s[8:9]
	v_cndmask_b32_e32 v13, 0, v165, vcc
	v_sub_f32_e32 v14, v2, v13
	v_mul_f32_e64 v2, |v16|, s82
	v_exp_f32_e32 v2, v2
	v_min_f32_e32 v13, 0, v16
	v_min_f32_e32 v16, 0, v17
	v_add_f32_e32 v2, 1.0, v2
	v_cmp_gt_f32_e32 vcc, s83, v2
	s_nop 1
	v_cndmask_b32_e64 v15, 0, 32, vcc
	v_ldexp_f32 v2, v2, v15
	v_log_f32_e32 v2, v2
	s_nop 0
	v_mul_f32_e32 v15, 0x3f317217, v2
	v_fma_f32 v15, v2, s86, -v15
	v_fmac_f32_e32 v15, 0x3377d1cf, v2
	v_fmac_f32_e32 v15, 0x3f317217, v2
	v_cmp_lt_f32_e64 s[8:9], |v2|, s87
	s_nop 1
	v_cndmask_b32_e64 v2, v2, v15, s[8:9]
	v_cndmask_b32_e32 v15, 0, v165, vcc
	v_sub_f32_e32 v15, v2, v15
	v_mul_f32_e64 v2, |v17|, s82
	v_exp_f32_e32 v2, v2
	v_pk_add_f32 v[12:13], v[12:13], v[14:15] neg_lo:[0,1] neg_hi:[0,1]
	v_add_f32_e32 v2, 1.0, v2
	v_cmp_gt_f32_e32 vcc, s83, v2
	v_pk_mul_f32 v[12:13], v[12:13], s[0:1] op_sel_hi:[1,0]
	s_nop 0
	v_cndmask_b32_e64 v17, 0, 32, vcc
	v_ldexp_f32 v2, v2, v17
	v_log_f32_e32 v2, v2
	s_nop 0
	v_mul_f32_e32 v17, 0x3f317217, v2
	v_fma_f32 v17, v2, s86, -v17
	v_fmac_f32_e32 v17, 0x3377d1cf, v2
	v_fmac_f32_e32 v17, 0x3f317217, v2
	v_cmp_lt_f32_e64 s[8:9], |v2|, s87
	s_nop 1
	v_cndmask_b32_e64 v2, v2, v17, s[8:9]
	v_cndmask_b32_e32 v17, 0, v165, vcc
	v_sub_f32_e32 v18, v2, v17
	v_mul_f32_e64 v2, |v19|, s82
	v_exp_f32_e32 v2, v2
	v_min_f32_e32 v17, 0, v19
	v_add_f32_e32 v2, 1.0, v2
	v_cmp_gt_f32_e32 vcc, s83, v2
	s_nop 1
	v_cndmask_b32_e64 v19, 0, 32, vcc
	v_ldexp_f32 v2, v2, v19
	v_log_f32_e32 v2, v2
	s_nop 0
	v_mul_f32_e32 v19, 0x3f317217, v2
	v_fma_f32 v19, v2, s86, -v19
	v_fmac_f32_e32 v19, 0x3377d1cf, v2
	v_fmac_f32_e32 v19, 0x3f317217, v2
	v_cmp_lt_f32_e64 s[8:9], |v2|, s87
	s_nop 1
	v_cndmask_b32_e64 v2, v2, v19, s[8:9]
	v_cndmask_b32_e32 v19, 0, v165, vcc
	v_sub_f32_e32 v19, v2, v19
	v_pk_add_f32 v[14:15], v[16:17], v[18:19] neg_lo:[0,1] neg_hi:[0,1]
	s_nop 0
	v_pk_mul_f32 v[14:15], v[14:15], s[0:1] op_sel_hi:[1,0]
	flat_store_dwordx4 v[20:21], v[12:15]

; __device__ __forceinline__ void gemm_phase(const Ctx& cx, const GemmArgs& g_, char* shm) {
;     ...
;             } else if (g.epi == EPI_RES) {
;               const float4 hv = *(const float4*)(g.hin + (size_t)tok * DM + n0);
;               const float h0 = hv.x + a[0], h1 = hv.y + a[1], h2 = hv.z + a[2], h3 = hv.w + a[3];
;               *(float4*)(g.hout + (size_t)tok * DM + n0) = make_float4(h0, h1, h2, h3);
;               if (g.w != nullptr) {
;                 const float4 nw = *(const float4*)(g.w + n0);
;                 uint2 o; o.x = pack2(h0 * nw.x, h1 * nw.y); o.y = pack2(h2 * nw.z, h3 * nw.w);
;                 EMIT_BF16(DM, o);
;                 ssq += h0 * h0 + h1 * h1 + h2 * h2 + h3 * h3;
;               }
.LBB0_1281:
	s_and_b64 vcc, exec, s[10:11]
	v_mov_b32_e32 v20, v22
	s_cbranch_vccz .LBB0_1284
	v_lshl_add_u64 v[18:19], v[120:121], 0, v[0:1]
	v_lshlrev_b64 v[12:13], 2, v[18:19]
	v_lshl_add_u64 v[14:15], v[42:43], 0, v[12:13]
	s_nop 0
	flat_load_dwordx4 v[14:17], v[14:15] offset:128
	v_lshl_add_u64 v[12:13], v[40:41], 0, v[12:13]
	s_andn2_b64 vcc, exec, s[42:43]
	v_mov_b32_e32 v20, v22
	s_waitcnt vmcnt(0) lgkmcnt(0)
	v_pk_add_f32 v[14:15], v[8:9], v[14:15]
	v_pk_add_f32 v[16:17], v[10:11], v[16:17]
	flat_store_dwordx4 v[12:13], v[14:17] offset:128
	v_mov_b32_e32 v13, v26
	v_mov_b32_e32 v12, v24
	s_cbranch_vccnz .LBB0_1284
	v_lshl_add_u64 v[12:13], v[18:19], 2, s[30:31]
	global_load_dwordx4 v[18:21], v[12:13], off offset:128
	v_pk_mul_f32 v[12:13], v[14:15], v[14:15]
	v_pk_mul_f32 v[28:29], v[16:17], v[16:17]
	v_add_f32_e32 v2, v12, v13
	v_add_f32_e32 v2, v2, v28
	v_add_f32_e32 v2, v2, v29
	s_waitcnt vmcnt(0)
	v_pk_mul_f32 v[12:13], v[16:17], v[20:21]
	v_pk_mul_f32 v[14:15], v[14:15], v[18:19]
	v_cvt_pk_bf16_f32 v13, v12, v13
	v_cvt_pk_bf16_f32 v12, v14, v15
	v_add_f32_e32 v20, v22, v2

; __device__ __forceinline__ float b2f(u16 b) { return __uint_as_float(((uint32_t)b) << 16); }
; __device__ __forceinline__ float sigmoidf_(float x) { return 1.0f / (1.0f + __expf(-x)); }
; __device__ __forceinline__ void gemm_phase(const Ctx& cx, const GemmArgs& g_, char* shm) {
;     ...
;               const uint2 gv = *(const uint2*)(g.gate + (size_t)tok * NP + n0);
;               float v0 = sigmoidf_(b2f((u16)(gv.x & 0xffff))) * a[0], v1 = sigmoidf_(b2f((u16)(gv.x >> 16))) * a[1];
;               float v2 = sigmoidf_(b2f((u16)(gv.y & 0xffff))) * a[2], v3 = sigmoidf_(b2f((u16)(gv.y >> 16))) * a[3];
;               uint2* mp = (uint2*)(g.outb + (size_t)tok * DM + n0);
;               if (g.epi != EPI_BR0) {
;                 const uint2 pv = *mp;
;                 v0 += b2f((u16)(pv.x & 0xffff)); v1 += b2f((u16)(pv.x >> 16));
;                 v2 += b2f((u16)(pv.y & 0xffff)); v3 += b2f((u16)(pv.y >> 16));
;               }
.LBB0_1286:
	v_lshl_add_u64 v[12:13], v[120:121], 0, v[0:1]
	v_lshlrev_b64 v[14:15], 1, v[12:13]
	v_lshl_add_u64 v[12:13], v[50:51], 0, v[14:15]
	s_nop 0
	flat_load_dwordx2 v[16:17], v[12:13] offset:64
	v_lshl_add_u64 v[14:15], v[36:37], 0, v[14:15]
	s_waitcnt vmcnt(0) lgkmcnt(0)
	v_lshlrev_b32_e32 v2, 16, v16
	v_mul_f32_e32 v2, 0xbfb8aa3b, v2
	v_exp_f32_e32 v12, v2
	v_and_b32_e32 v2, 0xffff0000, v16
	v_mul_f32_e32 v2, 0xbfb8aa3b, v2
	v_exp_f32_e32 v13, v2
	s_nop 0
	v_pk_add_f32 v[12:13], v[12:13], 1.0 op_sel_hi:[1,0]
	s_nop 0
	v_div_scale_f32 v2, s[2:3], v13, v13, 1.0
	v_rcp_f32_e32 v16, v2
	s_nop 0
	v_fma_f32 v18, -v2, v16, 1.0
	v_fmac_f32_e32 v16, v18, v16
	v_div_scale_f32 v18, vcc, 1.0, v13, 1.0
	v_mul_f32_e32 v19, v18, v16
	v_fma_f32 v20, -v2, v19, v18
	v_fmac_f32_e32 v19, v20, v16
	v_fma_f32 v2, -v2, v19, v18
	v_div_fmas_f32 v2, v2, v16, v19
	v_div_fixup_f32 v13, v2, v13, 1.0
	v_div_scale_f32 v2, s[2:3], v12, v12, 1.0
	v_rcp_f32_e32 v16, v2
	s_nop 0
	v_fma_f32 v18, -v2, v16, 1.0
	v_fmac_f32_e32 v16, v18, v16
	v_div_scale_f32 v18, vcc, 1.0, v12, 1.0
	v_mul_f32_e32 v19, v18, v16
	v_fma_f32 v20, -v2, v19, v18
	v_fmac_f32_e32 v19, v20, v16
	v_fma_f32 v2, -v2, v19, v18
	v_div_fmas_f32 v2, v2, v16, v19
	v_div_fixup_f32 v12, v2, v12, 1.0
	v_lshlrev_b32_e32 v2, 16, v17
	v_mul_f32_e32 v2, 0xbfb8aa3b, v2
	v_exp_f32_e32 v16, v2
	v_and_b32_e32 v2, 0xffff0000, v17
	v_mul_f32_e32 v2, 0xbfb8aa3b, v2
	v_exp_f32_e32 v17, v2
	v_pk_mul_f32 v[12:13], v[8:9], v[12:13]
	v_pk_add_f32 v[16:17], v[16:17], 1.0 op_sel_hi:[1,0]
	s_nop 0
	v_div_scale_f32 v2, s[2:3], v17, v17, 1.0
	v_rcp_f32_e32 v18, v2
	s_nop 0
	v_fma_f32 v19, -v2, v18, 1.0
	v_fmac_f32_e32 v18, v19, v18
	v_div_scale_f32 v19, vcc, 1.0, v17, 1.0
	v_mul_f32_e32 v20, v19, v18
	v_fma_f32 v21, -v2, v20, v19
	v_fmac_f32_e32 v20, v21, v18
	v_fma_f32 v2, -v2, v20, v19
	v_div_fmas_f32 v2, v2, v18, v20
	v_div_fixup_f32 v17, v2, v17, 1.0
	v_div_scale_f32 v2, s[2:3], v16, v16, 1.0
	v_rcp_f32_e32 v18, v2
	s_nop 0
	v_fma_f32 v19, -v2, v18, 1.0
	v_fmac_f32_e32 v18, v19, v18
	v_div_scale_f32 v19, vcc, 1.0, v16, 1.0
	v_mul_f32_e32 v20, v19, v18
	v_fma_f32 v21, -v2, v20, v19
	v_fmac_f32_e32 v20, v21, v18
	v_fma_f32 v2, -v2, v20, v19
	v_div_fmas_f32 v2, v2, v18, v20
	v_div_fixup_f32 v16, v2, v16, 1.0
	v_pk_mul_f32 v[16:17], v[10:11], v[16:17]
	s_and_b64 vcc, exec, s[4:5]
	s_cbranch_vccnz .LBB0_1288
	flat_load_dwordx2 v[18:19], v[14:15] offset:64
	s_waitcnt vmcnt(0) lgkmcnt(0)
	v_lshlrev_b32_e32 v20, 16, v18
	v_and_b32_e32 v21, 0xffff0000, v18
	v_lshlrev_b32_e32 v18, 16, v19
	v_and_b32_e32 v19, 0xffff0000, v19
	v_pk_add_f32 v[12:13], v[12:13], v[20:21]
	v_pk_add_f32 v[16:17], v[16:17], v[18:19]

; __device__ __forceinline__ void gemm_phase(const Ctx& cx, const GemmArgs& g_, char* shm) {
;     ...
;                 const bool r128 = (n0 >= C_DSAQ && n0 < C_HGQ) || (n0 >= C_DSAK && n0 < C_DSAV);
;                 const bool r64 = (n0 >= C_IDXQ && n0 < C_GLAA);
;                 if (r128 || r64) {
;                   float4 cs;
;                   float sc;
;                   if (r128) {
;                     cs = *(const float4*)(g.w + ((size_t)tok * 64 + ((n0 & 127) >> 1)) * 2);
;                     sc = (n0 < C_HGQ) ? 0.08838834764831845f : 1.0f;
;                   } else {
;                     cs = *(const float4*)(g.hout + ((size_t)tok * 32 + ((n0 & 63) >> 1)) * 2);
;                     sc = (n0 < C_IDXK) ? 0.125f : 1.0f;
;                   }
;                   o0 = (a[0] * cs.x - a[1] * cs.y) * sc; o1 = (a[1] * cs.x + a[0] * cs.y) * sc;
;                   o2 = (a[2] * cs.z - a[3] * cs.w) * sc; o3 = (a[3] * cs.z + a[2] * cs.w) * sc;
;                 }
.LBB0_1289:
	s_movk_i32 s0, 0x5c00
	v_cmp_gt_i32_e32 vcc, s0, v131
	s_and_saveexec_b64 s[2:3], vcc
	s_xor_b64 s[2:3], exec, s[2:3]
	s_cbranch_execz .LBB0_1297
	v_add_u32_e32 v2, 0xffffa780, v138
	v_cmp_gt_u32_e32 vcc, s77, v2
	s_or_b64 s[10:11], s[54:55], vcc
	s_and_saveexec_b64 s[8:9], s[10:11]
	s_cbranch_execz .LBB0_1296
	s_and_saveexec_b64 s[10:11], s[52:53]
	s_xor_b64 s[10:11], exec, s[10:11]
	v_lshlrev_b32_e32 v2, 2, v0
	s_movk_i32 s0, 0x5b00
	v_lshl_add_u64 v[12:13], v[48:49], 0, v[2:3]
	v_cmp_gt_u32_e32 vcc, s0, v120
	v_lshl_add_u64 v[12:13], v[12:13], 0, s[70:71]
	s_nop 0
	v_cndmask_b32_e32 v2, 1.0, v166, vcc
	s_andn2_saveexec_b64 s[10:11], s[10:11]
	v_and_b32_e32 v2, 0x6c, v131
	v_cmp_gt_i32_e32 vcc, s81, v131
	v_lshlrev_b32_e32 v2, 2, v2
	v_lshl_add_u64 v[12:13], v[44:45], 0, v[2:3]
	v_cndmask_b32_e32 v2, 1.0, v167, vcc
	s_or_b64 exec, exec, s[10:11]
	s_nop 0
	flat_load_dwordx4 v[12:15], v[12:13]
	s_waitcnt vmcnt(0) lgkmcnt(0)
	v_pk_mul_f32 v[16:17], v[8:9], v[12:13] op_sel:[1,1] op_sel_hi:[1,0]
	s_nop 0
	v_pk_fma_f32 v[18:19], v[8:9], v[12:13], v[16:17] neg_lo:[0,0,1] neg_hi:[0,0,1]
	v_pk_fma_f32 v[8:9], v[8:9], v[12:13], v[16:17] op_sel_hi:[0,1,1]
	v_mov_b32_e32 v12, v11
	v_pk_mul_f32 v[12:13], v[12:13], v[14:15] op_sel:[0,1] op_sel_hi:[0,0]
	v_pk_fma_f32 v[16:17], v[10:11], v[14:15], v[12:13] neg_lo:[0,0,1] neg_hi:[0,0,1]
	v_pk_fma_f32 v[10:11], v[10:11], v[14:15], v[12:13] op_sel_hi:[0,1,1]
	v_mov_b32_e32 v19, v9
	v_mov_b32_e32 v17, v11
	v_pk_mul_f32 v[8:9], v[2:3], v[18:19] op_sel_hi:[0,1]
	v_pk_mul_f32 v[10:11], v[2:3], v[16:17] op_sel_hi:[0,1]

; __device__ __forceinline__ void gemm_phase(const Ctx& cx, const GemmArgs& g_, char* shm) {
;     ...
;               if (n0 >= C_GLAX) {
;                 const int i = n0 - C_GLAX;
;                 const float4 b4 = *(const float4*)(g.hin + i);
;                 float xs[4] = {a[0] + b4.x, a[1] + b4.y, a[2] + b4.z, a[3] + b4.w};
; #pragma unroll
;                 for (int j = 0; j < 4; ++j)
;                   xs[j] = (fminf(xs[j], 0.f) - __logf(1.0f + __expf(-fabsf(xs[j])))) * (1.0f / 16.0f);
;                 *(float4*)(g.f32buf + (size_t)tok * 1024 + i) = make_float4(xs[0], xs[1], xs[2], xs[3]);
.LBB0_1297:
	s_andn2_saveexec_b64 s[2:3], s[2:3]
	s_cbranch_execz .LBB0_1299
	v_add_u32_e32 v2, 0xffffa400, v131
	v_lshlrev_b64 v[16:17], 2, v[2:3]
	v_lshl_add_u64 v[12:13], s[26:27], 0, v[16:17]
	s_nop 0
	flat_load_dwordx4 v[12:15], v[12:13]
	s_mov_b32 s0, 0x3d800000
	v_lshl_add_u64 v[16:17], v[38:39], 0, v[16:17]
	s_waitcnt vmcnt(0) lgkmcnt(0)
	v_add_f32_e32 v2, v8, v12
	v_min_f32_e32 v8, 0, v2
	v_mul_f32_e64 v2, |v2|, s82
	v_exp_f32_e32 v2, v2
	v_add_f32_e32 v12, v9, v13
	v_add_f32_e32 v13, v10, v14
	v_add_f32_e32 v15, v11, v15
	v_add_f32_e32 v2, 1.0, v2
	v_cmp_gt_f32_e32 vcc, s83, v2
	s_nop 1
	v_cndmask_b32_e64 v9, 0, 32, vcc
	v_ldexp_f32 v2, v2, v9
	v_log_f32_e32 v2, v2
	s_nop 0
	v_mul_f32_e32 v9, 0x3f317217, v2
	v_fma_f32 v9, v2, s86, -v9
	v_fmac_f32_e32 v9, 0x3377d1cf, v2
	v_fmac_f32_e32 v9, 0x3f317217, v2
	v_cmp_lt_f32_e64 s[8:9], |v2|, s87
	s_nop 1
	v_cndmask_b32_e64 v2, v2, v9, s[8:9]
	v_cndmask_b32_e32 v9, 0, v165, vcc
	v_sub_f32_e32 v10, v2, v9
	v_mul_f32_e64 v2, |v12|, s82
	v_exp_f32_e32 v2, v2
	v_min_f32_e32 v9, 0, v12
	v_min_f32_e32 v12, 0, v13
	v_add_f32_e32 v2, 1.0, v2
	v_cmp_gt_f32_e32 vcc, s83, v2
	s_nop 1
	v_cndmask_b32_e64 v11, 0, 32, vcc
	v_ldexp_f32 v2, v2, v11
	v_log_f32_e32 v2, v2
	s_nop 0
	v_mul_f32_e32 v11, 0x3f317217, v2
	v_fma_f32 v11, v2, s86, -v11
	v_fmac_f32_e32 v11, 0x3377d1cf, v2
	v_fmac_f32_e32 v11, 0x3f317217, v2
	v_cmp_lt_f32_e64 s[8:9], |v2|, s87
	s_nop 1
	v_cndmask_b32_e64 v2, v2, v11, s[8:9]
	v_cndmask_b32_e32 v11, 0, v165, vcc
	v_sub_f32_e32 v11, v2, v11
	v_mul_f32_e64 v2, |v13|, s82
	v_exp_f32_e32 v2, v2
	v_pk_add_f32 v[8:9], v[8:9], v[10:11] neg_lo:[0,1] neg_hi:[0,1]
	v_add_f32_e32 v2, 1.0, v2
	v_cmp_gt_f32_e32 vcc, s83, v2
	v_pk_mul_f32 v[8:9], v[8:9], s[0:1] op_sel_hi:[1,0]
	s_nop 0
	v_cndmask_b32_e64 v13, 0, 32, vcc
	v_ldexp_f32 v2, v2, v13
	v_log_f32_e32 v2, v2
	s_nop 0
	v_mul_f32_e32 v13, 0x3f317217, v2
	v_fma_f32 v13, v2, s86, -v13
	v_fmac_f32_e32 v13, 0x3377d1cf, v2
	v_fmac_f32_e32 v13, 0x3f317217, v2
	v_cmp_lt_f32_e64 s[8:9], |v2|, s87
	s_nop 1
	v_cndmask_b32_e64 v2, v2, v13, s[8:9]
	v_cndmask_b32_e32 v13, 0, v165, vcc
	v_sub_f32_e32 v14, v2, v13
	v_mul_f32_e64 v2, |v15|, s82
	v_exp_f32_e32 v2, v2
	v_min_f32_e32 v13, 0, v15
	v_add_f32_e32 v2, 1.0, v2
	v_cmp_gt_f32_e32 vcc, s83, v2
	s_nop 1
	v_cndmask_b32_e64 v15, 0, 32, vcc
	v_ldexp_f32 v2, v2, v15
	v_log_f32_e32 v2, v2
	s_nop 0
	v_mul_f32_e32 v15, 0x3f317217, v2
	v_fma_f32 v15, v2, s86, -v15
	v_fmac_f32_e32 v15, 0x3377d1cf, v2
	v_fmac_f32_e32 v15, 0x3f317217, v2
	v_cmp_lt_f32_e64 s[8:9], |v2|, s87
	s_nop 1
	v_cndmask_b32_e64 v2, v2, v15, s[8:9]
	v_cndmask_b32_e32 v15, 0, v165, vcc
	v_sub_f32_e32 v15, v2, v15
	v_pk_add_f32 v[10:11], v[12:13], v[14:15] neg_lo:[0,1] neg_hi:[0,1]
	v_mov_b32_e32 v13, v26
	v_pk_mul_f32 v[10:11], v[10:11], s[0:1] op_sel_hi:[1,0]
	v_mov_b32_e32 v12, v24
	flat_store_dwordx4 v[16:17], v[8:11]

; __device__ __forceinline__ void gemm_phase(const Ctx& cx, const GemmArgs& g_, char* shm) {
;     ...
;             } else if (g.epi == EPI_RELU2) {
;               float r0 = fmaxf(a[0], 0.f), r1 = fmaxf(a[1], 0.f), r2 = fmaxf(a[2], 0.f), r3 = fmaxf(a[3], 0.f);
;               uint2 o; o.x = pack2(r0 * r0, r1 * r1); o.y = pack2(r2 * r2, r3 * r3);
;               EMIT_BF16(g.ldo, o);
.LBB0_1309:
	s_cmp_gt_i32 s38, 4
	s_cbranch_scc0 .LBB0_1313
	s_cmp_eq_u32 s38, 5
	s_mov_b64 s[8:9], -1
	s_cbranch_scc0 .LBB0_1312
	v_max_f32_e32 v2, v6, v6
	v_max_f32_e32 v8, 0, v2
	v_max_f32_e32 v2, v7, v7
	v_max_f32_e32 v9, 0, v2
	v_pk_mul_f32 v[8:9], v[8:9], v[8:9]
	v_max_f32_e32 v2, v4, v4
	v_cvt_pk_bf16_f32 v11, v8, v9
	v_max_f32_e32 v8, 0, v2
	v_max_f32_e32 v2, v5, v5
	v_max_f32_e32 v9, 0, v2
	v_pk_mul_f32 v[8:9], v[8:9], v[8:9]
	v_ashrrev_i32_e32 v117, 31, v116
	v_cvt_pk_bf16_f32 v10, v8, v9
	v_mov_b32_e32 v8, v12
	v_mov_b32_e32 v9, v13
	s_nop 0
	v_permlane16_swap_b32_e32 v8, v10
	v_permlane16_swap_b32_e32 v9, v11
	v_lshl_add_u64 v[14:15], v[116:117], 1, v[52:53]
	s_nop 0
	flat_store_dwordx4 v[14:15], v[8:11] offset:96
	s_mov_b64 s[8:9], 0

; __device__ __forceinline__ void gemm_phase(const Ctx& cx, const GemmArgs& g_, char* shm) {
;     ...
;             } else if (g.epi == EPI_RES) {
;               const float4 hv = *(const float4*)(g.hin + (size_t)tok * DM + n0);
;               const float h0 = hv.x + a[0], h1 = hv.y + a[1], h2 = hv.z + a[2], h3 = hv.w + a[3];
;               *(float4*)(g.hout + (size_t)tok * DM + n0) = make_float4(h0, h1, h2, h3);
;               if (g.w != nullptr) {
;                 const float4 nw = *(const float4*)(g.w + n0);
;                 uint2 o; o.x = pack2(h0 * nw.x, h1 * nw.y); o.y = pack2(h2 * nw.z, h3 * nw.w);
;                 EMIT_BF16(DM, o);
;                 ssq += h0 * h0 + h1 * h1 + h2 * h2 + h3 * h3;
;               }
.LBB0_1313:
	s_and_b64 vcc, exec, s[10:11]
	v_mov_b32_e32 v2, v20
	s_cbranch_vccz .LBB0_1316
	v_lshl_add_u64 v[14:15], v[120:121], 0, v[0:1]
	v_lshlrev_b64 v[16:17], 2, v[14:15]
	v_lshl_add_u64 v[8:9], v[42:43], 0, v[16:17]
	s_nop 0
	flat_load_dwordx4 v[8:11], v[8:9] offset:192
	v_lshl_add_u64 v[16:17], v[40:41], 0, v[16:17]
	s_andn2_b64 vcc, exec, s[42:43]
	v_mov_b32_e32 v2, v20
	s_waitcnt vmcnt(0) lgkmcnt(0)
	v_pk_add_f32 v[8:9], v[4:5], v[8:9]
	v_pk_add_f32 v[10:11], v[6:7], v[10:11]
	flat_store_dwordx4 v[16:17], v[8:11] offset:192
	s_cbranch_vccnz .LBB0_1316
	v_lshl_add_u64 v[14:15], v[14:15], 2, s[30:31]
	global_load_dwordx4 v[14:17], v[14:15], off offset:192
	v_ashrrev_i32_e32 v117, 31, v116
	v_lshl_add_u64 v[18:19], v[116:117], 1, v[36:37]
	s_waitcnt vmcnt(0)
	v_pk_mul_f32 v[14:15], v[8:9], v[14:15]
	v_pk_mul_f32 v[8:9], v[8:9], v[8:9]
	v_pk_mul_f32 v[16:17], v[10:11], v[16:17]
	v_pk_mul_f32 v[10:11], v[10:11], v[10:11]
	v_add_f32_e32 v2, v8, v9
	v_cvt_pk_bf16_f32 v17, v16, v17
	v_cvt_pk_bf16_f32 v16, v14, v15
	v_mov_b32_e32 v14, v12
	v_mov_b32_e32 v15, v13
	v_add_f32_e32 v2, v2, v10
	v_permlane16_swap_b32_e32 v14, v16
	v_permlane16_swap_b32_e32 v15, v17
	v_add_f32_e32 v2, v2, v11
	flat_store_dwordx4 v[18:19], v[14:17] offset:96
	v_add_f32_e32 v2, v20, v2

; __device__ __forceinline__ float b2f(u16 b) { return __uint_as_float(((uint32_t)b) << 16); }
; __device__ __forceinline__ float sigmoidf_(float x) { return 1.0f / (1.0f + __expf(-x)); }
; __device__ __forceinline__ void gemm_phase(const Ctx& cx, const GemmArgs& g_, char* shm) {
;     ...
;               const uint2 gv = *(const uint2*)(g.gate + (size_t)tok * NP + n0);
;               float v0 = sigmoidf_(b2f((u16)(gv.x & 0xffff))) * a[0], v1 = sigmoidf_(b2f((u16)(gv.x >> 16))) * a[1];
;               float v2 = sigmoidf_(b2f((u16)(gv.y & 0xffff))) * a[2], v3 = sigmoidf_(b2f((u16)(gv.y >> 16))) * a[3];
;               uint2* mp = (uint2*)(g.outb + (size_t)tok * DM + n0);
;               if (g.epi != EPI_BR0) {
;                 const uint2 pv = *mp;
;                 v0 += b2f((u16)(pv.x & 0xffff)); v1 += b2f((u16)(pv.x >> 16));
;                 v2 += b2f((u16)(pv.y & 0xffff)); v3 += b2f((u16)(pv.y >> 16));
;               }
.LBB0_1318:
	v_lshl_add_u64 v[8:9], v[120:121], 0, v[0:1]
	v_lshlrev_b64 v[10:11], 1, v[8:9]
	v_lshl_add_u64 v[8:9], v[50:51], 0, v[10:11]
	s_nop 0
	flat_load_dwordx2 v[14:15], v[8:9] offset:96
	v_lshl_add_u64 v[10:11], v[36:37], 0, v[10:11]
	s_waitcnt vmcnt(0) lgkmcnt(0)
	v_lshlrev_b32_e32 v2, 16, v14
	v_mul_f32_e32 v2, 0xbfb8aa3b, v2
	v_exp_f32_e32 v8, v2
	v_and_b32_e32 v2, 0xffff0000, v14
	v_mul_f32_e32 v2, 0xbfb8aa3b, v2
	v_exp_f32_e32 v9, v2
	s_nop 0
	v_pk_add_f32 v[8:9], v[8:9], 1.0 op_sel_hi:[1,0]
	s_nop 0
	v_div_scale_f32 v2, s[2:3], v9, v9, 1.0
	v_rcp_f32_e32 v14, v2
	s_nop 0
	v_fma_f32 v16, -v2, v14, 1.0
	v_fmac_f32_e32 v14, v16, v14
	v_div_scale_f32 v16, vcc, 1.0, v9, 1.0
	v_mul_f32_e32 v17, v16, v14
	v_fma_f32 v18, -v2, v17, v16
	v_fmac_f32_e32 v17, v18, v14
	v_fma_f32 v2, -v2, v17, v16
	v_div_fmas_f32 v2, v2, v14, v17
	v_div_fixup_f32 v9, v2, v9, 1.0
	v_div_scale_f32 v2, s[2:3], v8, v8, 1.0
	v_rcp_f32_e32 v14, v2
	s_nop 0
	v_fma_f32 v16, -v2, v14, 1.0
	v_fmac_f32_e32 v14, v16, v14
	v_div_scale_f32 v16, vcc, 1.0, v8, 1.0
	v_mul_f32_e32 v17, v16, v14
	v_fma_f32 v18, -v2, v17, v16
	v_fmac_f32_e32 v17, v18, v14
	v_fma_f32 v2, -v2, v17, v16
	v_div_fmas_f32 v2, v2, v14, v17
	v_div_fixup_f32 v8, v2, v8, 1.0
	v_lshlrev_b32_e32 v2, 16, v15
	v_mul_f32_e32 v2, 0xbfb8aa3b, v2
	v_exp_f32_e32 v14, v2
	v_and_b32_e32 v2, 0xffff0000, v15
	v_mul_f32_e32 v2, 0xbfb8aa3b, v2
	v_exp_f32_e32 v15, v2
	v_pk_mul_f32 v[8:9], v[4:5], v[8:9]
	v_pk_add_f32 v[14:15], v[14:15], 1.0 op_sel_hi:[1,0]
	s_nop 0
	v_div_scale_f32 v2, s[2:3], v15, v15, 1.0
	v_rcp_f32_e32 v16, v2
	s_nop 0
	v_fma_f32 v17, -v2, v16, 1.0
	v_fmac_f32_e32 v16, v17, v16
	v_div_scale_f32 v17, vcc, 1.0, v15, 1.0
	v_mul_f32_e32 v18, v17, v16
	v_fma_f32 v19, -v2, v18, v17
	v_fmac_f32_e32 v18, v19, v16
	v_fma_f32 v2, -v2, v18, v17
	v_div_fmas_f32 v2, v2, v16, v18
	v_div_fixup_f32 v15, v2, v15, 1.0
	v_div_scale_f32 v2, s[2:3], v14, v14, 1.0
	v_rcp_f32_e32 v16, v2
	s_nop 0
	v_fma_f32 v17, -v2, v16, 1.0
	v_fmac_f32_e32 v16, v17, v16
	v_div_scale_f32 v17, vcc, 1.0, v14, 1.0
	v_mul_f32_e32 v18, v17, v16
	v_fma_f32 v19, -v2, v18, v17
	v_fmac_f32_e32 v18, v19, v16
	v_fma_f32 v2, -v2, v18, v17
	v_div_fmas_f32 v2, v2, v16, v18
	v_div_fixup_f32 v14, v2, v14, 1.0
	v_pk_mul_f32 v[14:15], v[6:7], v[14:15]
	s_and_b64 vcc, exec, s[4:5]
	s_cbranch_vccnz .LBB0_1320
	flat_load_dwordx2 v[16:17], v[10:11] offset:96
	s_waitcnt vmcnt(0) lgkmcnt(0)
	v_lshlrev_b32_e32 v18, 16, v16
	v_and_b32_e32 v19, 0xffff0000, v16
	v_lshlrev_b32_e32 v16, 16, v17
	v_and_b32_e32 v17, 0xffff0000, v17
	v_pk_add_f32 v[8:9], v[8:9], v[18:19]
	v_pk_add_f32 v[14:15], v[14:15], v[16:17]

; __device__ __forceinline__ void gemm_phase(const Ctx& cx, const GemmArgs& g_, char* shm) {
;     ...
;               if (n0 >= C_GLAX) {
;                 const int i = n0 - C_GLAX;
;                 const float4 b4 = *(const float4*)(g.hin + i);
;                 float xs[4] = {a[0] + b4.x, a[1] + b4.y, a[2] + b4.z, a[3] + b4.w};
; #pragma unroll
;                 for (int j = 0; j < 4; ++j)
;                   xs[j] = (fminf(xs[j], 0.f) - __logf(1.0f + __expf(-fabsf(xs[j])))) * (1.0f / 16.0f);
;                 *(float4*)(g.f32buf + (size_t)tok * 1024 + i) = make_float4(xs[0], xs[1], xs[2], xs[3]);
;               } else {
;                 float o0 = a[0], o1 = a[1], o2 = a[2], o3 = a[3];
;                 const bool r128 = (n0 >= C_DSAQ && n0 < C_HGQ) || (n0 >= C_DSAK && n0 < C_DSAV);
;                 const bool r64 = (n0 >= C_IDXQ && n0 < C_GLAA);
;                 if (r128 || r64) {
;                   float4 cs;
;                   float sc;
;                   if (r128) {
;                     cs = *(const float4*)(g.w + ((size_t)tok * 64 + ((n0 & 127) >> 1)) * 2);
;                     sc = (n0 < C_HGQ) ? 0.08838834764831845f : 1.0f;
;                   } else {
;                     cs = *(const float4*)(g.hout + ((size_t)tok * 32 + ((n0 & 63) >> 1)) * 2);
;                     sc = (n0 < C_IDXK) ? 0.125f : 1.0f;
;                   }
;                   o0 = (a[0] * cs.x - a[1] * cs.y) * sc; o1 = (a[1] * cs.x + a[0] * cs.y) * sc;
;                   o2 = (a[2] * cs.z - a[3] * cs.w) * sc; o3 = (a[3] * cs.z + a[2] * cs.w) * sc;
;                 }
;                 uint2 o; o.x = pack2(o0, o1); o.y = pack2(o2, o3);
;                 EMIT_BF16(g.ldo, o);
.LBB0_1321:
	s_movk_i32 s0, 0x5c00
	v_cmp_gt_i32_e32 vcc, s0, v130
	s_and_saveexec_b64 s[2:3], vcc
	s_xor_b64 s[2:3], exec, s[2:3]
	s_cbranch_execz .LBB0_1329
	v_add_u32_e32 v2, 0xffffa780, v138
	v_cmp_gt_u32_e32 vcc, s77, v2
	s_or_b64 s[8:9], s[54:55], vcc
	s_and_saveexec_b64 s[4:5], s[8:9]
	s_cbranch_execz .LBB0_1328
	s_and_saveexec_b64 s[8:9], s[52:53]
	s_xor_b64 s[8:9], exec, s[8:9]
	v_lshlrev_b32_e32 v2, 2, v0
	s_movk_i32 s0, 0x5b00
	v_lshl_add_u64 v[8:9], v[48:49], 0, v[2:3]
	s_mov_b64 s[10:11], 0xc0
	v_cmp_gt_u32_e32 vcc, s0, v120
	v_lshl_add_u64 v[8:9], v[8:9], 0, s[10:11]
	s_nop 0
	v_cndmask_b32_e32 v2, 1.0, v166, vcc
	s_andn2_saveexec_b64 s[8:9], s[8:9]
	v_and_b32_e32 v2, 0x7c, v130
	v_cmp_gt_i32_e32 vcc, s81, v130
	v_lshlrev_b32_e32 v2, 2, v2
	v_lshl_add_u64 v[8:9], v[44:45], 0, v[2:3]
	v_cndmask_b32_e32 v2, 1.0, v167, vcc
	s_or_b64 exec, exec, s[8:9]
	s_nop 0
	flat_load_dwordx4 v[8:11], v[8:9]
	s_waitcnt vmcnt(0) lgkmcnt(0)
	v_pk_mul_f32 v[14:15], v[4:5], v[8:9] op_sel:[1,1] op_sel_hi:[1,0]
	s_nop 0
	v_pk_fma_f32 v[16:17], v[4:5], v[8:9], v[14:15] neg_lo:[0,0,1] neg_hi:[0,0,1]
	v_pk_fma_f32 v[4:5], v[4:5], v[8:9], v[14:15] op_sel_hi:[0,1,1]
	v_mov_b32_e32 v8, v7
	v_pk_mul_f32 v[8:9], v[8:9], v[10:11] op_sel:[0,1] op_sel_hi:[0,0]
	v_pk_fma_f32 v[14:15], v[6:7], v[10:11], v[8:9] neg_lo:[0,0,1] neg_hi:[0,0,1]
	v_pk_fma_f32 v[6:7], v[6:7], v[10:11], v[8:9] op_sel_hi:[0,1,1]
	v_mov_b32_e32 v17, v5
	v_mov_b32_e32 v15, v7
	v_pk_mul_f32 v[4:5], v[2:3], v[16:17] op_sel_hi:[0,1]
	v_pk_mul_f32 v[6:7], v[2:3], v[14:15] op_sel_hi:[0,1]
.LBB0_1328:
	s_or_b64 exec, exec, s[4:5]
	v_cvt_pk_bf16_f32 v2, v6, v7
	v_cvt_pk_bf16_f32 v6, v4, v5
	s_nop 1
	v_permlane16_swap_b32_e32 v12, v6
	v_permlane16_swap_b32_e32 v13, v2
	v_ashrrev_i32_e32 v117, 31, v116
	v_lshl_add_u64 v[4:5], v[116:117], 1, v[52:53]
	v_mov_b32_e32 v14, v6
	v_mov_b32_e32 v15, v2
	s_nop 0
	flat_store_dwordx4 v[4:5], v[12:15] offset:96
.LBB0_1329:
	s_andn2_saveexec_b64 s[2:3], s[2:3]
	s_cbranch_execz .LBB0_1331
	v_add_u32_e32 v2, 0xffffa400, v130
	v_lshlrev_b64 v[12:13], 2, v[2:3]
	v_lshl_add_u64 v[8:9], s[26:27], 0, v[12:13]
	s_nop 0
	flat_load_dwordx4 v[8:11], v[8:9]
	s_mov_b32 s0, 0x3d800000
	v_lshl_add_u64 v[12:13], v[38:39], 0, v[12:13]
	s_waitcnt vmcnt(0) lgkmcnt(0)
	v_add_f32_e32 v2, v4, v8
	v_min_f32_e32 v4, 0, v2
	v_mul_f32_e64 v2, |v2|, s82
	v_exp_f32_e32 v2, v2
	v_add_f32_e32 v8, v5, v9
	v_add_f32_e32 v9, v6, v10
	v_add_f32_e32 v11, v7, v11
	v_add_f32_e32 v2, 1.0, v2
	v_cmp_gt_f32_e32 vcc, s83, v2
	s_nop 1
	v_cndmask_b32_e64 v5, 0, 32, vcc
	v_ldexp_f32 v2, v2, v5
	v_log_f32_e32 v2, v2
	s_nop 0
	v_mul_f32_e32 v5, 0x3f317217, v2
	v_fma_f32 v5, v2, s86, -v5
	v_fmac_f32_e32 v5, 0x3377d1cf, v2
	v_fmac_f32_e32 v5, 0x3f317217, v2
	v_cmp_lt_f32_e64 s[4:5], |v2|, s87
	s_nop 1
	v_cndmask_b32_e64 v2, v2, v5, s[4:5]
	v_cndmask_b32_e32 v5, 0, v165, vcc
	v_sub_f32_e32 v6, v2, v5
	v_mul_f32_e64 v2, |v8|, s82
	v_exp_f32_e32 v2, v2
	v_min_f32_e32 v5, 0, v8
	v_min_f32_e32 v8, 0, v9
	v_add_f32_e32 v2, 1.0, v2
	v_cmp_gt_f32_e32 vcc, s83, v2
	s_nop 1
	v_cndmask_b32_e64 v7, 0, 32, vcc
	v_ldexp_f32 v2, v2, v7
	v_log_f32_e32 v2, v2
	s_nop 0
	v_mul_f32_e32 v7, 0x3f317217, v2
	v_fma_f32 v7, v2, s86, -v7
	v_fmac_f32_e32 v7, 0x3377d1cf, v2
	v_fmac_f32_e32 v7, 0x3f317217, v2
	v_cmp_lt_f32_e64 s[4:5], |v2|, s87
	s_nop 1
	v_cndmask_b32_e64 v2, v2, v7, s[4:5]
	v_cndmask_b32_e32 v7, 0, v165, vcc
	v_sub_f32_e32 v7, v2, v7
	v_mul_f32_e64 v2, |v9|, s82
	v_exp_f32_e32 v2, v2
	v_pk_add_f32 v[4:5], v[4:5], v[6:7] neg_lo:[0,1] neg_hi:[0,1]
	v_add_f32_e32 v2, 1.0, v2
	v_cmp_gt_f32_e32 vcc, s83, v2
	v_pk_mul_f32 v[4:5], v[4:5], s[0:1] op_sel_hi:[1,0]
	s_nop 0
	v_cndmask_b32_e64 v9, 0, 32, vcc
	v_ldexp_f32 v2, v2, v9
	v_log_f32_e32 v2, v2
	s_nop 0
	v_mul_f32_e32 v9, 0x3f317217, v2
	v_fma_f32 v9, v2, s86, -v9
	v_fmac_f32_e32 v9, 0x3377d1cf, v2
	v_fmac_f32_e32 v9, 0x3f317217, v2
	v_cmp_lt_f32_e64 s[4:5], |v2|, s87
	s_nop 1
	v_cndmask_b32_e64 v2, v2, v9, s[4:5]
	v_cndmask_b32_e32 v9, 0, v165, vcc
	v_sub_f32_e32 v10, v2, v9
	v_mul_f32_e64 v2, |v11|, s82
	v_exp_f32_e32 v2, v2
	v_min_f32_e32 v9, 0, v11
	v_add_f32_e32 v2, 1.0, v2
	v_cmp_gt_f32_e32 vcc, s83, v2
	s_nop 1
	v_cndmask_b32_e64 v11, 0, 32, vcc
	v_ldexp_f32 v2, v2, v11
	v_log_f32_e32 v2, v2
	s_nop 0
	v_mul_f32_e32 v11, 0x3f317217, v2
	v_fma_f32 v11, v2, s86, -v11
	v_fmac_f32_e32 v11, 0x3377d1cf, v2
	v_fmac_f32_e32 v11, 0x3f317217, v2
	v_cmp_lt_f32_e64 s[4:5], |v2|, s87
	s_nop 1
	v_cndmask_b32_e64 v2, v2, v11, s[4:5]
	v_cndmask_b32_e32 v11, 0, v165, vcc
	v_sub_f32_e32 v11, v2, v11
	v_pk_add_f32 v[6:7], v[8:9], v[10:11] neg_lo:[0,1] neg_hi:[0,1]
	s_nop 0
	v_pk_mul_f32 v[6:7], v[6:7], s[0:1] op_sel_hi:[1,0]
	flat_store_dwordx4 v[12:13], v[4:7]

; __device__ __forceinline__ void gemm_phase(const Ctx& cx, const GemmArgs& g_, char* shm) {
;     ...
;         if (g.epi == EPI_RES && g.w != nullptr) {
;           float v2 = ssq;
;           v2 += shx(lane, v2, 16);
;           v2 += shx(lane, v2, 32);
;           if (fq == 0) __hip_atomic_fetch_add(g.f32buf + tok, v2, __ATOMIC_RELAXED, __HIP_MEMORY_SCOPE_AGENT);
;         }
.LBB0_1332:
	ds_bpermute_b32 v4, v171, v2
	s_waitcnt lgkmcnt(0)
	v_add_f32_e32 v2, v2, v4
	ds_bpermute_b32 v4, v172, v2
	s_and_saveexec_b64 s[2:3], s[12:13]
	s_cbranch_execz .LBB0_230
	s_waitcnt lgkmcnt(0)
	v_add_f32_e32 v2, v2, v4
	v_lshl_add_u64 v[4:5], v[136:137], 2, s[24:25]
	s_nop 0
	flat_atomic_add_f32 v[4:5], v2 offset:576
	s_branch .LBB0_230
